# loop-edge edit: GEMM K-loop counter/compare SALU moved ahead of the loop-back barrier; one static s_setprio 1 for waves 4-7 in the attention phase
# baseline (speedup 1.0000x reference)
; #define PG8_STAGE(bufoff, gbase, voff) do { _Pragma("unroll") for (int _i = 0; _i < 2; ++_i) \
;         __builtin_amdgcn_global_load_lds((const unsigned*)((const char*)(gbase) + (voff)[_i]), (PG8_LAS unsigned*)(lds + (bufoff) + ldsw + _i * 8192), 16, 0, 0); } while (0)
; #define PG8_LDA(dst, b, h) do { _Pragma("unroll") for (int m = 0; m < 4; ++m) _Pragma("unroll") for (int k = 0; k < 2; ++k) dst[m][k] = *(const PG8_LAS bf16x8*)(lds + PG8_SA(b, h) + aoff + m * 2048 + k * 1024); } while (0)
; #define PG8_LDB(dst, b, h) do { _Pragma("unroll") for (int n = 0; n < 2; ++n) _Pragma("unroll") for (int k = 0; k < 2; ++k) dst[n][k] = *(const PG8_LAS bf16x8*)(lds + PG8_SB(b, h) + boff + n * 2048 + k * 1024); } while (0)
; #define PG8_MMA(ai, bj, At, Bt) do { __builtin_amdgcn_s_setprio(1); _Pragma("unroll") for (int m = 0; m < 4; ++m) _Pragma("unroll") for (int n = 0; n < 2; ++n) _Pragma("unroll") for (int k = 0; k < 2; ++k) \
;         acc[ai][bj][m][n] = __builtin_amdgcn_mfma_f32_16x16x32_bf16(Bt[n][k], At[m][k], acc[ai][bj][m][n], 0, 0, 0); __builtin_amdgcn_s_setprio(0); } while (0)
; #define PG8_WAIT_V(n) asm volatile("s_waitcnt vmcnt(" #n ")" ::: "memory")
; #define PG8_WAIT_L(n) asm volatile("s_waitcnt lgkmcnt(" #n ")" ::: "memory")
; #define PG8_BAR __builtin_amdgcn_s_barrier()
; #define PG8_SCHED __builtin_amdgcn_sched_barrier(0)
; template <class Epi, class Sched, bool ALIGN_EPI = false, bool SP2 = false>
; __device__ __forceinline__ void gemm_phase(PG8_LAS unsigned char* lds, const Gemm g, const Sched& S, const Epi& E) {
;     ...
;             const char* a2 = last ? nA : cA + (size_t)(t + 2) * kstep; const char* b2 = last ? nB : cB + (size_t)(t + 2) * kstep;
;             const char* a3 = a2 + kstep; const char* b3 = b2 + kstep;
;             if (last && has_next) S.a_ready(nxt);
;             if constexpr (SP2) {
;             PG8_LDB(B0, 0, 0); PG8_LDB(B1, 0, 1); PG8_SCHED; PG8_LDA(At, 0, 0); PG8_STAGE(PG8_SA(1, 1), a1 + hstep, voffA);
;             PG8_WAIT_V(8); PG8_WAIT_L(0); PG8_BAR; PG8_MMA(0, 0, At, B0); PG8_MMA(0, 1, At, B1); PG8_BAR; PG8_SCHED;
;             PG8_LDA(At, 0, 1); PG8_STAGE(PG8_SB(0, 0), b2, voffB); PG8_STAGE(PG8_SB(0, 1), b2 + hstep, voffB); PG8_STAGE(PG8_SA(0, 0), a2, voffA);
;             PG8_WAIT_V(8); PG8_WAIT_L(0); PG8_BAR; PG8_MMA(1, 0, At, B0); PG8_MMA(1, 1, At, B1); PG8_BAR; PG8_SCHED;
.LBB0_192:
	ds_read_b128 v[48:51], v169
	ds_read_b128 v[52:55], v169 offset:1024
	ds_read_b128 v[64:67], v169 offset:2048
	ds_read_b128 v[68:71], v169 offset:3072
	ds_read_b128 v[160:163], v170
	ds_read_b128 v[172:175], v170 offset:1024
	ds_read_b128 v[176:179], v170 offset:2048
	ds_read_b128 v[180:183], v170 offset:3072
	s_add_u32 s66, s6, 0xfff80080
	s_addc_u32 s67, s7, -1
	s_cmp_eq_u32 s88, 28
	s_cselect_b32 s69, s55, s67
	s_cselect_b32 s68, s84, s66
	s_cselect_b32 s67, s57, s87
	s_cselect_b32 s66, s85, s86
	v_lshl_add_u64 v[164:165], s[6:7], 0, v[154:155]
	s_add_i32 m0, s63, 0xc000
	ds_read_b128 v[184:187], v171
	ds_read_b128 v[188:191], v171 offset:1024
	ds_read_b128 v[194:197], v171 offset:2048
	ds_read_b128 v[198:201], v171 offset:3072
	ds_read_b128 v[202:205], v171 offset:4096
	ds_read_b128 v[206:209], v171 offset:5120
	ds_read_b128 v[210:213], v171 offset:6144
	ds_read_b128 v[214:217], v171 offset:7168
	global_load_lds_dwordx4 v[164:165], off
	v_lshl_add_u64 v[164:165], s[6:7], 0, v[152:153]
	s_add_i32 m0, s63, 0xe000
	s_nop 0
	global_load_lds_dwordx4 v[164:165], off
	s_waitcnt vmcnt(8)
	s_waitcnt lgkmcnt(0)
	s_barrier
	s_setprio 1
	s_waitcnt lgkmcnt(0)
	v_mfma_f32_16x16x32_bf16 v[140:143], v[48:51], v[184:187], v[140:143]
	v_mfma_f32_16x16x32_bf16 v[136:139], v[64:67], v[184:187], v[136:139]
	v_mfma_f32_16x16x32_bf16 v[124:127], v[48:51], v[194:197], v[124:127]
	v_mfma_f32_16x16x32_bf16 v[120:123], v[64:67], v[194:197], v[120:123]
	v_mfma_f32_16x16x32_bf16 v[108:111], v[48:51], v[202:205], v[108:111]
	v_mfma_f32_16x16x32_bf16 v[104:107], v[64:67], v[202:205], v[104:107]
	v_mfma_f32_16x16x32_bf16 v[92:95], v[48:51], v[210:213], v[92:95]
	v_mfma_f32_16x16x32_bf16 v[88:91], v[64:67], v[210:213], v[88:91]
	v_mfma_f32_16x16x32_bf16 v[140:143], v[52:55], v[188:191], v[140:143]
	v_mfma_f32_16x16x32_bf16 v[136:139], v[68:71], v[188:191], v[136:139]
	v_mfma_f32_16x16x32_bf16 v[124:127], v[52:55], v[198:201], v[124:127]
	v_mfma_f32_16x16x32_bf16 v[120:123], v[68:71], v[198:201], v[120:123]
	v_mfma_f32_16x16x32_bf16 v[108:111], v[52:55], v[206:209], v[108:111]
	v_mfma_f32_16x16x32_bf16 v[104:107], v[68:71], v[206:209], v[104:107]
	v_mfma_f32_16x16x32_bf16 v[92:95], v[52:55], v[214:217], v[92:95]
	v_mfma_f32_16x16x32_bf16 v[88:91], v[68:71], v[214:217], v[88:91]
	s_setprio 0
	s_setprio 1
	v_mfma_f32_16x16x32_bf16 v[132:135], v[160:163], v[184:187], v[132:135]
	v_mfma_f32_16x16x32_bf16 v[128:131], v[176:179], v[184:187], v[128:131]
	v_mfma_f32_16x16x32_bf16 v[116:119], v[160:163], v[194:197], v[116:119]
	v_mfma_f32_16x16x32_bf16 v[112:115], v[176:179], v[194:197], v[112:115]
	v_mfma_f32_16x16x32_bf16 v[100:103], v[160:163], v[202:205], v[100:103]
	v_mfma_f32_16x16x32_bf16 v[96:99], v[176:179], v[202:205], v[96:99]
	v_mfma_f32_16x16x32_bf16 v[84:87], v[160:163], v[210:213], v[84:87]
	v_mfma_f32_16x16x32_bf16 v[80:83], v[176:179], v[210:213], v[80:83]
	v_mfma_f32_16x16x32_bf16 v[132:135], v[172:175], v[188:191], v[132:135]
	v_mfma_f32_16x16x32_bf16 v[128:131], v[180:183], v[188:191], v[128:131]
	v_mfma_f32_16x16x32_bf16 v[116:119], v[172:175], v[198:201], v[116:119]
	v_mfma_f32_16x16x32_bf16 v[112:115], v[180:183], v[198:201], v[112:115]
	v_mfma_f32_16x16x32_bf16 v[100:103], v[172:175], v[206:209], v[100:103]
	v_mfma_f32_16x16x32_bf16 v[96:99], v[180:183], v[206:209], v[96:99]
	v_mfma_f32_16x16x32_bf16 v[84:87], v[172:175], v[214:217], v[84:87]
	v_mfma_f32_16x16x32_bf16 v[80:83], v[180:183], v[214:217], v[80:83]
	s_setprio 0
	s_barrier
	s_add_i32 s89, s78, s37
	v_lshl_add_u64 v[164:165], s[66:67], 0, v[146:147]
	s_mov_b32 m0, s89
	ds_read_b128 v[184:187], v171 offset:16384
	ds_read_b128 v[188:191], v171 offset:17408
	ds_read_b128 v[194:197], v171 offset:18432
	ds_read_b128 v[198:201], v171 offset:19456
	ds_read_b128 v[202:205], v171 offset:20480
	ds_read_b128 v[206:209], v171 offset:21504
	ds_read_b128 v[210:213], v171 offset:22528
	ds_read_b128 v[214:217], v171 offset:23552
	global_load_lds_dwordx4 v[164:165], off
	s_add_i32 m0, s89, 0x2000
	s_add_u32 s90, s66, 0x80000
	v_lshl_add_u64 v[218:219], s[66:67], 0, v[150:151]
	s_addc_u32 s91, s67, 0
	s_add_i32 s89, s79, s37
	global_load_lds_dwordx4 v[218:219], off
	v_lshl_add_u64 v[220:221], s[90:91], 0, v[146:147]
	s_mov_b32 m0, s89
	v_lshl_add_u64 v[222:223], s[68:69], 0, v[148:149]
	global_load_lds_dwordx4 v[220:221], off
	v_lshl_add_u64 v[220:221], s[90:91], 0, v[150:151]
	s_add_i32 m0, s89, 0x2000
	s_nop 0
	global_load_lds_dwordx4 v[220:221], off
	v_lshl_add_u64 v[220:221], s[68:69], 0, v[144:145]
	s_mov_b32 m0, s63
	s_nop 0
	global_load_lds_dwordx4 v[220:221], off
	s_mov_b32 m0, s65
	s_nop 0
	global_load_lds_dwordx4 v[222:223], off
	s_waitcnt vmcnt(8)
	s_waitcnt lgkmcnt(0)
	s_barrier
; #define PG8_STAGE(bufoff, gbase, voff) do { _Pragma("unroll") for (int _i = 0; _i < 2; ++_i) \
;         __builtin_amdgcn_global_load_lds((const unsigned*)((const char*)(gbase) + (voff)[_i]), (PG8_LAS unsigned*)(lds + (bufoff) + ldsw + _i * 8192), 16, 0, 0); } while (0)
; #define PG8_LDA(dst, b, h) do { _Pragma("unroll") for (int m = 0; m < 4; ++m) _Pragma("unroll") for (int k = 0; k < 2; ++k) dst[m][k] = *(const PG8_LAS bf16x8*)(lds + PG8_SA(b, h) + aoff + m * 2048 + k * 1024); } while (0)
; #define PG8_LDB(dst, b, h) do { _Pragma("unroll") for (int n = 0; n < 2; ++n) _Pragma("unroll") for (int k = 0; k < 2; ++k) dst[n][k] = *(const PG8_LAS bf16x8*)(lds + PG8_SB(b, h) + boff + n * 2048 + k * 1024); } while (0)
; #define PG8_MMA(ai, bj, At, Bt) do { __builtin_amdgcn_s_setprio(1); _Pragma("unroll") for (int m = 0; m < 4; ++m) _Pragma("unroll") for (int n = 0; n < 2; ++n) _Pragma("unroll") for (int k = 0; k < 2; ++k) \
;         acc[ai][bj][m][n] = __builtin_amdgcn_mfma_f32_16x16x32_bf16(Bt[n][k], At[m][k], acc[ai][bj][m][n], 0, 0, 0); __builtin_amdgcn_s_setprio(0); } while (0)
; #define PG8_WAIT_V(n) asm volatile("s_waitcnt vmcnt(" #n ")" ::: "memory")
; #define PG8_WAIT_L(n) asm volatile("s_waitcnt lgkmcnt(" #n ")" ::: "memory")
; #define PG8_BAR __builtin_amdgcn_s_barrier()
; #define PG8_SCHED __builtin_amdgcn_sched_barrier(0)
; template <class Epi, class Sched, bool ALIGN_EPI = false, bool SP2 = false>
; __device__ __forceinline__ void gemm_phase(PG8_LAS unsigned char* lds, const Gemm g, const Sched& S, const Epi& E) {
;     ...
;             PG8_WAIT_V(8); PG8_WAIT_L(0); PG8_BAR; PG8_MMA(1, 0, At, B0); PG8_MMA(1, 1, At, B1); PG8_BAR; PG8_SCHED;
;             PG8_LDB(B0, 1, 0); PG8_LDB(B1, 1, 1); PG8_SCHED; PG8_LDA(At, 1, 0); PG8_STAGE(PG8_SA(0, 1), a2 + hstep, voffA);
;             PG8_WAIT_V(8); PG8_WAIT_L(0); PG8_BAR; PG8_MMA(0, 0, At, B0); PG8_MMA(0, 1, At, B1); PG8_BAR; PG8_SCHED;
	s_setprio 1
	s_waitcnt lgkmcnt(0)
	v_mfma_f32_16x16x32_bf16 v[76:79], v[48:51], v[184:187], v[76:79]
	v_mfma_f32_16x16x32_bf16 v[72:75], v[64:67], v[184:187], v[72:75]
	v_mfma_f32_16x16x32_bf16 v[44:47], v[48:51], v[194:197], v[44:47]
	v_mfma_f32_16x16x32_bf16 v[40:43], v[64:67], v[194:197], v[40:43]
	v_mfma_f32_16x16x32_bf16 v[28:31], v[48:51], v[202:205], v[28:31]
	v_mfma_f32_16x16x32_bf16 v[24:27], v[64:67], v[202:205], v[24:27]
	v_mfma_f32_16x16x32_bf16 v[12:15], v[48:51], v[210:213], v[12:15]
	v_mfma_f32_16x16x32_bf16 v[8:11], v[64:67], v[210:213], v[8:11]
	v_mfma_f32_16x16x32_bf16 v[76:79], v[52:55], v[188:191], v[76:79]
	v_mfma_f32_16x16x32_bf16 v[72:75], v[68:71], v[188:191], v[72:75]
	v_mfma_f32_16x16x32_bf16 v[44:47], v[52:55], v[198:201], v[44:47]
	v_mfma_f32_16x16x32_bf16 v[40:43], v[68:71], v[198:201], v[40:43]
	v_mfma_f32_16x16x32_bf16 v[28:31], v[52:55], v[206:209], v[28:31]
	v_mfma_f32_16x16x32_bf16 v[24:27], v[68:71], v[206:209], v[24:27]
	v_mfma_f32_16x16x32_bf16 v[12:15], v[52:55], v[214:217], v[12:15]
	v_mfma_f32_16x16x32_bf16 v[8:11], v[68:71], v[214:217], v[8:11]
	s_setprio 0
	s_setprio 1
	v_mfma_f32_16x16x32_bf16 v[36:39], v[160:163], v[194:197], v[36:39]
	v_mfma_f32_16x16x32_bf16 v[32:35], v[176:179], v[194:197], v[32:35]
	v_mfma_f32_16x16x32_bf16 v[20:23], v[160:163], v[202:205], v[20:23]
	v_mfma_f32_16x16x32_bf16 v[16:19], v[176:179], v[202:205], v[16:19]
	v_mfma_f32_16x16x32_bf16 v[4:7], v[160:163], v[210:213], v[4:7]
	v_mfma_f32_16x16x32_bf16 v[0:3], v[176:179], v[210:213], v[0:3]
	v_mfma_f32_16x16x32_bf16 v[48:51], v[160:163], v[184:187], v[60:63]
	v_mfma_f32_16x16x32_bf16 v[52:55], v[176:179], v[184:187], v[56:59]
	v_mfma_f32_16x16x32_bf16 v[36:39], v[172:175], v[198:201], v[36:39]
	v_mfma_f32_16x16x32_bf16 v[32:35], v[180:183], v[198:201], v[32:35]
	v_mfma_f32_16x16x32_bf16 v[20:23], v[172:175], v[206:209], v[20:23]
	v_mfma_f32_16x16x32_bf16 v[16:19], v[180:183], v[206:209], v[16:19]
	v_mfma_f32_16x16x32_bf16 v[4:7], v[172:175], v[214:217], v[4:7]
	v_mfma_f32_16x16x32_bf16 v[0:3], v[180:183], v[214:217], v[0:3]
	v_mfma_f32_16x16x32_bf16 v[48:51], v[172:175], v[188:191], v[48:51]
	v_mfma_f32_16x16x32_bf16 v[52:55], v[180:183], v[188:191], v[52:55]
	s_setprio 0
	s_barrier
	s_add_i32 s89, 0, 0x18000
	s_add_i32 s90, 0, 0x1c000
	v_add_u32_e32 v68, s89, v167
	v_add_u32_e32 v180, s90, v167
	ds_read_b128 v[56:59], v68
	ds_read_b128 v[60:63], v68 offset:1024
	ds_read_b128 v[64:67], v68 offset:2048
	ds_read_b128 v[68:71], v68 offset:3072
	ds_read_b128 v[160:163], v180
	ds_read_b128 v[172:175], v180 offset:1024
	ds_read_b128 v[176:179], v180 offset:2048
	ds_read_b128 v[180:183], v180 offset:3072
	s_add_u32 s68, s68, 0x80000
	s_addc_u32 s69, s69, 0
	s_mov_b32 m0, s70
	v_lshl_add_u64 v[224:225], s[68:69], 0, v[144:145]
	ds_read_b128 v[184:187], v171 offset:32768
	ds_read_b128 v[188:191], v171 offset:33792
	ds_read_b128 v[194:197], v171 offset:34816
	ds_read_b128 v[198:201], v171 offset:35840
	ds_read_b128 v[202:205], v171 offset:36864
	ds_read_b128 v[206:209], v171 offset:37888
	ds_read_b128 v[210:213], v171 offset:38912
	ds_read_b128 v[214:217], v171 offset:39936
	global_load_lds_dwordx4 v[224:225], off
	v_lshl_add_u64 v[224:225], s[68:69], 0, v[148:149]
	s_mov_b32 m0, s71
	s_nop 0
	global_load_lds_dwordx4 v[224:225], off
	s_waitcnt vmcnt(8)
	s_waitcnt lgkmcnt(0)
	s_barrier
	s_setprio 1
	s_waitcnt lgkmcnt(0)
	v_mfma_f32_16x16x32_bf16 v[140:143], v[56:59], v[184:187], v[140:143]
	v_mfma_f32_16x16x32_bf16 v[136:139], v[64:67], v[184:187], v[136:139]
	v_mfma_f32_16x16x32_bf16 v[124:127], v[56:59], v[194:197], v[124:127]
	v_mfma_f32_16x16x32_bf16 v[120:123], v[64:67], v[194:197], v[120:123]
	v_mfma_f32_16x16x32_bf16 v[108:111], v[56:59], v[202:205], v[108:111]
	v_mfma_f32_16x16x32_bf16 v[104:107], v[64:67], v[202:205], v[104:107]
	v_mfma_f32_16x16x32_bf16 v[92:95], v[56:59], v[210:213], v[92:95]
	v_mfma_f32_16x16x32_bf16 v[88:91], v[64:67], v[210:213], v[88:91]
	v_mfma_f32_16x16x32_bf16 v[140:143], v[60:63], v[188:191], v[140:143]
	v_mfma_f32_16x16x32_bf16 v[136:139], v[68:71], v[188:191], v[136:139]
	v_mfma_f32_16x16x32_bf16 v[124:127], v[60:63], v[198:201], v[124:127]
	v_mfma_f32_16x16x32_bf16 v[120:123], v[68:71], v[198:201], v[120:123]
	v_mfma_f32_16x16x32_bf16 v[108:111], v[60:63], v[206:209], v[108:111]
	v_mfma_f32_16x16x32_bf16 v[104:107], v[68:71], v[206:209], v[104:107]
	v_mfma_f32_16x16x32_bf16 v[92:95], v[60:63], v[214:217], v[92:95]
	v_mfma_f32_16x16x32_bf16 v[88:91], v[68:71], v[214:217], v[88:91]
	s_setprio 0
	s_setprio 1
	v_mfma_f32_16x16x32_bf16 v[132:135], v[160:163], v[184:187], v[132:135]
	v_mfma_f32_16x16x32_bf16 v[128:131], v[176:179], v[184:187], v[128:131]
	v_mfma_f32_16x16x32_bf16 v[116:119], v[160:163], v[194:197], v[116:119]
	v_mfma_f32_16x16x32_bf16 v[112:115], v[176:179], v[194:197], v[112:115]
	v_mfma_f32_16x16x32_bf16 v[100:103], v[160:163], v[202:205], v[100:103]
	v_mfma_f32_16x16x32_bf16 v[96:99], v[176:179], v[202:205], v[96:99]
	v_mfma_f32_16x16x32_bf16 v[84:87], v[160:163], v[210:213], v[84:87]
	v_mfma_f32_16x16x32_bf16 v[80:83], v[176:179], v[210:213], v[80:83]
	v_mfma_f32_16x16x32_bf16 v[132:135], v[172:175], v[188:191], v[132:135]
	v_mfma_f32_16x16x32_bf16 v[128:131], v[180:183], v[188:191], v[128:131]
	v_mfma_f32_16x16x32_bf16 v[116:119], v[172:175], v[198:201], v[116:119]
	v_mfma_f32_16x16x32_bf16 v[112:115], v[180:183], v[198:201], v[112:115]
	v_mfma_f32_16x16x32_bf16 v[100:103], v[172:175], v[206:209], v[100:103]
	v_mfma_f32_16x16x32_bf16 v[96:99], v[180:183], v[206:209], v[96:99]
	v_mfma_f32_16x16x32_bf16 v[84:87], v[172:175], v[214:217], v[84:87]
	v_mfma_f32_16x16x32_bf16 v[80:83], v[180:183], v[214:217], v[80:83]
	s_setprio 0
	s_barrier
; #define PG8_STAGE(bufoff, gbase, voff) do { _Pragma("unroll") for (int _i = 0; _i < 2; ++_i) \
;         __builtin_amdgcn_global_load_lds((const unsigned*)((const char*)(gbase) + (voff)[_i]), (PG8_LAS unsigned*)(lds + (bufoff) + ldsw + _i * 8192), 16, 0, 0); } while (0)
; #define PG8_LDA(dst, b, h) do { _Pragma("unroll") for (int m = 0; m < 4; ++m) _Pragma("unroll") for (int k = 0; k < 2; ++k) dst[m][k] = *(const PG8_LAS bf16x8*)(lds + PG8_SA(b, h) + aoff + m * 2048 + k * 1024); } while (0)
; #define PG8_MMA(ai, bj, At, Bt) do { __builtin_amdgcn_s_setprio(1); _Pragma("unroll") for (int m = 0; m < 4; ++m) _Pragma("unroll") for (int n = 0; n < 2; ++n) _Pragma("unroll") for (int k = 0; k < 2; ++k) \
;         acc[ai][bj][m][n] = __builtin_amdgcn_mfma_f32_16x16x32_bf16(Bt[n][k], At[m][k], acc[ai][bj][m][n], 0, 0, 0); __builtin_amdgcn_s_setprio(0); } while (0)
; #define PG8_WAIT_V(n) asm volatile("s_waitcnt vmcnt(" #n ")" ::: "memory")
; #define PG8_WAIT_L(n) asm volatile("s_waitcnt lgkmcnt(" #n ")" ::: "memory")
; #define PG8_BAR __builtin_amdgcn_s_barrier()
; #define PG8_SCHED __builtin_amdgcn_sched_barrier(0)
; template <class Epi, class Sched, bool ALIGN_EPI = false, bool SP2 = false>
; __device__ __forceinline__ void gemm_phase(PG8_LAS unsigned char* lds, const Gemm g, const Sched& S, const Epi& E) {
;     ...
;         for (int t = 0; t < nt; t += 2) {
;     ...
;             PG8_LDA(At, 1, 1); PG8_STAGE(PG8_SB(1, 0), b3, voffB); PG8_STAGE(PG8_SB(1, 1), b3 + hstep, voffB); PG8_STAGE(PG8_SA(1, 0), a3, voffA);
;             PG8_WAIT_V(8); PG8_WAIT_L(0); PG8_BAR; PG8_MMA(1, 0, At, B0); PG8_MMA(1, 1, At, B1); PG8_BAR; PG8_SCHED;
	s_add_i32 s68, s89, s37
	v_lshl_add_u64 v[164:165], v[164:165], 0, s[16:17]
	s_mov_b32 m0, s68
	ds_read_b128 v[184:187], v171 offset:49152
	ds_read_b128 v[188:191], v171 offset:50176
	ds_read_b128 v[194:197], v171 offset:51200
	ds_read_b128 v[198:201], v171 offset:52224
	ds_read_b128 v[202:205], v171 offset:53248
	ds_read_b128 v[206:209], v171 offset:54272
	ds_read_b128 v[210:213], v171 offset:55296
	ds_read_b128 v[214:217], v171 offset:56320
	global_load_lds_dwordx4 v[164:165], off
	s_add_i32 m0, s68, 0x2000
	s_add_u32 s66, s66, 0x80080
	v_lshl_add_u64 v[164:165], v[218:219], 0, s[16:17]
	s_addc_u32 s67, s67, 0
	s_add_i32 s68, s90, s37
	global_load_lds_dwordx4 v[164:165], off
	v_lshl_add_u64 v[164:165], s[66:67], 0, v[146:147]
	s_mov_b32 m0, s68
	s_nop 0
	global_load_lds_dwordx4 v[164:165], off
	v_lshl_add_u64 v[164:165], s[66:67], 0, v[150:151]
	s_add_i32 m0, s68, 0x2000
	s_nop 0
	global_load_lds_dwordx4 v[164:165], off
	v_lshl_add_u64 v[164:165], v[220:221], 0, s[16:17]
	s_mov_b32 m0, s75
	s_nop 0
	global_load_lds_dwordx4 v[164:165], off
	v_lshl_add_u64 v[164:165], v[222:223], 0, s[16:17]
	s_mov_b32 m0, s76
	s_nop 0
	global_load_lds_dwordx4 v[164:165], off
	s_waitcnt vmcnt(8)
	s_waitcnt lgkmcnt(0)
	s_barrier
	s_setprio 1
	s_waitcnt lgkmcnt(0)
	v_mfma_f32_16x16x32_bf16 v[76:79], v[56:59], v[184:187], v[76:79]
	v_mfma_f32_16x16x32_bf16 v[72:75], v[64:67], v[184:187], v[72:75]
	v_mfma_f32_16x16x32_bf16 v[44:47], v[56:59], v[194:197], v[44:47]
	v_mfma_f32_16x16x32_bf16 v[40:43], v[64:67], v[194:197], v[40:43]
	v_mfma_f32_16x16x32_bf16 v[28:31], v[56:59], v[202:205], v[28:31]
	v_mfma_f32_16x16x32_bf16 v[24:27], v[64:67], v[202:205], v[24:27]
	v_mfma_f32_16x16x32_bf16 v[12:15], v[56:59], v[210:213], v[12:15]
	v_mfma_f32_16x16x32_bf16 v[8:11], v[64:67], v[210:213], v[8:11]
	v_mfma_f32_16x16x32_bf16 v[76:79], v[60:63], v[188:191], v[76:79]
	v_mfma_f32_16x16x32_bf16 v[72:75], v[68:71], v[188:191], v[72:75]
	v_mfma_f32_16x16x32_bf16 v[44:47], v[60:63], v[198:201], v[44:47]
	v_mfma_f32_16x16x32_bf16 v[40:43], v[68:71], v[198:201], v[40:43]
	v_mfma_f32_16x16x32_bf16 v[28:31], v[60:63], v[206:209], v[28:31]
	v_mfma_f32_16x16x32_bf16 v[24:27], v[68:71], v[206:209], v[24:27]
	v_mfma_f32_16x16x32_bf16 v[12:15], v[60:63], v[214:217], v[12:15]
	v_mfma_f32_16x16x32_bf16 v[8:11], v[68:71], v[214:217], v[8:11]
	s_setprio 0
	s_setprio 1
	v_mfma_f32_16x16x32_bf16 v[48:51], v[160:163], v[184:187], v[48:51]
	v_mfma_f32_16x16x32_bf16 v[60:63], v[172:175], v[188:191], v[48:51]
	v_mfma_f32_16x16x32_bf16 v[48:51], v[176:179], v[184:187], v[52:55]
	v_mfma_f32_16x16x32_bf16 v[36:39], v[160:163], v[194:197], v[36:39]
	v_mfma_f32_16x16x32_bf16 v[32:35], v[176:179], v[194:197], v[32:35]
	v_mfma_f32_16x16x32_bf16 v[20:23], v[160:163], v[202:205], v[20:23]
	v_mfma_f32_16x16x32_bf16 v[16:19], v[176:179], v[202:205], v[16:19]
	v_mfma_f32_16x16x32_bf16 v[4:7], v[160:163], v[210:213], v[4:7]
	v_mfma_f32_16x16x32_bf16 v[0:3], v[176:179], v[210:213], v[0:3]
	v_mfma_f32_16x16x32_bf16 v[56:59], v[180:183], v[188:191], v[48:51]
	v_mfma_f32_16x16x32_bf16 v[36:39], v[172:175], v[198:201], v[36:39]
	v_mfma_f32_16x16x32_bf16 v[32:35], v[180:183], v[198:201], v[32:35]
	v_mfma_f32_16x16x32_bf16 v[20:23], v[172:175], v[206:209], v[20:23]
	v_mfma_f32_16x16x32_bf16 v[16:19], v[180:183], v[206:209], v[16:19]
	v_mfma_f32_16x16x32_bf16 v[4:7], v[172:175], v[214:217], v[4:7]
	v_mfma_f32_16x16x32_bf16 v[0:3], v[180:183], v[214:217], v[0:3]
	s_add_i32 s88, s88, 2
	s_add_u32 s86, s86, 0x100
	s_addc_u32 s87, s87, 0
	s_add_u32 s6, s6, 0x100
	s_addc_u32 s7, s7, 0
	s_cmp_gt_u32 s88, 29
	s_setprio 0
	s_barrier
	s_cbranch_scc0 .LBB0_192
	s_and_b64 vcc, exec, s[18:19]
	s_cbranch_vccz .LBB0_195
	s_barrier

; #define PG8_STAGE(bufoff, gbase, voff) do { _Pragma("unroll") for (int _i = 0; _i < 2; ++_i) \
;         __builtin_amdgcn_global_load_lds((const unsigned*)((const char*)(gbase) + (voff)[_i]), (PG8_LAS unsigned*)(lds + (bufoff) + ldsw + _i * 8192), 16, 0, 0); } while (0)
; #define PG8_LDA(dst, b, h) do { _Pragma("unroll") for (int m = 0; m < 4; ++m) _Pragma("unroll") for (int k = 0; k < 2; ++k) dst[m][k] = *(const PG8_LAS bf16x8*)(lds + PG8_SA(b, h) + aoff + m * 2048 + k * 1024); } while (0)
; #define PG8_LDB(dst, b, h) do { _Pragma("unroll") for (int n = 0; n < 2; ++n) _Pragma("unroll") for (int k = 0; k < 2; ++k) dst[n][k] = *(const PG8_LAS bf16x8*)(lds + PG8_SB(b, h) + boff + n * 2048 + k * 1024); } while (0)
; #define PG8_MMA(ai, bj, At, Bt) do { __builtin_amdgcn_s_setprio(1); _Pragma("unroll") for (int m = 0; m < 4; ++m) _Pragma("unroll") for (int n = 0; n < 2; ++n) _Pragma("unroll") for (int k = 0; k < 2; ++k) \
;         acc[ai][bj][m][n] = __builtin_amdgcn_mfma_f32_16x16x32_bf16(Bt[n][k], At[m][k], acc[ai][bj][m][n], 0, 0, 0); __builtin_amdgcn_s_setprio(0); } while (0)
; #define PG8_WAIT_V(n) asm volatile("s_waitcnt vmcnt(" #n ")" ::: "memory")
; template <class Epi, class Sched, bool ALIGN_EPI = false, bool SP2 = false>
; __device__ __forceinline__ void gemm_phase(PG8_LAS unsigned char* lds, const Gemm g, const Sched& S, const Epi& E) {
;     ...
;         const char* nA = has_next ? (const char*)g.A + (size_t)nxt.pm * tstep : cA; const char* nB = has_next ? (const char*)g.Bt + (size_t)nxt.pn * tstep : cB;
;         for (int t = 0; t < nt; t += 2) {
;             const bool last = (t == nt - 2);
;             const char* a1 = cA + (size_t)(t + 1) * kstep;
;             const char* a2 = last ? nA : cA + (size_t)(t + 2) * kstep; const char* b2 = last ? nB : cB + (size_t)(t + 2) * kstep;
;             const char* a3 = a2 + kstep; const char* b3 = b2 + kstep;
;             if (last && has_next) S.a_ready(nxt);
;             if constexpr (SP2) {
;             PG8_LDB(B0, 0, 0); PG8_LDB(B1, 0, 1); PG8_SCHED; PG8_LDA(At, 0, 0); PG8_STAGE(PG8_SA(1, 1), a1 + hstep, voffA);
;             PG8_WAIT_V(8); PG8_WAIT_L(0); PG8_BAR; PG8_MMA(0, 0, At, B0); PG8_MMA(0, 1, At, B1); PG8_BAR; PG8_SCHED;
;             PG8_LDA(At, 0, 1); PG8_STAGE(PG8_SB(0, 0), b2, voffB); PG8_STAGE(PG8_SB(0, 1), b2 + hstep, voffB); PG8_STAGE(PG8_SA(0, 0), a2, voffA);
.LBB0_352:
	s_ashr_i32 s27, s26, 31
	s_lshl_b64 s[30:31], s[26:27], 20
	s_add_u32 s30, s60, s30
	s_addc_u32 s31, s61, s31
	s_and_b64 s[34:35], s[6:7], exec
	s_cselect_b32 s27, s31, s53
	s_cselect_b32 s73, s30, s52
	s_ashr_i32 s29, s28, 31
	s_lshl_b64 s[34:35], s[28:29], 20
	s_add_u32 s34, s58, s34
	s_addc_u32 s35, s59, s35
	s_and_b64 s[54:55], s[6:7], exec
	s_cselect_b32 s29, s35, s51
	s_cselect_b32 s74, s34, s50
	s_add_u32 s75, s50, 0x100
	s_addc_u32 s76, s51, 0
	s_add_u32 s50, s52, 0x80080
	s_addc_u32 s51, s53, 0
	s_mov_b32 s77, -2
	ds_read_b128 v[128:131], v169
	ds_read_b128 v[132:135], v169 offset:1024
	ds_read_b128 v[136:139], v169 offset:2048
	ds_read_b128 v[140:143], v169 offset:3072
	ds_read_b128 v[160:163], v170
	ds_read_b128 v[172:175], v170 offset:1024
	ds_read_b128 v[176:179], v170 offset:2048
	ds_read_b128 v[180:183], v170 offset:3072
	s_add_u32 s52, s50, 0xfff80080
	s_addc_u32 s53, s51, -1
	s_cmp_eq_u32 s77, 28
	s_cselect_b32 s55, s27, s53
	s_cselect_b32 s54, s73, s52
	s_cselect_b32 s53, s29, s76
	s_cselect_b32 s52, s74, s75
	v_lshl_add_u64 v[164:165], s[50:51], 0, v[154:155]
	s_add_i32 m0, s37, 0xc000
	ds_read_b128 v[184:187], v171
	ds_read_b128 v[188:191], v171 offset:1024
	ds_read_b128 v[194:197], v171 offset:2048
	ds_read_b128 v[198:201], v171 offset:3072
	ds_read_b128 v[202:205], v171 offset:4096
	ds_read_b128 v[206:209], v171 offset:5120
	ds_read_b128 v[210:213], v171 offset:6144
	ds_read_b128 v[214:217], v171 offset:7168
	global_load_lds_dwordx4 v[164:165], off
	v_lshl_add_u64 v[164:165], s[50:51], 0, v[152:153]
	s_add_i32 m0, s37, 0xe000
	s_nop 0
	global_load_lds_dwordx4 v[164:165], off
	s_waitcnt vmcnt(8)
	s_waitcnt lgkmcnt(0)
	s_barrier
	s_setprio 1
	s_waitcnt lgkmcnt(0)
	v_mfma_f32_16x16x32_bf16 v[124:127], v[128:131], v[184:187], 0
	v_mfma_f32_16x16x32_bf16 v[120:123], v[136:139], v[184:187], 0
	v_mfma_f32_16x16x32_bf16 v[108:111], v[128:131], v[194:197], 0
	v_mfma_f32_16x16x32_bf16 v[104:107], v[136:139], v[194:197], 0
	v_mfma_f32_16x16x32_bf16 v[92:95], v[128:131], v[202:205], 0
	v_mfma_f32_16x16x32_bf16 v[88:91], v[136:139], v[202:205], 0
	v_mfma_f32_16x16x32_bf16 v[76:79], v[128:131], v[210:213], 0
	v_mfma_f32_16x16x32_bf16 v[72:75], v[136:139], v[210:213], 0
	v_mfma_f32_16x16x32_bf16 v[124:127], v[132:135], v[188:191], v[124:127]
	v_mfma_f32_16x16x32_bf16 v[120:123], v[140:143], v[188:191], v[120:123]
	v_mfma_f32_16x16x32_bf16 v[108:111], v[132:135], v[198:201], v[108:111]
	v_mfma_f32_16x16x32_bf16 v[104:107], v[140:143], v[198:201], v[104:107]
	v_mfma_f32_16x16x32_bf16 v[92:95], v[132:135], v[206:209], v[92:95]
	v_mfma_f32_16x16x32_bf16 v[88:91], v[140:143], v[206:209], v[88:91]
	v_mfma_f32_16x16x32_bf16 v[76:79], v[132:135], v[214:217], v[76:79]
	v_mfma_f32_16x16x32_bf16 v[72:75], v[140:143], v[214:217], v[72:75]
	s_setprio 0
	s_setprio 1
	v_mfma_f32_16x16x32_bf16 v[116:119], v[160:163], v[184:187], 0
	v_mfma_f32_16x16x32_bf16 v[112:115], v[176:179], v[184:187], 0
	v_mfma_f32_16x16x32_bf16 v[100:103], v[160:163], v[194:197], 0
	v_mfma_f32_16x16x32_bf16 v[96:99], v[176:179], v[194:197], 0
	v_mfma_f32_16x16x32_bf16 v[84:87], v[160:163], v[202:205], 0
	v_mfma_f32_16x16x32_bf16 v[80:83], v[176:179], v[202:205], 0
	v_mfma_f32_16x16x32_bf16 v[68:71], v[160:163], v[210:213], 0
	v_mfma_f32_16x16x32_bf16 v[64:67], v[176:179], v[210:213], 0
	v_mfma_f32_16x16x32_bf16 v[116:119], v[172:175], v[188:191], v[116:119]
	v_mfma_f32_16x16x32_bf16 v[112:115], v[180:183], v[188:191], v[112:115]
	v_mfma_f32_16x16x32_bf16 v[100:103], v[172:175], v[198:201], v[100:103]
	v_mfma_f32_16x16x32_bf16 v[96:99], v[180:183], v[198:201], v[96:99]
	v_mfma_f32_16x16x32_bf16 v[84:87], v[172:175], v[206:209], v[84:87]
	v_mfma_f32_16x16x32_bf16 v[80:83], v[180:183], v[206:209], v[80:83]
	v_mfma_f32_16x16x32_bf16 v[68:71], v[172:175], v[214:217], v[68:71]
	v_mfma_f32_16x16x32_bf16 v[64:67], v[180:183], v[214:217], v[64:67]
	s_setprio 0
	s_barrier
	s_add_i32 s78, s71, s62
	v_lshl_add_u64 v[164:165], s[52:53], 0, v[146:147]
	s_mov_b32 m0, s78
	ds_read_b128 v[184:187], v171 offset:16384
	ds_read_b128 v[188:191], v171 offset:17408
	ds_read_b128 v[194:197], v171 offset:18432
	ds_read_b128 v[198:201], v171 offset:19456
	ds_read_b128 v[202:205], v171 offset:20480
	ds_read_b128 v[206:209], v171 offset:21504
	ds_read_b128 v[210:213], v171 offset:22528
	ds_read_b128 v[214:217], v171 offset:23552
	global_load_lds_dwordx4 v[164:165], off
	s_add_i32 m0, s78, 0x2000
	s_add_u32 s78, s52, 0x80000
	v_lshl_add_u64 v[218:219], s[52:53], 0, v[150:151]
	s_addc_u32 s79, s53, 0
	s_add_i32 s80, s72, s62
	global_load_lds_dwordx4 v[218:219], off
	v_lshl_add_u64 v[220:221], s[78:79], 0, v[146:147]
	s_mov_b32 m0, s80
	v_lshl_add_u64 v[222:223], s[54:55], 0, v[148:149]
	global_load_lds_dwordx4 v[220:221], off
	v_lshl_add_u64 v[220:221], s[78:79], 0, v[150:151]
	s_add_i32 m0, s80, 0x2000
	s_nop 0
	global_load_lds_dwordx4 v[220:221], off
	v_lshl_add_u64 v[220:221], s[54:55], 0, v[144:145]
	s_mov_b32 m0, s37
	s_nop 0
	global_load_lds_dwordx4 v[220:221], off
	s_mov_b32 m0, s49
	s_nop 0
	global_load_lds_dwordx4 v[222:223], off
	s_waitcnt vmcnt(8)
	s_waitcnt lgkmcnt(0)
	s_barrier
; #define PG8_STAGE(bufoff, gbase, voff) do { _Pragma("unroll") for (int _i = 0; _i < 2; ++_i) \
;         __builtin_amdgcn_global_load_lds((const unsigned*)((const char*)(gbase) + (voff)[_i]), (PG8_LAS unsigned*)(lds + (bufoff) + ldsw + _i * 8192), 16, 0, 0); } while (0)
; #define PG8_LDA(dst, b, h) do { _Pragma("unroll") for (int m = 0; m < 4; ++m) _Pragma("unroll") for (int k = 0; k < 2; ++k) dst[m][k] = *(const PG8_LAS bf16x8*)(lds + PG8_SA(b, h) + aoff + m * 2048 + k * 1024); } while (0)
; #define PG8_LDB(dst, b, h) do { _Pragma("unroll") for (int n = 0; n < 2; ++n) _Pragma("unroll") for (int k = 0; k < 2; ++k) dst[n][k] = *(const PG8_LAS bf16x8*)(lds + PG8_SB(b, h) + boff + n * 2048 + k * 1024); } while (0)
; #define PG8_MMA(ai, bj, At, Bt) do { __builtin_amdgcn_s_setprio(1); _Pragma("unroll") for (int m = 0; m < 4; ++m) _Pragma("unroll") for (int n = 0; n < 2; ++n) _Pragma("unroll") for (int k = 0; k < 2; ++k) \
;         acc[ai][bj][m][n] = __builtin_amdgcn_mfma_f32_16x16x32_bf16(Bt[n][k], At[m][k], acc[ai][bj][m][n], 0, 0, 0); __builtin_amdgcn_s_setprio(0); } while (0)
; #define PG8_WAIT_V(n) asm volatile("s_waitcnt vmcnt(" #n ")" ::: "memory")
; #define PG8_WAIT_L(n) asm volatile("s_waitcnt lgkmcnt(" #n ")" ::: "memory")
; #define PG8_BAR __builtin_amdgcn_s_barrier()
; #define PG8_SCHED __builtin_amdgcn_sched_barrier(0)
; template <class Epi, class Sched, bool ALIGN_EPI = false, bool SP2 = false>
; __device__ __forceinline__ void gemm_phase(PG8_LAS unsigned char* lds, const Gemm g, const Sched& S, const Epi& E) {
;     ...
;             PG8_WAIT_V(8); PG8_WAIT_L(0); PG8_BAR; PG8_MMA(1, 0, At, B0); PG8_MMA(1, 1, At, B1); PG8_BAR; PG8_SCHED;
;             PG8_LDB(B0, 1, 0); PG8_LDB(B1, 1, 1); PG8_SCHED; PG8_LDA(At, 1, 0); PG8_STAGE(PG8_SA(0, 1), a2 + hstep, voffA);
;             PG8_WAIT_V(8); PG8_WAIT_L(0); PG8_BAR; PG8_MMA(0, 0, At, B0); PG8_MMA(0, 1, At, B1); PG8_BAR; PG8_SCHED;
	s_setprio 1
	s_waitcnt lgkmcnt(0)
	v_mfma_f32_16x16x32_bf16 v[60:63], v[128:131], v[184:187], 0
	v_mfma_f32_16x16x32_bf16 v[56:59], v[136:139], v[184:187], 0
	v_mfma_f32_16x16x32_bf16 v[44:47], v[128:131], v[194:197], 0
	v_mfma_f32_16x16x32_bf16 v[40:43], v[136:139], v[194:197], 0
	v_mfma_f32_16x16x32_bf16 v[28:31], v[128:131], v[202:205], 0
	v_mfma_f32_16x16x32_bf16 v[24:27], v[136:139], v[202:205], 0
	v_mfma_f32_16x16x32_bf16 v[12:15], v[128:131], v[210:213], 0
	v_mfma_f32_16x16x32_bf16 v[8:11], v[136:139], v[210:213], 0
	v_mfma_f32_16x16x32_bf16 v[60:63], v[132:135], v[188:191], v[60:63]
	v_mfma_f32_16x16x32_bf16 v[56:59], v[140:143], v[188:191], v[56:59]
	v_mfma_f32_16x16x32_bf16 v[44:47], v[132:135], v[198:201], v[44:47]
	v_mfma_f32_16x16x32_bf16 v[40:43], v[140:143], v[198:201], v[40:43]
	v_mfma_f32_16x16x32_bf16 v[28:31], v[132:135], v[206:209], v[28:31]
	v_mfma_f32_16x16x32_bf16 v[24:27], v[140:143], v[206:209], v[24:27]
	v_mfma_f32_16x16x32_bf16 v[12:15], v[132:135], v[214:217], v[12:15]
	v_mfma_f32_16x16x32_bf16 v[8:11], v[140:143], v[214:217], v[8:11]
	s_setprio 0
	s_setprio 1
	v_mfma_f32_16x16x32_bf16 v[52:55], v[160:163], v[184:187], 0
	v_mfma_f32_16x16x32_bf16 v[48:51], v[176:179], v[184:187], 0
	v_mfma_f32_16x16x32_bf16 v[36:39], v[160:163], v[194:197], 0
	v_mfma_f32_16x16x32_bf16 v[32:35], v[176:179], v[194:197], 0
	v_mfma_f32_16x16x32_bf16 v[20:23], v[160:163], v[202:205], 0
	v_mfma_f32_16x16x32_bf16 v[16:19], v[176:179], v[202:205], 0
	v_mfma_f32_16x16x32_bf16 v[4:7], v[160:163], v[210:213], 0
	v_mfma_f32_16x16x32_bf16 v[0:3], v[176:179], v[210:213], 0
	v_mfma_f32_16x16x32_bf16 v[52:55], v[172:175], v[188:191], v[52:55]
	v_mfma_f32_16x16x32_bf16 v[48:51], v[180:183], v[188:191], v[48:51]
	v_mfma_f32_16x16x32_bf16 v[36:39], v[172:175], v[198:201], v[36:39]
	v_mfma_f32_16x16x32_bf16 v[32:35], v[180:183], v[198:201], v[32:35]
	v_mfma_f32_16x16x32_bf16 v[20:23], v[172:175], v[206:209], v[20:23]
	v_mfma_f32_16x16x32_bf16 v[16:19], v[180:183], v[206:209], v[16:19]
	v_mfma_f32_16x16x32_bf16 v[4:7], v[172:175], v[214:217], v[4:7]
	v_mfma_f32_16x16x32_bf16 v[0:3], v[180:183], v[214:217], v[0:3]
	s_setprio 0
	s_barrier
	s_add_i32 s78, 0, 0x18000
	s_add_i32 s79, 0, 0x1c000
	v_add_u32_e32 v140, s78, v167
	v_add_u32_e32 v180, s79, v167
	ds_read_b128 v[128:131], v140
	ds_read_b128 v[132:135], v140 offset:1024
	ds_read_b128 v[136:139], v140 offset:2048
	ds_read_b128 v[140:143], v140 offset:3072
	ds_read_b128 v[160:163], v180
	ds_read_b128 v[172:175], v180 offset:1024
	ds_read_b128 v[176:179], v180 offset:2048
	ds_read_b128 v[180:183], v180 offset:3072
	s_add_u32 s54, s54, 0x80000
	s_addc_u32 s55, s55, 0
	s_mov_b32 m0, s63
	v_lshl_add_u64 v[224:225], s[54:55], 0, v[144:145]
	ds_read_b128 v[184:187], v171 offset:32768
	ds_read_b128 v[188:191], v171 offset:33792
	ds_read_b128 v[194:197], v171 offset:34816
	ds_read_b128 v[198:201], v171 offset:35840
	ds_read_b128 v[202:205], v171 offset:36864
	ds_read_b128 v[206:209], v171 offset:37888
	ds_read_b128 v[210:213], v171 offset:38912
	ds_read_b128 v[214:217], v171 offset:39936
	global_load_lds_dwordx4 v[224:225], off
	v_lshl_add_u64 v[224:225], s[54:55], 0, v[148:149]
	s_mov_b32 m0, s64
	s_nop 0
	global_load_lds_dwordx4 v[224:225], off
	s_waitcnt vmcnt(8)
	s_waitcnt lgkmcnt(0)
	s_barrier
	s_setprio 1
	s_waitcnt lgkmcnt(0)
	v_mfma_f32_16x16x32_bf16 v[124:127], v[128:131], v[184:187], v[124:127]
	v_mfma_f32_16x16x32_bf16 v[120:123], v[136:139], v[184:187], v[120:123]
	v_mfma_f32_16x16x32_bf16 v[108:111], v[128:131], v[194:197], v[108:111]
	v_mfma_f32_16x16x32_bf16 v[104:107], v[136:139], v[194:197], v[104:107]
	v_mfma_f32_16x16x32_bf16 v[92:95], v[128:131], v[202:205], v[92:95]
	v_mfma_f32_16x16x32_bf16 v[88:91], v[136:139], v[202:205], v[88:91]
	v_mfma_f32_16x16x32_bf16 v[76:79], v[128:131], v[210:213], v[76:79]
	v_mfma_f32_16x16x32_bf16 v[72:75], v[136:139], v[210:213], v[72:75]
	v_mfma_f32_16x16x32_bf16 v[124:127], v[132:135], v[188:191], v[124:127]
	v_mfma_f32_16x16x32_bf16 v[120:123], v[140:143], v[188:191], v[120:123]
	v_mfma_f32_16x16x32_bf16 v[108:111], v[132:135], v[198:201], v[108:111]
	v_mfma_f32_16x16x32_bf16 v[104:107], v[140:143], v[198:201], v[104:107]
	v_mfma_f32_16x16x32_bf16 v[92:95], v[132:135], v[206:209], v[92:95]
	v_mfma_f32_16x16x32_bf16 v[88:91], v[140:143], v[206:209], v[88:91]
	v_mfma_f32_16x16x32_bf16 v[76:79], v[132:135], v[214:217], v[76:79]
	v_mfma_f32_16x16x32_bf16 v[72:75], v[140:143], v[214:217], v[72:75]
	s_setprio 0
	s_setprio 1
	v_mfma_f32_16x16x32_bf16 v[116:119], v[160:163], v[184:187], v[116:119]
	v_mfma_f32_16x16x32_bf16 v[112:115], v[176:179], v[184:187], v[112:115]
	v_mfma_f32_16x16x32_bf16 v[100:103], v[160:163], v[194:197], v[100:103]
	v_mfma_f32_16x16x32_bf16 v[96:99], v[176:179], v[194:197], v[96:99]
	v_mfma_f32_16x16x32_bf16 v[84:87], v[160:163], v[202:205], v[84:87]
	v_mfma_f32_16x16x32_bf16 v[80:83], v[176:179], v[202:205], v[80:83]
	v_mfma_f32_16x16x32_bf16 v[68:71], v[160:163], v[210:213], v[68:71]
	v_mfma_f32_16x16x32_bf16 v[64:67], v[176:179], v[210:213], v[64:67]
	v_mfma_f32_16x16x32_bf16 v[116:119], v[172:175], v[188:191], v[116:119]
	v_mfma_f32_16x16x32_bf16 v[112:115], v[180:183], v[188:191], v[112:115]
	v_mfma_f32_16x16x32_bf16 v[100:103], v[172:175], v[198:201], v[100:103]
	v_mfma_f32_16x16x32_bf16 v[96:99], v[180:183], v[198:201], v[96:99]
	v_mfma_f32_16x16x32_bf16 v[84:87], v[172:175], v[206:209], v[84:87]
	v_mfma_f32_16x16x32_bf16 v[80:83], v[180:183], v[206:209], v[80:83]
	v_mfma_f32_16x16x32_bf16 v[68:71], v[172:175], v[214:217], v[68:71]
	v_mfma_f32_16x16x32_bf16 v[64:67], v[180:183], v[214:217], v[64:67]
	s_setprio 0
	s_barrier
; #define PG8_STAGE(bufoff, gbase, voff) do { _Pragma("unroll") for (int _i = 0; _i < 2; ++_i) \
;         __builtin_amdgcn_global_load_lds((const unsigned*)((const char*)(gbase) + (voff)[_i]), (PG8_LAS unsigned*)(lds + (bufoff) + ldsw + _i * 8192), 16, 0, 0); } while (0)
; #define PG8_LDA(dst, b, h) do { _Pragma("unroll") for (int m = 0; m < 4; ++m) _Pragma("unroll") for (int k = 0; k < 2; ++k) dst[m][k] = *(const PG8_LAS bf16x8*)(lds + PG8_SA(b, h) + aoff + m * 2048 + k * 1024); } while (0)
; #define PG8_LDB(dst, b, h) do { _Pragma("unroll") for (int n = 0; n < 2; ++n) _Pragma("unroll") for (int k = 0; k < 2; ++k) dst[n][k] = *(const PG8_LAS bf16x8*)(lds + PG8_SB(b, h) + boff + n * 2048 + k * 1024); } while (0)
; #define PG8_MMA(ai, bj, At, Bt) do { __builtin_amdgcn_s_setprio(1); _Pragma("unroll") for (int m = 0; m < 4; ++m) _Pragma("unroll") for (int n = 0; n < 2; ++n) _Pragma("unroll") for (int k = 0; k < 2; ++k) \
;         acc[ai][bj][m][n] = __builtin_amdgcn_mfma_f32_16x16x32_bf16(Bt[n][k], At[m][k], acc[ai][bj][m][n], 0, 0, 0); __builtin_amdgcn_s_setprio(0); } while (0)
; #define PG8_WAIT_V(n) asm volatile("s_waitcnt vmcnt(" #n ")" ::: "memory")
; #define PG8_WAIT_L(n) asm volatile("s_waitcnt lgkmcnt(" #n ")" ::: "memory")
; #define PG8_BAR __builtin_amdgcn_s_barrier()
; #define PG8_SCHED __builtin_amdgcn_sched_barrier(0)
; template <class Epi, class Sched, bool ALIGN_EPI = false, bool SP2 = false>
; __device__ __forceinline__ void gemm_phase(PG8_LAS unsigned char* lds, const Gemm g, const Sched& S, const Epi& E) {
;     ...
;             PG8_LDB(B0, 0, 0); PG8_LDB(B1, 0, 1); PG8_SCHED; PG8_LDA(At, 0, 0); PG8_STAGE(PG8_SA(1, 1), a1 + hstep, voffA);
;             PG8_WAIT_V(8); PG8_WAIT_L(0); PG8_BAR; PG8_MMA(0, 0, At, B0); PG8_MMA(0, 1, At, B1); PG8_BAR; PG8_SCHED;
;     ...
;             PG8_LDA(At, 1, 1); PG8_STAGE(PG8_SB(1, 0), b3, voffB); PG8_STAGE(PG8_SB(1, 1), b3 + hstep, voffB); PG8_STAGE(PG8_SA(1, 0), a3, voffA);
;             PG8_WAIT_V(8); PG8_WAIT_L(0); PG8_BAR; PG8_MMA(1, 0, At, B0); PG8_MMA(1, 1, At, B1); PG8_BAR; PG8_SCHED;
	s_add_i32 s54, s78, s62
	v_lshl_add_u64 v[164:165], v[164:165], 0, s[14:15]
	s_mov_b32 m0, s54
	ds_read_b128 v[184:187], v171 offset:49152
	ds_read_b128 v[188:191], v171 offset:50176
	ds_read_b128 v[194:197], v171 offset:51200
	ds_read_b128 v[198:201], v171 offset:52224
	ds_read_b128 v[202:205], v171 offset:53248
	ds_read_b128 v[206:209], v171 offset:54272
	ds_read_b128 v[210:213], v171 offset:55296
	ds_read_b128 v[214:217], v171 offset:56320
	global_load_lds_dwordx4 v[164:165], off
	s_add_i32 m0, s54, 0x2000
	s_add_u32 s52, s52, 0x80080
	v_lshl_add_u64 v[164:165], v[218:219], 0, s[14:15]
	s_addc_u32 s53, s53, 0
	s_add_i32 s54, s79, s62
	global_load_lds_dwordx4 v[164:165], off
	v_lshl_add_u64 v[164:165], s[52:53], 0, v[146:147]
	s_mov_b32 m0, s54
	s_nop 0
	global_load_lds_dwordx4 v[164:165], off
	v_lshl_add_u64 v[164:165], s[52:53], 0, v[150:151]
	s_add_i32 m0, s54, 0x2000
	s_nop 0
	global_load_lds_dwordx4 v[164:165], off
	v_lshl_add_u64 v[164:165], v[220:221], 0, s[14:15]
	s_mov_b32 m0, s68
	s_nop 0
	global_load_lds_dwordx4 v[164:165], off
	v_lshl_add_u64 v[164:165], v[222:223], 0, s[14:15]
	s_mov_b32 m0, s69
	s_nop 0
	global_load_lds_dwordx4 v[164:165], off
	s_waitcnt vmcnt(8)
	s_waitcnt lgkmcnt(0)
	s_barrier
	s_setprio 1
	s_waitcnt lgkmcnt(0)
	v_mfma_f32_16x16x32_bf16 v[60:63], v[128:131], v[184:187], v[60:63]
	v_mfma_f32_16x16x32_bf16 v[56:59], v[136:139], v[184:187], v[56:59]
	v_mfma_f32_16x16x32_bf16 v[44:47], v[128:131], v[194:197], v[44:47]
	v_mfma_f32_16x16x32_bf16 v[40:43], v[136:139], v[194:197], v[40:43]
	v_mfma_f32_16x16x32_bf16 v[28:31], v[128:131], v[202:205], v[28:31]
	v_mfma_f32_16x16x32_bf16 v[24:27], v[136:139], v[202:205], v[24:27]
	v_mfma_f32_16x16x32_bf16 v[12:15], v[128:131], v[210:213], v[12:15]
	v_mfma_f32_16x16x32_bf16 v[8:11], v[136:139], v[210:213], v[8:11]
	v_mfma_f32_16x16x32_bf16 v[60:63], v[132:135], v[188:191], v[60:63]
	v_mfma_f32_16x16x32_bf16 v[56:59], v[140:143], v[188:191], v[56:59]
	v_mfma_f32_16x16x32_bf16 v[44:47], v[132:135], v[198:201], v[44:47]
	v_mfma_f32_16x16x32_bf16 v[40:43], v[140:143], v[198:201], v[40:43]
	v_mfma_f32_16x16x32_bf16 v[28:31], v[132:135], v[206:209], v[28:31]
	v_mfma_f32_16x16x32_bf16 v[24:27], v[140:143], v[206:209], v[24:27]
	v_mfma_f32_16x16x32_bf16 v[12:15], v[132:135], v[214:217], v[12:15]
	v_mfma_f32_16x16x32_bf16 v[8:11], v[140:143], v[214:217], v[8:11]
	s_setprio 0
	s_setprio 1
	v_mfma_f32_16x16x32_bf16 v[52:55], v[160:163], v[184:187], v[52:55]
	v_mfma_f32_16x16x32_bf16 v[48:51], v[176:179], v[184:187], v[48:51]
	v_mfma_f32_16x16x32_bf16 v[36:39], v[160:163], v[194:197], v[36:39]
	v_mfma_f32_16x16x32_bf16 v[32:35], v[176:179], v[194:197], v[32:35]
	v_mfma_f32_16x16x32_bf16 v[20:23], v[160:163], v[202:205], v[20:23]
	v_mfma_f32_16x16x32_bf16 v[16:19], v[176:179], v[202:205], v[16:19]
	v_mfma_f32_16x16x32_bf16 v[4:7], v[160:163], v[210:213], v[4:7]
	v_mfma_f32_16x16x32_bf16 v[0:3], v[176:179], v[210:213], v[0:3]
	v_mfma_f32_16x16x32_bf16 v[52:55], v[172:175], v[188:191], v[52:55]
	v_mfma_f32_16x16x32_bf16 v[48:51], v[180:183], v[188:191], v[48:51]
	v_mfma_f32_16x16x32_bf16 v[36:39], v[172:175], v[198:201], v[36:39]
	v_mfma_f32_16x16x32_bf16 v[32:35], v[180:183], v[198:201], v[32:35]
	v_mfma_f32_16x16x32_bf16 v[20:23], v[172:175], v[206:209], v[20:23]
	v_mfma_f32_16x16x32_bf16 v[16:19], v[180:183], v[206:209], v[16:19]
	v_mfma_f32_16x16x32_bf16 v[4:7], v[172:175], v[214:217], v[4:7]
	v_mfma_f32_16x16x32_bf16 v[0:3], v[180:183], v[214:217], v[0:3]
	s_add_i32 s77, s77, 2
	s_add_u32 s75, s75, 0x100
	s_addc_u32 s76, s76, 0
	s_add_u32 s50, s50, 0x100
	s_addc_u32 s51, s51, 0
	s_cmp_gt_u32 s77, 29
	s_setprio 0
	s_barrier
	s_cbranch_scc1 .Lpeel_exit_1
.LBB0_353:
	ds_read_b128 v[128:131], v169
	ds_read_b128 v[132:135], v169 offset:1024
	ds_read_b128 v[136:139], v169 offset:2048
	ds_read_b128 v[140:143], v169 offset:3072
	ds_read_b128 v[160:163], v170
	ds_read_b128 v[172:175], v170 offset:1024
	ds_read_b128 v[176:179], v170 offset:2048
	ds_read_b128 v[180:183], v170 offset:3072
	s_add_u32 s52, s50, 0xfff80080
	s_addc_u32 s53, s51, -1
	s_cmp_eq_u32 s77, 28
	s_cselect_b32 s55, s27, s53
	s_cselect_b32 s54, s73, s52
	s_cselect_b32 s53, s29, s76
	s_cselect_b32 s52, s74, s75
	v_lshl_add_u64 v[164:165], s[50:51], 0, v[154:155]
	s_add_i32 m0, s37, 0xc000
	ds_read_b128 v[184:187], v171
	ds_read_b128 v[188:191], v171 offset:1024
	ds_read_b128 v[194:197], v171 offset:2048
	ds_read_b128 v[198:201], v171 offset:3072
	ds_read_b128 v[202:205], v171 offset:4096
	ds_read_b128 v[206:209], v171 offset:5120
	ds_read_b128 v[210:213], v171 offset:6144
	ds_read_b128 v[214:217], v171 offset:7168
	global_load_lds_dwordx4 v[164:165], off
	v_lshl_add_u64 v[164:165], s[50:51], 0, v[152:153]
	s_add_i32 m0, s37, 0xe000
	s_nop 0
	global_load_lds_dwordx4 v[164:165], off
	s_waitcnt vmcnt(8)
	s_waitcnt lgkmcnt(0)
	s_barrier
; #define PG8_STAGE(bufoff, gbase, voff) do { _Pragma("unroll") for (int _i = 0; _i < 2; ++_i) \
;         __builtin_amdgcn_global_load_lds((const unsigned*)((const char*)(gbase) + (voff)[_i]), (PG8_LAS unsigned*)(lds + (bufoff) + ldsw + _i * 8192), 16, 0, 0); } while (0)
; #define PG8_LDA(dst, b, h) do { _Pragma("unroll") for (int m = 0; m < 4; ++m) _Pragma("unroll") for (int k = 0; k < 2; ++k) dst[m][k] = *(const PG8_LAS bf16x8*)(lds + PG8_SA(b, h) + aoff + m * 2048 + k * 1024); } while (0)
; #define PG8_MMA(ai, bj, At, Bt) do { __builtin_amdgcn_s_setprio(1); _Pragma("unroll") for (int m = 0; m < 4; ++m) _Pragma("unroll") for (int n = 0; n < 2; ++n) _Pragma("unroll") for (int k = 0; k < 2; ++k) \
;         acc[ai][bj][m][n] = __builtin_amdgcn_mfma_f32_16x16x32_bf16(Bt[n][k], At[m][k], acc[ai][bj][m][n], 0, 0, 0); __builtin_amdgcn_s_setprio(0); } while (0)
; #define PG8_WAIT_V(n) asm volatile("s_waitcnt vmcnt(" #n ")" ::: "memory")
; #define PG8_WAIT_L(n) asm volatile("s_waitcnt lgkmcnt(" #n ")" ::: "memory")
; #define PG8_BAR __builtin_amdgcn_s_barrier()
; #define PG8_SCHED __builtin_amdgcn_sched_barrier(0)
; template <class Epi, class Sched, bool ALIGN_EPI = false, bool SP2 = false>
; __device__ __forceinline__ void gemm_phase(PG8_LAS unsigned char* lds, const Gemm g, const Sched& S, const Epi& E) {
;     ...
;             PG8_WAIT_V(8); PG8_WAIT_L(0); PG8_BAR; PG8_MMA(0, 0, At, B0); PG8_MMA(0, 1, At, B1); PG8_BAR; PG8_SCHED;
;             PG8_LDA(At, 0, 1); PG8_STAGE(PG8_SB(0, 0), b2, voffB); PG8_STAGE(PG8_SB(0, 1), b2 + hstep, voffB); PG8_STAGE(PG8_SA(0, 0), a2, voffA);
;             PG8_WAIT_V(8); PG8_WAIT_L(0); PG8_BAR; PG8_MMA(1, 0, At, B0); PG8_MMA(1, 1, At, B1); PG8_BAR; PG8_SCHED;
	s_setprio 1
	s_waitcnt lgkmcnt(0)
	v_mfma_f32_16x16x32_bf16 v[124:127], v[128:131], v[184:187], v[124:127]
	v_mfma_f32_16x16x32_bf16 v[120:123], v[136:139], v[184:187], v[120:123]
	v_mfma_f32_16x16x32_bf16 v[108:111], v[128:131], v[194:197], v[108:111]
	v_mfma_f32_16x16x32_bf16 v[104:107], v[136:139], v[194:197], v[104:107]
	v_mfma_f32_16x16x32_bf16 v[92:95], v[128:131], v[202:205], v[92:95]
	v_mfma_f32_16x16x32_bf16 v[88:91], v[136:139], v[202:205], v[88:91]
	v_mfma_f32_16x16x32_bf16 v[76:79], v[128:131], v[210:213], v[76:79]
	v_mfma_f32_16x16x32_bf16 v[72:75], v[136:139], v[210:213], v[72:75]
	v_mfma_f32_16x16x32_bf16 v[124:127], v[132:135], v[188:191], v[124:127]
	v_mfma_f32_16x16x32_bf16 v[120:123], v[140:143], v[188:191], v[120:123]
	v_mfma_f32_16x16x32_bf16 v[108:111], v[132:135], v[198:201], v[108:111]
	v_mfma_f32_16x16x32_bf16 v[104:107], v[140:143], v[198:201], v[104:107]
	v_mfma_f32_16x16x32_bf16 v[92:95], v[132:135], v[206:209], v[92:95]
	v_mfma_f32_16x16x32_bf16 v[88:91], v[140:143], v[206:209], v[88:91]
	v_mfma_f32_16x16x32_bf16 v[76:79], v[132:135], v[214:217], v[76:79]
	v_mfma_f32_16x16x32_bf16 v[72:75], v[140:143], v[214:217], v[72:75]
	s_setprio 0
	s_setprio 1
	v_mfma_f32_16x16x32_bf16 v[116:119], v[160:163], v[184:187], v[116:119]
	v_mfma_f32_16x16x32_bf16 v[112:115], v[176:179], v[184:187], v[112:115]
	v_mfma_f32_16x16x32_bf16 v[100:103], v[160:163], v[194:197], v[100:103]
	v_mfma_f32_16x16x32_bf16 v[96:99], v[176:179], v[194:197], v[96:99]
	v_mfma_f32_16x16x32_bf16 v[84:87], v[160:163], v[202:205], v[84:87]
	v_mfma_f32_16x16x32_bf16 v[80:83], v[176:179], v[202:205], v[80:83]
	v_mfma_f32_16x16x32_bf16 v[68:71], v[160:163], v[210:213], v[68:71]
	v_mfma_f32_16x16x32_bf16 v[64:67], v[176:179], v[210:213], v[64:67]
	v_mfma_f32_16x16x32_bf16 v[116:119], v[172:175], v[188:191], v[116:119]
	v_mfma_f32_16x16x32_bf16 v[112:115], v[180:183], v[188:191], v[112:115]
	v_mfma_f32_16x16x32_bf16 v[100:103], v[172:175], v[198:201], v[100:103]
	v_mfma_f32_16x16x32_bf16 v[96:99], v[180:183], v[198:201], v[96:99]
	v_mfma_f32_16x16x32_bf16 v[84:87], v[172:175], v[206:209], v[84:87]
	v_mfma_f32_16x16x32_bf16 v[80:83], v[180:183], v[206:209], v[80:83]
	v_mfma_f32_16x16x32_bf16 v[68:71], v[172:175], v[214:217], v[68:71]
	v_mfma_f32_16x16x32_bf16 v[64:67], v[180:183], v[214:217], v[64:67]
	s_setprio 0
	s_barrier
	s_add_i32 s78, s71, s62
	v_lshl_add_u64 v[164:165], s[52:53], 0, v[146:147]
	s_mov_b32 m0, s78
	ds_read_b128 v[184:187], v171 offset:16384
	ds_read_b128 v[188:191], v171 offset:17408
	ds_read_b128 v[194:197], v171 offset:18432
	ds_read_b128 v[198:201], v171 offset:19456
	ds_read_b128 v[202:205], v171 offset:20480
	ds_read_b128 v[206:209], v171 offset:21504
	ds_read_b128 v[210:213], v171 offset:22528
	ds_read_b128 v[214:217], v171 offset:23552
	global_load_lds_dwordx4 v[164:165], off
	s_add_i32 m0, s78, 0x2000
	s_add_u32 s78, s52, 0x80000
	v_lshl_add_u64 v[218:219], s[52:53], 0, v[150:151]
	s_addc_u32 s79, s53, 0
	s_add_i32 s80, s72, s62
	global_load_lds_dwordx4 v[218:219], off
	v_lshl_add_u64 v[220:221], s[78:79], 0, v[146:147]
	s_mov_b32 m0, s80
	v_lshl_add_u64 v[222:223], s[54:55], 0, v[148:149]
	global_load_lds_dwordx4 v[220:221], off
	v_lshl_add_u64 v[220:221], s[78:79], 0, v[150:151]
	s_add_i32 m0, s80, 0x2000
	s_nop 0
	global_load_lds_dwordx4 v[220:221], off
	v_lshl_add_u64 v[220:221], s[54:55], 0, v[144:145]
	s_mov_b32 m0, s37
	s_nop 0
	global_load_lds_dwordx4 v[220:221], off
	s_mov_b32 m0, s49
	s_nop 0
	global_load_lds_dwordx4 v[222:223], off
	s_waitcnt vmcnt(8)
	s_waitcnt lgkmcnt(0)
	s_barrier
	s_setprio 1
	s_waitcnt lgkmcnt(0)
	v_mfma_f32_16x16x32_bf16 v[60:63], v[128:131], v[184:187], v[60:63]
	v_mfma_f32_16x16x32_bf16 v[56:59], v[136:139], v[184:187], v[56:59]
	v_mfma_f32_16x16x32_bf16 v[44:47], v[128:131], v[194:197], v[44:47]
	v_mfma_f32_16x16x32_bf16 v[40:43], v[136:139], v[194:197], v[40:43]
	v_mfma_f32_16x16x32_bf16 v[28:31], v[128:131], v[202:205], v[28:31]
	v_mfma_f32_16x16x32_bf16 v[24:27], v[136:139], v[202:205], v[24:27]
	v_mfma_f32_16x16x32_bf16 v[12:15], v[128:131], v[210:213], v[12:15]
	v_mfma_f32_16x16x32_bf16 v[8:11], v[136:139], v[210:213], v[8:11]
	v_mfma_f32_16x16x32_bf16 v[60:63], v[132:135], v[188:191], v[60:63]
	v_mfma_f32_16x16x32_bf16 v[56:59], v[140:143], v[188:191], v[56:59]
	v_mfma_f32_16x16x32_bf16 v[44:47], v[132:135], v[198:201], v[44:47]
	v_mfma_f32_16x16x32_bf16 v[40:43], v[140:143], v[198:201], v[40:43]
	v_mfma_f32_16x16x32_bf16 v[28:31], v[132:135], v[206:209], v[28:31]
	v_mfma_f32_16x16x32_bf16 v[24:27], v[140:143], v[206:209], v[24:27]
	v_mfma_f32_16x16x32_bf16 v[12:15], v[132:135], v[214:217], v[12:15]
	v_mfma_f32_16x16x32_bf16 v[8:11], v[140:143], v[214:217], v[8:11]
	s_setprio 0
	s_setprio 1
	v_mfma_f32_16x16x32_bf16 v[52:55], v[160:163], v[184:187], v[52:55]
	v_mfma_f32_16x16x32_bf16 v[48:51], v[176:179], v[184:187], v[48:51]
	v_mfma_f32_16x16x32_bf16 v[36:39], v[160:163], v[194:197], v[36:39]
	v_mfma_f32_16x16x32_bf16 v[32:35], v[176:179], v[194:197], v[32:35]
	v_mfma_f32_16x16x32_bf16 v[20:23], v[160:163], v[202:205], v[20:23]
	v_mfma_f32_16x16x32_bf16 v[16:19], v[176:179], v[202:205], v[16:19]
	v_mfma_f32_16x16x32_bf16 v[4:7], v[160:163], v[210:213], v[4:7]
	v_mfma_f32_16x16x32_bf16 v[0:3], v[176:179], v[210:213], v[0:3]
	v_mfma_f32_16x16x32_bf16 v[52:55], v[172:175], v[188:191], v[52:55]
	v_mfma_f32_16x16x32_bf16 v[48:51], v[180:183], v[188:191], v[48:51]
	v_mfma_f32_16x16x32_bf16 v[36:39], v[172:175], v[198:201], v[36:39]
	v_mfma_f32_16x16x32_bf16 v[32:35], v[180:183], v[198:201], v[32:35]
	v_mfma_f32_16x16x32_bf16 v[20:23], v[172:175], v[206:209], v[20:23]
	v_mfma_f32_16x16x32_bf16 v[16:19], v[180:183], v[206:209], v[16:19]
	v_mfma_f32_16x16x32_bf16 v[4:7], v[172:175], v[214:217], v[4:7]
	v_mfma_f32_16x16x32_bf16 v[0:3], v[180:183], v[214:217], v[0:3]
	s_setprio 0
	s_barrier
; #define PG8_STAGE(bufoff, gbase, voff) do { _Pragma("unroll") for (int _i = 0; _i < 2; ++_i) \
;         __builtin_amdgcn_global_load_lds((const unsigned*)((const char*)(gbase) + (voff)[_i]), (PG8_LAS unsigned*)(lds + (bufoff) + ldsw + _i * 8192), 16, 0, 0); } while (0)
; #define PG8_LDA(dst, b, h) do { _Pragma("unroll") for (int m = 0; m < 4; ++m) _Pragma("unroll") for (int k = 0; k < 2; ++k) dst[m][k] = *(const PG8_LAS bf16x8*)(lds + PG8_SA(b, h) + aoff + m * 2048 + k * 1024); } while (0)
; #define PG8_LDB(dst, b, h) do { _Pragma("unroll") for (int n = 0; n < 2; ++n) _Pragma("unroll") for (int k = 0; k < 2; ++k) dst[n][k] = *(const PG8_LAS bf16x8*)(lds + PG8_SB(b, h) + boff + n * 2048 + k * 1024); } while (0)
; #define PG8_MMA(ai, bj, At, Bt) do { __builtin_amdgcn_s_setprio(1); _Pragma("unroll") for (int m = 0; m < 4; ++m) _Pragma("unroll") for (int n = 0; n < 2; ++n) _Pragma("unroll") for (int k = 0; k < 2; ++k) \
;         acc[ai][bj][m][n] = __builtin_amdgcn_mfma_f32_16x16x32_bf16(Bt[n][k], At[m][k], acc[ai][bj][m][n], 0, 0, 0); __builtin_amdgcn_s_setprio(0); } while (0)
; #define PG8_WAIT_V(n) asm volatile("s_waitcnt vmcnt(" #n ")" ::: "memory")
; #define PG8_WAIT_L(n) asm volatile("s_waitcnt lgkmcnt(" #n ")" ::: "memory")
; #define PG8_BAR __builtin_amdgcn_s_barrier()
; #define PG8_SCHED __builtin_amdgcn_sched_barrier(0)
; template <class Epi, class Sched, bool ALIGN_EPI = false, bool SP2 = false>
; __device__ __forceinline__ void gemm_phase(PG8_LAS unsigned char* lds, const Gemm g, const Sched& S, const Epi& E) {
;     ...
;             PG8_LDB(B0, 1, 0); PG8_LDB(B1, 1, 1); PG8_SCHED; PG8_LDA(At, 1, 0); PG8_STAGE(PG8_SA(0, 1), a2 + hstep, voffA);
;             PG8_WAIT_V(8); PG8_WAIT_L(0); PG8_BAR; PG8_MMA(0, 0, At, B0); PG8_MMA(0, 1, At, B1); PG8_BAR; PG8_SCHED;
	s_add_i32 s78, 0, 0x18000
	s_add_i32 s79, 0, 0x1c000
	v_add_u32_e32 v140, s78, v167
	v_add_u32_e32 v180, s79, v167
	ds_read_b128 v[128:131], v140
	ds_read_b128 v[132:135], v140 offset:1024
	ds_read_b128 v[136:139], v140 offset:2048
	ds_read_b128 v[140:143], v140 offset:3072
	ds_read_b128 v[160:163], v180
	ds_read_b128 v[172:175], v180 offset:1024
	ds_read_b128 v[176:179], v180 offset:2048
	ds_read_b128 v[180:183], v180 offset:3072
	s_add_u32 s54, s54, 0x80000
	s_addc_u32 s55, s55, 0
	s_mov_b32 m0, s63
	v_lshl_add_u64 v[224:225], s[54:55], 0, v[144:145]
	ds_read_b128 v[184:187], v171 offset:32768
	ds_read_b128 v[188:191], v171 offset:33792
	ds_read_b128 v[194:197], v171 offset:34816
	ds_read_b128 v[198:201], v171 offset:35840
	ds_read_b128 v[202:205], v171 offset:36864
	ds_read_b128 v[206:209], v171 offset:37888
	ds_read_b128 v[210:213], v171 offset:38912
	ds_read_b128 v[214:217], v171 offset:39936
	global_load_lds_dwordx4 v[224:225], off
	v_lshl_add_u64 v[224:225], s[54:55], 0, v[148:149]
	s_mov_b32 m0, s64
	s_nop 0
	global_load_lds_dwordx4 v[224:225], off
	s_waitcnt vmcnt(8)
	s_waitcnt lgkmcnt(0)
	s_barrier
	s_setprio 1
	s_waitcnt lgkmcnt(0)
	v_mfma_f32_16x16x32_bf16 v[124:127], v[128:131], v[184:187], v[124:127]
	v_mfma_f32_16x16x32_bf16 v[120:123], v[136:139], v[184:187], v[120:123]
	v_mfma_f32_16x16x32_bf16 v[108:111], v[128:131], v[194:197], v[108:111]
	v_mfma_f32_16x16x32_bf16 v[104:107], v[136:139], v[194:197], v[104:107]
	v_mfma_f32_16x16x32_bf16 v[92:95], v[128:131], v[202:205], v[92:95]
	v_mfma_f32_16x16x32_bf16 v[88:91], v[136:139], v[202:205], v[88:91]
	v_mfma_f32_16x16x32_bf16 v[76:79], v[128:131], v[210:213], v[76:79]
	v_mfma_f32_16x16x32_bf16 v[72:75], v[136:139], v[210:213], v[72:75]
	v_mfma_f32_16x16x32_bf16 v[124:127], v[132:135], v[188:191], v[124:127]
	v_mfma_f32_16x16x32_bf16 v[120:123], v[140:143], v[188:191], v[120:123]
	v_mfma_f32_16x16x32_bf16 v[108:111], v[132:135], v[198:201], v[108:111]
	v_mfma_f32_16x16x32_bf16 v[104:107], v[140:143], v[198:201], v[104:107]
	v_mfma_f32_16x16x32_bf16 v[92:95], v[132:135], v[206:209], v[92:95]
	v_mfma_f32_16x16x32_bf16 v[88:91], v[140:143], v[206:209], v[88:91]
	v_mfma_f32_16x16x32_bf16 v[76:79], v[132:135], v[214:217], v[76:79]
	v_mfma_f32_16x16x32_bf16 v[72:75], v[140:143], v[214:217], v[72:75]
	s_setprio 0
	s_setprio 1
	v_mfma_f32_16x16x32_bf16 v[116:119], v[160:163], v[184:187], v[116:119]
	v_mfma_f32_16x16x32_bf16 v[112:115], v[176:179], v[184:187], v[112:115]
	v_mfma_f32_16x16x32_bf16 v[100:103], v[160:163], v[194:197], v[100:103]
	v_mfma_f32_16x16x32_bf16 v[96:99], v[176:179], v[194:197], v[96:99]
	v_mfma_f32_16x16x32_bf16 v[84:87], v[160:163], v[202:205], v[84:87]
	v_mfma_f32_16x16x32_bf16 v[80:83], v[176:179], v[202:205], v[80:83]
	v_mfma_f32_16x16x32_bf16 v[68:71], v[160:163], v[210:213], v[68:71]
	v_mfma_f32_16x16x32_bf16 v[64:67], v[176:179], v[210:213], v[64:67]
	v_mfma_f32_16x16x32_bf16 v[116:119], v[172:175], v[188:191], v[116:119]
	v_mfma_f32_16x16x32_bf16 v[112:115], v[180:183], v[188:191], v[112:115]
	v_mfma_f32_16x16x32_bf16 v[100:103], v[172:175], v[198:201], v[100:103]
	v_mfma_f32_16x16x32_bf16 v[96:99], v[180:183], v[198:201], v[96:99]
	v_mfma_f32_16x16x32_bf16 v[84:87], v[172:175], v[206:209], v[84:87]
	v_mfma_f32_16x16x32_bf16 v[80:83], v[180:183], v[206:209], v[80:83]
	v_mfma_f32_16x16x32_bf16 v[68:71], v[172:175], v[214:217], v[68:71]
	v_mfma_f32_16x16x32_bf16 v[64:67], v[180:183], v[214:217], v[64:67]
	s_setprio 0
	s_barrier
; #define PG8_STAGE(bufoff, gbase, voff) do { _Pragma("unroll") for (int _i = 0; _i < 2; ++_i) \
;         __builtin_amdgcn_global_load_lds((const unsigned*)((const char*)(gbase) + (voff)[_i]), (PG8_LAS unsigned*)(lds + (bufoff) + ldsw + _i * 8192), 16, 0, 0); } while (0)
; #define PG8_LDA(dst, b, h) do { _Pragma("unroll") for (int m = 0; m < 4; ++m) _Pragma("unroll") for (int k = 0; k < 2; ++k) dst[m][k] = *(const PG8_LAS bf16x8*)(lds + PG8_SA(b, h) + aoff + m * 2048 + k * 1024); } while (0)
; #define PG8_MMA(ai, bj, At, Bt) do { __builtin_amdgcn_s_setprio(1); _Pragma("unroll") for (int m = 0; m < 4; ++m) _Pragma("unroll") for (int n = 0; n < 2; ++n) _Pragma("unroll") for (int k = 0; k < 2; ++k) \
;         acc[ai][bj][m][n] = __builtin_amdgcn_mfma_f32_16x16x32_bf16(Bt[n][k], At[m][k], acc[ai][bj][m][n], 0, 0, 0); __builtin_amdgcn_s_setprio(0); } while (0)
; #define PG8_WAIT_V(n) asm volatile("s_waitcnt vmcnt(" #n ")" ::: "memory")
; #define PG8_WAIT_L(n) asm volatile("s_waitcnt lgkmcnt(" #n ")" ::: "memory")
; #define PG8_BAR __builtin_amdgcn_s_barrier()
; #define PG8_SCHED __builtin_amdgcn_sched_barrier(0)
; template <class Epi, class Sched, bool ALIGN_EPI = false, bool SP2 = false>
; __device__ __forceinline__ void gemm_phase(PG8_LAS unsigned char* lds, const Gemm g, const Sched& S, const Epi& E) {
;     ...
;         for (int t = 0; t < nt; t += 2) {
;     ...
;             PG8_LDA(At, 1, 1); PG8_STAGE(PG8_SB(1, 0), b3, voffB); PG8_STAGE(PG8_SB(1, 1), b3 + hstep, voffB); PG8_STAGE(PG8_SA(1, 0), a3, voffA);
;             PG8_WAIT_V(8); PG8_WAIT_L(0); PG8_BAR; PG8_MMA(1, 0, At, B0); PG8_MMA(1, 1, At, B1); PG8_BAR; PG8_SCHED;
	s_add_i32 s54, s78, s62
	v_lshl_add_u64 v[164:165], v[164:165], 0, s[14:15]
	s_mov_b32 m0, s54
	ds_read_b128 v[184:187], v171 offset:49152
	ds_read_b128 v[188:191], v171 offset:50176
	ds_read_b128 v[194:197], v171 offset:51200
	ds_read_b128 v[198:201], v171 offset:52224
	ds_read_b128 v[202:205], v171 offset:53248
	ds_read_b128 v[206:209], v171 offset:54272
	ds_read_b128 v[210:213], v171 offset:55296
	ds_read_b128 v[214:217], v171 offset:56320
	global_load_lds_dwordx4 v[164:165], off
	s_add_i32 m0, s54, 0x2000
	s_add_u32 s52, s52, 0x80080
	v_lshl_add_u64 v[164:165], v[218:219], 0, s[14:15]
	s_addc_u32 s53, s53, 0
	s_add_i32 s54, s79, s62
	global_load_lds_dwordx4 v[164:165], off
	v_lshl_add_u64 v[164:165], s[52:53], 0, v[146:147]
	s_mov_b32 m0, s54
	s_nop 0
	global_load_lds_dwordx4 v[164:165], off
	v_lshl_add_u64 v[164:165], s[52:53], 0, v[150:151]
	s_add_i32 m0, s54, 0x2000
	s_nop 0
	global_load_lds_dwordx4 v[164:165], off
	v_lshl_add_u64 v[164:165], v[220:221], 0, s[14:15]
	s_mov_b32 m0, s68
	s_nop 0
	global_load_lds_dwordx4 v[164:165], off
	v_lshl_add_u64 v[164:165], v[222:223], 0, s[14:15]
	s_mov_b32 m0, s69
	s_nop 0
	global_load_lds_dwordx4 v[164:165], off
	s_waitcnt vmcnt(8)
	s_waitcnt lgkmcnt(0)
	s_barrier
	s_setprio 1
	s_waitcnt lgkmcnt(0)
	v_mfma_f32_16x16x32_bf16 v[60:63], v[128:131], v[184:187], v[60:63]
	v_mfma_f32_16x16x32_bf16 v[56:59], v[136:139], v[184:187], v[56:59]
	v_mfma_f32_16x16x32_bf16 v[44:47], v[128:131], v[194:197], v[44:47]
	v_mfma_f32_16x16x32_bf16 v[40:43], v[136:139], v[194:197], v[40:43]
	v_mfma_f32_16x16x32_bf16 v[28:31], v[128:131], v[202:205], v[28:31]
	v_mfma_f32_16x16x32_bf16 v[24:27], v[136:139], v[202:205], v[24:27]
	v_mfma_f32_16x16x32_bf16 v[12:15], v[128:131], v[210:213], v[12:15]
	v_mfma_f32_16x16x32_bf16 v[8:11], v[136:139], v[210:213], v[8:11]
	v_mfma_f32_16x16x32_bf16 v[60:63], v[132:135], v[188:191], v[60:63]
	v_mfma_f32_16x16x32_bf16 v[56:59], v[140:143], v[188:191], v[56:59]
	v_mfma_f32_16x16x32_bf16 v[44:47], v[132:135], v[198:201], v[44:47]
	v_mfma_f32_16x16x32_bf16 v[40:43], v[140:143], v[198:201], v[40:43]
	v_mfma_f32_16x16x32_bf16 v[28:31], v[132:135], v[206:209], v[28:31]
	v_mfma_f32_16x16x32_bf16 v[24:27], v[140:143], v[206:209], v[24:27]
	v_mfma_f32_16x16x32_bf16 v[12:15], v[132:135], v[214:217], v[12:15]
	v_mfma_f32_16x16x32_bf16 v[8:11], v[140:143], v[214:217], v[8:11]
	s_setprio 0
	s_setprio 1
	v_mfma_f32_16x16x32_bf16 v[52:55], v[160:163], v[184:187], v[52:55]
	v_mfma_f32_16x16x32_bf16 v[48:51], v[176:179], v[184:187], v[48:51]
	v_mfma_f32_16x16x32_bf16 v[36:39], v[160:163], v[194:197], v[36:39]
	v_mfma_f32_16x16x32_bf16 v[32:35], v[176:179], v[194:197], v[32:35]
	v_mfma_f32_16x16x32_bf16 v[20:23], v[160:163], v[202:205], v[20:23]
	v_mfma_f32_16x16x32_bf16 v[16:19], v[176:179], v[202:205], v[16:19]
	v_mfma_f32_16x16x32_bf16 v[4:7], v[160:163], v[210:213], v[4:7]
	v_mfma_f32_16x16x32_bf16 v[0:3], v[176:179], v[210:213], v[0:3]
	v_mfma_f32_16x16x32_bf16 v[52:55], v[172:175], v[188:191], v[52:55]
	v_mfma_f32_16x16x32_bf16 v[48:51], v[180:183], v[188:191], v[48:51]
	v_mfma_f32_16x16x32_bf16 v[36:39], v[172:175], v[198:201], v[36:39]
	v_mfma_f32_16x16x32_bf16 v[32:35], v[180:183], v[198:201], v[32:35]
	v_mfma_f32_16x16x32_bf16 v[20:23], v[172:175], v[206:209], v[20:23]
	v_mfma_f32_16x16x32_bf16 v[16:19], v[180:183], v[206:209], v[16:19]
	v_mfma_f32_16x16x32_bf16 v[4:7], v[172:175], v[214:217], v[4:7]
	v_mfma_f32_16x16x32_bf16 v[0:3], v[180:183], v[214:217], v[0:3]
	s_add_i32 s77, s77, 2
	s_add_u32 s75, s75, 0x100
	s_addc_u32 s76, s76, 0
	s_add_u32 s50, s50, 0x100
	s_addc_u32 s51, s51, 0
	s_cmp_gt_u32 s77, 29
	s_setprio 0
	s_barrier
	s_cbranch_scc0 .LBB0_353

; #define PG8_STAGE(bufoff, gbase, voff) do { _Pragma("unroll") for (int _i = 0; _i < 2; ++_i) \
;         __builtin_amdgcn_global_load_lds((const unsigned*)((const char*)(gbase) + (voff)[_i]), (PG8_LAS unsigned*)(lds + (bufoff) + ldsw + _i * 8192), 16, 0, 0); } while (0)
; #define PG8_LDA(dst, b, h) do { _Pragma("unroll") for (int m = 0; m < 4; ++m) _Pragma("unroll") for (int k = 0; k < 2; ++k) dst[m][k] = *(const PG8_LAS bf16x8*)(lds + PG8_SA(b, h) + aoff + m * 2048 + k * 1024); } while (0)
; #define PG8_LDB(dst, b, h) do { _Pragma("unroll") for (int n = 0; n < 2; ++n) _Pragma("unroll") for (int k = 0; k < 2; ++k) dst[n][k] = *(const PG8_LAS bf16x8*)(lds + PG8_SB(b, h) + boff + n * 2048 + k * 1024); } while (0)
; #define PG8_MMA(ai, bj, At, Bt) do { __builtin_amdgcn_s_setprio(1); _Pragma("unroll") for (int m = 0; m < 4; ++m) _Pragma("unroll") for (int n = 0; n < 2; ++n) _Pragma("unroll") for (int k = 0; k < 2; ++k) \
;         acc[ai][bj][m][n] = __builtin_amdgcn_mfma_f32_16x16x32_bf16(Bt[n][k], At[m][k], acc[ai][bj][m][n], 0, 0, 0); __builtin_amdgcn_s_setprio(0); } while (0)
; #define PG8_WAIT_V(n) asm volatile("s_waitcnt vmcnt(" #n ")" ::: "memory")
; template <class Epi, class Sched, bool ALIGN_EPI = false, bool SP2 = false>
; __device__ __forceinline__ void gemm_phase(PG8_LAS unsigned char* lds, const Gemm g, const Sched& S, const Epi& E) {
;     ...
;         const char* nA = has_next ? (const char*)g.A + (size_t)nxt.pm * tstep : cA; const char* nB = has_next ? (const char*)g.Bt + (size_t)nxt.pn * tstep : cB;
;         for (int t = 0; t < nt; t += 2) {
;             const bool last = (t == nt - 2);
;             const char* a1 = cA + (size_t)(t + 1) * kstep;
;             const char* a2 = last ? nA : cA + (size_t)(t + 2) * kstep; const char* b2 = last ? nB : cB + (size_t)(t + 2) * kstep;
;             const char* a3 = a2 + kstep; const char* b3 = b2 + kstep;
;             if (last && has_next) S.a_ready(nxt);
;             if constexpr (SP2) {
;             PG8_LDB(B0, 0, 0); PG8_LDB(B1, 0, 1); PG8_SCHED; PG8_LDA(At, 0, 0); PG8_STAGE(PG8_SA(1, 1), a1 + hstep, voffA);
;             PG8_WAIT_V(8); PG8_WAIT_L(0); PG8_BAR; PG8_MMA(0, 0, At, B0); PG8_MMA(0, 1, At, B1); PG8_BAR; PG8_SCHED;
;             PG8_LDA(At, 0, 1); PG8_STAGE(PG8_SB(0, 0), b2, voffB); PG8_STAGE(PG8_SB(0, 1), b2 + hstep, voffB); PG8_STAGE(PG8_SA(0, 0), a2, voffA);
.LBB0_480:
	s_ashr_i32 s17, s16, 31
	s_lshl_b64 s[20:21], s[16:17], 20
	s_add_u32 s20, s49, s20
	s_addc_u32 s21, s50, s21
	s_and_b64 s[22:23], s[6:7], exec
	s_cselect_b32 s17, s21, s31
	s_cselect_b32 s63, s20, s30
	s_ashr_i32 s19, s18, 31
	s_lshl_b64 s[22:23], s[18:19], 20
	s_add_u32 s22, s37, s22
	s_addc_u32 s23, s48, s23
	s_and_b64 s[34:35], s[6:7], exec
	s_cselect_b32 s19, s23, s29
	s_cselect_b32 s64, s22, s28
	s_add_u32 s65, s28, 0x100
	s_addc_u32 s66, s29, 0
	s_add_u32 s28, s30, 0x80080
	s_addc_u32 s29, s31, 0
	s_mov_b32 s67, -2
	ds_read_b128 v[144:147], v151
	ds_read_b128 v[154:157], v151 offset:1024
	ds_read_b128 v[158:161], v151 offset:2048
	ds_read_b128 v[162:165], v151 offset:3072
	ds_read_b128 v[166:169], v152
	ds_read_b128 v[170:173], v152 offset:1024
	ds_read_b128 v[174:177], v152 offset:2048
	ds_read_b128 v[178:181], v152 offset:3072
	s_add_u32 s30, s28, 0xfff80080
	s_addc_u32 s31, s29, -1
	s_cmp_eq_u32 s67, 28
	s_cselect_b32 s35, s17, s31
	s_cselect_b32 s34, s63, s30
	s_cselect_b32 s31, s19, s66
	s_cselect_b32 s30, s64, s65
	v_lshl_add_u64 v[190:191], s[28:29], 0, v[138:139]
	s_add_i32 m0, s25, 0xc000
	ds_read_b128 v[182:185], v153
	ds_read_b128 v[186:189], v153 offset:1024
	ds_read_b128 v[194:197], v153 offset:2048
	ds_read_b128 v[198:201], v153 offset:3072
	ds_read_b128 v[202:205], v153 offset:4096
	ds_read_b128 v[206:209], v153 offset:5120
	ds_read_b128 v[210:213], v153 offset:6144
	ds_read_b128 v[214:217], v153 offset:7168
	global_load_lds_dwordx4 v[190:191], off
	v_lshl_add_u64 v[190:191], s[28:29], 0, v[136:137]
	s_add_i32 m0, s25, 0xe000
	s_nop 0
	global_load_lds_dwordx4 v[190:191], off
	s_waitcnt vmcnt(8)
	s_waitcnt lgkmcnt(0)
	s_barrier
	s_setprio 1
	s_waitcnt lgkmcnt(0)
	v_mfma_f32_16x16x32_bf16 v[124:127], v[144:147], v[182:185], 0
	v_mfma_f32_16x16x32_bf16 v[120:123], v[158:161], v[182:185], 0
	v_mfma_f32_16x16x32_bf16 v[108:111], v[144:147], v[194:197], 0
	v_mfma_f32_16x16x32_bf16 v[104:107], v[158:161], v[194:197], 0
	v_mfma_f32_16x16x32_bf16 v[92:95], v[144:147], v[202:205], 0
	v_mfma_f32_16x16x32_bf16 v[88:91], v[158:161], v[202:205], 0
	v_mfma_f32_16x16x32_bf16 v[76:79], v[144:147], v[210:213], 0
	v_mfma_f32_16x16x32_bf16 v[72:75], v[158:161], v[210:213], 0
	v_mfma_f32_16x16x32_bf16 v[124:127], v[154:157], v[186:189], v[124:127]
	v_mfma_f32_16x16x32_bf16 v[120:123], v[162:165], v[186:189], v[120:123]
	v_mfma_f32_16x16x32_bf16 v[108:111], v[154:157], v[198:201], v[108:111]
	v_mfma_f32_16x16x32_bf16 v[104:107], v[162:165], v[198:201], v[104:107]
	v_mfma_f32_16x16x32_bf16 v[92:95], v[154:157], v[206:209], v[92:95]
	v_mfma_f32_16x16x32_bf16 v[88:91], v[162:165], v[206:209], v[88:91]
	v_mfma_f32_16x16x32_bf16 v[76:79], v[154:157], v[214:217], v[76:79]
	v_mfma_f32_16x16x32_bf16 v[72:75], v[162:165], v[214:217], v[72:75]
	s_setprio 0
	s_setprio 1
	v_mfma_f32_16x16x32_bf16 v[116:119], v[166:169], v[182:185], 0
	v_mfma_f32_16x16x32_bf16 v[112:115], v[174:177], v[182:185], 0
	v_mfma_f32_16x16x32_bf16 v[100:103], v[166:169], v[194:197], 0
	v_mfma_f32_16x16x32_bf16 v[96:99], v[174:177], v[194:197], 0
	v_mfma_f32_16x16x32_bf16 v[84:87], v[166:169], v[202:205], 0
	v_mfma_f32_16x16x32_bf16 v[80:83], v[174:177], v[202:205], 0
	v_mfma_f32_16x16x32_bf16 v[68:71], v[166:169], v[210:213], 0
	v_mfma_f32_16x16x32_bf16 v[64:67], v[174:177], v[210:213], 0
	v_mfma_f32_16x16x32_bf16 v[116:119], v[170:173], v[186:189], v[116:119]
	v_mfma_f32_16x16x32_bf16 v[112:115], v[178:181], v[186:189], v[112:115]
	v_mfma_f32_16x16x32_bf16 v[100:103], v[170:173], v[198:201], v[100:103]
	v_mfma_f32_16x16x32_bf16 v[96:99], v[178:181], v[198:201], v[96:99]
	v_mfma_f32_16x16x32_bf16 v[84:87], v[170:173], v[206:209], v[84:87]
	v_mfma_f32_16x16x32_bf16 v[80:83], v[178:181], v[206:209], v[80:83]
	v_mfma_f32_16x16x32_bf16 v[68:71], v[170:173], v[214:217], v[68:71]
	v_mfma_f32_16x16x32_bf16 v[64:67], v[178:181], v[214:217], v[64:67]
	s_setprio 0
	s_barrier
	s_add_i32 s68, s60, s51
	v_lshl_add_u64 v[190:191], s[30:31], 0, v[132:133]
	s_mov_b32 m0, s68
	ds_read_b128 v[182:185], v153 offset:16384
	ds_read_b128 v[186:189], v153 offset:17408
	ds_read_b128 v[194:197], v153 offset:18432
	ds_read_b128 v[198:201], v153 offset:19456
	ds_read_b128 v[202:205], v153 offset:20480
	ds_read_b128 v[206:209], v153 offset:21504
	ds_read_b128 v[210:213], v153 offset:22528
	ds_read_b128 v[214:217], v153 offset:23552
	global_load_lds_dwordx4 v[190:191], off
	s_add_i32 m0, s68, 0x2000
	s_add_u32 s68, s30, 0x80000
	v_lshl_add_u64 v[218:219], s[30:31], 0, v[128:129]
	s_addc_u32 s69, s31, 0
	s_add_i32 s70, s61, s51
	global_load_lds_dwordx4 v[218:219], off
	v_lshl_add_u64 v[220:221], s[68:69], 0, v[132:133]
	s_mov_b32 m0, s70
	v_lshl_add_u64 v[222:223], s[34:35], 0, v[130:131]
	global_load_lds_dwordx4 v[220:221], off
	v_lshl_add_u64 v[220:221], s[68:69], 0, v[128:129]
	s_add_i32 m0, s70, 0x2000
	s_nop 0
	global_load_lds_dwordx4 v[220:221], off
	v_lshl_add_u64 v[220:221], s[34:35], 0, v[134:135]
	s_mov_b32 m0, s25
	s_nop 0
	global_load_lds_dwordx4 v[220:221], off
	s_mov_b32 m0, s27
	s_nop 0
	global_load_lds_dwordx4 v[222:223], off
	s_waitcnt vmcnt(8)
	s_waitcnt lgkmcnt(0)
	s_barrier
; #define PG8_STAGE(bufoff, gbase, voff) do { _Pragma("unroll") for (int _i = 0; _i < 2; ++_i) \
;         __builtin_amdgcn_global_load_lds((const unsigned*)((const char*)(gbase) + (voff)[_i]), (PG8_LAS unsigned*)(lds + (bufoff) + ldsw + _i * 8192), 16, 0, 0); } while (0)
; #define PG8_LDA(dst, b, h) do { _Pragma("unroll") for (int m = 0; m < 4; ++m) _Pragma("unroll") for (int k = 0; k < 2; ++k) dst[m][k] = *(const PG8_LAS bf16x8*)(lds + PG8_SA(b, h) + aoff + m * 2048 + k * 1024); } while (0)
; #define PG8_LDB(dst, b, h) do { _Pragma("unroll") for (int n = 0; n < 2; ++n) _Pragma("unroll") for (int k = 0; k < 2; ++k) dst[n][k] = *(const PG8_LAS bf16x8*)(lds + PG8_SB(b, h) + boff + n * 2048 + k * 1024); } while (0)
; #define PG8_MMA(ai, bj, At, Bt) do { __builtin_amdgcn_s_setprio(1); _Pragma("unroll") for (int m = 0; m < 4; ++m) _Pragma("unroll") for (int n = 0; n < 2; ++n) _Pragma("unroll") for (int k = 0; k < 2; ++k) \
;         acc[ai][bj][m][n] = __builtin_amdgcn_mfma_f32_16x16x32_bf16(Bt[n][k], At[m][k], acc[ai][bj][m][n], 0, 0, 0); __builtin_amdgcn_s_setprio(0); } while (0)
; #define PG8_WAIT_V(n) asm volatile("s_waitcnt vmcnt(" #n ")" ::: "memory")
; #define PG8_WAIT_L(n) asm volatile("s_waitcnt lgkmcnt(" #n ")" ::: "memory")
; #define PG8_BAR __builtin_amdgcn_s_barrier()
; #define PG8_SCHED __builtin_amdgcn_sched_barrier(0)
; template <class Epi, class Sched, bool ALIGN_EPI = false, bool SP2 = false>
; __device__ __forceinline__ void gemm_phase(PG8_LAS unsigned char* lds, const Gemm g, const Sched& S, const Epi& E) {
;     ...
;             PG8_WAIT_V(8); PG8_WAIT_L(0); PG8_BAR; PG8_MMA(1, 0, At, B0); PG8_MMA(1, 1, At, B1); PG8_BAR; PG8_SCHED;
;             PG8_LDB(B0, 1, 0); PG8_LDB(B1, 1, 1); PG8_SCHED; PG8_LDA(At, 1, 0); PG8_STAGE(PG8_SA(0, 1), a2 + hstep, voffA);
;             PG8_WAIT_V(8); PG8_WAIT_L(0); PG8_BAR; PG8_MMA(0, 0, At, B0); PG8_MMA(0, 1, At, B1); PG8_BAR; PG8_SCHED;
	s_setprio 1
	s_waitcnt lgkmcnt(0)
	v_mfma_f32_16x16x32_bf16 v[60:63], v[144:147], v[182:185], 0
	v_mfma_f32_16x16x32_bf16 v[56:59], v[158:161], v[182:185], 0
	v_mfma_f32_16x16x32_bf16 v[44:47], v[144:147], v[194:197], 0
	v_mfma_f32_16x16x32_bf16 v[40:43], v[158:161], v[194:197], 0
	v_mfma_f32_16x16x32_bf16 v[28:31], v[144:147], v[202:205], 0
	v_mfma_f32_16x16x32_bf16 v[24:27], v[158:161], v[202:205], 0
	v_mfma_f32_16x16x32_bf16 v[12:15], v[144:147], v[210:213], 0
	v_mfma_f32_16x16x32_bf16 v[8:11], v[158:161], v[210:213], 0
	v_mfma_f32_16x16x32_bf16 v[60:63], v[154:157], v[186:189], v[60:63]
	v_mfma_f32_16x16x32_bf16 v[56:59], v[162:165], v[186:189], v[56:59]
	v_mfma_f32_16x16x32_bf16 v[44:47], v[154:157], v[198:201], v[44:47]
	v_mfma_f32_16x16x32_bf16 v[40:43], v[162:165], v[198:201], v[40:43]
	v_mfma_f32_16x16x32_bf16 v[28:31], v[154:157], v[206:209], v[28:31]
	v_mfma_f32_16x16x32_bf16 v[24:27], v[162:165], v[206:209], v[24:27]
	v_mfma_f32_16x16x32_bf16 v[12:15], v[154:157], v[214:217], v[12:15]
	v_mfma_f32_16x16x32_bf16 v[8:11], v[162:165], v[214:217], v[8:11]
	s_setprio 0
	s_setprio 1
	v_mfma_f32_16x16x32_bf16 v[52:55], v[166:169], v[182:185], 0
	v_mfma_f32_16x16x32_bf16 v[48:51], v[174:177], v[182:185], 0
	v_mfma_f32_16x16x32_bf16 v[36:39], v[166:169], v[194:197], 0
	v_mfma_f32_16x16x32_bf16 v[32:35], v[174:177], v[194:197], 0
	v_mfma_f32_16x16x32_bf16 v[20:23], v[166:169], v[202:205], 0
	v_mfma_f32_16x16x32_bf16 v[16:19], v[174:177], v[202:205], 0
	v_mfma_f32_16x16x32_bf16 v[4:7], v[166:169], v[210:213], 0
	v_mfma_f32_16x16x32_bf16 v[0:3], v[174:177], v[210:213], 0
	v_mfma_f32_16x16x32_bf16 v[52:55], v[170:173], v[186:189], v[52:55]
	v_mfma_f32_16x16x32_bf16 v[48:51], v[178:181], v[186:189], v[48:51]
	v_mfma_f32_16x16x32_bf16 v[36:39], v[170:173], v[198:201], v[36:39]
	v_mfma_f32_16x16x32_bf16 v[32:35], v[178:181], v[198:201], v[32:35]
	v_mfma_f32_16x16x32_bf16 v[20:23], v[170:173], v[206:209], v[20:23]
	v_mfma_f32_16x16x32_bf16 v[16:19], v[178:181], v[206:209], v[16:19]
	v_mfma_f32_16x16x32_bf16 v[4:7], v[170:173], v[214:217], v[4:7]
	v_mfma_f32_16x16x32_bf16 v[0:3], v[178:181], v[214:217], v[0:3]
	s_setprio 0
	s_barrier
	s_add_i32 s68, 0, 0x18000
	s_add_i32 s69, 0, 0x1c000
	v_add_u32_e32 v162, s68, v149
	v_add_u32_e32 v178, s69, v149
	ds_read_b128 v[144:147], v162
	ds_read_b128 v[154:157], v162 offset:1024
	ds_read_b128 v[158:161], v162 offset:2048
	ds_read_b128 v[162:165], v162 offset:3072
	ds_read_b128 v[166:169], v178
	ds_read_b128 v[170:173], v178 offset:1024
	ds_read_b128 v[174:177], v178 offset:2048
	ds_read_b128 v[178:181], v178 offset:3072
	s_add_u32 s34, s34, 0x80000
	s_addc_u32 s35, s35, 0
	s_mov_b32 m0, s54
	v_lshl_add_u64 v[224:225], s[34:35], 0, v[134:135]
	ds_read_b128 v[182:185], v153 offset:32768
	ds_read_b128 v[186:189], v153 offset:33792
	ds_read_b128 v[194:197], v153 offset:34816
	ds_read_b128 v[198:201], v153 offset:35840
	ds_read_b128 v[202:205], v153 offset:36864
	ds_read_b128 v[206:209], v153 offset:37888
	ds_read_b128 v[210:213], v153 offset:38912
	ds_read_b128 v[214:217], v153 offset:39936
	global_load_lds_dwordx4 v[224:225], off
	v_lshl_add_u64 v[224:225], s[34:35], 0, v[130:131]
	s_mov_b32 m0, s55
	s_nop 0
	global_load_lds_dwordx4 v[224:225], off
	s_waitcnt vmcnt(8)
	s_waitcnt lgkmcnt(0)
	s_barrier
	s_setprio 1
	s_waitcnt lgkmcnt(0)
	v_mfma_f32_16x16x32_bf16 v[124:127], v[144:147], v[182:185], v[124:127]
	v_mfma_f32_16x16x32_bf16 v[120:123], v[158:161], v[182:185], v[120:123]
	v_mfma_f32_16x16x32_bf16 v[108:111], v[144:147], v[194:197], v[108:111]
	v_mfma_f32_16x16x32_bf16 v[104:107], v[158:161], v[194:197], v[104:107]
	v_mfma_f32_16x16x32_bf16 v[92:95], v[144:147], v[202:205], v[92:95]
	v_mfma_f32_16x16x32_bf16 v[88:91], v[158:161], v[202:205], v[88:91]
	v_mfma_f32_16x16x32_bf16 v[76:79], v[144:147], v[210:213], v[76:79]
	v_mfma_f32_16x16x32_bf16 v[72:75], v[158:161], v[210:213], v[72:75]
	v_mfma_f32_16x16x32_bf16 v[124:127], v[154:157], v[186:189], v[124:127]
	v_mfma_f32_16x16x32_bf16 v[120:123], v[162:165], v[186:189], v[120:123]
	v_mfma_f32_16x16x32_bf16 v[108:111], v[154:157], v[198:201], v[108:111]
	v_mfma_f32_16x16x32_bf16 v[104:107], v[162:165], v[198:201], v[104:107]
	v_mfma_f32_16x16x32_bf16 v[92:95], v[154:157], v[206:209], v[92:95]
	v_mfma_f32_16x16x32_bf16 v[88:91], v[162:165], v[206:209], v[88:91]
	v_mfma_f32_16x16x32_bf16 v[76:79], v[154:157], v[214:217], v[76:79]
	v_mfma_f32_16x16x32_bf16 v[72:75], v[162:165], v[214:217], v[72:75]
	s_setprio 0
	s_setprio 1
	v_mfma_f32_16x16x32_bf16 v[116:119], v[166:169], v[182:185], v[116:119]
	v_mfma_f32_16x16x32_bf16 v[112:115], v[174:177], v[182:185], v[112:115]
	v_mfma_f32_16x16x32_bf16 v[100:103], v[166:169], v[194:197], v[100:103]
	v_mfma_f32_16x16x32_bf16 v[96:99], v[174:177], v[194:197], v[96:99]
	v_mfma_f32_16x16x32_bf16 v[84:87], v[166:169], v[202:205], v[84:87]
	v_mfma_f32_16x16x32_bf16 v[80:83], v[174:177], v[202:205], v[80:83]
	v_mfma_f32_16x16x32_bf16 v[68:71], v[166:169], v[210:213], v[68:71]
	v_mfma_f32_16x16x32_bf16 v[64:67], v[174:177], v[210:213], v[64:67]
	v_mfma_f32_16x16x32_bf16 v[116:119], v[170:173], v[186:189], v[116:119]
	v_mfma_f32_16x16x32_bf16 v[112:115], v[178:181], v[186:189], v[112:115]
	v_mfma_f32_16x16x32_bf16 v[100:103], v[170:173], v[198:201], v[100:103]
	v_mfma_f32_16x16x32_bf16 v[96:99], v[178:181], v[198:201], v[96:99]
	v_mfma_f32_16x16x32_bf16 v[84:87], v[170:173], v[206:209], v[84:87]
	v_mfma_f32_16x16x32_bf16 v[80:83], v[178:181], v[206:209], v[80:83]
	v_mfma_f32_16x16x32_bf16 v[68:71], v[170:173], v[214:217], v[68:71]
	v_mfma_f32_16x16x32_bf16 v[64:67], v[178:181], v[214:217], v[64:67]
	s_setprio 0
	s_barrier
; #define PG8_STAGE(bufoff, gbase, voff) do { _Pragma("unroll") for (int _i = 0; _i < 2; ++_i) \
;         __builtin_amdgcn_global_load_lds((const unsigned*)((const char*)(gbase) + (voff)[_i]), (PG8_LAS unsigned*)(lds + (bufoff) + ldsw + _i * 8192), 16, 0, 0); } while (0)
; #define PG8_LDA(dst, b, h) do { _Pragma("unroll") for (int m = 0; m < 4; ++m) _Pragma("unroll") for (int k = 0; k < 2; ++k) dst[m][k] = *(const PG8_LAS bf16x8*)(lds + PG8_SA(b, h) + aoff + m * 2048 + k * 1024); } while (0)
; #define PG8_LDB(dst, b, h) do { _Pragma("unroll") for (int n = 0; n < 2; ++n) _Pragma("unroll") for (int k = 0; k < 2; ++k) dst[n][k] = *(const PG8_LAS bf16x8*)(lds + PG8_SB(b, h) + boff + n * 2048 + k * 1024); } while (0)
; #define PG8_MMA(ai, bj, At, Bt) do { __builtin_amdgcn_s_setprio(1); _Pragma("unroll") for (int m = 0; m < 4; ++m) _Pragma("unroll") for (int n = 0; n < 2; ++n) _Pragma("unroll") for (int k = 0; k < 2; ++k) \
;         acc[ai][bj][m][n] = __builtin_amdgcn_mfma_f32_16x16x32_bf16(Bt[n][k], At[m][k], acc[ai][bj][m][n], 0, 0, 0); __builtin_amdgcn_s_setprio(0); } while (0)
; #define PG8_WAIT_V(n) asm volatile("s_waitcnt vmcnt(" #n ")" ::: "memory")
; #define PG8_WAIT_L(n) asm volatile("s_waitcnt lgkmcnt(" #n ")" ::: "memory")
; #define PG8_BAR __builtin_amdgcn_s_barrier()
; #define PG8_SCHED __builtin_amdgcn_sched_barrier(0)
; template <class Epi, class Sched, bool ALIGN_EPI = false, bool SP2 = false>
; __device__ __forceinline__ void gemm_phase(PG8_LAS unsigned char* lds, const Gemm g, const Sched& S, const Epi& E) {
;     ...
;             PG8_LDB(B0, 0, 0); PG8_LDB(B1, 0, 1); PG8_SCHED; PG8_LDA(At, 0, 0); PG8_STAGE(PG8_SA(1, 1), a1 + hstep, voffA);
;             PG8_WAIT_V(8); PG8_WAIT_L(0); PG8_BAR; PG8_MMA(0, 0, At, B0); PG8_MMA(0, 1, At, B1); PG8_BAR; PG8_SCHED;
;     ...
;             PG8_LDA(At, 1, 1); PG8_STAGE(PG8_SB(1, 0), b3, voffB); PG8_STAGE(PG8_SB(1, 1), b3 + hstep, voffB); PG8_STAGE(PG8_SA(1, 0), a3, voffA);
;             PG8_WAIT_V(8); PG8_WAIT_L(0); PG8_BAR; PG8_MMA(1, 0, At, B0); PG8_MMA(1, 1, At, B1); PG8_BAR; PG8_SCHED;
	s_add_i32 s34, s68, s51
	v_lshl_add_u64 v[190:191], v[190:191], 0, s[12:13]
	s_mov_b32 m0, s34
	ds_read_b128 v[182:185], v153 offset:49152
	ds_read_b128 v[186:189], v153 offset:50176
	ds_read_b128 v[194:197], v153 offset:51200
	ds_read_b128 v[198:201], v153 offset:52224
	ds_read_b128 v[202:205], v153 offset:53248
	ds_read_b128 v[206:209], v153 offset:54272
	ds_read_b128 v[210:213], v153 offset:55296
	ds_read_b128 v[214:217], v153 offset:56320
	global_load_lds_dwordx4 v[190:191], off
	s_add_i32 m0, s34, 0x2000
	s_add_u32 s30, s30, 0x80080
	v_lshl_add_u64 v[190:191], v[218:219], 0, s[12:13]
	s_addc_u32 s31, s31, 0
	s_add_i32 s34, s69, s51
	global_load_lds_dwordx4 v[190:191], off
	v_lshl_add_u64 v[190:191], s[30:31], 0, v[132:133]
	s_mov_b32 m0, s34
	s_nop 0
	global_load_lds_dwordx4 v[190:191], off
	v_lshl_add_u64 v[190:191], s[30:31], 0, v[128:129]
	s_add_i32 m0, s34, 0x2000
	s_nop 0
	global_load_lds_dwordx4 v[190:191], off
	v_lshl_add_u64 v[190:191], v[220:221], 0, s[12:13]
	s_mov_b32 m0, s57
	s_nop 0
	global_load_lds_dwordx4 v[190:191], off
	v_lshl_add_u64 v[190:191], v[222:223], 0, s[12:13]
	s_mov_b32 m0, s58
	s_nop 0
	global_load_lds_dwordx4 v[190:191], off
	s_waitcnt vmcnt(8)
	s_waitcnt lgkmcnt(0)
	s_barrier
	s_setprio 1
	s_waitcnt lgkmcnt(0)
	v_mfma_f32_16x16x32_bf16 v[60:63], v[144:147], v[182:185], v[60:63]
	v_mfma_f32_16x16x32_bf16 v[56:59], v[158:161], v[182:185], v[56:59]
	v_mfma_f32_16x16x32_bf16 v[44:47], v[144:147], v[194:197], v[44:47]
	v_mfma_f32_16x16x32_bf16 v[40:43], v[158:161], v[194:197], v[40:43]
	v_mfma_f32_16x16x32_bf16 v[28:31], v[144:147], v[202:205], v[28:31]
	v_mfma_f32_16x16x32_bf16 v[24:27], v[158:161], v[202:205], v[24:27]
	v_mfma_f32_16x16x32_bf16 v[12:15], v[144:147], v[210:213], v[12:15]
	v_mfma_f32_16x16x32_bf16 v[8:11], v[158:161], v[210:213], v[8:11]
	v_mfma_f32_16x16x32_bf16 v[60:63], v[154:157], v[186:189], v[60:63]
	v_mfma_f32_16x16x32_bf16 v[56:59], v[162:165], v[186:189], v[56:59]
	v_mfma_f32_16x16x32_bf16 v[44:47], v[154:157], v[198:201], v[44:47]
	v_mfma_f32_16x16x32_bf16 v[40:43], v[162:165], v[198:201], v[40:43]
	v_mfma_f32_16x16x32_bf16 v[28:31], v[154:157], v[206:209], v[28:31]
	v_mfma_f32_16x16x32_bf16 v[24:27], v[162:165], v[206:209], v[24:27]
	v_mfma_f32_16x16x32_bf16 v[12:15], v[154:157], v[214:217], v[12:15]
	v_mfma_f32_16x16x32_bf16 v[8:11], v[162:165], v[214:217], v[8:11]
	s_setprio 0
	s_setprio 1
	v_mfma_f32_16x16x32_bf16 v[52:55], v[166:169], v[182:185], v[52:55]
	v_mfma_f32_16x16x32_bf16 v[48:51], v[174:177], v[182:185], v[48:51]
	v_mfma_f32_16x16x32_bf16 v[36:39], v[166:169], v[194:197], v[36:39]
	v_mfma_f32_16x16x32_bf16 v[32:35], v[174:177], v[194:197], v[32:35]
	v_mfma_f32_16x16x32_bf16 v[20:23], v[166:169], v[202:205], v[20:23]
	v_mfma_f32_16x16x32_bf16 v[16:19], v[174:177], v[202:205], v[16:19]
	v_mfma_f32_16x16x32_bf16 v[4:7], v[166:169], v[210:213], v[4:7]
	v_mfma_f32_16x16x32_bf16 v[0:3], v[174:177], v[210:213], v[0:3]
	v_mfma_f32_16x16x32_bf16 v[52:55], v[170:173], v[186:189], v[52:55]
	v_mfma_f32_16x16x32_bf16 v[48:51], v[178:181], v[186:189], v[48:51]
	v_mfma_f32_16x16x32_bf16 v[36:39], v[170:173], v[198:201], v[36:39]
	v_mfma_f32_16x16x32_bf16 v[32:35], v[178:181], v[198:201], v[32:35]
	v_mfma_f32_16x16x32_bf16 v[20:23], v[170:173], v[206:209], v[20:23]
	v_mfma_f32_16x16x32_bf16 v[16:19], v[178:181], v[206:209], v[16:19]
	v_mfma_f32_16x16x32_bf16 v[4:7], v[170:173], v[214:217], v[4:7]
	v_mfma_f32_16x16x32_bf16 v[0:3], v[178:181], v[214:217], v[0:3]
	s_add_i32 s67, s67, 2
	s_add_u32 s65, s65, 0x100
	s_addc_u32 s66, s66, 0
	s_add_u32 s28, s28, 0x100
	s_addc_u32 s29, s29, 0
	s_cmp_gt_u32 s67, 29
	s_setprio 0
	s_barrier
	s_cbranch_scc1 .Lpeel_exit_2
.LBB0_481:
	ds_read_b128 v[144:147], v151
	ds_read_b128 v[154:157], v151 offset:1024
	ds_read_b128 v[158:161], v151 offset:2048
	ds_read_b128 v[162:165], v151 offset:3072
	ds_read_b128 v[166:169], v152
	ds_read_b128 v[170:173], v152 offset:1024
	ds_read_b128 v[174:177], v152 offset:2048
	ds_read_b128 v[178:181], v152 offset:3072
	s_add_u32 s30, s28, 0xfff80080
	s_addc_u32 s31, s29, -1
	s_cmp_eq_u32 s67, 28
	s_cselect_b32 s35, s17, s31
	s_cselect_b32 s34, s63, s30
	s_cselect_b32 s31, s19, s66
	s_cselect_b32 s30, s64, s65
	v_lshl_add_u64 v[190:191], s[28:29], 0, v[138:139]
	s_add_i32 m0, s25, 0xc000
	ds_read_b128 v[182:185], v153
	ds_read_b128 v[186:189], v153 offset:1024
	ds_read_b128 v[194:197], v153 offset:2048
	ds_read_b128 v[198:201], v153 offset:3072
	ds_read_b128 v[202:205], v153 offset:4096
	ds_read_b128 v[206:209], v153 offset:5120
	ds_read_b128 v[210:213], v153 offset:6144
	ds_read_b128 v[214:217], v153 offset:7168
	global_load_lds_dwordx4 v[190:191], off
	v_lshl_add_u64 v[190:191], s[28:29], 0, v[136:137]
	s_add_i32 m0, s25, 0xe000
	s_nop 0
	global_load_lds_dwordx4 v[190:191], off
	s_waitcnt vmcnt(8)
	s_waitcnt lgkmcnt(0)
	s_barrier
; #define PG8_STAGE(bufoff, gbase, voff) do { _Pragma("unroll") for (int _i = 0; _i < 2; ++_i) \
;         __builtin_amdgcn_global_load_lds((const unsigned*)((const char*)(gbase) + (voff)[_i]), (PG8_LAS unsigned*)(lds + (bufoff) + ldsw + _i * 8192), 16, 0, 0); } while (0)
; #define PG8_LDA(dst, b, h) do { _Pragma("unroll") for (int m = 0; m < 4; ++m) _Pragma("unroll") for (int k = 0; k < 2; ++k) dst[m][k] = *(const PG8_LAS bf16x8*)(lds + PG8_SA(b, h) + aoff + m * 2048 + k * 1024); } while (0)
; #define PG8_MMA(ai, bj, At, Bt) do { __builtin_amdgcn_s_setprio(1); _Pragma("unroll") for (int m = 0; m < 4; ++m) _Pragma("unroll") for (int n = 0; n < 2; ++n) _Pragma("unroll") for (int k = 0; k < 2; ++k) \
;         acc[ai][bj][m][n] = __builtin_amdgcn_mfma_f32_16x16x32_bf16(Bt[n][k], At[m][k], acc[ai][bj][m][n], 0, 0, 0); __builtin_amdgcn_s_setprio(0); } while (0)
; #define PG8_WAIT_V(n) asm volatile("s_waitcnt vmcnt(" #n ")" ::: "memory")
; #define PG8_WAIT_L(n) asm volatile("s_waitcnt lgkmcnt(" #n ")" ::: "memory")
; #define PG8_BAR __builtin_amdgcn_s_barrier()
; #define PG8_SCHED __builtin_amdgcn_sched_barrier(0)
; template <class Epi, class Sched, bool ALIGN_EPI = false, bool SP2 = false>
; __device__ __forceinline__ void gemm_phase(PG8_LAS unsigned char* lds, const Gemm g, const Sched& S, const Epi& E) {
;     ...
;             PG8_WAIT_V(8); PG8_WAIT_L(0); PG8_BAR; PG8_MMA(0, 0, At, B0); PG8_MMA(0, 1, At, B1); PG8_BAR; PG8_SCHED;
;             PG8_LDA(At, 0, 1); PG8_STAGE(PG8_SB(0, 0), b2, voffB); PG8_STAGE(PG8_SB(0, 1), b2 + hstep, voffB); PG8_STAGE(PG8_SA(0, 0), a2, voffA);
;             PG8_WAIT_V(8); PG8_WAIT_L(0); PG8_BAR; PG8_MMA(1, 0, At, B0); PG8_MMA(1, 1, At, B1); PG8_BAR; PG8_SCHED;
	s_setprio 1
	s_waitcnt lgkmcnt(0)
	v_mfma_f32_16x16x32_bf16 v[124:127], v[144:147], v[182:185], v[124:127]
	v_mfma_f32_16x16x32_bf16 v[120:123], v[158:161], v[182:185], v[120:123]
	v_mfma_f32_16x16x32_bf16 v[108:111], v[144:147], v[194:197], v[108:111]
	v_mfma_f32_16x16x32_bf16 v[104:107], v[158:161], v[194:197], v[104:107]
	v_mfma_f32_16x16x32_bf16 v[92:95], v[144:147], v[202:205], v[92:95]
	v_mfma_f32_16x16x32_bf16 v[88:91], v[158:161], v[202:205], v[88:91]
	v_mfma_f32_16x16x32_bf16 v[76:79], v[144:147], v[210:213], v[76:79]
	v_mfma_f32_16x16x32_bf16 v[72:75], v[158:161], v[210:213], v[72:75]
	v_mfma_f32_16x16x32_bf16 v[124:127], v[154:157], v[186:189], v[124:127]
	v_mfma_f32_16x16x32_bf16 v[120:123], v[162:165], v[186:189], v[120:123]
	v_mfma_f32_16x16x32_bf16 v[108:111], v[154:157], v[198:201], v[108:111]
	v_mfma_f32_16x16x32_bf16 v[104:107], v[162:165], v[198:201], v[104:107]
	v_mfma_f32_16x16x32_bf16 v[92:95], v[154:157], v[206:209], v[92:95]
	v_mfma_f32_16x16x32_bf16 v[88:91], v[162:165], v[206:209], v[88:91]
	v_mfma_f32_16x16x32_bf16 v[76:79], v[154:157], v[214:217], v[76:79]
	v_mfma_f32_16x16x32_bf16 v[72:75], v[162:165], v[214:217], v[72:75]
	s_setprio 0
	s_setprio 1
	v_mfma_f32_16x16x32_bf16 v[116:119], v[166:169], v[182:185], v[116:119]
	v_mfma_f32_16x16x32_bf16 v[112:115], v[174:177], v[182:185], v[112:115]
	v_mfma_f32_16x16x32_bf16 v[100:103], v[166:169], v[194:197], v[100:103]
	v_mfma_f32_16x16x32_bf16 v[96:99], v[174:177], v[194:197], v[96:99]
	v_mfma_f32_16x16x32_bf16 v[84:87], v[166:169], v[202:205], v[84:87]
	v_mfma_f32_16x16x32_bf16 v[80:83], v[174:177], v[202:205], v[80:83]
	v_mfma_f32_16x16x32_bf16 v[68:71], v[166:169], v[210:213], v[68:71]
	v_mfma_f32_16x16x32_bf16 v[64:67], v[174:177], v[210:213], v[64:67]
	v_mfma_f32_16x16x32_bf16 v[116:119], v[170:173], v[186:189], v[116:119]
	v_mfma_f32_16x16x32_bf16 v[112:115], v[178:181], v[186:189], v[112:115]
	v_mfma_f32_16x16x32_bf16 v[100:103], v[170:173], v[198:201], v[100:103]
	v_mfma_f32_16x16x32_bf16 v[96:99], v[178:181], v[198:201], v[96:99]
	v_mfma_f32_16x16x32_bf16 v[84:87], v[170:173], v[206:209], v[84:87]
	v_mfma_f32_16x16x32_bf16 v[80:83], v[178:181], v[206:209], v[80:83]
	v_mfma_f32_16x16x32_bf16 v[68:71], v[170:173], v[214:217], v[68:71]
	v_mfma_f32_16x16x32_bf16 v[64:67], v[178:181], v[214:217], v[64:67]
	s_setprio 0
	s_barrier
	s_add_i32 s68, s60, s51
	v_lshl_add_u64 v[190:191], s[30:31], 0, v[132:133]
	s_mov_b32 m0, s68
	ds_read_b128 v[182:185], v153 offset:16384
	ds_read_b128 v[186:189], v153 offset:17408
	ds_read_b128 v[194:197], v153 offset:18432
	ds_read_b128 v[198:201], v153 offset:19456
	ds_read_b128 v[202:205], v153 offset:20480
	ds_read_b128 v[206:209], v153 offset:21504
	ds_read_b128 v[210:213], v153 offset:22528
	ds_read_b128 v[214:217], v153 offset:23552
	global_load_lds_dwordx4 v[190:191], off
	s_add_i32 m0, s68, 0x2000
	s_add_u32 s68, s30, 0x80000
	v_lshl_add_u64 v[218:219], s[30:31], 0, v[128:129]
	s_addc_u32 s69, s31, 0
	s_add_i32 s70, s61, s51
	global_load_lds_dwordx4 v[218:219], off
	v_lshl_add_u64 v[220:221], s[68:69], 0, v[132:133]
	s_mov_b32 m0, s70
	v_lshl_add_u64 v[222:223], s[34:35], 0, v[130:131]
	global_load_lds_dwordx4 v[220:221], off
	v_lshl_add_u64 v[220:221], s[68:69], 0, v[128:129]
	s_add_i32 m0, s70, 0x2000
	s_nop 0
	global_load_lds_dwordx4 v[220:221], off
	v_lshl_add_u64 v[220:221], s[34:35], 0, v[134:135]
	s_mov_b32 m0, s25
	s_nop 0
	global_load_lds_dwordx4 v[220:221], off
	s_mov_b32 m0, s27
	s_nop 0
	global_load_lds_dwordx4 v[222:223], off
	s_waitcnt vmcnt(8)
	s_waitcnt lgkmcnt(0)
	s_barrier
	s_setprio 1
	s_waitcnt lgkmcnt(0)
	v_mfma_f32_16x16x32_bf16 v[60:63], v[144:147], v[182:185], v[60:63]
	v_mfma_f32_16x16x32_bf16 v[56:59], v[158:161], v[182:185], v[56:59]
	v_mfma_f32_16x16x32_bf16 v[44:47], v[144:147], v[194:197], v[44:47]
	v_mfma_f32_16x16x32_bf16 v[40:43], v[158:161], v[194:197], v[40:43]
	v_mfma_f32_16x16x32_bf16 v[28:31], v[144:147], v[202:205], v[28:31]
	v_mfma_f32_16x16x32_bf16 v[24:27], v[158:161], v[202:205], v[24:27]
	v_mfma_f32_16x16x32_bf16 v[12:15], v[144:147], v[210:213], v[12:15]
	v_mfma_f32_16x16x32_bf16 v[8:11], v[158:161], v[210:213], v[8:11]
	v_mfma_f32_16x16x32_bf16 v[60:63], v[154:157], v[186:189], v[60:63]
	v_mfma_f32_16x16x32_bf16 v[56:59], v[162:165], v[186:189], v[56:59]
	v_mfma_f32_16x16x32_bf16 v[44:47], v[154:157], v[198:201], v[44:47]
	v_mfma_f32_16x16x32_bf16 v[40:43], v[162:165], v[198:201], v[40:43]
	v_mfma_f32_16x16x32_bf16 v[28:31], v[154:157], v[206:209], v[28:31]
	v_mfma_f32_16x16x32_bf16 v[24:27], v[162:165], v[206:209], v[24:27]
	v_mfma_f32_16x16x32_bf16 v[12:15], v[154:157], v[214:217], v[12:15]
	v_mfma_f32_16x16x32_bf16 v[8:11], v[162:165], v[214:217], v[8:11]
	s_setprio 0
	s_setprio 1
	v_mfma_f32_16x16x32_bf16 v[52:55], v[166:169], v[182:185], v[52:55]
	v_mfma_f32_16x16x32_bf16 v[48:51], v[174:177], v[182:185], v[48:51]
	v_mfma_f32_16x16x32_bf16 v[36:39], v[166:169], v[194:197], v[36:39]
	v_mfma_f32_16x16x32_bf16 v[32:35], v[174:177], v[194:197], v[32:35]
	v_mfma_f32_16x16x32_bf16 v[20:23], v[166:169], v[202:205], v[20:23]
	v_mfma_f32_16x16x32_bf16 v[16:19], v[174:177], v[202:205], v[16:19]
	v_mfma_f32_16x16x32_bf16 v[4:7], v[166:169], v[210:213], v[4:7]
	v_mfma_f32_16x16x32_bf16 v[0:3], v[174:177], v[210:213], v[0:3]
	v_mfma_f32_16x16x32_bf16 v[52:55], v[170:173], v[186:189], v[52:55]
	v_mfma_f32_16x16x32_bf16 v[48:51], v[178:181], v[186:189], v[48:51]
	v_mfma_f32_16x16x32_bf16 v[36:39], v[170:173], v[198:201], v[36:39]
	v_mfma_f32_16x16x32_bf16 v[32:35], v[178:181], v[198:201], v[32:35]
	v_mfma_f32_16x16x32_bf16 v[20:23], v[170:173], v[206:209], v[20:23]
	v_mfma_f32_16x16x32_bf16 v[16:19], v[178:181], v[206:209], v[16:19]
	v_mfma_f32_16x16x32_bf16 v[4:7], v[170:173], v[214:217], v[4:7]
	v_mfma_f32_16x16x32_bf16 v[0:3], v[178:181], v[214:217], v[0:3]
	s_setprio 0
	s_barrier
; #define PG8_STAGE(bufoff, gbase, voff) do { _Pragma("unroll") for (int _i = 0; _i < 2; ++_i) \
;         __builtin_amdgcn_global_load_lds((const unsigned*)((const char*)(gbase) + (voff)[_i]), (PG8_LAS unsigned*)(lds + (bufoff) + ldsw + _i * 8192), 16, 0, 0); } while (0)
; #define PG8_LDA(dst, b, h) do { _Pragma("unroll") for (int m = 0; m < 4; ++m) _Pragma("unroll") for (int k = 0; k < 2; ++k) dst[m][k] = *(const PG8_LAS bf16x8*)(lds + PG8_SA(b, h) + aoff + m * 2048 + k * 1024); } while (0)
; #define PG8_LDB(dst, b, h) do { _Pragma("unroll") for (int n = 0; n < 2; ++n) _Pragma("unroll") for (int k = 0; k < 2; ++k) dst[n][k] = *(const PG8_LAS bf16x8*)(lds + PG8_SB(b, h) + boff + n * 2048 + k * 1024); } while (0)
; #define PG8_MMA(ai, bj, At, Bt) do { __builtin_amdgcn_s_setprio(1); _Pragma("unroll") for (int m = 0; m < 4; ++m) _Pragma("unroll") for (int n = 0; n < 2; ++n) _Pragma("unroll") for (int k = 0; k < 2; ++k) \
;         acc[ai][bj][m][n] = __builtin_amdgcn_mfma_f32_16x16x32_bf16(Bt[n][k], At[m][k], acc[ai][bj][m][n], 0, 0, 0); __builtin_amdgcn_s_setprio(0); } while (0)
; #define PG8_WAIT_V(n) asm volatile("s_waitcnt vmcnt(" #n ")" ::: "memory")
; #define PG8_WAIT_L(n) asm volatile("s_waitcnt lgkmcnt(" #n ")" ::: "memory")
; #define PG8_BAR __builtin_amdgcn_s_barrier()
; #define PG8_SCHED __builtin_amdgcn_sched_barrier(0)
; template <class Epi, class Sched, bool ALIGN_EPI = false, bool SP2 = false>
; __device__ __forceinline__ void gemm_phase(PG8_LAS unsigned char* lds, const Gemm g, const Sched& S, const Epi& E) {
;     ...
;             PG8_LDB(B0, 1, 0); PG8_LDB(B1, 1, 1); PG8_SCHED; PG8_LDA(At, 1, 0); PG8_STAGE(PG8_SA(0, 1), a2 + hstep, voffA);
;             PG8_WAIT_V(8); PG8_WAIT_L(0); PG8_BAR; PG8_MMA(0, 0, At, B0); PG8_MMA(0, 1, At, B1); PG8_BAR; PG8_SCHED;
	s_add_i32 s68, 0, 0x18000
	s_add_i32 s69, 0, 0x1c000
	v_add_u32_e32 v162, s68, v149
	v_add_u32_e32 v178, s69, v149
	ds_read_b128 v[144:147], v162
	ds_read_b128 v[154:157], v162 offset:1024
	ds_read_b128 v[158:161], v162 offset:2048
	ds_read_b128 v[162:165], v162 offset:3072
	ds_read_b128 v[166:169], v178
	ds_read_b128 v[170:173], v178 offset:1024
	ds_read_b128 v[174:177], v178 offset:2048
	ds_read_b128 v[178:181], v178 offset:3072
	s_add_u32 s34, s34, 0x80000
	s_addc_u32 s35, s35, 0
	s_mov_b32 m0, s54
	v_lshl_add_u64 v[224:225], s[34:35], 0, v[134:135]
	ds_read_b128 v[182:185], v153 offset:32768
	ds_read_b128 v[186:189], v153 offset:33792
	ds_read_b128 v[194:197], v153 offset:34816
	ds_read_b128 v[198:201], v153 offset:35840
	ds_read_b128 v[202:205], v153 offset:36864
	ds_read_b128 v[206:209], v153 offset:37888
	ds_read_b128 v[210:213], v153 offset:38912
	ds_read_b128 v[214:217], v153 offset:39936
	global_load_lds_dwordx4 v[224:225], off
	v_lshl_add_u64 v[224:225], s[34:35], 0, v[130:131]
	s_mov_b32 m0, s55
	s_nop 0
	global_load_lds_dwordx4 v[224:225], off
	s_waitcnt vmcnt(8)
	s_waitcnt lgkmcnt(0)
	s_barrier
	s_setprio 1
	s_waitcnt lgkmcnt(0)
	v_mfma_f32_16x16x32_bf16 v[124:127], v[144:147], v[182:185], v[124:127]
	v_mfma_f32_16x16x32_bf16 v[120:123], v[158:161], v[182:185], v[120:123]
	v_mfma_f32_16x16x32_bf16 v[108:111], v[144:147], v[194:197], v[108:111]
	v_mfma_f32_16x16x32_bf16 v[104:107], v[158:161], v[194:197], v[104:107]
	v_mfma_f32_16x16x32_bf16 v[92:95], v[144:147], v[202:205], v[92:95]
	v_mfma_f32_16x16x32_bf16 v[88:91], v[158:161], v[202:205], v[88:91]
	v_mfma_f32_16x16x32_bf16 v[76:79], v[144:147], v[210:213], v[76:79]
	v_mfma_f32_16x16x32_bf16 v[72:75], v[158:161], v[210:213], v[72:75]
	v_mfma_f32_16x16x32_bf16 v[124:127], v[154:157], v[186:189], v[124:127]
	v_mfma_f32_16x16x32_bf16 v[120:123], v[162:165], v[186:189], v[120:123]
	v_mfma_f32_16x16x32_bf16 v[108:111], v[154:157], v[198:201], v[108:111]
	v_mfma_f32_16x16x32_bf16 v[104:107], v[162:165], v[198:201], v[104:107]
	v_mfma_f32_16x16x32_bf16 v[92:95], v[154:157], v[206:209], v[92:95]
	v_mfma_f32_16x16x32_bf16 v[88:91], v[162:165], v[206:209], v[88:91]
	v_mfma_f32_16x16x32_bf16 v[76:79], v[154:157], v[214:217], v[76:79]
	v_mfma_f32_16x16x32_bf16 v[72:75], v[162:165], v[214:217], v[72:75]
	s_setprio 0
	s_setprio 1
	v_mfma_f32_16x16x32_bf16 v[116:119], v[166:169], v[182:185], v[116:119]
	v_mfma_f32_16x16x32_bf16 v[112:115], v[174:177], v[182:185], v[112:115]
	v_mfma_f32_16x16x32_bf16 v[100:103], v[166:169], v[194:197], v[100:103]
	v_mfma_f32_16x16x32_bf16 v[96:99], v[174:177], v[194:197], v[96:99]
	v_mfma_f32_16x16x32_bf16 v[84:87], v[166:169], v[202:205], v[84:87]
	v_mfma_f32_16x16x32_bf16 v[80:83], v[174:177], v[202:205], v[80:83]
	v_mfma_f32_16x16x32_bf16 v[68:71], v[166:169], v[210:213], v[68:71]
	v_mfma_f32_16x16x32_bf16 v[64:67], v[174:177], v[210:213], v[64:67]
	v_mfma_f32_16x16x32_bf16 v[116:119], v[170:173], v[186:189], v[116:119]
	v_mfma_f32_16x16x32_bf16 v[112:115], v[178:181], v[186:189], v[112:115]
	v_mfma_f32_16x16x32_bf16 v[100:103], v[170:173], v[198:201], v[100:103]
	v_mfma_f32_16x16x32_bf16 v[96:99], v[178:181], v[198:201], v[96:99]
	v_mfma_f32_16x16x32_bf16 v[84:87], v[170:173], v[206:209], v[84:87]
	v_mfma_f32_16x16x32_bf16 v[80:83], v[178:181], v[206:209], v[80:83]
	v_mfma_f32_16x16x32_bf16 v[68:71], v[170:173], v[214:217], v[68:71]
	v_mfma_f32_16x16x32_bf16 v[64:67], v[178:181], v[214:217], v[64:67]
	s_setprio 0
	s_barrier
; #define PG8_STAGE(bufoff, gbase, voff) do { _Pragma("unroll") for (int _i = 0; _i < 2; ++_i) \
;         __builtin_amdgcn_global_load_lds((const unsigned*)((const char*)(gbase) + (voff)[_i]), (PG8_LAS unsigned*)(lds + (bufoff) + ldsw + _i * 8192), 16, 0, 0); } while (0)
; #define PG8_LDA(dst, b, h) do { _Pragma("unroll") for (int m = 0; m < 4; ++m) _Pragma("unroll") for (int k = 0; k < 2; ++k) dst[m][k] = *(const PG8_LAS bf16x8*)(lds + PG8_SA(b, h) + aoff + m * 2048 + k * 1024); } while (0)
; #define PG8_MMA(ai, bj, At, Bt) do { __builtin_amdgcn_s_setprio(1); _Pragma("unroll") for (int m = 0; m < 4; ++m) _Pragma("unroll") for (int n = 0; n < 2; ++n) _Pragma("unroll") for (int k = 0; k < 2; ++k) \
;         acc[ai][bj][m][n] = __builtin_amdgcn_mfma_f32_16x16x32_bf16(Bt[n][k], At[m][k], acc[ai][bj][m][n], 0, 0, 0); __builtin_amdgcn_s_setprio(0); } while (0)
; #define PG8_WAIT_V(n) asm volatile("s_waitcnt vmcnt(" #n ")" ::: "memory")
; #define PG8_WAIT_L(n) asm volatile("s_waitcnt lgkmcnt(" #n ")" ::: "memory")
; #define PG8_BAR __builtin_amdgcn_s_barrier()
; #define PG8_SCHED __builtin_amdgcn_sched_barrier(0)
; template <class Epi, class Sched, bool ALIGN_EPI = false, bool SP2 = false>
; __device__ __forceinline__ void gemm_phase(PG8_LAS unsigned char* lds, const Gemm g, const Sched& S, const Epi& E) {
;     ...
;         for (int t = 0; t < nt; t += 2) {
;     ...
;             PG8_LDA(At, 1, 1); PG8_STAGE(PG8_SB(1, 0), b3, voffB); PG8_STAGE(PG8_SB(1, 1), b3 + hstep, voffB); PG8_STAGE(PG8_SA(1, 0), a3, voffA);
;             PG8_WAIT_V(8); PG8_WAIT_L(0); PG8_BAR; PG8_MMA(1, 0, At, B0); PG8_MMA(1, 1, At, B1); PG8_BAR; PG8_SCHED;
	s_add_i32 s34, s68, s51
	v_lshl_add_u64 v[190:191], v[190:191], 0, s[12:13]
	s_mov_b32 m0, s34
	ds_read_b128 v[182:185], v153 offset:49152
	ds_read_b128 v[186:189], v153 offset:50176
	ds_read_b128 v[194:197], v153 offset:51200
	ds_read_b128 v[198:201], v153 offset:52224
	ds_read_b128 v[202:205], v153 offset:53248
	ds_read_b128 v[206:209], v153 offset:54272
	ds_read_b128 v[210:213], v153 offset:55296
	ds_read_b128 v[214:217], v153 offset:56320
	global_load_lds_dwordx4 v[190:191], off
	s_add_i32 m0, s34, 0x2000
	s_add_u32 s30, s30, 0x80080
	v_lshl_add_u64 v[190:191], v[218:219], 0, s[12:13]
	s_addc_u32 s31, s31, 0
	s_add_i32 s34, s69, s51
	global_load_lds_dwordx4 v[190:191], off
	v_lshl_add_u64 v[190:191], s[30:31], 0, v[132:133]
	s_mov_b32 m0, s34
	s_nop 0
	global_load_lds_dwordx4 v[190:191], off
	v_lshl_add_u64 v[190:191], s[30:31], 0, v[128:129]
	s_add_i32 m0, s34, 0x2000
	s_nop 0
	global_load_lds_dwordx4 v[190:191], off
	v_lshl_add_u64 v[190:191], v[220:221], 0, s[12:13]
	s_mov_b32 m0, s57
	s_nop 0
	global_load_lds_dwordx4 v[190:191], off
	v_lshl_add_u64 v[190:191], v[222:223], 0, s[12:13]
	s_mov_b32 m0, s58
	s_nop 0
	global_load_lds_dwordx4 v[190:191], off
	s_waitcnt vmcnt(8)
	s_waitcnt lgkmcnt(0)
	s_barrier
	s_setprio 1
	s_waitcnt lgkmcnt(0)
	v_mfma_f32_16x16x32_bf16 v[60:63], v[144:147], v[182:185], v[60:63]
	v_mfma_f32_16x16x32_bf16 v[56:59], v[158:161], v[182:185], v[56:59]
	v_mfma_f32_16x16x32_bf16 v[44:47], v[144:147], v[194:197], v[44:47]
	v_mfma_f32_16x16x32_bf16 v[40:43], v[158:161], v[194:197], v[40:43]
	v_mfma_f32_16x16x32_bf16 v[28:31], v[144:147], v[202:205], v[28:31]
	v_mfma_f32_16x16x32_bf16 v[24:27], v[158:161], v[202:205], v[24:27]
	v_mfma_f32_16x16x32_bf16 v[12:15], v[144:147], v[210:213], v[12:15]
	v_mfma_f32_16x16x32_bf16 v[8:11], v[158:161], v[210:213], v[8:11]
	v_mfma_f32_16x16x32_bf16 v[60:63], v[154:157], v[186:189], v[60:63]
	v_mfma_f32_16x16x32_bf16 v[56:59], v[162:165], v[186:189], v[56:59]
	v_mfma_f32_16x16x32_bf16 v[44:47], v[154:157], v[198:201], v[44:47]
	v_mfma_f32_16x16x32_bf16 v[40:43], v[162:165], v[198:201], v[40:43]
	v_mfma_f32_16x16x32_bf16 v[28:31], v[154:157], v[206:209], v[28:31]
	v_mfma_f32_16x16x32_bf16 v[24:27], v[162:165], v[206:209], v[24:27]
	v_mfma_f32_16x16x32_bf16 v[12:15], v[154:157], v[214:217], v[12:15]
	v_mfma_f32_16x16x32_bf16 v[8:11], v[162:165], v[214:217], v[8:11]
	s_setprio 0
	s_setprio 1
	v_mfma_f32_16x16x32_bf16 v[52:55], v[166:169], v[182:185], v[52:55]
	v_mfma_f32_16x16x32_bf16 v[48:51], v[174:177], v[182:185], v[48:51]
	v_mfma_f32_16x16x32_bf16 v[36:39], v[166:169], v[194:197], v[36:39]
	v_mfma_f32_16x16x32_bf16 v[32:35], v[174:177], v[194:197], v[32:35]
	v_mfma_f32_16x16x32_bf16 v[20:23], v[166:169], v[202:205], v[20:23]
	v_mfma_f32_16x16x32_bf16 v[16:19], v[174:177], v[202:205], v[16:19]
	v_mfma_f32_16x16x32_bf16 v[4:7], v[166:169], v[210:213], v[4:7]
	v_mfma_f32_16x16x32_bf16 v[0:3], v[174:177], v[210:213], v[0:3]
	v_mfma_f32_16x16x32_bf16 v[52:55], v[170:173], v[186:189], v[52:55]
	v_mfma_f32_16x16x32_bf16 v[48:51], v[178:181], v[186:189], v[48:51]
	v_mfma_f32_16x16x32_bf16 v[36:39], v[170:173], v[198:201], v[36:39]
	v_mfma_f32_16x16x32_bf16 v[32:35], v[178:181], v[198:201], v[32:35]
	v_mfma_f32_16x16x32_bf16 v[20:23], v[170:173], v[206:209], v[20:23]
	v_mfma_f32_16x16x32_bf16 v[16:19], v[178:181], v[206:209], v[16:19]
	v_mfma_f32_16x16x32_bf16 v[4:7], v[170:173], v[214:217], v[4:7]
	v_mfma_f32_16x16x32_bf16 v[0:3], v[178:181], v[214:217], v[0:3]
	s_add_i32 s67, s67, 2
	s_add_u32 s65, s65, 0x100
	s_addc_u32 s66, s66, 0
	s_add_u32 s28, s28, 0x100
	s_addc_u32 s29, s29, 0
	s_cmp_gt_u32 s67, 29
	s_setprio 0
	s_barrier
	s_cbranch_scc0 .LBB0_481

; #define PG8_STAGE(bufoff, gbase, voff) do { _Pragma("unroll") for (int _i = 0; _i < 2; ++_i) \
;         __builtin_amdgcn_global_load_lds((const unsigned*)((const char*)(gbase) + (voff)[_i]), (PG8_LAS unsigned*)(lds + (bufoff) + ldsw + _i * 8192), 16, 0, 0); } while (0)
; #define PG8_LDA(dst, b, h) do { _Pragma("unroll") for (int m = 0; m < 4; ++m) _Pragma("unroll") for (int k = 0; k < 2; ++k) dst[m][k] = *(const PG8_LAS bf16x8*)(lds + PG8_SA(b, h) + aoff + m * 2048 + k * 1024); } while (0)
; #define PG8_LDB(dst, b, h) do { _Pragma("unroll") for (int n = 0; n < 2; ++n) _Pragma("unroll") for (int k = 0; k < 2; ++k) dst[n][k] = *(const PG8_LAS bf16x8*)(lds + PG8_SB(b, h) + boff + n * 2048 + k * 1024); } while (0)
; #define PG8_MMA(ai, bj, At, Bt) do { __builtin_amdgcn_s_setprio(1); _Pragma("unroll") for (int m = 0; m < 4; ++m) _Pragma("unroll") for (int n = 0; n < 2; ++n) _Pragma("unroll") for (int k = 0; k < 2; ++k) \
;         acc[ai][bj][m][n] = __builtin_amdgcn_mfma_f32_16x16x32_bf16(Bt[n][k], At[m][k], acc[ai][bj][m][n], 0, 0, 0); __builtin_amdgcn_s_setprio(0); } while (0)
; #define PG8_WAIT_V(n) asm volatile("s_waitcnt vmcnt(" #n ")" ::: "memory")
; #define PG8_WAIT_L(n) asm volatile("s_waitcnt lgkmcnt(" #n ")" ::: "memory")
; #define PG8_BAR __builtin_amdgcn_s_barrier()
; #define PG8_SCHED __builtin_amdgcn_sched_barrier(0)
; template <class Epi, class Sched, bool ALIGN_EPI = false, bool SP2 = false>
; __device__ __forceinline__ void gemm_phase(PG8_LAS unsigned char* lds, const Gemm g, const Sched& S, const Epi& E) {
;     ...
;             const char* a2 = last ? nA : cA + (size_t)(t + 2) * kstep; const char* b2 = last ? nB : cB + (size_t)(t + 2) * kstep;
;             const char* a3 = a2 + kstep; const char* b3 = b2 + kstep;
;             if (last && has_next) S.a_ready(nxt);
;             if constexpr (SP2) {
;             PG8_LDB(B0, 0, 0); PG8_LDB(B1, 0, 1); PG8_SCHED; PG8_LDA(At, 0, 0); PG8_STAGE(PG8_SA(1, 1), a1 + hstep, voffA);
;             PG8_WAIT_V(8); PG8_WAIT_L(0); PG8_BAR; PG8_MMA(0, 0, At, B0); PG8_MMA(0, 1, At, B1); PG8_BAR; PG8_SCHED;
;             PG8_LDA(At, 0, 1); PG8_STAGE(PG8_SB(0, 0), b2, voffB); PG8_STAGE(PG8_SB(0, 1), b2 + hstep, voffB); PG8_STAGE(PG8_SA(0, 0), a2, voffA);
.LBB0_560:
	s_add_u32 s75, s30, 0x100
	s_addc_u32 s76, s31, 0
	s_mov_b32 s77, -2
	ds_read_b128 v[120:123], v169
	ds_read_b128 v[124:127], v169 offset:1024
	ds_read_b128 v[128:131], v169 offset:2048
	ds_read_b128 v[132:135], v169 offset:3072
	ds_read_b128 v[160:163], v170
	ds_read_b128 v[172:175], v170 offset:1024
	ds_read_b128 v[176:179], v170 offset:2048
	ds_read_b128 v[180:183], v170 offset:3072
	s_add_u32 s30, s28, 0x100
	s_addc_u32 s31, s29, 0
	s_cmpk_eq_i32 s77, 0x54
	s_cselect_b32 s37, s9, s31
	s_cselect_b32 s36, s8, s30
	s_cselect_b32 s35, s27, s76
	s_cselect_b32 s34, s26, s75
	v_lshl_add_u64 v[164:165], s[28:29], 0, v[154:155]
	s_add_i32 m0, s55, 0xc000
	ds_read_b128 v[184:187], v171
	ds_read_b128 v[188:191], v171 offset:1024
	ds_read_b128 v[194:197], v171 offset:2048
	ds_read_b128 v[198:201], v171 offset:3072
	ds_read_b128 v[202:205], v171 offset:4096
	ds_read_b128 v[206:209], v171 offset:5120
	ds_read_b128 v[210:213], v171 offset:6144
	ds_read_b128 v[214:217], v171 offset:7168
	global_load_lds_dwordx4 v[164:165], off
	v_lshl_add_u64 v[164:165], s[28:29], 0, v[152:153]
	s_add_i32 m0, s55, 0xe000
	s_nop 0
	global_load_lds_dwordx4 v[164:165], off
	s_waitcnt vmcnt(8)
	s_waitcnt lgkmcnt(0)
	s_barrier
	s_setprio 1
	s_waitcnt lgkmcnt(0)
	v_mfma_f32_16x16x32_bf16 v[140:143], v[120:123], v[184:187], 0
	v_mfma_f32_16x16x32_bf16 v[136:139], v[128:131], v[184:187], 0
	v_mfma_f32_16x16x32_bf16 v[112:115], v[120:123], v[194:197], 0
	v_mfma_f32_16x16x32_bf16 v[104:107], v[128:131], v[194:197], 0
	v_mfma_f32_16x16x32_bf16 v[96:99], v[120:123], v[202:205], 0
	v_mfma_f32_16x16x32_bf16 v[88:91], v[128:131], v[202:205], 0
	v_mfma_f32_16x16x32_bf16 v[80:83], v[120:123], v[210:213], 0
	v_mfma_f32_16x16x32_bf16 v[72:75], v[128:131], v[210:213], 0
	v_mfma_f32_16x16x32_bf16 v[140:143], v[124:127], v[188:191], v[140:143]
	v_mfma_f32_16x16x32_bf16 v[136:139], v[132:135], v[188:191], v[136:139]
	v_mfma_f32_16x16x32_bf16 v[112:115], v[124:127], v[198:201], v[112:115]
	v_mfma_f32_16x16x32_bf16 v[104:107], v[132:135], v[198:201], v[104:107]
	v_mfma_f32_16x16x32_bf16 v[96:99], v[124:127], v[206:209], v[96:99]
	v_mfma_f32_16x16x32_bf16 v[88:91], v[132:135], v[206:209], v[88:91]
	v_mfma_f32_16x16x32_bf16 v[80:83], v[124:127], v[214:217], v[80:83]
	v_mfma_f32_16x16x32_bf16 v[72:75], v[132:135], v[214:217], v[72:75]
	s_setprio 0
	s_setprio 1
	v_mfma_f32_16x16x32_bf16 v[116:119], v[160:163], v[184:187], 0
	v_mfma_f32_16x16x32_bf16 v[108:111], v[176:179], v[184:187], 0
	v_mfma_f32_16x16x32_bf16 v[100:103], v[160:163], v[194:197], 0
	v_mfma_f32_16x16x32_bf16 v[92:95], v[176:179], v[194:197], 0
	v_mfma_f32_16x16x32_bf16 v[84:87], v[160:163], v[202:205], 0
	v_mfma_f32_16x16x32_bf16 v[76:79], v[176:179], v[202:205], 0
	v_mfma_f32_16x16x32_bf16 v[68:71], v[160:163], v[210:213], 0
	v_mfma_f32_16x16x32_bf16 v[64:67], v[176:179], v[210:213], 0
	v_mfma_f32_16x16x32_bf16 v[116:119], v[172:175], v[188:191], v[116:119]
	v_mfma_f32_16x16x32_bf16 v[108:111], v[180:183], v[188:191], v[108:111]
	v_mfma_f32_16x16x32_bf16 v[100:103], v[172:175], v[198:201], v[100:103]
	v_mfma_f32_16x16x32_bf16 v[92:95], v[180:183], v[198:201], v[92:95]
	v_mfma_f32_16x16x32_bf16 v[84:87], v[172:175], v[206:209], v[84:87]
	v_mfma_f32_16x16x32_bf16 v[76:79], v[180:183], v[206:209], v[76:79]
	v_mfma_f32_16x16x32_bf16 v[68:71], v[172:175], v[214:217], v[68:71]
	v_mfma_f32_16x16x32_bf16 v[64:67], v[180:183], v[214:217], v[64:67]
	s_setprio 0
	s_barrier
	s_add_i32 s28, s65, s54
	v_lshl_add_u64 v[164:165], s[34:35], 0, v[146:147]
	s_mov_b32 m0, s28
	ds_read_b128 v[184:187], v171 offset:16384
	ds_read_b128 v[188:191], v171 offset:17408
	ds_read_b128 v[194:197], v171 offset:18432
	ds_read_b128 v[198:201], v171 offset:19456
	ds_read_b128 v[202:205], v171 offset:20480
	ds_read_b128 v[206:209], v171 offset:21504
	ds_read_b128 v[210:213], v171 offset:22528
	ds_read_b128 v[214:217], v171 offset:23552
	global_load_lds_dwordx4 v[164:165], off
	s_add_i32 m0, s28, 0x2000
	s_add_u32 s28, s34, 0x160000
	v_lshl_add_u64 v[218:219], s[34:35], 0, v[150:151]
	s_addc_u32 s29, s35, 0
	s_add_i32 s78, s66, s54
	global_load_lds_dwordx4 v[218:219], off
	v_lshl_add_u64 v[220:221], s[28:29], 0, v[146:147]
	s_mov_b32 m0, s78
	v_lshl_add_u64 v[222:223], s[36:37], 0, v[148:149]
	global_load_lds_dwordx4 v[220:221], off
	v_lshl_add_u64 v[220:221], s[28:29], 0, v[150:151]
	s_add_i32 m0, s78, 0x2000
	s_nop 0
	global_load_lds_dwordx4 v[220:221], off
	v_lshl_add_u64 v[220:221], s[36:37], 0, v[144:145]
	s_mov_b32 m0, s55
	s_nop 0
	global_load_lds_dwordx4 v[220:221], off
	s_mov_b32 m0, s56
	s_nop 0
	global_load_lds_dwordx4 v[222:223], off
	s_waitcnt vmcnt(8)
	s_waitcnt lgkmcnt(0)
	s_barrier
; #define PG8_STAGE(bufoff, gbase, voff) do { _Pragma("unroll") for (int _i = 0; _i < 2; ++_i) \
;         __builtin_amdgcn_global_load_lds((const unsigned*)((const char*)(gbase) + (voff)[_i]), (PG8_LAS unsigned*)(lds + (bufoff) + ldsw + _i * 8192), 16, 0, 0); } while (0)
; #define PG8_LDA(dst, b, h) do { _Pragma("unroll") for (int m = 0; m < 4; ++m) _Pragma("unroll") for (int k = 0; k < 2; ++k) dst[m][k] = *(const PG8_LAS bf16x8*)(lds + PG8_SA(b, h) + aoff + m * 2048 + k * 1024); } while (0)
; #define PG8_LDB(dst, b, h) do { _Pragma("unroll") for (int n = 0; n < 2; ++n) _Pragma("unroll") for (int k = 0; k < 2; ++k) dst[n][k] = *(const PG8_LAS bf16x8*)(lds + PG8_SB(b, h) + boff + n * 2048 + k * 1024); } while (0)
; #define PG8_MMA(ai, bj, At, Bt) do { __builtin_amdgcn_s_setprio(1); _Pragma("unroll") for (int m = 0; m < 4; ++m) _Pragma("unroll") for (int n = 0; n < 2; ++n) _Pragma("unroll") for (int k = 0; k < 2; ++k) \
;         acc[ai][bj][m][n] = __builtin_amdgcn_mfma_f32_16x16x32_bf16(Bt[n][k], At[m][k], acc[ai][bj][m][n], 0, 0, 0); __builtin_amdgcn_s_setprio(0); } while (0)
; #define PG8_WAIT_V(n) asm volatile("s_waitcnt vmcnt(" #n ")" ::: "memory")
; #define PG8_WAIT_L(n) asm volatile("s_waitcnt lgkmcnt(" #n ")" ::: "memory")
; #define PG8_BAR __builtin_amdgcn_s_barrier()
; #define PG8_SCHED __builtin_amdgcn_sched_barrier(0)
; template <class Epi, class Sched, bool ALIGN_EPI = false, bool SP2 = false>
; __device__ __forceinline__ void gemm_phase(PG8_LAS unsigned char* lds, const Gemm g, const Sched& S, const Epi& E) {
;     ...
;             PG8_WAIT_V(8); PG8_WAIT_L(0); PG8_BAR; PG8_MMA(1, 0, At, B0); PG8_MMA(1, 1, At, B1); PG8_BAR; PG8_SCHED;
;             PG8_LDB(B0, 1, 0); PG8_LDB(B1, 1, 1); PG8_SCHED; PG8_LDA(At, 1, 0); PG8_STAGE(PG8_SA(0, 1), a2 + hstep, voffA);
;             PG8_WAIT_V(8); PG8_WAIT_L(0); PG8_BAR; PG8_MMA(0, 0, At, B0); PG8_MMA(0, 1, At, B1); PG8_BAR; PG8_SCHED;
	s_setprio 1
	s_waitcnt lgkmcnt(0)
	v_mfma_f32_16x16x32_bf16 v[60:63], v[120:123], v[184:187], 0
	v_mfma_f32_16x16x32_bf16 v[56:59], v[128:131], v[184:187], 0
	v_mfma_f32_16x16x32_bf16 v[48:51], v[120:123], v[194:197], 0
	v_mfma_f32_16x16x32_bf16 v[40:43], v[128:131], v[194:197], 0
	v_mfma_f32_16x16x32_bf16 v[32:35], v[120:123], v[202:205], 0
	v_mfma_f32_16x16x32_bf16 v[24:27], v[128:131], v[202:205], 0
	v_mfma_f32_16x16x32_bf16 v[16:19], v[120:123], v[210:213], 0
	v_mfma_f32_16x16x32_bf16 v[8:11], v[128:131], v[210:213], 0
	v_mfma_f32_16x16x32_bf16 v[60:63], v[124:127], v[188:191], v[60:63]
	v_mfma_f32_16x16x32_bf16 v[56:59], v[132:135], v[188:191], v[56:59]
	v_mfma_f32_16x16x32_bf16 v[48:51], v[124:127], v[198:201], v[48:51]
	v_mfma_f32_16x16x32_bf16 v[40:43], v[132:135], v[198:201], v[40:43]
	v_mfma_f32_16x16x32_bf16 v[32:35], v[124:127], v[206:209], v[32:35]
	v_mfma_f32_16x16x32_bf16 v[24:27], v[132:135], v[206:209], v[24:27]
	v_mfma_f32_16x16x32_bf16 v[16:19], v[124:127], v[214:217], v[16:19]
	v_mfma_f32_16x16x32_bf16 v[8:11], v[132:135], v[214:217], v[8:11]
	s_setprio 0
	s_setprio 1
	v_mfma_f32_16x16x32_bf16 v[52:55], v[160:163], v[184:187], 0
	v_mfma_f32_16x16x32_bf16 v[44:47], v[176:179], v[184:187], 0
	v_mfma_f32_16x16x32_bf16 v[36:39], v[160:163], v[194:197], 0
	v_mfma_f32_16x16x32_bf16 v[28:31], v[176:179], v[194:197], 0
	v_mfma_f32_16x16x32_bf16 v[20:23], v[160:163], v[202:205], 0
	v_mfma_f32_16x16x32_bf16 v[12:15], v[176:179], v[202:205], 0
	v_mfma_f32_16x16x32_bf16 v[4:7], v[160:163], v[210:213], 0
	v_mfma_f32_16x16x32_bf16 v[0:3], v[176:179], v[210:213], 0
	v_mfma_f32_16x16x32_bf16 v[52:55], v[172:175], v[188:191], v[52:55]
	v_mfma_f32_16x16x32_bf16 v[44:47], v[180:183], v[188:191], v[44:47]
	v_mfma_f32_16x16x32_bf16 v[36:39], v[172:175], v[198:201], v[36:39]
	v_mfma_f32_16x16x32_bf16 v[28:31], v[180:183], v[198:201], v[28:31]
	v_mfma_f32_16x16x32_bf16 v[20:23], v[172:175], v[206:209], v[20:23]
	v_mfma_f32_16x16x32_bf16 v[12:15], v[180:183], v[206:209], v[12:15]
	v_mfma_f32_16x16x32_bf16 v[4:7], v[172:175], v[214:217], v[4:7]
	v_mfma_f32_16x16x32_bf16 v[0:3], v[180:183], v[214:217], v[0:3]
	s_setprio 0
	s_barrier
	s_add_i32 s78, 0, 0x18000
	s_add_i32 s79, 0, 0x1c000
	v_add_u32_e32 v132, s78, v167
	v_add_u32_e32 v180, s79, v167
	ds_read_b128 v[120:123], v132
	ds_read_b128 v[124:127], v132 offset:1024
	ds_read_b128 v[128:131], v132 offset:2048
	ds_read_b128 v[132:135], v132 offset:3072
	ds_read_b128 v[160:163], v180
	ds_read_b128 v[172:175], v180 offset:1024
	ds_read_b128 v[176:179], v180 offset:2048
	ds_read_b128 v[180:183], v180 offset:3072
	s_add_u32 s28, s36, 0x160000
	s_addc_u32 s29, s37, 0
	s_mov_b32 m0, s57
	v_lshl_add_u64 v[224:225], s[28:29], 0, v[144:145]
	ds_read_b128 v[184:187], v171 offset:32768
	ds_read_b128 v[188:191], v171 offset:33792
	ds_read_b128 v[194:197], v171 offset:34816
	ds_read_b128 v[198:201], v171 offset:35840
	ds_read_b128 v[202:205], v171 offset:36864
	ds_read_b128 v[206:209], v171 offset:37888
	ds_read_b128 v[210:213], v171 offset:38912
	ds_read_b128 v[214:217], v171 offset:39936
	global_load_lds_dwordx4 v[224:225], off
	v_lshl_add_u64 v[224:225], s[28:29], 0, v[148:149]
	s_mov_b32 m0, s58
	s_nop 0
	global_load_lds_dwordx4 v[224:225], off
	s_waitcnt vmcnt(8)
	s_waitcnt lgkmcnt(0)
	s_barrier
	s_setprio 1
	s_waitcnt lgkmcnt(0)
	v_mfma_f32_16x16x32_bf16 v[140:143], v[120:123], v[184:187], v[140:143]
	v_mfma_f32_16x16x32_bf16 v[136:139], v[128:131], v[184:187], v[136:139]
	v_mfma_f32_16x16x32_bf16 v[112:115], v[120:123], v[194:197], v[112:115]
	v_mfma_f32_16x16x32_bf16 v[104:107], v[128:131], v[194:197], v[104:107]
	v_mfma_f32_16x16x32_bf16 v[96:99], v[120:123], v[202:205], v[96:99]
	v_mfma_f32_16x16x32_bf16 v[88:91], v[128:131], v[202:205], v[88:91]
	v_mfma_f32_16x16x32_bf16 v[80:83], v[120:123], v[210:213], v[80:83]
	v_mfma_f32_16x16x32_bf16 v[72:75], v[128:131], v[210:213], v[72:75]
	v_mfma_f32_16x16x32_bf16 v[140:143], v[124:127], v[188:191], v[140:143]
	v_mfma_f32_16x16x32_bf16 v[136:139], v[132:135], v[188:191], v[136:139]
	v_mfma_f32_16x16x32_bf16 v[112:115], v[124:127], v[198:201], v[112:115]
	v_mfma_f32_16x16x32_bf16 v[104:107], v[132:135], v[198:201], v[104:107]
	v_mfma_f32_16x16x32_bf16 v[96:99], v[124:127], v[206:209], v[96:99]
	v_mfma_f32_16x16x32_bf16 v[88:91], v[132:135], v[206:209], v[88:91]
	v_mfma_f32_16x16x32_bf16 v[80:83], v[124:127], v[214:217], v[80:83]
	v_mfma_f32_16x16x32_bf16 v[72:75], v[132:135], v[214:217], v[72:75]
	s_setprio 0
	s_setprio 1
	v_mfma_f32_16x16x32_bf16 v[116:119], v[160:163], v[184:187], v[116:119]
	v_mfma_f32_16x16x32_bf16 v[108:111], v[176:179], v[184:187], v[108:111]
	v_mfma_f32_16x16x32_bf16 v[100:103], v[160:163], v[194:197], v[100:103]
	v_mfma_f32_16x16x32_bf16 v[92:95], v[176:179], v[194:197], v[92:95]
	v_mfma_f32_16x16x32_bf16 v[84:87], v[160:163], v[202:205], v[84:87]
	v_mfma_f32_16x16x32_bf16 v[76:79], v[176:179], v[202:205], v[76:79]
	v_mfma_f32_16x16x32_bf16 v[68:71], v[160:163], v[210:213], v[68:71]
	v_mfma_f32_16x16x32_bf16 v[64:67], v[176:179], v[210:213], v[64:67]
	v_mfma_f32_16x16x32_bf16 v[116:119], v[172:175], v[188:191], v[116:119]
	v_mfma_f32_16x16x32_bf16 v[108:111], v[180:183], v[188:191], v[108:111]
	v_mfma_f32_16x16x32_bf16 v[100:103], v[172:175], v[198:201], v[100:103]
	v_mfma_f32_16x16x32_bf16 v[92:95], v[180:183], v[198:201], v[92:95]
	v_mfma_f32_16x16x32_bf16 v[84:87], v[172:175], v[206:209], v[84:87]
	v_mfma_f32_16x16x32_bf16 v[76:79], v[180:183], v[206:209], v[76:79]
	v_mfma_f32_16x16x32_bf16 v[68:71], v[172:175], v[214:217], v[68:71]
	v_mfma_f32_16x16x32_bf16 v[64:67], v[180:183], v[214:217], v[64:67]
	s_setprio 0
	s_barrier
; #define PG8_STAGE(bufoff, gbase, voff) do { _Pragma("unroll") for (int _i = 0; _i < 2; ++_i) \
;         __builtin_amdgcn_global_load_lds((const unsigned*)((const char*)(gbase) + (voff)[_i]), (PG8_LAS unsigned*)(lds + (bufoff) + ldsw + _i * 8192), 16, 0, 0); } while (0)
; #define PG8_LDA(dst, b, h) do { _Pragma("unroll") for (int m = 0; m < 4; ++m) _Pragma("unroll") for (int k = 0; k < 2; ++k) dst[m][k] = *(const PG8_LAS bf16x8*)(lds + PG8_SA(b, h) + aoff + m * 2048 + k * 1024); } while (0)
; #define PG8_LDB(dst, b, h) do { _Pragma("unroll") for (int n = 0; n < 2; ++n) _Pragma("unroll") for (int k = 0; k < 2; ++k) dst[n][k] = *(const PG8_LAS bf16x8*)(lds + PG8_SB(b, h) + boff + n * 2048 + k * 1024); } while (0)
; template <class Epi, class Sched, bool ALIGN_EPI = false, bool SP2 = false>
; __device__ __forceinline__ void gemm_phase(PG8_LAS unsigned char* lds, const Gemm g, const Sched& S, const Epi& E) {
;     ...
;         for (int t = 0; t < nt; t += 2) {
;             const bool last = (t == nt - 2);
;             const char* a1 = cA + (size_t)(t + 1) * kstep;
;             const char* a2 = last ? nA : cA + (size_t)(t + 2) * kstep; const char* b2 = last ? nB : cB + (size_t)(t + 2) * kstep;
;             const char* a3 = a2 + kstep; const char* b3 = b2 + kstep;
;             if (last && has_next) S.a_ready(nxt);
;             if constexpr (SP2) {
;             PG8_LDB(B0, 0, 0); PG8_LDB(B1, 0, 1); PG8_SCHED; PG8_LDA(At, 0, 0); PG8_STAGE(PG8_SA(1, 1), a1 + hstep, voffA);
;             PG8_WAIT_V(8); PG8_WAIT_L(0); PG8_BAR; PG8_MMA(0, 0, At, B0); PG8_MMA(0, 1, At, B1); PG8_BAR; PG8_SCHED;
;             PG8_LDA(At, 0, 1); PG8_STAGE(PG8_SB(0, 0), b2, voffB); PG8_STAGE(PG8_SB(0, 1), b2 + hstep, voffB); PG8_STAGE(PG8_SA(0, 0), a2, voffA);
;             PG8_WAIT_V(8); PG8_WAIT_L(0); PG8_BAR; PG8_MMA(1, 0, At, B0); PG8_MMA(1, 1, At, B1); PG8_BAR; PG8_SCHED;
;             PG8_LDB(B0, 1, 0); PG8_LDB(B1, 1, 1); PG8_SCHED; PG8_LDA(At, 1, 0); PG8_STAGE(PG8_SA(0, 1), a2 + hstep, voffA);
;             PG8_WAIT_V(8); PG8_WAIT_L(0); PG8_BAR; PG8_MMA(0, 0, At, B0); PG8_MMA(0, 1, At, B1); PG8_BAR; PG8_SCHED;
;             PG8_LDA(At, 1, 1); PG8_STAGE(PG8_SB(1, 0), b3, voffB); PG8_STAGE(PG8_SB(1, 1), b3 + hstep, voffB); PG8_STAGE(PG8_SA(1, 0), a3, voffA);
;             PG8_WAIT_V(8); PG8_WAIT_L(0); PG8_BAR; PG8_MMA(1, 0, At, B0); PG8_MMA(1, 1, At, B1); PG8_BAR; PG8_SCHED;
	s_add_i32 s28, s78, s54
	v_lshl_add_u64 v[164:165], v[164:165], 0, s[14:15]
	s_mov_b32 m0, s28
	ds_read_b128 v[184:187], v171 offset:49152
	ds_read_b128 v[188:191], v171 offset:50176
	ds_read_b128 v[194:197], v171 offset:51200
	ds_read_b128 v[198:201], v171 offset:52224
	ds_read_b128 v[202:205], v171 offset:53248
	ds_read_b128 v[206:209], v171 offset:54272
	ds_read_b128 v[210:213], v171 offset:55296
	ds_read_b128 v[214:217], v171 offset:56320
	global_load_lds_dwordx4 v[164:165], off
	s_add_i32 m0, s28, 0x2000
	s_add_u32 s28, s34, 0x160080
	v_lshl_add_u64 v[164:165], v[218:219], 0, s[14:15]
	s_addc_u32 s29, s35, 0
	s_add_i32 s34, s79, s54
	global_load_lds_dwordx4 v[164:165], off
	v_lshl_add_u64 v[164:165], s[28:29], 0, v[146:147]
	s_mov_b32 m0, s34
	s_nop 0
	global_load_lds_dwordx4 v[164:165], off
	v_lshl_add_u64 v[164:165], s[28:29], 0, v[150:151]
	s_add_i32 m0, s34, 0x2000
	s_nop 0
	global_load_lds_dwordx4 v[164:165], off
	v_lshl_add_u64 v[164:165], v[220:221], 0, s[14:15]
	s_mov_b32 m0, s62
	s_nop 0
	global_load_lds_dwordx4 v[164:165], off
	v_lshl_add_u64 v[164:165], v[222:223], 0, s[14:15]
	s_mov_b32 m0, s63
	s_nop 0
	global_load_lds_dwordx4 v[164:165], off
	s_waitcnt vmcnt(8)
	s_waitcnt lgkmcnt(0)
	s_barrier
	s_setprio 1
	s_waitcnt lgkmcnt(0)
	v_mfma_f32_16x16x32_bf16 v[60:63], v[120:123], v[184:187], v[60:63]
	v_mfma_f32_16x16x32_bf16 v[56:59], v[128:131], v[184:187], v[56:59]
	v_mfma_f32_16x16x32_bf16 v[48:51], v[120:123], v[194:197], v[48:51]
	v_mfma_f32_16x16x32_bf16 v[40:43], v[128:131], v[194:197], v[40:43]
	v_mfma_f32_16x16x32_bf16 v[32:35], v[120:123], v[202:205], v[32:35]
	v_mfma_f32_16x16x32_bf16 v[24:27], v[128:131], v[202:205], v[24:27]
	v_mfma_f32_16x16x32_bf16 v[16:19], v[120:123], v[210:213], v[16:19]
	v_mfma_f32_16x16x32_bf16 v[8:11], v[128:131], v[210:213], v[8:11]
	v_mfma_f32_16x16x32_bf16 v[60:63], v[124:127], v[188:191], v[60:63]
	v_mfma_f32_16x16x32_bf16 v[56:59], v[132:135], v[188:191], v[56:59]
	v_mfma_f32_16x16x32_bf16 v[48:51], v[124:127], v[198:201], v[48:51]
	v_mfma_f32_16x16x32_bf16 v[40:43], v[132:135], v[198:201], v[40:43]
	v_mfma_f32_16x16x32_bf16 v[32:35], v[124:127], v[206:209], v[32:35]
	v_mfma_f32_16x16x32_bf16 v[24:27], v[132:135], v[206:209], v[24:27]
	v_mfma_f32_16x16x32_bf16 v[16:19], v[124:127], v[214:217], v[16:19]
	v_mfma_f32_16x16x32_bf16 v[8:11], v[132:135], v[214:217], v[8:11]
	s_setprio 0
	s_setprio 1
	v_mfma_f32_16x16x32_bf16 v[52:55], v[160:163], v[184:187], v[52:55]
	v_mfma_f32_16x16x32_bf16 v[44:47], v[176:179], v[184:187], v[44:47]
	v_mfma_f32_16x16x32_bf16 v[36:39], v[160:163], v[194:197], v[36:39]
	v_mfma_f32_16x16x32_bf16 v[28:31], v[176:179], v[194:197], v[28:31]
	v_mfma_f32_16x16x32_bf16 v[20:23], v[160:163], v[202:205], v[20:23]
	v_mfma_f32_16x16x32_bf16 v[12:15], v[176:179], v[202:205], v[12:15]
	v_mfma_f32_16x16x32_bf16 v[4:7], v[160:163], v[210:213], v[4:7]
	v_mfma_f32_16x16x32_bf16 v[0:3], v[176:179], v[210:213], v[0:3]
	v_mfma_f32_16x16x32_bf16 v[52:55], v[172:175], v[188:191], v[52:55]
	v_mfma_f32_16x16x32_bf16 v[44:47], v[180:183], v[188:191], v[44:47]
	v_mfma_f32_16x16x32_bf16 v[36:39], v[172:175], v[198:201], v[36:39]
	v_mfma_f32_16x16x32_bf16 v[28:31], v[180:183], v[198:201], v[28:31]
	v_mfma_f32_16x16x32_bf16 v[20:23], v[172:175], v[206:209], v[20:23]
	v_mfma_f32_16x16x32_bf16 v[12:15], v[180:183], v[206:209], v[12:15]
	v_mfma_f32_16x16x32_bf16 v[4:7], v[172:175], v[214:217], v[4:7]
	v_mfma_f32_16x16x32_bf16 v[0:3], v[180:183], v[214:217], v[0:3]
	s_add_i32 s77, s77, 2
	s_add_u32 s75, s75, 0x100
	s_addc_u32 s76, s76, 0
	s_cmpk_gt_u32 s77, 0x55
	s_mov_b64 s[28:29], s[30:31]
	s_setprio 0
	s_barrier
	s_cbranch_scc1 .Lpeel_exit_3
.LBB0_561:
	ds_read_b128 v[120:123], v169
	ds_read_b128 v[124:127], v169 offset:1024
	ds_read_b128 v[128:131], v169 offset:2048
	ds_read_b128 v[132:135], v169 offset:3072
	ds_read_b128 v[160:163], v170
	ds_read_b128 v[172:175], v170 offset:1024
	ds_read_b128 v[176:179], v170 offset:2048
	ds_read_b128 v[180:183], v170 offset:3072
	s_add_u32 s30, s28, 0x100
	s_addc_u32 s31, s29, 0
	s_cmpk_eq_i32 s77, 0x54
	s_cselect_b32 s37, s9, s31
	s_cselect_b32 s36, s8, s30
	s_cselect_b32 s35, s27, s76
	s_cselect_b32 s34, s26, s75
	v_lshl_add_u64 v[164:165], s[28:29], 0, v[154:155]
	s_add_i32 m0, s55, 0xc000
	ds_read_b128 v[184:187], v171
	ds_read_b128 v[188:191], v171 offset:1024
	ds_read_b128 v[194:197], v171 offset:2048
	ds_read_b128 v[198:201], v171 offset:3072
	ds_read_b128 v[202:205], v171 offset:4096
	ds_read_b128 v[206:209], v171 offset:5120
	ds_read_b128 v[210:213], v171 offset:6144
	ds_read_b128 v[214:217], v171 offset:7168
	global_load_lds_dwordx4 v[164:165], off
	v_lshl_add_u64 v[164:165], s[28:29], 0, v[152:153]
	s_add_i32 m0, s55, 0xe000
	s_nop 0
	global_load_lds_dwordx4 v[164:165], off
	s_waitcnt vmcnt(8)
	s_waitcnt lgkmcnt(0)
	s_barrier
; #define PG8_STAGE(bufoff, gbase, voff) do { _Pragma("unroll") for (int _i = 0; _i < 2; ++_i) \
;         __builtin_amdgcn_global_load_lds((const unsigned*)((const char*)(gbase) + (voff)[_i]), (PG8_LAS unsigned*)(lds + (bufoff) + ldsw + _i * 8192), 16, 0, 0); } while (0)
; #define PG8_LDA(dst, b, h) do { _Pragma("unroll") for (int m = 0; m < 4; ++m) _Pragma("unroll") for (int k = 0; k < 2; ++k) dst[m][k] = *(const PG8_LAS bf16x8*)(lds + PG8_SA(b, h) + aoff + m * 2048 + k * 1024); } while (0)
; #define PG8_LDB(dst, b, h) do { _Pragma("unroll") for (int n = 0; n < 2; ++n) _Pragma("unroll") for (int k = 0; k < 2; ++k) dst[n][k] = *(const PG8_LAS bf16x8*)(lds + PG8_SB(b, h) + boff + n * 2048 + k * 1024); } while (0)
; #define PG8_MMA(ai, bj, At, Bt) do { __builtin_amdgcn_s_setprio(1); _Pragma("unroll") for (int m = 0; m < 4; ++m) _Pragma("unroll") for (int n = 0; n < 2; ++n) _Pragma("unroll") for (int k = 0; k < 2; ++k) \
;         acc[ai][bj][m][n] = __builtin_amdgcn_mfma_f32_16x16x32_bf16(Bt[n][k], At[m][k], acc[ai][bj][m][n], 0, 0, 0); __builtin_amdgcn_s_setprio(0); } while (0)
; #define PG8_WAIT_V(n) asm volatile("s_waitcnt vmcnt(" #n ")" ::: "memory")
; #define PG8_WAIT_L(n) asm volatile("s_waitcnt lgkmcnt(" #n ")" ::: "memory")
; #define PG8_BAR __builtin_amdgcn_s_barrier()
; #define PG8_SCHED __builtin_amdgcn_sched_barrier(0)
; template <class Epi, class Sched, bool ALIGN_EPI = false, bool SP2 = false>
; __device__ __forceinline__ void gemm_phase(PG8_LAS unsigned char* lds, const Gemm g, const Sched& S, const Epi& E) {
;     ...
;             PG8_WAIT_V(8); PG8_WAIT_L(0); PG8_BAR; PG8_MMA(0, 0, At, B0); PG8_MMA(0, 1, At, B1); PG8_BAR; PG8_SCHED;
;             PG8_LDA(At, 0, 1); PG8_STAGE(PG8_SB(0, 0), b2, voffB); PG8_STAGE(PG8_SB(0, 1), b2 + hstep, voffB); PG8_STAGE(PG8_SA(0, 0), a2, voffA);
;             PG8_WAIT_V(8); PG8_WAIT_L(0); PG8_BAR; PG8_MMA(1, 0, At, B0); PG8_MMA(1, 1, At, B1); PG8_BAR; PG8_SCHED;
;             PG8_LDB(B0, 1, 0); PG8_LDB(B1, 1, 1); PG8_SCHED; PG8_LDA(At, 1, 0); PG8_STAGE(PG8_SA(0, 1), a2 + hstep, voffA);
;             PG8_WAIT_V(8); PG8_WAIT_L(0); PG8_BAR; PG8_MMA(0, 0, At, B0); PG8_MMA(0, 1, At, B1); PG8_BAR; PG8_SCHED;
	s_setprio 1
	s_waitcnt lgkmcnt(0)
	v_mfma_f32_16x16x32_bf16 v[140:143], v[120:123], v[184:187], v[140:143]
	v_mfma_f32_16x16x32_bf16 v[136:139], v[128:131], v[184:187], v[136:139]
	v_mfma_f32_16x16x32_bf16 v[112:115], v[120:123], v[194:197], v[112:115]
	v_mfma_f32_16x16x32_bf16 v[104:107], v[128:131], v[194:197], v[104:107]
	v_mfma_f32_16x16x32_bf16 v[96:99], v[120:123], v[202:205], v[96:99]
	v_mfma_f32_16x16x32_bf16 v[88:91], v[128:131], v[202:205], v[88:91]
	v_mfma_f32_16x16x32_bf16 v[80:83], v[120:123], v[210:213], v[80:83]
	v_mfma_f32_16x16x32_bf16 v[72:75], v[128:131], v[210:213], v[72:75]
	v_mfma_f32_16x16x32_bf16 v[140:143], v[124:127], v[188:191], v[140:143]
	v_mfma_f32_16x16x32_bf16 v[136:139], v[132:135], v[188:191], v[136:139]
	v_mfma_f32_16x16x32_bf16 v[112:115], v[124:127], v[198:201], v[112:115]
	v_mfma_f32_16x16x32_bf16 v[104:107], v[132:135], v[198:201], v[104:107]
	v_mfma_f32_16x16x32_bf16 v[96:99], v[124:127], v[206:209], v[96:99]
	v_mfma_f32_16x16x32_bf16 v[88:91], v[132:135], v[206:209], v[88:91]
	v_mfma_f32_16x16x32_bf16 v[80:83], v[124:127], v[214:217], v[80:83]
	v_mfma_f32_16x16x32_bf16 v[72:75], v[132:135], v[214:217], v[72:75]
	s_setprio 0
	s_setprio 1
	v_mfma_f32_16x16x32_bf16 v[116:119], v[160:163], v[184:187], v[116:119]
	v_mfma_f32_16x16x32_bf16 v[108:111], v[176:179], v[184:187], v[108:111]
	v_mfma_f32_16x16x32_bf16 v[100:103], v[160:163], v[194:197], v[100:103]
	v_mfma_f32_16x16x32_bf16 v[92:95], v[176:179], v[194:197], v[92:95]
	v_mfma_f32_16x16x32_bf16 v[84:87], v[160:163], v[202:205], v[84:87]
	v_mfma_f32_16x16x32_bf16 v[76:79], v[176:179], v[202:205], v[76:79]
	v_mfma_f32_16x16x32_bf16 v[68:71], v[160:163], v[210:213], v[68:71]
	v_mfma_f32_16x16x32_bf16 v[64:67], v[176:179], v[210:213], v[64:67]
	v_mfma_f32_16x16x32_bf16 v[116:119], v[172:175], v[188:191], v[116:119]
	v_mfma_f32_16x16x32_bf16 v[108:111], v[180:183], v[188:191], v[108:111]
	v_mfma_f32_16x16x32_bf16 v[100:103], v[172:175], v[198:201], v[100:103]
	v_mfma_f32_16x16x32_bf16 v[92:95], v[180:183], v[198:201], v[92:95]
	v_mfma_f32_16x16x32_bf16 v[84:87], v[172:175], v[206:209], v[84:87]
	v_mfma_f32_16x16x32_bf16 v[76:79], v[180:183], v[206:209], v[76:79]
	v_mfma_f32_16x16x32_bf16 v[68:71], v[172:175], v[214:217], v[68:71]
	v_mfma_f32_16x16x32_bf16 v[64:67], v[180:183], v[214:217], v[64:67]
	s_setprio 0
	s_barrier
	s_add_i32 s28, s65, s54
	v_lshl_add_u64 v[164:165], s[34:35], 0, v[146:147]
	s_mov_b32 m0, s28
	ds_read_b128 v[184:187], v171 offset:16384
	ds_read_b128 v[188:191], v171 offset:17408
	ds_read_b128 v[194:197], v171 offset:18432
	ds_read_b128 v[198:201], v171 offset:19456
	ds_read_b128 v[202:205], v171 offset:20480
	ds_read_b128 v[206:209], v171 offset:21504
	ds_read_b128 v[210:213], v171 offset:22528
	ds_read_b128 v[214:217], v171 offset:23552
	global_load_lds_dwordx4 v[164:165], off
	s_add_i32 m0, s28, 0x2000
	s_add_u32 s28, s34, 0x160000
	v_lshl_add_u64 v[218:219], s[34:35], 0, v[150:151]
	s_addc_u32 s29, s35, 0
	s_add_i32 s78, s66, s54
	global_load_lds_dwordx4 v[218:219], off
	v_lshl_add_u64 v[220:221], s[28:29], 0, v[146:147]
	s_mov_b32 m0, s78
	v_lshl_add_u64 v[222:223], s[36:37], 0, v[148:149]
	global_load_lds_dwordx4 v[220:221], off
	v_lshl_add_u64 v[220:221], s[28:29], 0, v[150:151]
	s_add_i32 m0, s78, 0x2000
	s_nop 0
	global_load_lds_dwordx4 v[220:221], off
	v_lshl_add_u64 v[220:221], s[36:37], 0, v[144:145]
	s_mov_b32 m0, s55
	s_nop 0
	global_load_lds_dwordx4 v[220:221], off
	s_mov_b32 m0, s56
	s_nop 0
	global_load_lds_dwordx4 v[222:223], off
	s_waitcnt vmcnt(8)
	s_waitcnt lgkmcnt(0)
	s_barrier
	s_setprio 1
	s_waitcnt lgkmcnt(0)
	v_mfma_f32_16x16x32_bf16 v[60:63], v[120:123], v[184:187], v[60:63]
	v_mfma_f32_16x16x32_bf16 v[56:59], v[128:131], v[184:187], v[56:59]
	v_mfma_f32_16x16x32_bf16 v[48:51], v[120:123], v[194:197], v[48:51]
	v_mfma_f32_16x16x32_bf16 v[40:43], v[128:131], v[194:197], v[40:43]
	v_mfma_f32_16x16x32_bf16 v[32:35], v[120:123], v[202:205], v[32:35]
	v_mfma_f32_16x16x32_bf16 v[24:27], v[128:131], v[202:205], v[24:27]
	v_mfma_f32_16x16x32_bf16 v[16:19], v[120:123], v[210:213], v[16:19]
	v_mfma_f32_16x16x32_bf16 v[8:11], v[128:131], v[210:213], v[8:11]
	v_mfma_f32_16x16x32_bf16 v[60:63], v[124:127], v[188:191], v[60:63]
	v_mfma_f32_16x16x32_bf16 v[56:59], v[132:135], v[188:191], v[56:59]
	v_mfma_f32_16x16x32_bf16 v[48:51], v[124:127], v[198:201], v[48:51]
	v_mfma_f32_16x16x32_bf16 v[40:43], v[132:135], v[198:201], v[40:43]
	v_mfma_f32_16x16x32_bf16 v[32:35], v[124:127], v[206:209], v[32:35]
	v_mfma_f32_16x16x32_bf16 v[24:27], v[132:135], v[206:209], v[24:27]
	v_mfma_f32_16x16x32_bf16 v[16:19], v[124:127], v[214:217], v[16:19]
	v_mfma_f32_16x16x32_bf16 v[8:11], v[132:135], v[214:217], v[8:11]
	s_setprio 0
	s_setprio 1
	v_mfma_f32_16x16x32_bf16 v[52:55], v[160:163], v[184:187], v[52:55]
	v_mfma_f32_16x16x32_bf16 v[44:47], v[176:179], v[184:187], v[44:47]
	v_mfma_f32_16x16x32_bf16 v[36:39], v[160:163], v[194:197], v[36:39]
	v_mfma_f32_16x16x32_bf16 v[28:31], v[176:179], v[194:197], v[28:31]
	v_mfma_f32_16x16x32_bf16 v[20:23], v[160:163], v[202:205], v[20:23]
	v_mfma_f32_16x16x32_bf16 v[12:15], v[176:179], v[202:205], v[12:15]
	v_mfma_f32_16x16x32_bf16 v[4:7], v[160:163], v[210:213], v[4:7]
	v_mfma_f32_16x16x32_bf16 v[0:3], v[176:179], v[210:213], v[0:3]
	v_mfma_f32_16x16x32_bf16 v[52:55], v[172:175], v[188:191], v[52:55]
	v_mfma_f32_16x16x32_bf16 v[44:47], v[180:183], v[188:191], v[44:47]
	v_mfma_f32_16x16x32_bf16 v[36:39], v[172:175], v[198:201], v[36:39]
	v_mfma_f32_16x16x32_bf16 v[28:31], v[180:183], v[198:201], v[28:31]
	v_mfma_f32_16x16x32_bf16 v[20:23], v[172:175], v[206:209], v[20:23]
	v_mfma_f32_16x16x32_bf16 v[12:15], v[180:183], v[206:209], v[12:15]
	v_mfma_f32_16x16x32_bf16 v[4:7], v[172:175], v[214:217], v[4:7]
	v_mfma_f32_16x16x32_bf16 v[0:3], v[180:183], v[214:217], v[0:3]
	s_setprio 0
	s_barrier
; #define PG8_STAGE(bufoff, gbase, voff) do { _Pragma("unroll") for (int _i = 0; _i < 2; ++_i) \
;         __builtin_amdgcn_global_load_lds((const unsigned*)((const char*)(gbase) + (voff)[_i]), (PG8_LAS unsigned*)(lds + (bufoff) + ldsw + _i * 8192), 16, 0, 0); } while (0)
; #define PG8_LDA(dst, b, h) do { _Pragma("unroll") for (int m = 0; m < 4; ++m) _Pragma("unroll") for (int k = 0; k < 2; ++k) dst[m][k] = *(const PG8_LAS bf16x8*)(lds + PG8_SA(b, h) + aoff + m * 2048 + k * 1024); } while (0)
; #define PG8_LDB(dst, b, h) do { _Pragma("unroll") for (int n = 0; n < 2; ++n) _Pragma("unroll") for (int k = 0; k < 2; ++k) dst[n][k] = *(const PG8_LAS bf16x8*)(lds + PG8_SB(b, h) + boff + n * 2048 + k * 1024); } while (0)
; #define PG8_MMA(ai, bj, At, Bt) do { __builtin_amdgcn_s_setprio(1); _Pragma("unroll") for (int m = 0; m < 4; ++m) _Pragma("unroll") for (int n = 0; n < 2; ++n) _Pragma("unroll") for (int k = 0; k < 2; ++k) \
;         acc[ai][bj][m][n] = __builtin_amdgcn_mfma_f32_16x16x32_bf16(Bt[n][k], At[m][k], acc[ai][bj][m][n], 0, 0, 0); __builtin_amdgcn_s_setprio(0); } while (0)
; #define PG8_WAIT_V(n) asm volatile("s_waitcnt vmcnt(" #n ")" ::: "memory")
; #define PG8_WAIT_L(n) asm volatile("s_waitcnt lgkmcnt(" #n ")" ::: "memory")
; #define PG8_BAR __builtin_amdgcn_s_barrier()
; #define PG8_SCHED __builtin_amdgcn_sched_barrier(0)
; template <class Epi, class Sched, bool ALIGN_EPI = false, bool SP2 = false>
; __device__ __forceinline__ void gemm_phase(PG8_LAS unsigned char* lds, const Gemm g, const Sched& S, const Epi& E) {
;     ...
;             PG8_LDB(B0, 1, 0); PG8_LDB(B1, 1, 1); PG8_SCHED; PG8_LDA(At, 1, 0); PG8_STAGE(PG8_SA(0, 1), a2 + hstep, voffA);
;             PG8_WAIT_V(8); PG8_WAIT_L(0); PG8_BAR; PG8_MMA(0, 0, At, B0); PG8_MMA(0, 1, At, B1); PG8_BAR; PG8_SCHED;
	s_add_i32 s78, 0, 0x18000
	s_add_i32 s79, 0, 0x1c000
	v_add_u32_e32 v132, s78, v167
	v_add_u32_e32 v180, s79, v167
	ds_read_b128 v[120:123], v132
	ds_read_b128 v[124:127], v132 offset:1024
	ds_read_b128 v[128:131], v132 offset:2048
	ds_read_b128 v[132:135], v132 offset:3072
	ds_read_b128 v[160:163], v180
	ds_read_b128 v[172:175], v180 offset:1024
	ds_read_b128 v[176:179], v180 offset:2048
	ds_read_b128 v[180:183], v180 offset:3072
	s_add_u32 s28, s36, 0x160000
	s_addc_u32 s29, s37, 0
	s_mov_b32 m0, s57
	v_lshl_add_u64 v[224:225], s[28:29], 0, v[144:145]
	ds_read_b128 v[184:187], v171 offset:32768
	ds_read_b128 v[188:191], v171 offset:33792
	ds_read_b128 v[194:197], v171 offset:34816
	ds_read_b128 v[198:201], v171 offset:35840
	ds_read_b128 v[202:205], v171 offset:36864
	ds_read_b128 v[206:209], v171 offset:37888
	ds_read_b128 v[210:213], v171 offset:38912
	ds_read_b128 v[214:217], v171 offset:39936
	global_load_lds_dwordx4 v[224:225], off
	v_lshl_add_u64 v[224:225], s[28:29], 0, v[148:149]
	s_mov_b32 m0, s58
	s_nop 0
	global_load_lds_dwordx4 v[224:225], off
	s_waitcnt vmcnt(8)
	s_waitcnt lgkmcnt(0)
	s_barrier
	s_setprio 1
	s_waitcnt lgkmcnt(0)
	v_mfma_f32_16x16x32_bf16 v[140:143], v[120:123], v[184:187], v[140:143]
	v_mfma_f32_16x16x32_bf16 v[136:139], v[128:131], v[184:187], v[136:139]
	v_mfma_f32_16x16x32_bf16 v[112:115], v[120:123], v[194:197], v[112:115]
	v_mfma_f32_16x16x32_bf16 v[104:107], v[128:131], v[194:197], v[104:107]
	v_mfma_f32_16x16x32_bf16 v[96:99], v[120:123], v[202:205], v[96:99]
	v_mfma_f32_16x16x32_bf16 v[88:91], v[128:131], v[202:205], v[88:91]
	v_mfma_f32_16x16x32_bf16 v[80:83], v[120:123], v[210:213], v[80:83]
	v_mfma_f32_16x16x32_bf16 v[72:75], v[128:131], v[210:213], v[72:75]
	v_mfma_f32_16x16x32_bf16 v[140:143], v[124:127], v[188:191], v[140:143]
	v_mfma_f32_16x16x32_bf16 v[136:139], v[132:135], v[188:191], v[136:139]
	v_mfma_f32_16x16x32_bf16 v[112:115], v[124:127], v[198:201], v[112:115]
	v_mfma_f32_16x16x32_bf16 v[104:107], v[132:135], v[198:201], v[104:107]
	v_mfma_f32_16x16x32_bf16 v[96:99], v[124:127], v[206:209], v[96:99]
	v_mfma_f32_16x16x32_bf16 v[88:91], v[132:135], v[206:209], v[88:91]
	v_mfma_f32_16x16x32_bf16 v[80:83], v[124:127], v[214:217], v[80:83]
	v_mfma_f32_16x16x32_bf16 v[72:75], v[132:135], v[214:217], v[72:75]
	s_setprio 0
	s_setprio 1
	v_mfma_f32_16x16x32_bf16 v[116:119], v[160:163], v[184:187], v[116:119]
	v_mfma_f32_16x16x32_bf16 v[108:111], v[176:179], v[184:187], v[108:111]
	v_mfma_f32_16x16x32_bf16 v[100:103], v[160:163], v[194:197], v[100:103]
	v_mfma_f32_16x16x32_bf16 v[92:95], v[176:179], v[194:197], v[92:95]
	v_mfma_f32_16x16x32_bf16 v[84:87], v[160:163], v[202:205], v[84:87]
	v_mfma_f32_16x16x32_bf16 v[76:79], v[176:179], v[202:205], v[76:79]
	v_mfma_f32_16x16x32_bf16 v[68:71], v[160:163], v[210:213], v[68:71]
	v_mfma_f32_16x16x32_bf16 v[64:67], v[176:179], v[210:213], v[64:67]
	v_mfma_f32_16x16x32_bf16 v[116:119], v[172:175], v[188:191], v[116:119]
	v_mfma_f32_16x16x32_bf16 v[108:111], v[180:183], v[188:191], v[108:111]
	v_mfma_f32_16x16x32_bf16 v[100:103], v[172:175], v[198:201], v[100:103]
	v_mfma_f32_16x16x32_bf16 v[92:95], v[180:183], v[198:201], v[92:95]
	v_mfma_f32_16x16x32_bf16 v[84:87], v[172:175], v[206:209], v[84:87]
	v_mfma_f32_16x16x32_bf16 v[76:79], v[180:183], v[206:209], v[76:79]
	v_mfma_f32_16x16x32_bf16 v[68:71], v[172:175], v[214:217], v[68:71]
	v_mfma_f32_16x16x32_bf16 v[64:67], v[180:183], v[214:217], v[64:67]
	s_setprio 0
	s_barrier
; #define PG8_STAGE(bufoff, gbase, voff) do { _Pragma("unroll") for (int _i = 0; _i < 2; ++_i) \
;         __builtin_amdgcn_global_load_lds((const unsigned*)((const char*)(gbase) + (voff)[_i]), (PG8_LAS unsigned*)(lds + (bufoff) + ldsw + _i * 8192), 16, 0, 0); } while (0)
; #define PG8_LDA(dst, b, h) do { _Pragma("unroll") for (int m = 0; m < 4; ++m) _Pragma("unroll") for (int k = 0; k < 2; ++k) dst[m][k] = *(const PG8_LAS bf16x8*)(lds + PG8_SA(b, h) + aoff + m * 2048 + k * 1024); } while (0)
; #define PG8_MMA(ai, bj, At, Bt) do { __builtin_amdgcn_s_setprio(1); _Pragma("unroll") for (int m = 0; m < 4; ++m) _Pragma("unroll") for (int n = 0; n < 2; ++n) _Pragma("unroll") for (int k = 0; k < 2; ++k) \
;         acc[ai][bj][m][n] = __builtin_amdgcn_mfma_f32_16x16x32_bf16(Bt[n][k], At[m][k], acc[ai][bj][m][n], 0, 0, 0); __builtin_amdgcn_s_setprio(0); } while (0)
; #define PG8_WAIT_V(n) asm volatile("s_waitcnt vmcnt(" #n ")" ::: "memory")
; #define PG8_WAIT_L(n) asm volatile("s_waitcnt lgkmcnt(" #n ")" ::: "memory")
; #define PG8_BAR __builtin_amdgcn_s_barrier()
; #define PG8_SCHED __builtin_amdgcn_sched_barrier(0)
; template <class Epi, class Sched, bool ALIGN_EPI = false, bool SP2 = false>
; __device__ __forceinline__ void gemm_phase(PG8_LAS unsigned char* lds, const Gemm g, const Sched& S, const Epi& E) {
;     ...
;         for (int t = 0; t < nt; t += 2) {
;             const bool last = (t == nt - 2);
;             const char* a1 = cA + (size_t)(t + 1) * kstep;
;             const char* a2 = last ? nA : cA + (size_t)(t + 2) * kstep; const char* b2 = last ? nB : cB + (size_t)(t + 2) * kstep;
;     ...
;             PG8_LDA(At, 1, 1); PG8_STAGE(PG8_SB(1, 0), b3, voffB); PG8_STAGE(PG8_SB(1, 1), b3 + hstep, voffB); PG8_STAGE(PG8_SA(1, 0), a3, voffA);
;             PG8_WAIT_V(8); PG8_WAIT_L(0); PG8_BAR; PG8_MMA(1, 0, At, B0); PG8_MMA(1, 1, At, B1); PG8_BAR; PG8_SCHED;
	s_add_i32 s28, s78, s54
	v_lshl_add_u64 v[164:165], v[164:165], 0, s[14:15]
	s_mov_b32 m0, s28
	ds_read_b128 v[184:187], v171 offset:49152
	ds_read_b128 v[188:191], v171 offset:50176
	ds_read_b128 v[194:197], v171 offset:51200
	ds_read_b128 v[198:201], v171 offset:52224
	ds_read_b128 v[202:205], v171 offset:53248
	ds_read_b128 v[206:209], v171 offset:54272
	ds_read_b128 v[210:213], v171 offset:55296
	ds_read_b128 v[214:217], v171 offset:56320
	global_load_lds_dwordx4 v[164:165], off
	s_add_i32 m0, s28, 0x2000
	s_add_u32 s28, s34, 0x160080
	v_lshl_add_u64 v[164:165], v[218:219], 0, s[14:15]
	s_addc_u32 s29, s35, 0
	s_add_i32 s34, s79, s54
	global_load_lds_dwordx4 v[164:165], off
	v_lshl_add_u64 v[164:165], s[28:29], 0, v[146:147]
	s_mov_b32 m0, s34
	s_nop 0
	global_load_lds_dwordx4 v[164:165], off
	v_lshl_add_u64 v[164:165], s[28:29], 0, v[150:151]
	s_add_i32 m0, s34, 0x2000
	s_nop 0
	global_load_lds_dwordx4 v[164:165], off
	v_lshl_add_u64 v[164:165], v[220:221], 0, s[14:15]
	s_mov_b32 m0, s62
	s_nop 0
	global_load_lds_dwordx4 v[164:165], off
	v_lshl_add_u64 v[164:165], v[222:223], 0, s[14:15]
	s_mov_b32 m0, s63
	s_nop 0
	global_load_lds_dwordx4 v[164:165], off
	s_waitcnt vmcnt(8)
	s_waitcnt lgkmcnt(0)
	s_barrier
	s_setprio 1
	s_waitcnt lgkmcnt(0)
	v_mfma_f32_16x16x32_bf16 v[60:63], v[120:123], v[184:187], v[60:63]
	v_mfma_f32_16x16x32_bf16 v[56:59], v[128:131], v[184:187], v[56:59]
	v_mfma_f32_16x16x32_bf16 v[48:51], v[120:123], v[194:197], v[48:51]
	v_mfma_f32_16x16x32_bf16 v[40:43], v[128:131], v[194:197], v[40:43]
	v_mfma_f32_16x16x32_bf16 v[32:35], v[120:123], v[202:205], v[32:35]
	v_mfma_f32_16x16x32_bf16 v[24:27], v[128:131], v[202:205], v[24:27]
	v_mfma_f32_16x16x32_bf16 v[16:19], v[120:123], v[210:213], v[16:19]
	v_mfma_f32_16x16x32_bf16 v[8:11], v[128:131], v[210:213], v[8:11]
	v_mfma_f32_16x16x32_bf16 v[60:63], v[124:127], v[188:191], v[60:63]
	v_mfma_f32_16x16x32_bf16 v[56:59], v[132:135], v[188:191], v[56:59]
	v_mfma_f32_16x16x32_bf16 v[48:51], v[124:127], v[198:201], v[48:51]
	v_mfma_f32_16x16x32_bf16 v[40:43], v[132:135], v[198:201], v[40:43]
	v_mfma_f32_16x16x32_bf16 v[32:35], v[124:127], v[206:209], v[32:35]
	v_mfma_f32_16x16x32_bf16 v[24:27], v[132:135], v[206:209], v[24:27]
	v_mfma_f32_16x16x32_bf16 v[16:19], v[124:127], v[214:217], v[16:19]
	v_mfma_f32_16x16x32_bf16 v[8:11], v[132:135], v[214:217], v[8:11]
	s_setprio 0
	s_setprio 1
	v_mfma_f32_16x16x32_bf16 v[52:55], v[160:163], v[184:187], v[52:55]
	v_mfma_f32_16x16x32_bf16 v[44:47], v[176:179], v[184:187], v[44:47]
	v_mfma_f32_16x16x32_bf16 v[36:39], v[160:163], v[194:197], v[36:39]
	v_mfma_f32_16x16x32_bf16 v[28:31], v[176:179], v[194:197], v[28:31]
	v_mfma_f32_16x16x32_bf16 v[20:23], v[160:163], v[202:205], v[20:23]
	v_mfma_f32_16x16x32_bf16 v[12:15], v[176:179], v[202:205], v[12:15]
	v_mfma_f32_16x16x32_bf16 v[4:7], v[160:163], v[210:213], v[4:7]
	v_mfma_f32_16x16x32_bf16 v[0:3], v[176:179], v[210:213], v[0:3]
	v_mfma_f32_16x16x32_bf16 v[52:55], v[172:175], v[188:191], v[52:55]
	v_mfma_f32_16x16x32_bf16 v[44:47], v[180:183], v[188:191], v[44:47]
	v_mfma_f32_16x16x32_bf16 v[36:39], v[172:175], v[198:201], v[36:39]
	v_mfma_f32_16x16x32_bf16 v[28:31], v[180:183], v[198:201], v[28:31]
	v_mfma_f32_16x16x32_bf16 v[20:23], v[172:175], v[206:209], v[20:23]
	v_mfma_f32_16x16x32_bf16 v[12:15], v[180:183], v[206:209], v[12:15]
	v_mfma_f32_16x16x32_bf16 v[4:7], v[172:175], v[214:217], v[4:7]
	v_mfma_f32_16x16x32_bf16 v[0:3], v[180:183], v[214:217], v[0:3]
	s_add_i32 s77, s77, 2
	s_add_u32 s75, s75, 0x100
	s_addc_u32 s76, s76, 0
	s_cmpk_gt_u32 s77, 0x55
	s_mov_b64 s[28:29], s[30:31]
	s_setprio 0
	s_barrier
	s_cbranch_scc0 .LBB0_561

; #define PG8_STAGE(bufoff, gbase, voff) do { _Pragma("unroll") for (int _i = 0; _i < 2; ++_i) \
;         __builtin_amdgcn_global_load_lds((const unsigned*)((const char*)(gbase) + (voff)[_i]), (PG8_LAS unsigned*)(lds + (bufoff) + ldsw + _i * 8192), 16, 0, 0); } while (0)
; #define PG8_LDA(dst, b, h) do { _Pragma("unroll") for (int m = 0; m < 4; ++m) _Pragma("unroll") for (int k = 0; k < 2; ++k) dst[m][k] = *(const PG8_LAS bf16x8*)(lds + PG8_SA(b, h) + aoff + m * 2048 + k * 1024); } while (0)
; #define PG8_LDB(dst, b, h) do { _Pragma("unroll") for (int n = 0; n < 2; ++n) _Pragma("unroll") for (int k = 0; k < 2; ++k) dst[n][k] = *(const PG8_LAS bf16x8*)(lds + PG8_SB(b, h) + boff + n * 2048 + k * 1024); } while (0)
; #define PG8_MMA(ai, bj, At, Bt) do { __builtin_amdgcn_s_setprio(1); _Pragma("unroll") for (int m = 0; m < 4; ++m) _Pragma("unroll") for (int n = 0; n < 2; ++n) _Pragma("unroll") for (int k = 0; k < 2; ++k) \
;         acc[ai][bj][m][n] = __builtin_amdgcn_mfma_f32_16x16x32_bf16(Bt[n][k], At[m][k], acc[ai][bj][m][n], 0, 0, 0); __builtin_amdgcn_s_setprio(0); } while (0)
; #define PG8_WAIT_V(n) asm volatile("s_waitcnt vmcnt(" #n ")" ::: "memory")
; #define PG8_WAIT_L(n) asm volatile("s_waitcnt lgkmcnt(" #n ")" ::: "memory")
; #define PG8_BAR __builtin_amdgcn_s_barrier()
; template <class Epi, class Sched, bool ALIGN_EPI = false, bool SP2 = false>
; __device__ __forceinline__ void gemm_phase(PG8_LAS unsigned char* lds, const Gemm g, const Sched& S, const Epi& E) {
;     ...
;         const bool has_next = S.next(ui + 1, nxt);
;         const char* nA = has_next ? (const char*)g.A + (size_t)nxt.pm * tstep : cA; const char* nB = has_next ? (const char*)g.Bt + (size_t)nxt.pn * tstep : cB;
;         for (int t = 0; t < nt; t += 2) {
;             const bool last = (t == nt - 2);
;             const char* a1 = cA + (size_t)(t + 1) * kstep;
;             const char* a2 = last ? nA : cA + (size_t)(t + 2) * kstep; const char* b2 = last ? nB : cB + (size_t)(t + 2) * kstep;
;             const char* a3 = a2 + kstep; const char* b3 = b2 + kstep;
;             if (last && has_next) S.a_ready(nxt);
;             if constexpr (SP2) {
;             PG8_LDB(B0, 0, 0); PG8_LDB(B1, 0, 1); PG8_SCHED; PG8_LDA(At, 0, 0); PG8_STAGE(PG8_SA(1, 1), a1 + hstep, voffA);
;             PG8_WAIT_V(8); PG8_WAIT_L(0); PG8_BAR; PG8_MMA(0, 0, At, B0); PG8_MMA(0, 1, At, B1); PG8_BAR; PG8_SCHED;
.LBB0_725:
	s_ashr_i32 s17, s16, 31
	s_lshl_b64 s[20:21], s[16:17], 20
	s_add_u32 s20, s52, s20
	s_addc_u32 s21, s53, s21
	s_and_b64 s[22:23], s[6:7], exec
	s_cselect_b32 s17, s21, s31
	s_cselect_b32 s78, s20, s30
	s_ashr_i32 s19, s18, 31
	s_lshl_b64 s[22:23], s[18:19], 20
	s_add_u32 s22, s37, s22
	s_addc_u32 s23, s50, s23
	s_and_b64 s[34:35], s[6:7], exec
	s_cselect_b32 s19, s23, s29
	s_cselect_b32 s79, s22, s28
	s_add_u32 s80, s28, 0x100
	s_addc_u32 s81, s29, 0
	s_add_u32 s28, s30, 0x80080
	s_addc_u32 s29, s31, 0
	s_mov_b32 s82, -2
	ds_read_b128 v[154:157], v150
	ds_read_b128 v[158:161], v150 offset:1024
	ds_read_b128 v[162:165], v150 offset:2048
	ds_read_b128 v[166:169], v150 offset:3072
	ds_read_b128 v[170:173], v151
	ds_read_b128 v[174:177], v151 offset:1024
	ds_read_b128 v[178:181], v151 offset:2048
	ds_read_b128 v[182:185], v151 offset:3072
	s_add_u32 s30, s28, 0xfff80080
	s_addc_u32 s31, s29, -1
	s_cmp_eq_u32 s82, 28
	s_cselect_b32 s35, s17, s31
	s_cselect_b32 s34, s78, s30
	s_cselect_b32 s31, s19, s81
	s_cselect_b32 s30, s79, s80
	v_lshl_add_u64 v[146:147], s[28:29], 0, v[140:141]
	s_add_i32 m0, s25, 0xc000
	ds_read_b128 v[186:189], v152
	ds_read_b128 v[194:197], v152 offset:1024
	ds_read_b128 v[198:201], v152 offset:2048
	ds_read_b128 v[202:205], v152 offset:3072
	ds_read_b128 v[206:209], v152 offset:4096
	ds_read_b128 v[210:213], v152 offset:5120
	ds_read_b128 v[214:217], v152 offset:6144
	ds_read_b128 v[218:221], v152 offset:7168
	global_load_lds_dwordx4 v[146:147], off
	v_lshl_add_u64 v[146:147], s[28:29], 0, v[138:139]
	s_add_i32 m0, s25, 0xe000
	s_nop 0
	global_load_lds_dwordx4 v[146:147], off
	s_waitcnt vmcnt(8)
	s_waitcnt lgkmcnt(0)
	s_barrier
	s_setprio 1
	s_waitcnt lgkmcnt(0)
	v_mfma_f32_16x16x32_bf16 v[124:127], v[154:157], v[186:189], 0
	v_mfma_f32_16x16x32_bf16 v[120:123], v[162:165], v[186:189], 0
	v_mfma_f32_16x16x32_bf16 v[116:119], v[154:157], v[198:201], 0
	v_mfma_f32_16x16x32_bf16 v[108:111], v[162:165], v[198:201], 0
	v_mfma_f32_16x16x32_bf16 v[100:103], v[154:157], v[206:209], 0
	v_mfma_f32_16x16x32_bf16 v[92:95], v[162:165], v[206:209], 0
	v_mfma_f32_16x16x32_bf16 v[84:87], v[154:157], v[214:217], 0
	v_mfma_f32_16x16x32_bf16 v[76:79], v[162:165], v[214:217], 0
	v_mfma_f32_16x16x32_bf16 v[124:127], v[158:161], v[194:197], v[124:127]
	v_mfma_f32_16x16x32_bf16 v[120:123], v[166:169], v[194:197], v[120:123]
	v_mfma_f32_16x16x32_bf16 v[116:119], v[158:161], v[202:205], v[116:119]
	v_mfma_f32_16x16x32_bf16 v[108:111], v[166:169], v[202:205], v[108:111]
	v_mfma_f32_16x16x32_bf16 v[100:103], v[158:161], v[210:213], v[100:103]
	v_mfma_f32_16x16x32_bf16 v[92:95], v[166:169], v[210:213], v[92:95]
	v_mfma_f32_16x16x32_bf16 v[84:87], v[158:161], v[218:221], v[84:87]
	v_mfma_f32_16x16x32_bf16 v[76:79], v[166:169], v[218:221], v[76:79]
	s_setprio 0
	s_setprio 1
	v_mfma_f32_16x16x32_bf16 v[112:115], v[170:173], v[186:189], 0
	v_mfma_f32_16x16x32_bf16 v[104:107], v[178:181], v[186:189], 0
	v_mfma_f32_16x16x32_bf16 v[96:99], v[170:173], v[198:201], 0
	v_mfma_f32_16x16x32_bf16 v[88:91], v[178:181], v[198:201], 0
	v_mfma_f32_16x16x32_bf16 v[80:83], v[170:173], v[206:209], 0
	v_mfma_f32_16x16x32_bf16 v[72:75], v[178:181], v[206:209], 0
	v_mfma_f32_16x16x32_bf16 v[68:71], v[170:173], v[214:217], 0
	v_mfma_f32_16x16x32_bf16 v[64:67], v[178:181], v[214:217], 0
	v_mfma_f32_16x16x32_bf16 v[112:115], v[174:177], v[194:197], v[112:115]
	v_mfma_f32_16x16x32_bf16 v[104:107], v[182:185], v[194:197], v[104:107]
	v_mfma_f32_16x16x32_bf16 v[96:99], v[174:177], v[202:205], v[96:99]
	v_mfma_f32_16x16x32_bf16 v[88:91], v[182:185], v[202:205], v[88:91]
	v_mfma_f32_16x16x32_bf16 v[80:83], v[174:177], v[210:213], v[80:83]
	v_mfma_f32_16x16x32_bf16 v[72:75], v[182:185], v[210:213], v[72:75]
	v_mfma_f32_16x16x32_bf16 v[68:71], v[174:177], v[218:221], v[68:71]
	v_mfma_f32_16x16x32_bf16 v[64:67], v[182:185], v[218:221], v[64:67]
	s_setprio 0
	s_barrier
	s_add_i32 s83, s64, s36
	v_lshl_add_u64 v[146:147], s[30:31], 0, v[132:133]
	s_mov_b32 m0, s83
	ds_read_b128 v[186:189], v152 offset:16384
	ds_read_b128 v[194:197], v152 offset:17408
	ds_read_b128 v[198:201], v152 offset:18432
	ds_read_b128 v[202:205], v152 offset:19456
	ds_read_b128 v[206:209], v152 offset:20480
	ds_read_b128 v[210:213], v152 offset:21504
	ds_read_b128 v[214:217], v152 offset:22528
	ds_read_b128 v[218:221], v152 offset:23552
	global_load_lds_dwordx4 v[146:147], off
	s_add_i32 m0, s83, 0x2000
	s_add_u32 s84, s30, 0x80000
	v_lshl_add_u64 v[190:191], s[30:31], 0, v[128:129]
	s_addc_u32 s85, s31, 0
	s_add_i32 s83, s65, s36
	global_load_lds_dwordx4 v[190:191], off
	v_lshl_add_u64 v[222:223], s[84:85], 0, v[132:133]
	s_mov_b32 m0, s83
	v_lshl_add_u64 v[224:225], s[34:35], 0, v[130:131]
	global_load_lds_dwordx4 v[222:223], off
	v_lshl_add_u64 v[222:223], s[84:85], 0, v[128:129]
	s_add_i32 m0, s83, 0x2000
	s_nop 0
	global_load_lds_dwordx4 v[222:223], off
	v_lshl_add_u64 v[222:223], s[34:35], 0, v[134:135]
	s_mov_b32 m0, s25
	s_nop 0
	global_load_lds_dwordx4 v[222:223], off
	s_mov_b32 m0, s27
	s_nop 0
	global_load_lds_dwordx4 v[224:225], off
	s_waitcnt vmcnt(8)
	s_waitcnt lgkmcnt(0)
	s_barrier
; #define PG8_STAGE(bufoff, gbase, voff) do { _Pragma("unroll") for (int _i = 0; _i < 2; ++_i) \
;         __builtin_amdgcn_global_load_lds((const unsigned*)((const char*)(gbase) + (voff)[_i]), (PG8_LAS unsigned*)(lds + (bufoff) + ldsw + _i * 8192), 16, 0, 0); } while (0)
; #define PG8_LDA(dst, b, h) do { _Pragma("unroll") for (int m = 0; m < 4; ++m) _Pragma("unroll") for (int k = 0; k < 2; ++k) dst[m][k] = *(const PG8_LAS bf16x8*)(lds + PG8_SA(b, h) + aoff + m * 2048 + k * 1024); } while (0)
; #define PG8_LDB(dst, b, h) do { _Pragma("unroll") for (int n = 0; n < 2; ++n) _Pragma("unroll") for (int k = 0; k < 2; ++k) dst[n][k] = *(const PG8_LAS bf16x8*)(lds + PG8_SB(b, h) + boff + n * 2048 + k * 1024); } while (0)
; #define PG8_MMA(ai, bj, At, Bt) do { __builtin_amdgcn_s_setprio(1); _Pragma("unroll") for (int m = 0; m < 4; ++m) _Pragma("unroll") for (int n = 0; n < 2; ++n) _Pragma("unroll") for (int k = 0; k < 2; ++k) \
;         acc[ai][bj][m][n] = __builtin_amdgcn_mfma_f32_16x16x32_bf16(Bt[n][k], At[m][k], acc[ai][bj][m][n], 0, 0, 0); __builtin_amdgcn_s_setprio(0); } while (0)
; #define PG8_WAIT_V(n) asm volatile("s_waitcnt vmcnt(" #n ")" ::: "memory")
; #define PG8_WAIT_L(n) asm volatile("s_waitcnt lgkmcnt(" #n ")" ::: "memory")
; #define PG8_BAR __builtin_amdgcn_s_barrier()
; #define PG8_SCHED __builtin_amdgcn_sched_barrier(0)
; template <class Epi, class Sched, bool ALIGN_EPI = false, bool SP2 = false>
; __device__ __forceinline__ void gemm_phase(PG8_LAS unsigned char* lds, const Gemm g, const Sched& S, const Epi& E) {
;     ...
;             PG8_WAIT_V(8); PG8_WAIT_L(0); PG8_BAR; PG8_MMA(0, 0, At, B0); PG8_MMA(0, 1, At, B1); PG8_BAR; PG8_SCHED;
;             PG8_LDA(At, 0, 1); PG8_STAGE(PG8_SB(0, 0), b2, voffB); PG8_STAGE(PG8_SB(0, 1), b2 + hstep, voffB); PG8_STAGE(PG8_SA(0, 0), a2, voffA);
;             PG8_WAIT_V(8); PG8_WAIT_L(0); PG8_BAR; PG8_MMA(1, 0, At, B0); PG8_MMA(1, 1, At, B1); PG8_BAR; PG8_SCHED;
;             PG8_LDB(B0, 1, 0); PG8_LDB(B1, 1, 1); PG8_SCHED; PG8_LDA(At, 1, 0); PG8_STAGE(PG8_SA(0, 1), a2 + hstep, voffA);
;             PG8_WAIT_V(8); PG8_WAIT_L(0); PG8_BAR; PG8_MMA(0, 0, At, B0); PG8_MMA(0, 1, At, B1); PG8_BAR; PG8_SCHED;
	s_setprio 1
	s_waitcnt lgkmcnt(0)
	v_mfma_f32_16x16x32_bf16 v[60:63], v[154:157], v[186:189], 0
	v_mfma_f32_16x16x32_bf16 v[56:59], v[162:165], v[186:189], 0
	v_mfma_f32_16x16x32_bf16 v[52:55], v[154:157], v[198:201], 0
	v_mfma_f32_16x16x32_bf16 v[44:47], v[162:165], v[198:201], 0
	v_mfma_f32_16x16x32_bf16 v[36:39], v[154:157], v[206:209], 0
	v_mfma_f32_16x16x32_bf16 v[28:31], v[162:165], v[206:209], 0
	v_mfma_f32_16x16x32_bf16 v[20:23], v[154:157], v[214:217], 0
	v_mfma_f32_16x16x32_bf16 v[12:15], v[162:165], v[214:217], 0
	v_mfma_f32_16x16x32_bf16 v[60:63], v[158:161], v[194:197], v[60:63]
	v_mfma_f32_16x16x32_bf16 v[56:59], v[166:169], v[194:197], v[56:59]
	v_mfma_f32_16x16x32_bf16 v[52:55], v[158:161], v[202:205], v[52:55]
	v_mfma_f32_16x16x32_bf16 v[44:47], v[166:169], v[202:205], v[44:47]
	v_mfma_f32_16x16x32_bf16 v[36:39], v[158:161], v[210:213], v[36:39]
	v_mfma_f32_16x16x32_bf16 v[28:31], v[166:169], v[210:213], v[28:31]
	v_mfma_f32_16x16x32_bf16 v[20:23], v[158:161], v[218:221], v[20:23]
	v_mfma_f32_16x16x32_bf16 v[12:15], v[166:169], v[218:221], v[12:15]
	s_setprio 0
	s_setprio 1
	v_mfma_f32_16x16x32_bf16 v[48:51], v[170:173], v[186:189], 0
	v_mfma_f32_16x16x32_bf16 v[40:43], v[178:181], v[186:189], 0
	v_mfma_f32_16x16x32_bf16 v[32:35], v[170:173], v[198:201], 0
	v_mfma_f32_16x16x32_bf16 v[24:27], v[178:181], v[198:201], 0
	v_mfma_f32_16x16x32_bf16 v[16:19], v[170:173], v[206:209], 0
	v_mfma_f32_16x16x32_bf16 v[8:11], v[178:181], v[206:209], 0
	v_mfma_f32_16x16x32_bf16 v[4:7], v[170:173], v[214:217], 0
	v_mfma_f32_16x16x32_bf16 v[0:3], v[178:181], v[214:217], 0
	v_mfma_f32_16x16x32_bf16 v[48:51], v[174:177], v[194:197], v[48:51]
	v_mfma_f32_16x16x32_bf16 v[40:43], v[182:185], v[194:197], v[40:43]
	v_mfma_f32_16x16x32_bf16 v[32:35], v[174:177], v[202:205], v[32:35]
	v_mfma_f32_16x16x32_bf16 v[24:27], v[182:185], v[202:205], v[24:27]
	v_mfma_f32_16x16x32_bf16 v[16:19], v[174:177], v[210:213], v[16:19]
	v_mfma_f32_16x16x32_bf16 v[8:11], v[182:185], v[210:213], v[8:11]
	v_mfma_f32_16x16x32_bf16 v[4:7], v[174:177], v[218:221], v[4:7]
	v_mfma_f32_16x16x32_bf16 v[0:3], v[182:185], v[218:221], v[0:3]
	s_setprio 0
	s_barrier
	s_add_i32 s83, 0, 0x18000
	v_add_u32_e32 v153, s83, v149
	s_add_i32 s84, 0, 0x1c000
	ds_read_b128 v[154:157], v153
	ds_read_b128 v[158:161], v153 offset:1024
	ds_read_b128 v[162:165], v153 offset:2048
	ds_read_b128 v[166:169], v153 offset:3072
	v_add_u32_e32 v153, s84, v149
	ds_read_b128 v[170:173], v153
	ds_read_b128 v[174:177], v153 offset:1024
	ds_read_b128 v[178:181], v153 offset:2048
	ds_read_b128 v[182:185], v153 offset:3072
	s_add_u32 s34, s34, 0x80000
	s_addc_u32 s35, s35, 0
	s_mov_b32 m0, s56
	v_lshl_add_u64 v[226:227], s[34:35], 0, v[134:135]
	ds_read_b128 v[186:189], v152 offset:32768
	ds_read_b128 v[194:197], v152 offset:33792
	ds_read_b128 v[198:201], v152 offset:34816
	ds_read_b128 v[202:205], v152 offset:35840
	ds_read_b128 v[206:209], v152 offset:36864
	ds_read_b128 v[210:213], v152 offset:37888
	ds_read_b128 v[214:217], v152 offset:38912
	ds_read_b128 v[218:221], v152 offset:39936
	global_load_lds_dwordx4 v[226:227], off
	v_lshl_add_u64 v[226:227], s[34:35], 0, v[130:131]
	s_mov_b32 m0, s57
	s_nop 0
	global_load_lds_dwordx4 v[226:227], off
	s_waitcnt vmcnt(8)
	s_waitcnt lgkmcnt(0)
	s_barrier
	s_setprio 1
	s_waitcnt lgkmcnt(0)
	v_mfma_f32_16x16x32_bf16 v[124:127], v[154:157], v[186:189], v[124:127]
	v_mfma_f32_16x16x32_bf16 v[120:123], v[162:165], v[186:189], v[120:123]
	v_mfma_f32_16x16x32_bf16 v[116:119], v[154:157], v[198:201], v[116:119]
	v_mfma_f32_16x16x32_bf16 v[108:111], v[162:165], v[198:201], v[108:111]
	v_mfma_f32_16x16x32_bf16 v[100:103], v[154:157], v[206:209], v[100:103]
	v_mfma_f32_16x16x32_bf16 v[92:95], v[162:165], v[206:209], v[92:95]
	v_mfma_f32_16x16x32_bf16 v[84:87], v[154:157], v[214:217], v[84:87]
	v_mfma_f32_16x16x32_bf16 v[76:79], v[162:165], v[214:217], v[76:79]
	v_mfma_f32_16x16x32_bf16 v[124:127], v[158:161], v[194:197], v[124:127]
	v_mfma_f32_16x16x32_bf16 v[120:123], v[166:169], v[194:197], v[120:123]
	v_mfma_f32_16x16x32_bf16 v[116:119], v[158:161], v[202:205], v[116:119]
	v_mfma_f32_16x16x32_bf16 v[108:111], v[166:169], v[202:205], v[108:111]
	v_mfma_f32_16x16x32_bf16 v[100:103], v[158:161], v[210:213], v[100:103]
	v_mfma_f32_16x16x32_bf16 v[92:95], v[166:169], v[210:213], v[92:95]
	v_mfma_f32_16x16x32_bf16 v[84:87], v[158:161], v[218:221], v[84:87]
	v_mfma_f32_16x16x32_bf16 v[76:79], v[166:169], v[218:221], v[76:79]
	s_setprio 0
	s_setprio 1
	v_mfma_f32_16x16x32_bf16 v[112:115], v[170:173], v[186:189], v[112:115]
	v_mfma_f32_16x16x32_bf16 v[104:107], v[178:181], v[186:189], v[104:107]
	v_mfma_f32_16x16x32_bf16 v[96:99], v[170:173], v[198:201], v[96:99]
	v_mfma_f32_16x16x32_bf16 v[88:91], v[178:181], v[198:201], v[88:91]
	v_mfma_f32_16x16x32_bf16 v[80:83], v[170:173], v[206:209], v[80:83]
	v_mfma_f32_16x16x32_bf16 v[72:75], v[178:181], v[206:209], v[72:75]
	v_mfma_f32_16x16x32_bf16 v[68:71], v[170:173], v[214:217], v[68:71]
	v_mfma_f32_16x16x32_bf16 v[64:67], v[178:181], v[214:217], v[64:67]
	v_mfma_f32_16x16x32_bf16 v[112:115], v[174:177], v[194:197], v[112:115]
	v_mfma_f32_16x16x32_bf16 v[104:107], v[182:185], v[194:197], v[104:107]
	v_mfma_f32_16x16x32_bf16 v[96:99], v[174:177], v[202:205], v[96:99]
	v_mfma_f32_16x16x32_bf16 v[88:91], v[182:185], v[202:205], v[88:91]
	v_mfma_f32_16x16x32_bf16 v[80:83], v[174:177], v[210:213], v[80:83]
	v_mfma_f32_16x16x32_bf16 v[72:75], v[182:185], v[210:213], v[72:75]
	v_mfma_f32_16x16x32_bf16 v[68:71], v[174:177], v[218:221], v[68:71]
	v_mfma_f32_16x16x32_bf16 v[64:67], v[182:185], v[218:221], v[64:67]
	s_setprio 0
	s_barrier
; #define PG8_STAGE(bufoff, gbase, voff) do { _Pragma("unroll") for (int _i = 0; _i < 2; ++_i) \
;         __builtin_amdgcn_global_load_lds((const unsigned*)((const char*)(gbase) + (voff)[_i]), (PG8_LAS unsigned*)(lds + (bufoff) + ldsw + _i * 8192), 16, 0, 0); } while (0)
; #define PG8_LDA(dst, b, h) do { _Pragma("unroll") for (int m = 0; m < 4; ++m) _Pragma("unroll") for (int k = 0; k < 2; ++k) dst[m][k] = *(const PG8_LAS bf16x8*)(lds + PG8_SA(b, h) + aoff + m * 2048 + k * 1024); } while (0)
; #define PG8_LDB(dst, b, h) do { _Pragma("unroll") for (int n = 0; n < 2; ++n) _Pragma("unroll") for (int k = 0; k < 2; ++k) dst[n][k] = *(const PG8_LAS bf16x8*)(lds + PG8_SB(b, h) + boff + n * 2048 + k * 1024); } while (0)
; template <class Epi, class Sched, bool ALIGN_EPI = false, bool SP2 = false>
; __device__ __forceinline__ void gemm_phase(PG8_LAS unsigned char* lds, const Gemm g, const Sched& S, const Epi& E) {
;     ...
;         for (int t = 0; t < nt; t += 2) {
;             const bool last = (t == nt - 2);
;             const char* a1 = cA + (size_t)(t + 1) * kstep;
;             const char* a2 = last ? nA : cA + (size_t)(t + 2) * kstep; const char* b2 = last ? nB : cB + (size_t)(t + 2) * kstep;
;             const char* a3 = a2 + kstep; const char* b3 = b2 + kstep;
;             if (last && has_next) S.a_ready(nxt);
;             if constexpr (SP2) {
;             PG8_LDB(B0, 0, 0); PG8_LDB(B1, 0, 1); PG8_SCHED; PG8_LDA(At, 0, 0); PG8_STAGE(PG8_SA(1, 1), a1 + hstep, voffA);
;             PG8_WAIT_V(8); PG8_WAIT_L(0); PG8_BAR; PG8_MMA(0, 0, At, B0); PG8_MMA(0, 1, At, B1); PG8_BAR; PG8_SCHED;
;             PG8_LDA(At, 0, 1); PG8_STAGE(PG8_SB(0, 0), b2, voffB); PG8_STAGE(PG8_SB(0, 1), b2 + hstep, voffB); PG8_STAGE(PG8_SA(0, 0), a2, voffA);
;             PG8_WAIT_V(8); PG8_WAIT_L(0); PG8_BAR; PG8_MMA(1, 0, At, B0); PG8_MMA(1, 1, At, B1); PG8_BAR; PG8_SCHED;
;             PG8_LDB(B0, 1, 0); PG8_LDB(B1, 1, 1); PG8_SCHED; PG8_LDA(At, 1, 0); PG8_STAGE(PG8_SA(0, 1), a2 + hstep, voffA);
;             PG8_WAIT_V(8); PG8_WAIT_L(0); PG8_BAR; PG8_MMA(0, 0, At, B0); PG8_MMA(0, 1, At, B1); PG8_BAR; PG8_SCHED;
;             PG8_LDA(At, 1, 1); PG8_STAGE(PG8_SB(1, 0), b3, voffB); PG8_STAGE(PG8_SB(1, 1), b3 + hstep, voffB); PG8_STAGE(PG8_SA(1, 0), a3, voffA);
;             PG8_WAIT_V(8); PG8_WAIT_L(0); PG8_BAR; PG8_MMA(1, 0, At, B0); PG8_MMA(1, 1, At, B1); PG8_BAR; PG8_SCHED;
	s_add_i32 s34, s83, s36
	v_lshl_add_u64 v[146:147], v[146:147], 0, s[12:13]
	s_mov_b32 m0, s34
	ds_read_b128 v[186:189], v152 offset:49152
	ds_read_b128 v[194:197], v152 offset:50176
	ds_read_b128 v[198:201], v152 offset:51200
	ds_read_b128 v[202:205], v152 offset:52224
	ds_read_b128 v[206:209], v152 offset:53248
	ds_read_b128 v[210:213], v152 offset:54272
	ds_read_b128 v[214:217], v152 offset:55296
	ds_read_b128 v[218:221], v152 offset:56320
	global_load_lds_dwordx4 v[146:147], off
	s_add_i32 m0, s34, 0x2000
	s_add_u32 s30, s30, 0x80080
	v_lshl_add_u64 v[146:147], v[190:191], 0, s[12:13]
	s_addc_u32 s31, s31, 0
	s_add_i32 s34, s84, s36
	global_load_lds_dwordx4 v[146:147], off
	v_lshl_add_u64 v[146:147], s[30:31], 0, v[132:133]
	s_mov_b32 m0, s34
	s_nop 0
	global_load_lds_dwordx4 v[146:147], off
	v_lshl_add_u64 v[146:147], s[30:31], 0, v[128:129]
	s_add_i32 m0, s34, 0x2000
	s_nop 0
	global_load_lds_dwordx4 v[146:147], off
	v_lshl_add_u64 v[146:147], v[222:223], 0, s[12:13]
	s_mov_b32 m0, s59
	s_nop 0
	global_load_lds_dwordx4 v[146:147], off
	v_lshl_add_u64 v[146:147], v[224:225], 0, s[12:13]
	s_mov_b32 m0, s60
	s_nop 0
	global_load_lds_dwordx4 v[146:147], off
	s_waitcnt vmcnt(8)
	s_waitcnt lgkmcnt(0)
	s_barrier
	s_setprio 1
	s_waitcnt lgkmcnt(0)
	v_mfma_f32_16x16x32_bf16 v[60:63], v[154:157], v[186:189], v[60:63]
	v_mfma_f32_16x16x32_bf16 v[56:59], v[162:165], v[186:189], v[56:59]
	v_mfma_f32_16x16x32_bf16 v[52:55], v[154:157], v[198:201], v[52:55]
	v_mfma_f32_16x16x32_bf16 v[44:47], v[162:165], v[198:201], v[44:47]
	v_mfma_f32_16x16x32_bf16 v[36:39], v[154:157], v[206:209], v[36:39]
	v_mfma_f32_16x16x32_bf16 v[28:31], v[162:165], v[206:209], v[28:31]
	v_mfma_f32_16x16x32_bf16 v[20:23], v[154:157], v[214:217], v[20:23]
	v_mfma_f32_16x16x32_bf16 v[12:15], v[162:165], v[214:217], v[12:15]
	v_mfma_f32_16x16x32_bf16 v[60:63], v[158:161], v[194:197], v[60:63]
	v_mfma_f32_16x16x32_bf16 v[56:59], v[166:169], v[194:197], v[56:59]
	v_mfma_f32_16x16x32_bf16 v[52:55], v[158:161], v[202:205], v[52:55]
	v_mfma_f32_16x16x32_bf16 v[44:47], v[166:169], v[202:205], v[44:47]
	v_mfma_f32_16x16x32_bf16 v[36:39], v[158:161], v[210:213], v[36:39]
	v_mfma_f32_16x16x32_bf16 v[28:31], v[166:169], v[210:213], v[28:31]
	v_mfma_f32_16x16x32_bf16 v[20:23], v[158:161], v[218:221], v[20:23]
	v_mfma_f32_16x16x32_bf16 v[12:15], v[166:169], v[218:221], v[12:15]
	s_setprio 0
	s_setprio 1
	v_mfma_f32_16x16x32_bf16 v[48:51], v[170:173], v[186:189], v[48:51]
	v_mfma_f32_16x16x32_bf16 v[40:43], v[178:181], v[186:189], v[40:43]
	v_mfma_f32_16x16x32_bf16 v[32:35], v[170:173], v[198:201], v[32:35]
	v_mfma_f32_16x16x32_bf16 v[24:27], v[178:181], v[198:201], v[24:27]
	v_mfma_f32_16x16x32_bf16 v[16:19], v[170:173], v[206:209], v[16:19]
	v_mfma_f32_16x16x32_bf16 v[8:11], v[178:181], v[206:209], v[8:11]
	v_mfma_f32_16x16x32_bf16 v[4:7], v[170:173], v[214:217], v[4:7]
	v_mfma_f32_16x16x32_bf16 v[0:3], v[178:181], v[214:217], v[0:3]
	v_mfma_f32_16x16x32_bf16 v[48:51], v[174:177], v[194:197], v[48:51]
	v_mfma_f32_16x16x32_bf16 v[40:43], v[182:185], v[194:197], v[40:43]
	v_mfma_f32_16x16x32_bf16 v[32:35], v[174:177], v[202:205], v[32:35]
	v_mfma_f32_16x16x32_bf16 v[24:27], v[182:185], v[202:205], v[24:27]
	v_mfma_f32_16x16x32_bf16 v[16:19], v[174:177], v[210:213], v[16:19]
	v_mfma_f32_16x16x32_bf16 v[8:11], v[182:185], v[210:213], v[8:11]
	v_mfma_f32_16x16x32_bf16 v[4:7], v[174:177], v[218:221], v[4:7]
	v_mfma_f32_16x16x32_bf16 v[0:3], v[182:185], v[218:221], v[0:3]
	s_add_i32 s82, s82, 2
	s_add_u32 s80, s80, 0x100
	s_addc_u32 s81, s81, 0
	s_add_u32 s28, s28, 0x100
	s_addc_u32 s29, s29, 0
	s_cmp_gt_u32 s82, 29
	s_setprio 0
	s_barrier
	s_cbranch_scc1 .Lpeel_exit_4
.LBB0_726:
	ds_read_b128 v[154:157], v150
	ds_read_b128 v[158:161], v150 offset:1024
	ds_read_b128 v[162:165], v150 offset:2048
	ds_read_b128 v[166:169], v150 offset:3072
	ds_read_b128 v[170:173], v151
	ds_read_b128 v[174:177], v151 offset:1024
	ds_read_b128 v[178:181], v151 offset:2048
	ds_read_b128 v[182:185], v151 offset:3072
	s_add_u32 s30, s28, 0xfff80080
	s_addc_u32 s31, s29, -1
	s_cmp_eq_u32 s82, 28
	s_cselect_b32 s35, s17, s31
	s_cselect_b32 s34, s78, s30
	s_cselect_b32 s31, s19, s81
	s_cselect_b32 s30, s79, s80
	v_lshl_add_u64 v[146:147], s[28:29], 0, v[140:141]
	s_add_i32 m0, s25, 0xc000
	ds_read_b128 v[186:189], v152
	ds_read_b128 v[194:197], v152 offset:1024
	ds_read_b128 v[198:201], v152 offset:2048
	ds_read_b128 v[202:205], v152 offset:3072
	ds_read_b128 v[206:209], v152 offset:4096
	ds_read_b128 v[210:213], v152 offset:5120
	ds_read_b128 v[214:217], v152 offset:6144
	ds_read_b128 v[218:221], v152 offset:7168
	global_load_lds_dwordx4 v[146:147], off
	v_lshl_add_u64 v[146:147], s[28:29], 0, v[138:139]
	s_add_i32 m0, s25, 0xe000
	s_nop 0
	global_load_lds_dwordx4 v[146:147], off
	s_waitcnt vmcnt(8)
	s_waitcnt lgkmcnt(0)
	s_barrier
; #define PG8_STAGE(bufoff, gbase, voff) do { _Pragma("unroll") for (int _i = 0; _i < 2; ++_i) \
;         __builtin_amdgcn_global_load_lds((const unsigned*)((const char*)(gbase) + (voff)[_i]), (PG8_LAS unsigned*)(lds + (bufoff) + ldsw + _i * 8192), 16, 0, 0); } while (0)
; #define PG8_LDA(dst, b, h) do { _Pragma("unroll") for (int m = 0; m < 4; ++m) _Pragma("unroll") for (int k = 0; k < 2; ++k) dst[m][k] = *(const PG8_LAS bf16x8*)(lds + PG8_SA(b, h) + aoff + m * 2048 + k * 1024); } while (0)
; #define PG8_LDB(dst, b, h) do { _Pragma("unroll") for (int n = 0; n < 2; ++n) _Pragma("unroll") for (int k = 0; k < 2; ++k) dst[n][k] = *(const PG8_LAS bf16x8*)(lds + PG8_SB(b, h) + boff + n * 2048 + k * 1024); } while (0)
; #define PG8_MMA(ai, bj, At, Bt) do { __builtin_amdgcn_s_setprio(1); _Pragma("unroll") for (int m = 0; m < 4; ++m) _Pragma("unroll") for (int n = 0; n < 2; ++n) _Pragma("unroll") for (int k = 0; k < 2; ++k) \
;         acc[ai][bj][m][n] = __builtin_amdgcn_mfma_f32_16x16x32_bf16(Bt[n][k], At[m][k], acc[ai][bj][m][n], 0, 0, 0); __builtin_amdgcn_s_setprio(0); } while (0)
; #define PG8_WAIT_V(n) asm volatile("s_waitcnt vmcnt(" #n ")" ::: "memory")
; #define PG8_WAIT_L(n) asm volatile("s_waitcnt lgkmcnt(" #n ")" ::: "memory")
; #define PG8_BAR __builtin_amdgcn_s_barrier()
; #define PG8_SCHED __builtin_amdgcn_sched_barrier(0)
; template <class Epi, class Sched, bool ALIGN_EPI = false, bool SP2 = false>
; __device__ __forceinline__ void gemm_phase(PG8_LAS unsigned char* lds, const Gemm g, const Sched& S, const Epi& E) {
;     ...
;             PG8_WAIT_V(8); PG8_WAIT_L(0); PG8_BAR; PG8_MMA(0, 0, At, B0); PG8_MMA(0, 1, At, B1); PG8_BAR; PG8_SCHED;
;             PG8_LDA(At, 0, 1); PG8_STAGE(PG8_SB(0, 0), b2, voffB); PG8_STAGE(PG8_SB(0, 1), b2 + hstep, voffB); PG8_STAGE(PG8_SA(0, 0), a2, voffA);
;             PG8_WAIT_V(8); PG8_WAIT_L(0); PG8_BAR; PG8_MMA(1, 0, At, B0); PG8_MMA(1, 1, At, B1); PG8_BAR; PG8_SCHED;
;             PG8_LDB(B0, 1, 0); PG8_LDB(B1, 1, 1); PG8_SCHED; PG8_LDA(At, 1, 0); PG8_STAGE(PG8_SA(0, 1), a2 + hstep, voffA);
;             PG8_WAIT_V(8); PG8_WAIT_L(0); PG8_BAR; PG8_MMA(0, 0, At, B0); PG8_MMA(0, 1, At, B1); PG8_BAR; PG8_SCHED;
	s_setprio 1
	s_waitcnt lgkmcnt(0)
	v_mfma_f32_16x16x32_bf16 v[124:127], v[154:157], v[186:189], v[124:127]
	v_mfma_f32_16x16x32_bf16 v[120:123], v[162:165], v[186:189], v[120:123]
	v_mfma_f32_16x16x32_bf16 v[116:119], v[154:157], v[198:201], v[116:119]
	v_mfma_f32_16x16x32_bf16 v[108:111], v[162:165], v[198:201], v[108:111]
	v_mfma_f32_16x16x32_bf16 v[100:103], v[154:157], v[206:209], v[100:103]
	v_mfma_f32_16x16x32_bf16 v[92:95], v[162:165], v[206:209], v[92:95]
	v_mfma_f32_16x16x32_bf16 v[84:87], v[154:157], v[214:217], v[84:87]
	v_mfma_f32_16x16x32_bf16 v[76:79], v[162:165], v[214:217], v[76:79]
	v_mfma_f32_16x16x32_bf16 v[124:127], v[158:161], v[194:197], v[124:127]
	v_mfma_f32_16x16x32_bf16 v[120:123], v[166:169], v[194:197], v[120:123]
	v_mfma_f32_16x16x32_bf16 v[116:119], v[158:161], v[202:205], v[116:119]
	v_mfma_f32_16x16x32_bf16 v[108:111], v[166:169], v[202:205], v[108:111]
	v_mfma_f32_16x16x32_bf16 v[100:103], v[158:161], v[210:213], v[100:103]
	v_mfma_f32_16x16x32_bf16 v[92:95], v[166:169], v[210:213], v[92:95]
	v_mfma_f32_16x16x32_bf16 v[84:87], v[158:161], v[218:221], v[84:87]
	v_mfma_f32_16x16x32_bf16 v[76:79], v[166:169], v[218:221], v[76:79]
	s_setprio 0
	s_setprio 1
	v_mfma_f32_16x16x32_bf16 v[112:115], v[170:173], v[186:189], v[112:115]
	v_mfma_f32_16x16x32_bf16 v[104:107], v[178:181], v[186:189], v[104:107]
	v_mfma_f32_16x16x32_bf16 v[96:99], v[170:173], v[198:201], v[96:99]
	v_mfma_f32_16x16x32_bf16 v[88:91], v[178:181], v[198:201], v[88:91]
	v_mfma_f32_16x16x32_bf16 v[80:83], v[170:173], v[206:209], v[80:83]
	v_mfma_f32_16x16x32_bf16 v[72:75], v[178:181], v[206:209], v[72:75]
	v_mfma_f32_16x16x32_bf16 v[68:71], v[170:173], v[214:217], v[68:71]
	v_mfma_f32_16x16x32_bf16 v[64:67], v[178:181], v[214:217], v[64:67]
	v_mfma_f32_16x16x32_bf16 v[112:115], v[174:177], v[194:197], v[112:115]
	v_mfma_f32_16x16x32_bf16 v[104:107], v[182:185], v[194:197], v[104:107]
	v_mfma_f32_16x16x32_bf16 v[96:99], v[174:177], v[202:205], v[96:99]
	v_mfma_f32_16x16x32_bf16 v[88:91], v[182:185], v[202:205], v[88:91]
	v_mfma_f32_16x16x32_bf16 v[80:83], v[174:177], v[210:213], v[80:83]
	v_mfma_f32_16x16x32_bf16 v[72:75], v[182:185], v[210:213], v[72:75]
	v_mfma_f32_16x16x32_bf16 v[68:71], v[174:177], v[218:221], v[68:71]
	v_mfma_f32_16x16x32_bf16 v[64:67], v[182:185], v[218:221], v[64:67]
	s_setprio 0
	s_barrier
	s_add_i32 s83, s64, s36
	v_lshl_add_u64 v[146:147], s[30:31], 0, v[132:133]
	s_mov_b32 m0, s83
	ds_read_b128 v[186:189], v152 offset:16384
	ds_read_b128 v[194:197], v152 offset:17408
	ds_read_b128 v[198:201], v152 offset:18432
	ds_read_b128 v[202:205], v152 offset:19456
	ds_read_b128 v[206:209], v152 offset:20480
	ds_read_b128 v[210:213], v152 offset:21504
	ds_read_b128 v[214:217], v152 offset:22528
	ds_read_b128 v[218:221], v152 offset:23552
	global_load_lds_dwordx4 v[146:147], off
	s_add_i32 m0, s83, 0x2000
	s_add_u32 s84, s30, 0x80000
	v_lshl_add_u64 v[190:191], s[30:31], 0, v[128:129]
	s_addc_u32 s85, s31, 0
	s_add_i32 s83, s65, s36
	global_load_lds_dwordx4 v[190:191], off
	v_lshl_add_u64 v[222:223], s[84:85], 0, v[132:133]
	s_mov_b32 m0, s83
	v_lshl_add_u64 v[224:225], s[34:35], 0, v[130:131]
	global_load_lds_dwordx4 v[222:223], off
	v_lshl_add_u64 v[222:223], s[84:85], 0, v[128:129]
	s_add_i32 m0, s83, 0x2000
	s_nop 0
	global_load_lds_dwordx4 v[222:223], off
	v_lshl_add_u64 v[222:223], s[34:35], 0, v[134:135]
	s_mov_b32 m0, s25
	s_nop 0
	global_load_lds_dwordx4 v[222:223], off
	s_mov_b32 m0, s27
	s_nop 0
	global_load_lds_dwordx4 v[224:225], off
	s_waitcnt vmcnt(8)
	s_waitcnt lgkmcnt(0)
	s_barrier
	s_setprio 1
	s_waitcnt lgkmcnt(0)
	v_mfma_f32_16x16x32_bf16 v[60:63], v[154:157], v[186:189], v[60:63]
	v_mfma_f32_16x16x32_bf16 v[56:59], v[162:165], v[186:189], v[56:59]
	v_mfma_f32_16x16x32_bf16 v[52:55], v[154:157], v[198:201], v[52:55]
	v_mfma_f32_16x16x32_bf16 v[44:47], v[162:165], v[198:201], v[44:47]
	v_mfma_f32_16x16x32_bf16 v[36:39], v[154:157], v[206:209], v[36:39]
	v_mfma_f32_16x16x32_bf16 v[28:31], v[162:165], v[206:209], v[28:31]
	v_mfma_f32_16x16x32_bf16 v[20:23], v[154:157], v[214:217], v[20:23]
	v_mfma_f32_16x16x32_bf16 v[12:15], v[162:165], v[214:217], v[12:15]
	v_mfma_f32_16x16x32_bf16 v[60:63], v[158:161], v[194:197], v[60:63]
	v_mfma_f32_16x16x32_bf16 v[56:59], v[166:169], v[194:197], v[56:59]
	v_mfma_f32_16x16x32_bf16 v[52:55], v[158:161], v[202:205], v[52:55]
	v_mfma_f32_16x16x32_bf16 v[44:47], v[166:169], v[202:205], v[44:47]
	v_mfma_f32_16x16x32_bf16 v[36:39], v[158:161], v[210:213], v[36:39]
	v_mfma_f32_16x16x32_bf16 v[28:31], v[166:169], v[210:213], v[28:31]
	v_mfma_f32_16x16x32_bf16 v[20:23], v[158:161], v[218:221], v[20:23]
	v_mfma_f32_16x16x32_bf16 v[12:15], v[166:169], v[218:221], v[12:15]
	s_setprio 0
	s_setprio 1
	v_mfma_f32_16x16x32_bf16 v[48:51], v[170:173], v[186:189], v[48:51]
	v_mfma_f32_16x16x32_bf16 v[40:43], v[178:181], v[186:189], v[40:43]
	v_mfma_f32_16x16x32_bf16 v[32:35], v[170:173], v[198:201], v[32:35]
	v_mfma_f32_16x16x32_bf16 v[24:27], v[178:181], v[198:201], v[24:27]
	v_mfma_f32_16x16x32_bf16 v[16:19], v[170:173], v[206:209], v[16:19]
	v_mfma_f32_16x16x32_bf16 v[8:11], v[178:181], v[206:209], v[8:11]
	v_mfma_f32_16x16x32_bf16 v[4:7], v[170:173], v[214:217], v[4:7]
	v_mfma_f32_16x16x32_bf16 v[0:3], v[178:181], v[214:217], v[0:3]
	v_mfma_f32_16x16x32_bf16 v[48:51], v[174:177], v[194:197], v[48:51]
	v_mfma_f32_16x16x32_bf16 v[40:43], v[182:185], v[194:197], v[40:43]
	v_mfma_f32_16x16x32_bf16 v[32:35], v[174:177], v[202:205], v[32:35]
	v_mfma_f32_16x16x32_bf16 v[24:27], v[182:185], v[202:205], v[24:27]
	v_mfma_f32_16x16x32_bf16 v[16:19], v[174:177], v[210:213], v[16:19]
	v_mfma_f32_16x16x32_bf16 v[8:11], v[182:185], v[210:213], v[8:11]
	v_mfma_f32_16x16x32_bf16 v[4:7], v[174:177], v[218:221], v[4:7]
	v_mfma_f32_16x16x32_bf16 v[0:3], v[182:185], v[218:221], v[0:3]
	s_setprio 0
	s_barrier
; #define PG8_STAGE(bufoff, gbase, voff) do { _Pragma("unroll") for (int _i = 0; _i < 2; ++_i) \
;         __builtin_amdgcn_global_load_lds((const unsigned*)((const char*)(gbase) + (voff)[_i]), (PG8_LAS unsigned*)(lds + (bufoff) + ldsw + _i * 8192), 16, 0, 0); } while (0)
; #define PG8_LDA(dst, b, h) do { _Pragma("unroll") for (int m = 0; m < 4; ++m) _Pragma("unroll") for (int k = 0; k < 2; ++k) dst[m][k] = *(const PG8_LAS bf16x8*)(lds + PG8_SA(b, h) + aoff + m * 2048 + k * 1024); } while (0)
; #define PG8_LDB(dst, b, h) do { _Pragma("unroll") for (int n = 0; n < 2; ++n) _Pragma("unroll") for (int k = 0; k < 2; ++k) dst[n][k] = *(const PG8_LAS bf16x8*)(lds + PG8_SB(b, h) + boff + n * 2048 + k * 1024); } while (0)
; #define PG8_MMA(ai, bj, At, Bt) do { __builtin_amdgcn_s_setprio(1); _Pragma("unroll") for (int m = 0; m < 4; ++m) _Pragma("unroll") for (int n = 0; n < 2; ++n) _Pragma("unroll") for (int k = 0; k < 2; ++k) \
;         acc[ai][bj][m][n] = __builtin_amdgcn_mfma_f32_16x16x32_bf16(Bt[n][k], At[m][k], acc[ai][bj][m][n], 0, 0, 0); __builtin_amdgcn_s_setprio(0); } while (0)
; #define PG8_WAIT_V(n) asm volatile("s_waitcnt vmcnt(" #n ")" ::: "memory")
; #define PG8_WAIT_L(n) asm volatile("s_waitcnt lgkmcnt(" #n ")" ::: "memory")
; #define PG8_BAR __builtin_amdgcn_s_barrier()
; #define PG8_SCHED __builtin_amdgcn_sched_barrier(0)
; template <class Epi, class Sched, bool ALIGN_EPI = false, bool SP2 = false>
; __device__ __forceinline__ void gemm_phase(PG8_LAS unsigned char* lds, const Gemm g, const Sched& S, const Epi& E) {
;     ...
;             PG8_LDB(B0, 1, 0); PG8_LDB(B1, 1, 1); PG8_SCHED; PG8_LDA(At, 1, 0); PG8_STAGE(PG8_SA(0, 1), a2 + hstep, voffA);
;             PG8_WAIT_V(8); PG8_WAIT_L(0); PG8_BAR; PG8_MMA(0, 0, At, B0); PG8_MMA(0, 1, At, B1); PG8_BAR; PG8_SCHED;
	s_add_i32 s83, 0, 0x18000
	v_add_u32_e32 v153, s83, v149
	s_add_i32 s84, 0, 0x1c000
	ds_read_b128 v[154:157], v153
	ds_read_b128 v[158:161], v153 offset:1024
	ds_read_b128 v[162:165], v153 offset:2048
	ds_read_b128 v[166:169], v153 offset:3072
	v_add_u32_e32 v153, s84, v149
	ds_read_b128 v[170:173], v153
	ds_read_b128 v[174:177], v153 offset:1024
	ds_read_b128 v[178:181], v153 offset:2048
	ds_read_b128 v[182:185], v153 offset:3072
	s_add_u32 s34, s34, 0x80000
	s_addc_u32 s35, s35, 0
	s_mov_b32 m0, s56
	v_lshl_add_u64 v[226:227], s[34:35], 0, v[134:135]
	ds_read_b128 v[186:189], v152 offset:32768
	ds_read_b128 v[194:197], v152 offset:33792
	ds_read_b128 v[198:201], v152 offset:34816
	ds_read_b128 v[202:205], v152 offset:35840
	ds_read_b128 v[206:209], v152 offset:36864
	ds_read_b128 v[210:213], v152 offset:37888
	ds_read_b128 v[214:217], v152 offset:38912
	ds_read_b128 v[218:221], v152 offset:39936
	global_load_lds_dwordx4 v[226:227], off
	v_lshl_add_u64 v[226:227], s[34:35], 0, v[130:131]
	s_mov_b32 m0, s57
	s_nop 0
	global_load_lds_dwordx4 v[226:227], off
	s_waitcnt vmcnt(8)
	s_waitcnt lgkmcnt(0)
	s_barrier
	s_setprio 1
	s_waitcnt lgkmcnt(0)
	v_mfma_f32_16x16x32_bf16 v[124:127], v[154:157], v[186:189], v[124:127]
	v_mfma_f32_16x16x32_bf16 v[120:123], v[162:165], v[186:189], v[120:123]
	v_mfma_f32_16x16x32_bf16 v[116:119], v[154:157], v[198:201], v[116:119]
	v_mfma_f32_16x16x32_bf16 v[108:111], v[162:165], v[198:201], v[108:111]
	v_mfma_f32_16x16x32_bf16 v[100:103], v[154:157], v[206:209], v[100:103]
	v_mfma_f32_16x16x32_bf16 v[92:95], v[162:165], v[206:209], v[92:95]
	v_mfma_f32_16x16x32_bf16 v[84:87], v[154:157], v[214:217], v[84:87]
	v_mfma_f32_16x16x32_bf16 v[76:79], v[162:165], v[214:217], v[76:79]
	v_mfma_f32_16x16x32_bf16 v[124:127], v[158:161], v[194:197], v[124:127]
	v_mfma_f32_16x16x32_bf16 v[120:123], v[166:169], v[194:197], v[120:123]
	v_mfma_f32_16x16x32_bf16 v[116:119], v[158:161], v[202:205], v[116:119]
	v_mfma_f32_16x16x32_bf16 v[108:111], v[166:169], v[202:205], v[108:111]
	v_mfma_f32_16x16x32_bf16 v[100:103], v[158:161], v[210:213], v[100:103]
	v_mfma_f32_16x16x32_bf16 v[92:95], v[166:169], v[210:213], v[92:95]
	v_mfma_f32_16x16x32_bf16 v[84:87], v[158:161], v[218:221], v[84:87]
	v_mfma_f32_16x16x32_bf16 v[76:79], v[166:169], v[218:221], v[76:79]
	s_setprio 0
	s_setprio 1
	v_mfma_f32_16x16x32_bf16 v[112:115], v[170:173], v[186:189], v[112:115]
	v_mfma_f32_16x16x32_bf16 v[104:107], v[178:181], v[186:189], v[104:107]
	v_mfma_f32_16x16x32_bf16 v[96:99], v[170:173], v[198:201], v[96:99]
	v_mfma_f32_16x16x32_bf16 v[88:91], v[178:181], v[198:201], v[88:91]
	v_mfma_f32_16x16x32_bf16 v[80:83], v[170:173], v[206:209], v[80:83]
	v_mfma_f32_16x16x32_bf16 v[72:75], v[178:181], v[206:209], v[72:75]
	v_mfma_f32_16x16x32_bf16 v[68:71], v[170:173], v[214:217], v[68:71]
	v_mfma_f32_16x16x32_bf16 v[64:67], v[178:181], v[214:217], v[64:67]
	v_mfma_f32_16x16x32_bf16 v[112:115], v[174:177], v[194:197], v[112:115]
	v_mfma_f32_16x16x32_bf16 v[104:107], v[182:185], v[194:197], v[104:107]
	v_mfma_f32_16x16x32_bf16 v[96:99], v[174:177], v[202:205], v[96:99]
	v_mfma_f32_16x16x32_bf16 v[88:91], v[182:185], v[202:205], v[88:91]
	v_mfma_f32_16x16x32_bf16 v[80:83], v[174:177], v[210:213], v[80:83]
	v_mfma_f32_16x16x32_bf16 v[72:75], v[182:185], v[210:213], v[72:75]
	v_mfma_f32_16x16x32_bf16 v[68:71], v[174:177], v[218:221], v[68:71]
	v_mfma_f32_16x16x32_bf16 v[64:67], v[182:185], v[218:221], v[64:67]
	s_setprio 0
	s_barrier
; #define PG8_STAGE(bufoff, gbase, voff) do { _Pragma("unroll") for (int _i = 0; _i < 2; ++_i) \
;         __builtin_amdgcn_global_load_lds((const unsigned*)((const char*)(gbase) + (voff)[_i]), (PG8_LAS unsigned*)(lds + (bufoff) + ldsw + _i * 8192), 16, 0, 0); } while (0)
; #define PG8_LDA(dst, b, h) do { _Pragma("unroll") for (int m = 0; m < 4; ++m) _Pragma("unroll") for (int k = 0; k < 2; ++k) dst[m][k] = *(const PG8_LAS bf16x8*)(lds + PG8_SA(b, h) + aoff + m * 2048 + k * 1024); } while (0)
; #define PG8_MMA(ai, bj, At, Bt) do { __builtin_amdgcn_s_setprio(1); _Pragma("unroll") for (int m = 0; m < 4; ++m) _Pragma("unroll") for (int n = 0; n < 2; ++n) _Pragma("unroll") for (int k = 0; k < 2; ++k) \
;         acc[ai][bj][m][n] = __builtin_amdgcn_mfma_f32_16x16x32_bf16(Bt[n][k], At[m][k], acc[ai][bj][m][n], 0, 0, 0); __builtin_amdgcn_s_setprio(0); } while (0)
; #define PG8_WAIT_V(n) asm volatile("s_waitcnt vmcnt(" #n ")" ::: "memory")
; #define PG8_WAIT_L(n) asm volatile("s_waitcnt lgkmcnt(" #n ")" ::: "memory")
; #define PG8_BAR __builtin_amdgcn_s_barrier()
; #define PG8_SCHED __builtin_amdgcn_sched_barrier(0)
; template <class Epi, class Sched, bool ALIGN_EPI = false, bool SP2 = false>
; __device__ __forceinline__ void gemm_phase(PG8_LAS unsigned char* lds, const Gemm g, const Sched& S, const Epi& E) {
;     ...
;         for (int t = 0; t < nt; t += 2) {
;             const bool last = (t == nt - 2);
;             const char* a1 = cA + (size_t)(t + 1) * kstep;
;             const char* a2 = last ? nA : cA + (size_t)(t + 2) * kstep; const char* b2 = last ? nB : cB + (size_t)(t + 2) * kstep;
;     ...
;             PG8_LDA(At, 1, 1); PG8_STAGE(PG8_SB(1, 0), b3, voffB); PG8_STAGE(PG8_SB(1, 1), b3 + hstep, voffB); PG8_STAGE(PG8_SA(1, 0), a3, voffA);
;             PG8_WAIT_V(8); PG8_WAIT_L(0); PG8_BAR; PG8_MMA(1, 0, At, B0); PG8_MMA(1, 1, At, B1); PG8_BAR; PG8_SCHED;
	s_add_i32 s34, s83, s36
	v_lshl_add_u64 v[146:147], v[146:147], 0, s[12:13]
	s_mov_b32 m0, s34
	ds_read_b128 v[186:189], v152 offset:49152
	ds_read_b128 v[194:197], v152 offset:50176
	ds_read_b128 v[198:201], v152 offset:51200
	ds_read_b128 v[202:205], v152 offset:52224
	ds_read_b128 v[206:209], v152 offset:53248
	ds_read_b128 v[210:213], v152 offset:54272
	ds_read_b128 v[214:217], v152 offset:55296
	ds_read_b128 v[218:221], v152 offset:56320
	global_load_lds_dwordx4 v[146:147], off
	s_add_i32 m0, s34, 0x2000
	s_add_u32 s30, s30, 0x80080
	v_lshl_add_u64 v[146:147], v[190:191], 0, s[12:13]
	s_addc_u32 s31, s31, 0
	s_add_i32 s34, s84, s36
	global_load_lds_dwordx4 v[146:147], off
	v_lshl_add_u64 v[146:147], s[30:31], 0, v[132:133]
	s_mov_b32 m0, s34
	s_nop 0
	global_load_lds_dwordx4 v[146:147], off
	v_lshl_add_u64 v[146:147], s[30:31], 0, v[128:129]
	s_add_i32 m0, s34, 0x2000
	s_nop 0
	global_load_lds_dwordx4 v[146:147], off
	v_lshl_add_u64 v[146:147], v[222:223], 0, s[12:13]
	s_mov_b32 m0, s59
	s_nop 0
	global_load_lds_dwordx4 v[146:147], off
	v_lshl_add_u64 v[146:147], v[224:225], 0, s[12:13]
	s_mov_b32 m0, s60
	s_nop 0
	global_load_lds_dwordx4 v[146:147], off
	s_waitcnt vmcnt(8)
	s_waitcnt lgkmcnt(0)
	s_barrier
	s_setprio 1
	s_waitcnt lgkmcnt(0)
	v_mfma_f32_16x16x32_bf16 v[60:63], v[154:157], v[186:189], v[60:63]
	v_mfma_f32_16x16x32_bf16 v[56:59], v[162:165], v[186:189], v[56:59]
	v_mfma_f32_16x16x32_bf16 v[52:55], v[154:157], v[198:201], v[52:55]
	v_mfma_f32_16x16x32_bf16 v[44:47], v[162:165], v[198:201], v[44:47]
	v_mfma_f32_16x16x32_bf16 v[36:39], v[154:157], v[206:209], v[36:39]
	v_mfma_f32_16x16x32_bf16 v[28:31], v[162:165], v[206:209], v[28:31]
	v_mfma_f32_16x16x32_bf16 v[20:23], v[154:157], v[214:217], v[20:23]
	v_mfma_f32_16x16x32_bf16 v[12:15], v[162:165], v[214:217], v[12:15]
	v_mfma_f32_16x16x32_bf16 v[60:63], v[158:161], v[194:197], v[60:63]
	v_mfma_f32_16x16x32_bf16 v[56:59], v[166:169], v[194:197], v[56:59]
	v_mfma_f32_16x16x32_bf16 v[52:55], v[158:161], v[202:205], v[52:55]
	v_mfma_f32_16x16x32_bf16 v[44:47], v[166:169], v[202:205], v[44:47]
	v_mfma_f32_16x16x32_bf16 v[36:39], v[158:161], v[210:213], v[36:39]
	v_mfma_f32_16x16x32_bf16 v[28:31], v[166:169], v[210:213], v[28:31]
	v_mfma_f32_16x16x32_bf16 v[20:23], v[158:161], v[218:221], v[20:23]
	v_mfma_f32_16x16x32_bf16 v[12:15], v[166:169], v[218:221], v[12:15]
	s_setprio 0
	s_setprio 1
	v_mfma_f32_16x16x32_bf16 v[48:51], v[170:173], v[186:189], v[48:51]
	v_mfma_f32_16x16x32_bf16 v[40:43], v[178:181], v[186:189], v[40:43]
	v_mfma_f32_16x16x32_bf16 v[32:35], v[170:173], v[198:201], v[32:35]
	v_mfma_f32_16x16x32_bf16 v[24:27], v[178:181], v[198:201], v[24:27]
	v_mfma_f32_16x16x32_bf16 v[16:19], v[170:173], v[206:209], v[16:19]
	v_mfma_f32_16x16x32_bf16 v[8:11], v[178:181], v[206:209], v[8:11]
	v_mfma_f32_16x16x32_bf16 v[4:7], v[170:173], v[214:217], v[4:7]
	v_mfma_f32_16x16x32_bf16 v[0:3], v[178:181], v[214:217], v[0:3]
	v_mfma_f32_16x16x32_bf16 v[48:51], v[174:177], v[194:197], v[48:51]
	v_mfma_f32_16x16x32_bf16 v[40:43], v[182:185], v[194:197], v[40:43]
	v_mfma_f32_16x16x32_bf16 v[32:35], v[174:177], v[202:205], v[32:35]
	v_mfma_f32_16x16x32_bf16 v[24:27], v[182:185], v[202:205], v[24:27]
	v_mfma_f32_16x16x32_bf16 v[16:19], v[174:177], v[210:213], v[16:19]
	v_mfma_f32_16x16x32_bf16 v[8:11], v[182:185], v[210:213], v[8:11]
	v_mfma_f32_16x16x32_bf16 v[4:7], v[174:177], v[218:221], v[4:7]
	v_mfma_f32_16x16x32_bf16 v[0:3], v[182:185], v[218:221], v[0:3]
	s_add_i32 s82, s82, 2
	s_add_u32 s80, s80, 0x100
	s_addc_u32 s81, s81, 0
	s_add_u32 s28, s28, 0x100
	s_addc_u32 s29, s29, 0
	s_cmp_gt_u32 s82, 29
	s_setprio 0
	s_barrier
	s_cbranch_scc0 .LBB0_726

; template <bool NB = false>
; __device__ __forceinline__ void attn_phase(char* lds, const bf16* Q, const bf16* K, const bf16* V, bf16* O, const float* G, int vcu, int nwg) {
;     constexpr int total = BATCH * NH * 8;
;     int L = vcu; if (L >= total) return;
;     int pass = 0;
;     fox::BlockRef<bf16, bf16> cur = attn_ref(L, 0, Q, K, V, O, G);
;     fox::Seam<bf16> S;
;     fox::causal_swa_prime<bf16, bf16>(cur, SEQ, lds, S);
; __global__ void __launch_bounds__(NTHR, 2) fwd_kernel(Args args) {
;     ...
;         if (IN_PH()) { FRESH();
;             if (layer == 0) sgu_phase(lds, R1, R1 + SZ_ACT / 2, R1 + SZ_ACT, Wm, INP(8), INP(9), INP(11), tid, wave, lane);
;     ...
;             if (layer == 0) { xcd_barrier(bar); sgu_phase(lds, R1, R1 + SZ_ACT / 2, R1 + SZ_ACT, Wm, INP(8), INP(9), INP(11), tid, wave, lane); }
;     ...
;             else attn_phase((char*)lds_raw, R1, R1 + SZ_ACT / 2, R1 + SZ_ACT, RA, Gb, vcu, G);
.LBB0_785:
	s_or_b64 exec, exec, s[6:7]
	s_waitcnt lgkmcnt(0)
	v_mov_b32_e32 v0, v192
	s_mov_b32 s50, s2
	s_andn2_b64 vcc, exec, s[46:47]
	s_barrier
	v_readfirstlane_b32 s92, v192
	s_bitcmp1_b32 s92, 8
	s_cbranch_scc0 .Lattn_prio_done
	s_setprio 1
.Lattn_prio_done:
	s_cbranch_vccnz .LBB0_787
	s_ashr_i32 s7, s50, 31
	s_lshr_b32 s7, s7, 29
	s_add_i32 s7, s50, s7
	s_ashr_i32 s8, s7, 3
	s_and_b32 s7, s7, -8
	s_ashr_i32 s6, s3, 3
	s_sub_i32 s7, s50, s7
	s_mul_i32 s6, s7, s6
	s_add_i32 s50, s6, s8

; __device__ __forceinline__ unsigned xb_ld(unsigned* p)              { return __hip_atomic_load(p, __ATOMIC_RELAXED, __HIP_MEMORY_SCOPE_AGENT); }
; __device__ __forceinline__ void xcd_barrier_complete(unsigned* bar, unsigned x, unsigned& nloc, unsigned& nx) {
;     const unsigned G = gridDim.x * gridDim.y * gridDim.z;
;     unsigned sum, cnt, mine, sp = 0u;
;     for (;;) {
;         sum = 0u; cnt = 0u; mine = 0u;
; #pragma unroll
;         for (unsigned j = 0; j < 16; ++j) { const unsigned c = xb_ld(&bar[XB_XCNT(j)]); sum += c; cnt += (c > 0u) ? 1u : 0u; mine = (j == x) ? c : mine; }
; __device__ __forceinline__ void xcd_barrier(const XcdBarrier& b) {
;     asm volatile("s_waitcnt vmcnt(0)" ::: "memory");
;     __syncthreads();
;     if (threadIdx.x == 0) {
;         unsigned* bar = b.bar;
;         __builtin_amdgcn_s_waitcnt(0);
;         unsigned nloc = b.st[0], nx = b.st[1];
;         if (nloc == 0u) { xcd_barrier_complete(bar, b.x, nloc, nx); b.st[0] = nloc; b.st[1] = nx; }
.LBB0_973:
	s_setprio 0
	s_waitcnt vmcnt(0)
	s_barrier
	s_and_saveexec_b64 s[6:7], s[38:39]
	s_cbranch_execz .LBB0_1025
	s_add_i32 s8, 0, 0x257c0
	v_mov_b32_e32 v0, s8
	s_waitcnt vmcnt(0) expcnt(0) lgkmcnt(0)
	ds_read_b32 v2, v0
	s_add_i32 s8, 0, 0x257c4
	v_mov_b32_e32 v0, s8
	ds_read_b32 v0, v0
	s_waitcnt lgkmcnt(1)
	v_cmp_ne_u32_e32 vcc, 0, v2
	s_cbranch_vccnz .LBB0_989
	s_load_dwordx2 s[12:13], s[44:45], 0x4
	s_add_u32 s8, s40, 0x4200
	s_addc_u32 s9, s41, 0
	s_add_u32 s10, s40, 0x4400
	s_addc_u32 s11, s41, 0
	s_waitcnt lgkmcnt(0)
	s_mul_i32 s58, s12, s3
	s_add_u32 s12, s40, 0x4500
	s_mul_i32 s58, s58, s13
	s_addc_u32 s13, s41, 0
	s_add_u32 s14, s40, 0x4600
	s_addc_u32 s15, s41, 0
	s_add_u32 s16, s40, 0x4700
	s_addc_u32 s17, s41, 0
	s_add_u32 s18, s40, 0x4800
	s_addc_u32 s19, s41, 0
	s_add_u32 s20, s40, 0x4900
	s_addc_u32 s21, s41, 0
	s_add_u32 s22, s40, 0x4a00
	s_addc_u32 s23, s41, 0
	s_add_u32 s24, s40, 0x4b00
	s_addc_u32 s25, s41, 0
	s_add_u32 s26, s40, 0x4c00
	s_addc_u32 s27, s41, 0
	s_add_u32 s28, s40, 0x4d00
	s_addc_u32 s29, s41, 0
	s_add_u32 s30, s40, 0x4e00
	s_addc_u32 s31, s41, 0
	s_add_u32 s34, s40, 0x4f00
	s_addc_u32 s35, s41, 0
	s_add_u32 s36, s40, 0x5000
	s_addc_u32 s37, s41, 0
	s_add_u32 s46, s40, 0x5100
	s_addc_u32 s47, s41, 0
	s_add_u32 s48, s40, 0x5200
	s_addc_u32 s49, s41, 0
	s_add_u32 s50, s40, 0x5300
	s_addc_u32 s51, s41, 0
	s_mov_b32 s59, 1
	v_mov_b32_e32 v16, 0
	s_branch .LBB0_977

; #define PG8_STAGE(bufoff, gbase, voff) do { _Pragma("unroll") for (int _i = 0; _i < 2; ++_i) \
;         __builtin_amdgcn_global_load_lds((const unsigned*)((const char*)(gbase) + (voff)[_i]), (PG8_LAS unsigned*)(lds + (bufoff) + ldsw + _i * 8192), 16, 0, 0); } while (0)
; #define PG8_LDA(dst, b, h) do { _Pragma("unroll") for (int m = 0; m < 4; ++m) _Pragma("unroll") for (int k = 0; k < 2; ++k) dst[m][k] = *(const PG8_LAS bf16x8*)(lds + PG8_SA(b, h) + aoff + m * 2048 + k * 1024); } while (0)
; #define PG8_LDB(dst, b, h) do { _Pragma("unroll") for (int n = 0; n < 2; ++n) _Pragma("unroll") for (int k = 0; k < 2; ++k) dst[n][k] = *(const PG8_LAS bf16x8*)(lds + PG8_SB(b, h) + boff + n * 2048 + k * 1024); } while (0)
; #define PG8_MMA(ai, bj, At, Bt) do { __builtin_amdgcn_s_setprio(1); _Pragma("unroll") for (int m = 0; m < 4; ++m) _Pragma("unroll") for (int n = 0; n < 2; ++n) _Pragma("unroll") for (int k = 0; k < 2; ++k) \
;         acc[ai][bj][m][n] = __builtin_amdgcn_mfma_f32_16x16x32_bf16(Bt[n][k], At[m][k], acc[ai][bj][m][n], 0, 0, 0); __builtin_amdgcn_s_setprio(0); } while (0)
; #define PG8_WAIT_V(n) asm volatile("s_waitcnt vmcnt(" #n ")" ::: "memory")
; #define PG8_WAIT_L(n) asm volatile("s_waitcnt lgkmcnt(" #n ")" ::: "memory")
; #define PG8_BAR __builtin_amdgcn_s_barrier()
; template <class Epi, class Sched, bool ALIGN_EPI = false, bool SP2 = false>
; __device__ __forceinline__ void gemm_phase(PG8_LAS unsigned char* lds, const Gemm g, const Sched& S, const Epi& E) {
;     ...
;         const bool has_next = S.next(ui + 1, nxt);
;         const char* nA = has_next ? (const char*)g.A + (size_t)nxt.pm * tstep : cA; const char* nB = has_next ? (const char*)g.Bt + (size_t)nxt.pn * tstep : cB;
;         for (int t = 0; t < nt; t += 2) {
;             const bool last = (t == nt - 2);
;             const char* a1 = cA + (size_t)(t + 1) * kstep;
;             const char* a2 = last ? nA : cA + (size_t)(t + 2) * kstep; const char* b2 = last ? nB : cB + (size_t)(t + 2) * kstep;
;             const char* a3 = a2 + kstep; const char* b3 = b2 + kstep;
;             if (last && has_next) S.a_ready(nxt);
;             if constexpr (SP2) {
;             PG8_LDB(B0, 0, 0); PG8_LDB(B1, 0, 1); PG8_SCHED; PG8_LDA(At, 0, 0); PG8_STAGE(PG8_SA(1, 1), a1 + hstep, voffA);
;             PG8_WAIT_V(8); PG8_WAIT_L(0); PG8_BAR; PG8_MMA(0, 0, At, B0); PG8_MMA(0, 1, At, B1); PG8_BAR; PG8_SCHED;
.LBB0_1041:
	s_ashr_i32 s25, s24, 31
	s_lshl_b64 s[28:29], s[24:25], 20
	s_add_u32 s28, s56, s28
	s_addc_u32 s29, s57, s29
	s_and_b64 s[30:31], s[6:7], exec
	s_cselect_b32 s25, s29, s49
	s_cselect_b32 s73, s28, s48
	s_ashr_i32 s27, s26, 31
	s_lshl_b64 s[30:31], s[26:27], 20
	s_add_u32 s30, s54, s30
	s_addc_u32 s31, s55, s31
	s_and_b64 s[50:51], s[6:7], exec
	s_cselect_b32 s27, s31, s47
	s_cselect_b32 s74, s30, s46
	s_add_u32 s75, s46, 0x100
	s_addc_u32 s76, s47, 0
	s_add_u32 s46, s48, 0x80080
	s_addc_u32 s47, s49, 0
	s_mov_b32 s77, -2
	ds_read_b128 v[120:123], v169
	ds_read_b128 v[124:127], v169 offset:1024
	ds_read_b128 v[128:131], v169 offset:2048
	ds_read_b128 v[132:135], v169 offset:3072
	ds_read_b128 v[160:163], v170
	ds_read_b128 v[172:175], v170 offset:1024
	ds_read_b128 v[176:179], v170 offset:2048
	ds_read_b128 v[180:183], v170 offset:3072
	s_add_u32 s48, s46, 0xfff80080
	s_addc_u32 s49, s47, -1
	s_cmp_eq_u32 s77, 28
	s_cselect_b32 s51, s25, s49
	s_cselect_b32 s50, s73, s48
	s_cselect_b32 s49, s27, s76
	s_cselect_b32 s48, s74, s75
	v_lshl_add_u64 v[164:165], s[46:47], 0, v[154:155]
	s_add_i32 m0, s35, 0xc000
	ds_read_b128 v[184:187], v171
	ds_read_b128 v[188:191], v171 offset:1024
	ds_read_b128 v[194:197], v171 offset:2048
	ds_read_b128 v[198:201], v171 offset:3072
	ds_read_b128 v[202:205], v171 offset:4096
	ds_read_b128 v[206:209], v171 offset:5120
	ds_read_b128 v[210:213], v171 offset:6144
	ds_read_b128 v[214:217], v171 offset:7168
	global_load_lds_dwordx4 v[164:165], off
	v_lshl_add_u64 v[164:165], s[46:47], 0, v[152:153]
	s_add_i32 m0, s35, 0xe000
	s_nop 0
	global_load_lds_dwordx4 v[164:165], off
	s_waitcnt vmcnt(8)
	s_waitcnt lgkmcnt(0)
	s_barrier
	s_setprio 1
	s_waitcnt lgkmcnt(0)
	v_mfma_f32_16x16x32_bf16 v[140:143], v[120:123], v[184:187], 0
	v_mfma_f32_16x16x32_bf16 v[136:139], v[128:131], v[184:187], 0
	v_mfma_f32_16x16x32_bf16 v[112:115], v[120:123], v[194:197], 0
	v_mfma_f32_16x16x32_bf16 v[104:107], v[128:131], v[194:197], 0
	v_mfma_f32_16x16x32_bf16 v[96:99], v[120:123], v[202:205], 0
	v_mfma_f32_16x16x32_bf16 v[88:91], v[128:131], v[202:205], 0
	v_mfma_f32_16x16x32_bf16 v[80:83], v[120:123], v[210:213], 0
	v_mfma_f32_16x16x32_bf16 v[72:75], v[128:131], v[210:213], 0
	v_mfma_f32_16x16x32_bf16 v[140:143], v[124:127], v[188:191], v[140:143]
	v_mfma_f32_16x16x32_bf16 v[136:139], v[132:135], v[188:191], v[136:139]
	v_mfma_f32_16x16x32_bf16 v[112:115], v[124:127], v[198:201], v[112:115]
	v_mfma_f32_16x16x32_bf16 v[104:107], v[132:135], v[198:201], v[104:107]
	v_mfma_f32_16x16x32_bf16 v[96:99], v[124:127], v[206:209], v[96:99]
	v_mfma_f32_16x16x32_bf16 v[88:91], v[132:135], v[206:209], v[88:91]
	v_mfma_f32_16x16x32_bf16 v[80:83], v[124:127], v[214:217], v[80:83]
	v_mfma_f32_16x16x32_bf16 v[72:75], v[132:135], v[214:217], v[72:75]
	s_setprio 0
	s_setprio 1
	v_mfma_f32_16x16x32_bf16 v[116:119], v[160:163], v[184:187], 0
	v_mfma_f32_16x16x32_bf16 v[108:111], v[176:179], v[184:187], 0
	v_mfma_f32_16x16x32_bf16 v[100:103], v[160:163], v[194:197], 0
	v_mfma_f32_16x16x32_bf16 v[92:95], v[176:179], v[194:197], 0
	v_mfma_f32_16x16x32_bf16 v[84:87], v[160:163], v[202:205], 0
	v_mfma_f32_16x16x32_bf16 v[76:79], v[176:179], v[202:205], 0
	v_mfma_f32_16x16x32_bf16 v[68:71], v[160:163], v[210:213], 0
	v_mfma_f32_16x16x32_bf16 v[64:67], v[176:179], v[210:213], 0
	v_mfma_f32_16x16x32_bf16 v[116:119], v[172:175], v[188:191], v[116:119]
	v_mfma_f32_16x16x32_bf16 v[108:111], v[180:183], v[188:191], v[108:111]
	v_mfma_f32_16x16x32_bf16 v[100:103], v[172:175], v[198:201], v[100:103]
	v_mfma_f32_16x16x32_bf16 v[92:95], v[180:183], v[198:201], v[92:95]
	v_mfma_f32_16x16x32_bf16 v[84:87], v[172:175], v[206:209], v[84:87]
	v_mfma_f32_16x16x32_bf16 v[76:79], v[180:183], v[206:209], v[76:79]
	v_mfma_f32_16x16x32_bf16 v[68:71], v[172:175], v[214:217], v[68:71]
	v_mfma_f32_16x16x32_bf16 v[64:67], v[180:183], v[214:217], v[64:67]
	s_setprio 0
	s_barrier
	s_add_i32 s78, s67, s58
	v_lshl_add_u64 v[164:165], s[48:49], 0, v[146:147]
	s_mov_b32 m0, s78
	ds_read_b128 v[184:187], v171 offset:16384
	ds_read_b128 v[188:191], v171 offset:17408
	ds_read_b128 v[194:197], v171 offset:18432
	ds_read_b128 v[198:201], v171 offset:19456
	ds_read_b128 v[202:205], v171 offset:20480
	ds_read_b128 v[206:209], v171 offset:21504
	ds_read_b128 v[210:213], v171 offset:22528
	ds_read_b128 v[214:217], v171 offset:23552
	global_load_lds_dwordx4 v[164:165], off
	s_add_i32 m0, s78, 0x2000
	s_add_u32 s78, s48, 0x80000
	v_lshl_add_u64 v[218:219], s[48:49], 0, v[150:151]
	s_addc_u32 s79, s49, 0
	s_add_i32 s80, s68, s58
	global_load_lds_dwordx4 v[218:219], off
	v_lshl_add_u64 v[220:221], s[78:79], 0, v[146:147]
	s_mov_b32 m0, s80
	v_lshl_add_u64 v[222:223], s[50:51], 0, v[148:149]
	global_load_lds_dwordx4 v[220:221], off
	v_lshl_add_u64 v[220:221], s[78:79], 0, v[150:151]
	s_add_i32 m0, s80, 0x2000
	s_nop 0
	global_load_lds_dwordx4 v[220:221], off
	v_lshl_add_u64 v[220:221], s[50:51], 0, v[144:145]
	s_mov_b32 m0, s35
	s_nop 0
	global_load_lds_dwordx4 v[220:221], off
	s_mov_b32 m0, s37
	s_nop 0
	global_load_lds_dwordx4 v[222:223], off
	s_waitcnt vmcnt(8)
	s_waitcnt lgkmcnt(0)
	s_barrier
; #define PG8_STAGE(bufoff, gbase, voff) do { _Pragma("unroll") for (int _i = 0; _i < 2; ++_i) \
;         __builtin_amdgcn_global_load_lds((const unsigned*)((const char*)(gbase) + (voff)[_i]), (PG8_LAS unsigned*)(lds + (bufoff) + ldsw + _i * 8192), 16, 0, 0); } while (0)
; #define PG8_LDA(dst, b, h) do { _Pragma("unroll") for (int m = 0; m < 4; ++m) _Pragma("unroll") for (int k = 0; k < 2; ++k) dst[m][k] = *(const PG8_LAS bf16x8*)(lds + PG8_SA(b, h) + aoff + m * 2048 + k * 1024); } while (0)
; #define PG8_LDB(dst, b, h) do { _Pragma("unroll") for (int n = 0; n < 2; ++n) _Pragma("unroll") for (int k = 0; k < 2; ++k) dst[n][k] = *(const PG8_LAS bf16x8*)(lds + PG8_SB(b, h) + boff + n * 2048 + k * 1024); } while (0)
; #define PG8_MMA(ai, bj, At, Bt) do { __builtin_amdgcn_s_setprio(1); _Pragma("unroll") for (int m = 0; m < 4; ++m) _Pragma("unroll") for (int n = 0; n < 2; ++n) _Pragma("unroll") for (int k = 0; k < 2; ++k) \
;         acc[ai][bj][m][n] = __builtin_amdgcn_mfma_f32_16x16x32_bf16(Bt[n][k], At[m][k], acc[ai][bj][m][n], 0, 0, 0); __builtin_amdgcn_s_setprio(0); } while (0)
; #define PG8_WAIT_V(n) asm volatile("s_waitcnt vmcnt(" #n ")" ::: "memory")
; #define PG8_WAIT_L(n) asm volatile("s_waitcnt lgkmcnt(" #n ")" ::: "memory")
; #define PG8_BAR __builtin_amdgcn_s_barrier()
; #define PG8_SCHED __builtin_amdgcn_sched_barrier(0)
; template <class Epi, class Sched, bool ALIGN_EPI = false, bool SP2 = false>
; __device__ __forceinline__ void gemm_phase(PG8_LAS unsigned char* lds, const Gemm g, const Sched& S, const Epi& E) {
;     ...
;             PG8_WAIT_V(8); PG8_WAIT_L(0); PG8_BAR; PG8_MMA(0, 0, At, B0); PG8_MMA(0, 1, At, B1); PG8_BAR; PG8_SCHED;
;             PG8_LDA(At, 0, 1); PG8_STAGE(PG8_SB(0, 0), b2, voffB); PG8_STAGE(PG8_SB(0, 1), b2 + hstep, voffB); PG8_STAGE(PG8_SA(0, 0), a2, voffA);
;             PG8_WAIT_V(8); PG8_WAIT_L(0); PG8_BAR; PG8_MMA(1, 0, At, B0); PG8_MMA(1, 1, At, B1); PG8_BAR; PG8_SCHED;
;             PG8_LDB(B0, 1, 0); PG8_LDB(B1, 1, 1); PG8_SCHED; PG8_LDA(At, 1, 0); PG8_STAGE(PG8_SA(0, 1), a2 + hstep, voffA);
;             PG8_WAIT_V(8); PG8_WAIT_L(0); PG8_BAR; PG8_MMA(0, 0, At, B0); PG8_MMA(0, 1, At, B1); PG8_BAR; PG8_SCHED;
	s_setprio 1
	s_waitcnt lgkmcnt(0)
	v_mfma_f32_16x16x32_bf16 v[60:63], v[120:123], v[184:187], 0
	v_mfma_f32_16x16x32_bf16 v[56:59], v[128:131], v[184:187], 0
	v_mfma_f32_16x16x32_bf16 v[48:51], v[120:123], v[194:197], 0
	v_mfma_f32_16x16x32_bf16 v[40:43], v[128:131], v[194:197], 0
	v_mfma_f32_16x16x32_bf16 v[32:35], v[120:123], v[202:205], 0
	v_mfma_f32_16x16x32_bf16 v[24:27], v[128:131], v[202:205], 0
	v_mfma_f32_16x16x32_bf16 v[16:19], v[120:123], v[210:213], 0
	v_mfma_f32_16x16x32_bf16 v[8:11], v[128:131], v[210:213], 0
	v_mfma_f32_16x16x32_bf16 v[60:63], v[124:127], v[188:191], v[60:63]
	v_mfma_f32_16x16x32_bf16 v[56:59], v[132:135], v[188:191], v[56:59]
	v_mfma_f32_16x16x32_bf16 v[48:51], v[124:127], v[198:201], v[48:51]
	v_mfma_f32_16x16x32_bf16 v[40:43], v[132:135], v[198:201], v[40:43]
	v_mfma_f32_16x16x32_bf16 v[32:35], v[124:127], v[206:209], v[32:35]
	v_mfma_f32_16x16x32_bf16 v[24:27], v[132:135], v[206:209], v[24:27]
	v_mfma_f32_16x16x32_bf16 v[16:19], v[124:127], v[214:217], v[16:19]
	v_mfma_f32_16x16x32_bf16 v[8:11], v[132:135], v[214:217], v[8:11]
	s_setprio 0
	s_setprio 1
	v_mfma_f32_16x16x32_bf16 v[52:55], v[160:163], v[184:187], 0
	v_mfma_f32_16x16x32_bf16 v[44:47], v[176:179], v[184:187], 0
	v_mfma_f32_16x16x32_bf16 v[36:39], v[160:163], v[194:197], 0
	v_mfma_f32_16x16x32_bf16 v[28:31], v[176:179], v[194:197], 0
	v_mfma_f32_16x16x32_bf16 v[20:23], v[160:163], v[202:205], 0
	v_mfma_f32_16x16x32_bf16 v[12:15], v[176:179], v[202:205], 0
	v_mfma_f32_16x16x32_bf16 v[4:7], v[160:163], v[210:213], 0
	v_mfma_f32_16x16x32_bf16 v[0:3], v[176:179], v[210:213], 0
	v_mfma_f32_16x16x32_bf16 v[52:55], v[172:175], v[188:191], v[52:55]
	v_mfma_f32_16x16x32_bf16 v[44:47], v[180:183], v[188:191], v[44:47]
	v_mfma_f32_16x16x32_bf16 v[36:39], v[172:175], v[198:201], v[36:39]
	v_mfma_f32_16x16x32_bf16 v[28:31], v[180:183], v[198:201], v[28:31]
	v_mfma_f32_16x16x32_bf16 v[20:23], v[172:175], v[206:209], v[20:23]
	v_mfma_f32_16x16x32_bf16 v[12:15], v[180:183], v[206:209], v[12:15]
	v_mfma_f32_16x16x32_bf16 v[4:7], v[172:175], v[214:217], v[4:7]
	v_mfma_f32_16x16x32_bf16 v[0:3], v[180:183], v[214:217], v[0:3]
	s_setprio 0
	s_barrier
	s_add_i32 s78, 0, 0x18000
	s_add_i32 s79, 0, 0x1c000
	v_add_u32_e32 v132, s78, v167
	v_add_u32_e32 v180, s79, v167
	ds_read_b128 v[120:123], v132
	ds_read_b128 v[124:127], v132 offset:1024
	ds_read_b128 v[128:131], v132 offset:2048
	ds_read_b128 v[132:135], v132 offset:3072
	ds_read_b128 v[160:163], v180
	ds_read_b128 v[172:175], v180 offset:1024
	ds_read_b128 v[176:179], v180 offset:2048
	ds_read_b128 v[180:183], v180 offset:3072
	s_add_u32 s50, s50, 0x80000
	s_addc_u32 s51, s51, 0
	s_mov_b32 m0, s59
	v_lshl_add_u64 v[224:225], s[50:51], 0, v[144:145]
	ds_read_b128 v[184:187], v171 offset:32768
	ds_read_b128 v[188:191], v171 offset:33792
	ds_read_b128 v[194:197], v171 offset:34816
	ds_read_b128 v[198:201], v171 offset:35840
	ds_read_b128 v[202:205], v171 offset:36864
	ds_read_b128 v[206:209], v171 offset:37888
	ds_read_b128 v[210:213], v171 offset:38912
	ds_read_b128 v[214:217], v171 offset:39936
	global_load_lds_dwordx4 v[224:225], off
	v_lshl_add_u64 v[224:225], s[50:51], 0, v[148:149]
	s_mov_b32 m0, s60
	s_nop 0
	global_load_lds_dwordx4 v[224:225], off
	s_waitcnt vmcnt(8)
	s_waitcnt lgkmcnt(0)
	s_barrier
	s_setprio 1
	s_waitcnt lgkmcnt(0)
	v_mfma_f32_16x16x32_bf16 v[140:143], v[120:123], v[184:187], v[140:143]
	v_mfma_f32_16x16x32_bf16 v[136:139], v[128:131], v[184:187], v[136:139]
	v_mfma_f32_16x16x32_bf16 v[112:115], v[120:123], v[194:197], v[112:115]
	v_mfma_f32_16x16x32_bf16 v[104:107], v[128:131], v[194:197], v[104:107]
	v_mfma_f32_16x16x32_bf16 v[96:99], v[120:123], v[202:205], v[96:99]
	v_mfma_f32_16x16x32_bf16 v[88:91], v[128:131], v[202:205], v[88:91]
	v_mfma_f32_16x16x32_bf16 v[80:83], v[120:123], v[210:213], v[80:83]
	v_mfma_f32_16x16x32_bf16 v[72:75], v[128:131], v[210:213], v[72:75]
	v_mfma_f32_16x16x32_bf16 v[140:143], v[124:127], v[188:191], v[140:143]
	v_mfma_f32_16x16x32_bf16 v[136:139], v[132:135], v[188:191], v[136:139]
	v_mfma_f32_16x16x32_bf16 v[112:115], v[124:127], v[198:201], v[112:115]
	v_mfma_f32_16x16x32_bf16 v[104:107], v[132:135], v[198:201], v[104:107]
	v_mfma_f32_16x16x32_bf16 v[96:99], v[124:127], v[206:209], v[96:99]
	v_mfma_f32_16x16x32_bf16 v[88:91], v[132:135], v[206:209], v[88:91]
	v_mfma_f32_16x16x32_bf16 v[80:83], v[124:127], v[214:217], v[80:83]
	v_mfma_f32_16x16x32_bf16 v[72:75], v[132:135], v[214:217], v[72:75]
	s_setprio 0
	s_setprio 1
	v_mfma_f32_16x16x32_bf16 v[116:119], v[160:163], v[184:187], v[116:119]
	v_mfma_f32_16x16x32_bf16 v[108:111], v[176:179], v[184:187], v[108:111]
	v_mfma_f32_16x16x32_bf16 v[100:103], v[160:163], v[194:197], v[100:103]
	v_mfma_f32_16x16x32_bf16 v[92:95], v[176:179], v[194:197], v[92:95]
	v_mfma_f32_16x16x32_bf16 v[84:87], v[160:163], v[202:205], v[84:87]
	v_mfma_f32_16x16x32_bf16 v[76:79], v[176:179], v[202:205], v[76:79]
	v_mfma_f32_16x16x32_bf16 v[68:71], v[160:163], v[210:213], v[68:71]
	v_mfma_f32_16x16x32_bf16 v[64:67], v[176:179], v[210:213], v[64:67]
	v_mfma_f32_16x16x32_bf16 v[116:119], v[172:175], v[188:191], v[116:119]
	v_mfma_f32_16x16x32_bf16 v[108:111], v[180:183], v[188:191], v[108:111]
	v_mfma_f32_16x16x32_bf16 v[100:103], v[172:175], v[198:201], v[100:103]
	v_mfma_f32_16x16x32_bf16 v[92:95], v[180:183], v[198:201], v[92:95]
	v_mfma_f32_16x16x32_bf16 v[84:87], v[172:175], v[206:209], v[84:87]
	v_mfma_f32_16x16x32_bf16 v[76:79], v[180:183], v[206:209], v[76:79]
	v_mfma_f32_16x16x32_bf16 v[68:71], v[172:175], v[214:217], v[68:71]
	v_mfma_f32_16x16x32_bf16 v[64:67], v[180:183], v[214:217], v[64:67]
	s_setprio 0
	s_barrier
; #define PG8_STAGE(bufoff, gbase, voff) do { _Pragma("unroll") for (int _i = 0; _i < 2; ++_i) \
;         __builtin_amdgcn_global_load_lds((const unsigned*)((const char*)(gbase) + (voff)[_i]), (PG8_LAS unsigned*)(lds + (bufoff) + ldsw + _i * 8192), 16, 0, 0); } while (0)
; #define PG8_LDA(dst, b, h) do { _Pragma("unroll") for (int m = 0; m < 4; ++m) _Pragma("unroll") for (int k = 0; k < 2; ++k) dst[m][k] = *(const PG8_LAS bf16x8*)(lds + PG8_SA(b, h) + aoff + m * 2048 + k * 1024); } while (0)
; #define PG8_LDB(dst, b, h) do { _Pragma("unroll") for (int n = 0; n < 2; ++n) _Pragma("unroll") for (int k = 0; k < 2; ++k) dst[n][k] = *(const PG8_LAS bf16x8*)(lds + PG8_SB(b, h) + boff + n * 2048 + k * 1024); } while (0)
; template <class Epi, class Sched, bool ALIGN_EPI = false, bool SP2 = false>
; __device__ __forceinline__ void gemm_phase(PG8_LAS unsigned char* lds, const Gemm g, const Sched& S, const Epi& E) {
;     ...
;         for (int t = 0; t < nt; t += 2) {
;             const bool last = (t == nt - 2);
;             const char* a1 = cA + (size_t)(t + 1) * kstep;
;             const char* a2 = last ? nA : cA + (size_t)(t + 2) * kstep; const char* b2 = last ? nB : cB + (size_t)(t + 2) * kstep;
;             const char* a3 = a2 + kstep; const char* b3 = b2 + kstep;
;             if (last && has_next) S.a_ready(nxt);
;             if constexpr (SP2) {
;             PG8_LDB(B0, 0, 0); PG8_LDB(B1, 0, 1); PG8_SCHED; PG8_LDA(At, 0, 0); PG8_STAGE(PG8_SA(1, 1), a1 + hstep, voffA);
;             PG8_WAIT_V(8); PG8_WAIT_L(0); PG8_BAR; PG8_MMA(0, 0, At, B0); PG8_MMA(0, 1, At, B1); PG8_BAR; PG8_SCHED;
;             PG8_LDA(At, 0, 1); PG8_STAGE(PG8_SB(0, 0), b2, voffB); PG8_STAGE(PG8_SB(0, 1), b2 + hstep, voffB); PG8_STAGE(PG8_SA(0, 0), a2, voffA);
;             PG8_WAIT_V(8); PG8_WAIT_L(0); PG8_BAR; PG8_MMA(1, 0, At, B0); PG8_MMA(1, 1, At, B1); PG8_BAR; PG8_SCHED;
;             PG8_LDB(B0, 1, 0); PG8_LDB(B1, 1, 1); PG8_SCHED; PG8_LDA(At, 1, 0); PG8_STAGE(PG8_SA(0, 1), a2 + hstep, voffA);
;             PG8_WAIT_V(8); PG8_WAIT_L(0); PG8_BAR; PG8_MMA(0, 0, At, B0); PG8_MMA(0, 1, At, B1); PG8_BAR; PG8_SCHED;
;             PG8_LDA(At, 1, 1); PG8_STAGE(PG8_SB(1, 0), b3, voffB); PG8_STAGE(PG8_SB(1, 1), b3 + hstep, voffB); PG8_STAGE(PG8_SA(1, 0), a3, voffA);
;             PG8_WAIT_V(8); PG8_WAIT_L(0); PG8_BAR; PG8_MMA(1, 0, At, B0); PG8_MMA(1, 1, At, B1); PG8_BAR; PG8_SCHED;
	s_add_i32 s50, s78, s58
	v_lshl_add_u64 v[164:165], v[164:165], 0, s[14:15]
	s_mov_b32 m0, s50
	ds_read_b128 v[184:187], v171 offset:49152
	ds_read_b128 v[188:191], v171 offset:50176
	ds_read_b128 v[194:197], v171 offset:51200
	ds_read_b128 v[198:201], v171 offset:52224
	ds_read_b128 v[202:205], v171 offset:53248
	ds_read_b128 v[206:209], v171 offset:54272
	ds_read_b128 v[210:213], v171 offset:55296
	ds_read_b128 v[214:217], v171 offset:56320
	global_load_lds_dwordx4 v[164:165], off
	s_add_i32 m0, s50, 0x2000
	s_add_u32 s48, s48, 0x80080
	v_lshl_add_u64 v[164:165], v[218:219], 0, s[14:15]
	s_addc_u32 s49, s49, 0
	s_add_i32 s50, s79, s58
	global_load_lds_dwordx4 v[164:165], off
	v_lshl_add_u64 v[164:165], s[48:49], 0, v[146:147]
	s_mov_b32 m0, s50
	s_nop 0
	global_load_lds_dwordx4 v[164:165], off
	v_lshl_add_u64 v[164:165], s[48:49], 0, v[150:151]
	s_add_i32 m0, s50, 0x2000
	s_nop 0
	global_load_lds_dwordx4 v[164:165], off
	v_lshl_add_u64 v[164:165], v[220:221], 0, s[14:15]
	s_mov_b32 m0, s64
	s_nop 0
	global_load_lds_dwordx4 v[164:165], off
	v_lshl_add_u64 v[164:165], v[222:223], 0, s[14:15]
	s_mov_b32 m0, s65
	s_nop 0
	global_load_lds_dwordx4 v[164:165], off
	s_waitcnt vmcnt(8)
	s_waitcnt lgkmcnt(0)
	s_barrier
	s_setprio 1
	s_waitcnt lgkmcnt(0)
	v_mfma_f32_16x16x32_bf16 v[60:63], v[120:123], v[184:187], v[60:63]
	v_mfma_f32_16x16x32_bf16 v[56:59], v[128:131], v[184:187], v[56:59]
	v_mfma_f32_16x16x32_bf16 v[48:51], v[120:123], v[194:197], v[48:51]
	v_mfma_f32_16x16x32_bf16 v[40:43], v[128:131], v[194:197], v[40:43]
	v_mfma_f32_16x16x32_bf16 v[32:35], v[120:123], v[202:205], v[32:35]
	v_mfma_f32_16x16x32_bf16 v[24:27], v[128:131], v[202:205], v[24:27]
	v_mfma_f32_16x16x32_bf16 v[16:19], v[120:123], v[210:213], v[16:19]
	v_mfma_f32_16x16x32_bf16 v[8:11], v[128:131], v[210:213], v[8:11]
	v_mfma_f32_16x16x32_bf16 v[60:63], v[124:127], v[188:191], v[60:63]
	v_mfma_f32_16x16x32_bf16 v[56:59], v[132:135], v[188:191], v[56:59]
	v_mfma_f32_16x16x32_bf16 v[48:51], v[124:127], v[198:201], v[48:51]
	v_mfma_f32_16x16x32_bf16 v[40:43], v[132:135], v[198:201], v[40:43]
	v_mfma_f32_16x16x32_bf16 v[32:35], v[124:127], v[206:209], v[32:35]
	v_mfma_f32_16x16x32_bf16 v[24:27], v[132:135], v[206:209], v[24:27]
	v_mfma_f32_16x16x32_bf16 v[16:19], v[124:127], v[214:217], v[16:19]
	v_mfma_f32_16x16x32_bf16 v[8:11], v[132:135], v[214:217], v[8:11]
	s_setprio 0
	s_setprio 1
	v_mfma_f32_16x16x32_bf16 v[52:55], v[160:163], v[184:187], v[52:55]
	v_mfma_f32_16x16x32_bf16 v[44:47], v[176:179], v[184:187], v[44:47]
	v_mfma_f32_16x16x32_bf16 v[36:39], v[160:163], v[194:197], v[36:39]
	v_mfma_f32_16x16x32_bf16 v[28:31], v[176:179], v[194:197], v[28:31]
	v_mfma_f32_16x16x32_bf16 v[20:23], v[160:163], v[202:205], v[20:23]
	v_mfma_f32_16x16x32_bf16 v[12:15], v[176:179], v[202:205], v[12:15]
	v_mfma_f32_16x16x32_bf16 v[4:7], v[160:163], v[210:213], v[4:7]
	v_mfma_f32_16x16x32_bf16 v[0:3], v[176:179], v[210:213], v[0:3]
	v_mfma_f32_16x16x32_bf16 v[52:55], v[172:175], v[188:191], v[52:55]
	v_mfma_f32_16x16x32_bf16 v[44:47], v[180:183], v[188:191], v[44:47]
	v_mfma_f32_16x16x32_bf16 v[36:39], v[172:175], v[198:201], v[36:39]
	v_mfma_f32_16x16x32_bf16 v[28:31], v[180:183], v[198:201], v[28:31]
	v_mfma_f32_16x16x32_bf16 v[20:23], v[172:175], v[206:209], v[20:23]
	v_mfma_f32_16x16x32_bf16 v[12:15], v[180:183], v[206:209], v[12:15]
	v_mfma_f32_16x16x32_bf16 v[4:7], v[172:175], v[214:217], v[4:7]
	v_mfma_f32_16x16x32_bf16 v[0:3], v[180:183], v[214:217], v[0:3]
	s_add_i32 s77, s77, 2
	s_add_u32 s75, s75, 0x100
	s_addc_u32 s76, s76, 0
	s_add_u32 s46, s46, 0x100
	s_addc_u32 s47, s47, 0
	s_cmp_gt_u32 s77, 29
	s_setprio 0
	s_barrier
	s_cbranch_scc1 .Lpeel_exit_5
.LBB0_1042:
	ds_read_b128 v[120:123], v169
	ds_read_b128 v[124:127], v169 offset:1024
	ds_read_b128 v[128:131], v169 offset:2048
	ds_read_b128 v[132:135], v169 offset:3072
	ds_read_b128 v[160:163], v170
	ds_read_b128 v[172:175], v170 offset:1024
	ds_read_b128 v[176:179], v170 offset:2048
	ds_read_b128 v[180:183], v170 offset:3072
	s_add_u32 s48, s46, 0xfff80080
	s_addc_u32 s49, s47, -1
	s_cmp_eq_u32 s77, 28
	s_cselect_b32 s51, s25, s49
	s_cselect_b32 s50, s73, s48
	s_cselect_b32 s49, s27, s76
	s_cselect_b32 s48, s74, s75
	v_lshl_add_u64 v[164:165], s[46:47], 0, v[154:155]
	s_add_i32 m0, s35, 0xc000
	ds_read_b128 v[184:187], v171
	ds_read_b128 v[188:191], v171 offset:1024
	ds_read_b128 v[194:197], v171 offset:2048
	ds_read_b128 v[198:201], v171 offset:3072
	ds_read_b128 v[202:205], v171 offset:4096
	ds_read_b128 v[206:209], v171 offset:5120
	ds_read_b128 v[210:213], v171 offset:6144
	ds_read_b128 v[214:217], v171 offset:7168
	global_load_lds_dwordx4 v[164:165], off
	v_lshl_add_u64 v[164:165], s[46:47], 0, v[152:153]
	s_add_i32 m0, s35, 0xe000
	s_nop 0
	global_load_lds_dwordx4 v[164:165], off
	s_waitcnt vmcnt(8)
	s_waitcnt lgkmcnt(0)
	s_barrier
; #define PG8_STAGE(bufoff, gbase, voff) do { _Pragma("unroll") for (int _i = 0; _i < 2; ++_i) \
;         __builtin_amdgcn_global_load_lds((const unsigned*)((const char*)(gbase) + (voff)[_i]), (PG8_LAS unsigned*)(lds + (bufoff) + ldsw + _i * 8192), 16, 0, 0); } while (0)
; #define PG8_LDA(dst, b, h) do { _Pragma("unroll") for (int m = 0; m < 4; ++m) _Pragma("unroll") for (int k = 0; k < 2; ++k) dst[m][k] = *(const PG8_LAS bf16x8*)(lds + PG8_SA(b, h) + aoff + m * 2048 + k * 1024); } while (0)
; #define PG8_LDB(dst, b, h) do { _Pragma("unroll") for (int n = 0; n < 2; ++n) _Pragma("unroll") for (int k = 0; k < 2; ++k) dst[n][k] = *(const PG8_LAS bf16x8*)(lds + PG8_SB(b, h) + boff + n * 2048 + k * 1024); } while (0)
; #define PG8_MMA(ai, bj, At, Bt) do { __builtin_amdgcn_s_setprio(1); _Pragma("unroll") for (int m = 0; m < 4; ++m) _Pragma("unroll") for (int n = 0; n < 2; ++n) _Pragma("unroll") for (int k = 0; k < 2; ++k) \
;         acc[ai][bj][m][n] = __builtin_amdgcn_mfma_f32_16x16x32_bf16(Bt[n][k], At[m][k], acc[ai][bj][m][n], 0, 0, 0); __builtin_amdgcn_s_setprio(0); } while (0)
; #define PG8_WAIT_V(n) asm volatile("s_waitcnt vmcnt(" #n ")" ::: "memory")
; #define PG8_WAIT_L(n) asm volatile("s_waitcnt lgkmcnt(" #n ")" ::: "memory")
; #define PG8_BAR __builtin_amdgcn_s_barrier()
; #define PG8_SCHED __builtin_amdgcn_sched_barrier(0)
; template <class Epi, class Sched, bool ALIGN_EPI = false, bool SP2 = false>
; __device__ __forceinline__ void gemm_phase(PG8_LAS unsigned char* lds, const Gemm g, const Sched& S, const Epi& E) {
;     ...
;             PG8_WAIT_V(8); PG8_WAIT_L(0); PG8_BAR; PG8_MMA(0, 0, At, B0); PG8_MMA(0, 1, At, B1); PG8_BAR; PG8_SCHED;
;             PG8_LDA(At, 0, 1); PG8_STAGE(PG8_SB(0, 0), b2, voffB); PG8_STAGE(PG8_SB(0, 1), b2 + hstep, voffB); PG8_STAGE(PG8_SA(0, 0), a2, voffA);
;             PG8_WAIT_V(8); PG8_WAIT_L(0); PG8_BAR; PG8_MMA(1, 0, At, B0); PG8_MMA(1, 1, At, B1); PG8_BAR; PG8_SCHED;
;             PG8_LDB(B0, 1, 0); PG8_LDB(B1, 1, 1); PG8_SCHED; PG8_LDA(At, 1, 0); PG8_STAGE(PG8_SA(0, 1), a2 + hstep, voffA);
;             PG8_WAIT_V(8); PG8_WAIT_L(0); PG8_BAR; PG8_MMA(0, 0, At, B0); PG8_MMA(0, 1, At, B1); PG8_BAR; PG8_SCHED;
	s_setprio 1
	s_waitcnt lgkmcnt(0)
	v_mfma_f32_16x16x32_bf16 v[140:143], v[120:123], v[184:187], v[140:143]
	v_mfma_f32_16x16x32_bf16 v[136:139], v[128:131], v[184:187], v[136:139]
	v_mfma_f32_16x16x32_bf16 v[112:115], v[120:123], v[194:197], v[112:115]
	v_mfma_f32_16x16x32_bf16 v[104:107], v[128:131], v[194:197], v[104:107]
	v_mfma_f32_16x16x32_bf16 v[96:99], v[120:123], v[202:205], v[96:99]
	v_mfma_f32_16x16x32_bf16 v[88:91], v[128:131], v[202:205], v[88:91]
	v_mfma_f32_16x16x32_bf16 v[80:83], v[120:123], v[210:213], v[80:83]
	v_mfma_f32_16x16x32_bf16 v[72:75], v[128:131], v[210:213], v[72:75]
	v_mfma_f32_16x16x32_bf16 v[140:143], v[124:127], v[188:191], v[140:143]
	v_mfma_f32_16x16x32_bf16 v[136:139], v[132:135], v[188:191], v[136:139]
	v_mfma_f32_16x16x32_bf16 v[112:115], v[124:127], v[198:201], v[112:115]
	v_mfma_f32_16x16x32_bf16 v[104:107], v[132:135], v[198:201], v[104:107]
	v_mfma_f32_16x16x32_bf16 v[96:99], v[124:127], v[206:209], v[96:99]
	v_mfma_f32_16x16x32_bf16 v[88:91], v[132:135], v[206:209], v[88:91]
	v_mfma_f32_16x16x32_bf16 v[80:83], v[124:127], v[214:217], v[80:83]
	v_mfma_f32_16x16x32_bf16 v[72:75], v[132:135], v[214:217], v[72:75]
	s_setprio 0
	s_setprio 1
	v_mfma_f32_16x16x32_bf16 v[116:119], v[160:163], v[184:187], v[116:119]
	v_mfma_f32_16x16x32_bf16 v[108:111], v[176:179], v[184:187], v[108:111]
	v_mfma_f32_16x16x32_bf16 v[100:103], v[160:163], v[194:197], v[100:103]
	v_mfma_f32_16x16x32_bf16 v[92:95], v[176:179], v[194:197], v[92:95]
	v_mfma_f32_16x16x32_bf16 v[84:87], v[160:163], v[202:205], v[84:87]
	v_mfma_f32_16x16x32_bf16 v[76:79], v[176:179], v[202:205], v[76:79]
	v_mfma_f32_16x16x32_bf16 v[68:71], v[160:163], v[210:213], v[68:71]
	v_mfma_f32_16x16x32_bf16 v[64:67], v[176:179], v[210:213], v[64:67]
	v_mfma_f32_16x16x32_bf16 v[116:119], v[172:175], v[188:191], v[116:119]
	v_mfma_f32_16x16x32_bf16 v[108:111], v[180:183], v[188:191], v[108:111]
	v_mfma_f32_16x16x32_bf16 v[100:103], v[172:175], v[198:201], v[100:103]
	v_mfma_f32_16x16x32_bf16 v[92:95], v[180:183], v[198:201], v[92:95]
	v_mfma_f32_16x16x32_bf16 v[84:87], v[172:175], v[206:209], v[84:87]
	v_mfma_f32_16x16x32_bf16 v[76:79], v[180:183], v[206:209], v[76:79]
	v_mfma_f32_16x16x32_bf16 v[68:71], v[172:175], v[214:217], v[68:71]
	v_mfma_f32_16x16x32_bf16 v[64:67], v[180:183], v[214:217], v[64:67]
	s_setprio 0
	s_barrier
	s_add_i32 s78, s67, s58
	v_lshl_add_u64 v[164:165], s[48:49], 0, v[146:147]
	s_mov_b32 m0, s78
	ds_read_b128 v[184:187], v171 offset:16384
	ds_read_b128 v[188:191], v171 offset:17408
	ds_read_b128 v[194:197], v171 offset:18432
	ds_read_b128 v[198:201], v171 offset:19456
	ds_read_b128 v[202:205], v171 offset:20480
	ds_read_b128 v[206:209], v171 offset:21504
	ds_read_b128 v[210:213], v171 offset:22528
	ds_read_b128 v[214:217], v171 offset:23552
	global_load_lds_dwordx4 v[164:165], off
	s_add_i32 m0, s78, 0x2000
	s_add_u32 s78, s48, 0x80000
	v_lshl_add_u64 v[218:219], s[48:49], 0, v[150:151]
	s_addc_u32 s79, s49, 0
	s_add_i32 s80, s68, s58
	global_load_lds_dwordx4 v[218:219], off
	v_lshl_add_u64 v[220:221], s[78:79], 0, v[146:147]
	s_mov_b32 m0, s80
	v_lshl_add_u64 v[222:223], s[50:51], 0, v[148:149]
	global_load_lds_dwordx4 v[220:221], off
	v_lshl_add_u64 v[220:221], s[78:79], 0, v[150:151]
	s_add_i32 m0, s80, 0x2000
	s_nop 0
	global_load_lds_dwordx4 v[220:221], off
	v_lshl_add_u64 v[220:221], s[50:51], 0, v[144:145]
	s_mov_b32 m0, s35
	s_nop 0
	global_load_lds_dwordx4 v[220:221], off
	s_mov_b32 m0, s37
	s_nop 0
	global_load_lds_dwordx4 v[222:223], off
	s_waitcnt vmcnt(8)
	s_waitcnt lgkmcnt(0)
	s_barrier
	s_setprio 1
	s_waitcnt lgkmcnt(0)
	v_mfma_f32_16x16x32_bf16 v[60:63], v[120:123], v[184:187], v[60:63]
	v_mfma_f32_16x16x32_bf16 v[56:59], v[128:131], v[184:187], v[56:59]
	v_mfma_f32_16x16x32_bf16 v[48:51], v[120:123], v[194:197], v[48:51]
	v_mfma_f32_16x16x32_bf16 v[40:43], v[128:131], v[194:197], v[40:43]
	v_mfma_f32_16x16x32_bf16 v[32:35], v[120:123], v[202:205], v[32:35]
	v_mfma_f32_16x16x32_bf16 v[24:27], v[128:131], v[202:205], v[24:27]
	v_mfma_f32_16x16x32_bf16 v[16:19], v[120:123], v[210:213], v[16:19]
	v_mfma_f32_16x16x32_bf16 v[8:11], v[128:131], v[210:213], v[8:11]
	v_mfma_f32_16x16x32_bf16 v[60:63], v[124:127], v[188:191], v[60:63]
	v_mfma_f32_16x16x32_bf16 v[56:59], v[132:135], v[188:191], v[56:59]
	v_mfma_f32_16x16x32_bf16 v[48:51], v[124:127], v[198:201], v[48:51]
	v_mfma_f32_16x16x32_bf16 v[40:43], v[132:135], v[198:201], v[40:43]
	v_mfma_f32_16x16x32_bf16 v[32:35], v[124:127], v[206:209], v[32:35]
	v_mfma_f32_16x16x32_bf16 v[24:27], v[132:135], v[206:209], v[24:27]
	v_mfma_f32_16x16x32_bf16 v[16:19], v[124:127], v[214:217], v[16:19]
	v_mfma_f32_16x16x32_bf16 v[8:11], v[132:135], v[214:217], v[8:11]
	s_setprio 0
	s_setprio 1
	v_mfma_f32_16x16x32_bf16 v[52:55], v[160:163], v[184:187], v[52:55]
	v_mfma_f32_16x16x32_bf16 v[44:47], v[176:179], v[184:187], v[44:47]
	v_mfma_f32_16x16x32_bf16 v[36:39], v[160:163], v[194:197], v[36:39]
	v_mfma_f32_16x16x32_bf16 v[28:31], v[176:179], v[194:197], v[28:31]
	v_mfma_f32_16x16x32_bf16 v[20:23], v[160:163], v[202:205], v[20:23]
	v_mfma_f32_16x16x32_bf16 v[12:15], v[176:179], v[202:205], v[12:15]
	v_mfma_f32_16x16x32_bf16 v[4:7], v[160:163], v[210:213], v[4:7]
	v_mfma_f32_16x16x32_bf16 v[0:3], v[176:179], v[210:213], v[0:3]
	v_mfma_f32_16x16x32_bf16 v[52:55], v[172:175], v[188:191], v[52:55]
	v_mfma_f32_16x16x32_bf16 v[44:47], v[180:183], v[188:191], v[44:47]
	v_mfma_f32_16x16x32_bf16 v[36:39], v[172:175], v[198:201], v[36:39]
	v_mfma_f32_16x16x32_bf16 v[28:31], v[180:183], v[198:201], v[28:31]
	v_mfma_f32_16x16x32_bf16 v[20:23], v[172:175], v[206:209], v[20:23]
	v_mfma_f32_16x16x32_bf16 v[12:15], v[180:183], v[206:209], v[12:15]
	v_mfma_f32_16x16x32_bf16 v[4:7], v[172:175], v[214:217], v[4:7]
	v_mfma_f32_16x16x32_bf16 v[0:3], v[180:183], v[214:217], v[0:3]
	s_setprio 0
	s_barrier
; #define PG8_STAGE(bufoff, gbase, voff) do { _Pragma("unroll") for (int _i = 0; _i < 2; ++_i) \
;         __builtin_amdgcn_global_load_lds((const unsigned*)((const char*)(gbase) + (voff)[_i]), (PG8_LAS unsigned*)(lds + (bufoff) + ldsw + _i * 8192), 16, 0, 0); } while (0)
; #define PG8_LDA(dst, b, h) do { _Pragma("unroll") for (int m = 0; m < 4; ++m) _Pragma("unroll") for (int k = 0; k < 2; ++k) dst[m][k] = *(const PG8_LAS bf16x8*)(lds + PG8_SA(b, h) + aoff + m * 2048 + k * 1024); } while (0)
; #define PG8_LDB(dst, b, h) do { _Pragma("unroll") for (int n = 0; n < 2; ++n) _Pragma("unroll") for (int k = 0; k < 2; ++k) dst[n][k] = *(const PG8_LAS bf16x8*)(lds + PG8_SB(b, h) + boff + n * 2048 + k * 1024); } while (0)
; #define PG8_MMA(ai, bj, At, Bt) do { __builtin_amdgcn_s_setprio(1); _Pragma("unroll") for (int m = 0; m < 4; ++m) _Pragma("unroll") for (int n = 0; n < 2; ++n) _Pragma("unroll") for (int k = 0; k < 2; ++k) \
;         acc[ai][bj][m][n] = __builtin_amdgcn_mfma_f32_16x16x32_bf16(Bt[n][k], At[m][k], acc[ai][bj][m][n], 0, 0, 0); __builtin_amdgcn_s_setprio(0); } while (0)
; #define PG8_WAIT_V(n) asm volatile("s_waitcnt vmcnt(" #n ")" ::: "memory")
; #define PG8_WAIT_L(n) asm volatile("s_waitcnt lgkmcnt(" #n ")" ::: "memory")
; #define PG8_BAR __builtin_amdgcn_s_barrier()
; #define PG8_SCHED __builtin_amdgcn_sched_barrier(0)
; template <class Epi, class Sched, bool ALIGN_EPI = false, bool SP2 = false>
; __device__ __forceinline__ void gemm_phase(PG8_LAS unsigned char* lds, const Gemm g, const Sched& S, const Epi& E) {
;     ...
;             PG8_LDB(B0, 1, 0); PG8_LDB(B1, 1, 1); PG8_SCHED; PG8_LDA(At, 1, 0); PG8_STAGE(PG8_SA(0, 1), a2 + hstep, voffA);
;             PG8_WAIT_V(8); PG8_WAIT_L(0); PG8_BAR; PG8_MMA(0, 0, At, B0); PG8_MMA(0, 1, At, B1); PG8_BAR; PG8_SCHED;
	s_add_i32 s78, 0, 0x18000
	s_add_i32 s79, 0, 0x1c000
	v_add_u32_e32 v132, s78, v167
	v_add_u32_e32 v180, s79, v167
	ds_read_b128 v[120:123], v132
	ds_read_b128 v[124:127], v132 offset:1024
	ds_read_b128 v[128:131], v132 offset:2048
	ds_read_b128 v[132:135], v132 offset:3072
	ds_read_b128 v[160:163], v180
	ds_read_b128 v[172:175], v180 offset:1024
	ds_read_b128 v[176:179], v180 offset:2048
	ds_read_b128 v[180:183], v180 offset:3072
	s_add_u32 s50, s50, 0x80000
	s_addc_u32 s51, s51, 0
	s_mov_b32 m0, s59
	v_lshl_add_u64 v[224:225], s[50:51], 0, v[144:145]
	ds_read_b128 v[184:187], v171 offset:32768
	ds_read_b128 v[188:191], v171 offset:33792
	ds_read_b128 v[194:197], v171 offset:34816
	ds_read_b128 v[198:201], v171 offset:35840
	ds_read_b128 v[202:205], v171 offset:36864
	ds_read_b128 v[206:209], v171 offset:37888
	ds_read_b128 v[210:213], v171 offset:38912
	ds_read_b128 v[214:217], v171 offset:39936
	global_load_lds_dwordx4 v[224:225], off
	v_lshl_add_u64 v[224:225], s[50:51], 0, v[148:149]
	s_mov_b32 m0, s60
	s_nop 0
	global_load_lds_dwordx4 v[224:225], off
	s_waitcnt vmcnt(8)
	s_waitcnt lgkmcnt(0)
	s_barrier
	s_setprio 1
	s_waitcnt lgkmcnt(0)
	v_mfma_f32_16x16x32_bf16 v[140:143], v[120:123], v[184:187], v[140:143]
	v_mfma_f32_16x16x32_bf16 v[136:139], v[128:131], v[184:187], v[136:139]
	v_mfma_f32_16x16x32_bf16 v[112:115], v[120:123], v[194:197], v[112:115]
	v_mfma_f32_16x16x32_bf16 v[104:107], v[128:131], v[194:197], v[104:107]
	v_mfma_f32_16x16x32_bf16 v[96:99], v[120:123], v[202:205], v[96:99]
	v_mfma_f32_16x16x32_bf16 v[88:91], v[128:131], v[202:205], v[88:91]
	v_mfma_f32_16x16x32_bf16 v[80:83], v[120:123], v[210:213], v[80:83]
	v_mfma_f32_16x16x32_bf16 v[72:75], v[128:131], v[210:213], v[72:75]
	v_mfma_f32_16x16x32_bf16 v[140:143], v[124:127], v[188:191], v[140:143]
	v_mfma_f32_16x16x32_bf16 v[136:139], v[132:135], v[188:191], v[136:139]
	v_mfma_f32_16x16x32_bf16 v[112:115], v[124:127], v[198:201], v[112:115]
	v_mfma_f32_16x16x32_bf16 v[104:107], v[132:135], v[198:201], v[104:107]
	v_mfma_f32_16x16x32_bf16 v[96:99], v[124:127], v[206:209], v[96:99]
	v_mfma_f32_16x16x32_bf16 v[88:91], v[132:135], v[206:209], v[88:91]
	v_mfma_f32_16x16x32_bf16 v[80:83], v[124:127], v[214:217], v[80:83]
	v_mfma_f32_16x16x32_bf16 v[72:75], v[132:135], v[214:217], v[72:75]
	s_setprio 0
	s_setprio 1
	v_mfma_f32_16x16x32_bf16 v[116:119], v[160:163], v[184:187], v[116:119]
	v_mfma_f32_16x16x32_bf16 v[108:111], v[176:179], v[184:187], v[108:111]
	v_mfma_f32_16x16x32_bf16 v[100:103], v[160:163], v[194:197], v[100:103]
	v_mfma_f32_16x16x32_bf16 v[92:95], v[176:179], v[194:197], v[92:95]
	v_mfma_f32_16x16x32_bf16 v[84:87], v[160:163], v[202:205], v[84:87]
	v_mfma_f32_16x16x32_bf16 v[76:79], v[176:179], v[202:205], v[76:79]
	v_mfma_f32_16x16x32_bf16 v[68:71], v[160:163], v[210:213], v[68:71]
	v_mfma_f32_16x16x32_bf16 v[64:67], v[176:179], v[210:213], v[64:67]
	v_mfma_f32_16x16x32_bf16 v[116:119], v[172:175], v[188:191], v[116:119]
	v_mfma_f32_16x16x32_bf16 v[108:111], v[180:183], v[188:191], v[108:111]
	v_mfma_f32_16x16x32_bf16 v[100:103], v[172:175], v[198:201], v[100:103]
	v_mfma_f32_16x16x32_bf16 v[92:95], v[180:183], v[198:201], v[92:95]
	v_mfma_f32_16x16x32_bf16 v[84:87], v[172:175], v[206:209], v[84:87]
	v_mfma_f32_16x16x32_bf16 v[76:79], v[180:183], v[206:209], v[76:79]
	v_mfma_f32_16x16x32_bf16 v[68:71], v[172:175], v[214:217], v[68:71]
	v_mfma_f32_16x16x32_bf16 v[64:67], v[180:183], v[214:217], v[64:67]
	s_setprio 0
	s_barrier
; #define PG8_STAGE(bufoff, gbase, voff) do { _Pragma("unroll") for (int _i = 0; _i < 2; ++_i) \
;         __builtin_amdgcn_global_load_lds((const unsigned*)((const char*)(gbase) + (voff)[_i]), (PG8_LAS unsigned*)(lds + (bufoff) + ldsw + _i * 8192), 16, 0, 0); } while (0)
; #define PG8_LDA(dst, b, h) do { _Pragma("unroll") for (int m = 0; m < 4; ++m) _Pragma("unroll") for (int k = 0; k < 2; ++k) dst[m][k] = *(const PG8_LAS bf16x8*)(lds + PG8_SA(b, h) + aoff + m * 2048 + k * 1024); } while (0)
; #define PG8_MMA(ai, bj, At, Bt) do { __builtin_amdgcn_s_setprio(1); _Pragma("unroll") for (int m = 0; m < 4; ++m) _Pragma("unroll") for (int n = 0; n < 2; ++n) _Pragma("unroll") for (int k = 0; k < 2; ++k) \
;         acc[ai][bj][m][n] = __builtin_amdgcn_mfma_f32_16x16x32_bf16(Bt[n][k], At[m][k], acc[ai][bj][m][n], 0, 0, 0); __builtin_amdgcn_s_setprio(0); } while (0)
; #define PG8_WAIT_V(n) asm volatile("s_waitcnt vmcnt(" #n ")" ::: "memory")
; #define PG8_WAIT_L(n) asm volatile("s_waitcnt lgkmcnt(" #n ")" ::: "memory")
; #define PG8_BAR __builtin_amdgcn_s_barrier()
; #define PG8_SCHED __builtin_amdgcn_sched_barrier(0)
; template <class Epi, class Sched, bool ALIGN_EPI = false, bool SP2 = false>
; __device__ __forceinline__ void gemm_phase(PG8_LAS unsigned char* lds, const Gemm g, const Sched& S, const Epi& E) {
;     ...
;         for (int t = 0; t < nt; t += 2) {
;             const bool last = (t == nt - 2);
;             const char* a1 = cA + (size_t)(t + 1) * kstep;
;             const char* a2 = last ? nA : cA + (size_t)(t + 2) * kstep; const char* b2 = last ? nB : cB + (size_t)(t + 2) * kstep;
;     ...
;             PG8_LDA(At, 1, 1); PG8_STAGE(PG8_SB(1, 0), b3, voffB); PG8_STAGE(PG8_SB(1, 1), b3 + hstep, voffB); PG8_STAGE(PG8_SA(1, 0), a3, voffA);
;             PG8_WAIT_V(8); PG8_WAIT_L(0); PG8_BAR; PG8_MMA(1, 0, At, B0); PG8_MMA(1, 1, At, B1); PG8_BAR; PG8_SCHED;
	s_add_i32 s50, s78, s58
	v_lshl_add_u64 v[164:165], v[164:165], 0, s[14:15]
	s_mov_b32 m0, s50
	ds_read_b128 v[184:187], v171 offset:49152
	ds_read_b128 v[188:191], v171 offset:50176
	ds_read_b128 v[194:197], v171 offset:51200
	ds_read_b128 v[198:201], v171 offset:52224
	ds_read_b128 v[202:205], v171 offset:53248
	ds_read_b128 v[206:209], v171 offset:54272
	ds_read_b128 v[210:213], v171 offset:55296
	ds_read_b128 v[214:217], v171 offset:56320
	global_load_lds_dwordx4 v[164:165], off
	s_add_i32 m0, s50, 0x2000
	s_add_u32 s48, s48, 0x80080
	v_lshl_add_u64 v[164:165], v[218:219], 0, s[14:15]
	s_addc_u32 s49, s49, 0
	s_add_i32 s50, s79, s58
	global_load_lds_dwordx4 v[164:165], off
	v_lshl_add_u64 v[164:165], s[48:49], 0, v[146:147]
	s_mov_b32 m0, s50
	s_nop 0
	global_load_lds_dwordx4 v[164:165], off
	v_lshl_add_u64 v[164:165], s[48:49], 0, v[150:151]
	s_add_i32 m0, s50, 0x2000
	s_nop 0
	global_load_lds_dwordx4 v[164:165], off
	v_lshl_add_u64 v[164:165], v[220:221], 0, s[14:15]
	s_mov_b32 m0, s64
	s_nop 0
	global_load_lds_dwordx4 v[164:165], off
	v_lshl_add_u64 v[164:165], v[222:223], 0, s[14:15]
	s_mov_b32 m0, s65
	s_nop 0
	global_load_lds_dwordx4 v[164:165], off
	s_waitcnt vmcnt(8)
	s_waitcnt lgkmcnt(0)
	s_barrier
	s_setprio 1
	s_waitcnt lgkmcnt(0)
	v_mfma_f32_16x16x32_bf16 v[60:63], v[120:123], v[184:187], v[60:63]
	v_mfma_f32_16x16x32_bf16 v[56:59], v[128:131], v[184:187], v[56:59]
	v_mfma_f32_16x16x32_bf16 v[48:51], v[120:123], v[194:197], v[48:51]
	v_mfma_f32_16x16x32_bf16 v[40:43], v[128:131], v[194:197], v[40:43]
	v_mfma_f32_16x16x32_bf16 v[32:35], v[120:123], v[202:205], v[32:35]
	v_mfma_f32_16x16x32_bf16 v[24:27], v[128:131], v[202:205], v[24:27]
	v_mfma_f32_16x16x32_bf16 v[16:19], v[120:123], v[210:213], v[16:19]
	v_mfma_f32_16x16x32_bf16 v[8:11], v[128:131], v[210:213], v[8:11]
	v_mfma_f32_16x16x32_bf16 v[60:63], v[124:127], v[188:191], v[60:63]
	v_mfma_f32_16x16x32_bf16 v[56:59], v[132:135], v[188:191], v[56:59]
	v_mfma_f32_16x16x32_bf16 v[48:51], v[124:127], v[198:201], v[48:51]
	v_mfma_f32_16x16x32_bf16 v[40:43], v[132:135], v[198:201], v[40:43]
	v_mfma_f32_16x16x32_bf16 v[32:35], v[124:127], v[206:209], v[32:35]
	v_mfma_f32_16x16x32_bf16 v[24:27], v[132:135], v[206:209], v[24:27]
	v_mfma_f32_16x16x32_bf16 v[16:19], v[124:127], v[214:217], v[16:19]
	v_mfma_f32_16x16x32_bf16 v[8:11], v[132:135], v[214:217], v[8:11]
	s_setprio 0
	s_setprio 1
	v_mfma_f32_16x16x32_bf16 v[52:55], v[160:163], v[184:187], v[52:55]
	v_mfma_f32_16x16x32_bf16 v[44:47], v[176:179], v[184:187], v[44:47]
	v_mfma_f32_16x16x32_bf16 v[36:39], v[160:163], v[194:197], v[36:39]
	v_mfma_f32_16x16x32_bf16 v[28:31], v[176:179], v[194:197], v[28:31]
	v_mfma_f32_16x16x32_bf16 v[20:23], v[160:163], v[202:205], v[20:23]
	v_mfma_f32_16x16x32_bf16 v[12:15], v[176:179], v[202:205], v[12:15]
	v_mfma_f32_16x16x32_bf16 v[4:7], v[160:163], v[210:213], v[4:7]
	v_mfma_f32_16x16x32_bf16 v[0:3], v[176:179], v[210:213], v[0:3]
	v_mfma_f32_16x16x32_bf16 v[52:55], v[172:175], v[188:191], v[52:55]
	v_mfma_f32_16x16x32_bf16 v[44:47], v[180:183], v[188:191], v[44:47]
	v_mfma_f32_16x16x32_bf16 v[36:39], v[172:175], v[198:201], v[36:39]
	v_mfma_f32_16x16x32_bf16 v[28:31], v[180:183], v[198:201], v[28:31]
	v_mfma_f32_16x16x32_bf16 v[20:23], v[172:175], v[206:209], v[20:23]
	v_mfma_f32_16x16x32_bf16 v[12:15], v[180:183], v[206:209], v[12:15]
	v_mfma_f32_16x16x32_bf16 v[4:7], v[172:175], v[214:217], v[4:7]
	v_mfma_f32_16x16x32_bf16 v[0:3], v[180:183], v[214:217], v[0:3]
	s_add_i32 s77, s77, 2
	s_add_u32 s75, s75, 0x100
	s_addc_u32 s76, s76, 0
	s_add_u32 s46, s46, 0x100
	s_addc_u32 s47, s47, 0
	s_cmp_gt_u32 s77, 29
	s_setprio 0
	s_barrier
	s_cbranch_scc0 .LBB0_1042

; #define PG8_STAGE(bufoff, gbase, voff) do { _Pragma("unroll") for (int _i = 0; _i < 2; ++_i) \
;         __builtin_amdgcn_global_load_lds((const unsigned*)((const char*)(gbase) + (voff)[_i]), (PG8_LAS unsigned*)(lds + (bufoff) + ldsw + _i * 8192), 16, 0, 0); } while (0)
; #define PG8_LDA(dst, b, h) do { _Pragma("unroll") for (int m = 0; m < 4; ++m) _Pragma("unroll") for (int k = 0; k < 2; ++k) dst[m][k] = *(const PG8_LAS bf16x8*)(lds + PG8_SA(b, h) + aoff + m * 2048 + k * 1024); } while (0)
; #define PG8_LDB(dst, b, h) do { _Pragma("unroll") for (int n = 0; n < 2; ++n) _Pragma("unroll") for (int k = 0; k < 2; ++k) dst[n][k] = *(const PG8_LAS bf16x8*)(lds + PG8_SB(b, h) + boff + n * 2048 + k * 1024); } while (0)
; #define PG8_MMA(ai, bj, At, Bt) do { __builtin_amdgcn_s_setprio(1); _Pragma("unroll") for (int m = 0; m < 4; ++m) _Pragma("unroll") for (int n = 0; n < 2; ++n) _Pragma("unroll") for (int k = 0; k < 2; ++k) \
;         acc[ai][bj][m][n] = __builtin_amdgcn_mfma_f32_16x16x32_bf16(Bt[n][k], At[m][k], acc[ai][bj][m][n], 0, 0, 0); __builtin_amdgcn_s_setprio(0); } while (0)
; #define PG8_WAIT_V(n) asm volatile("s_waitcnt vmcnt(" #n ")" ::: "memory")
; #define PG8_WAIT_L(n) asm volatile("s_waitcnt lgkmcnt(" #n ")" ::: "memory")
; #define PG8_BAR __builtin_amdgcn_s_barrier()
; template <class Epi, class Sched, bool ALIGN_EPI = false, bool SP2 = false>
; __device__ __forceinline__ void gemm_phase(PG8_LAS unsigned char* lds, const Gemm g, const Sched& S, const Epi& E) {
;     ...
;         const bool has_next = S.next(ui + 1, nxt);
;         const char* nA = has_next ? (const char*)g.A + (size_t)nxt.pm * tstep : cA; const char* nB = has_next ? (const char*)g.Bt + (size_t)nxt.pn * tstep : cB;
;         for (int t = 0; t < nt; t += 2) {
;             const bool last = (t == nt - 2);
;             const char* a1 = cA + (size_t)(t + 1) * kstep;
;             const char* a2 = last ? nA : cA + (size_t)(t + 2) * kstep; const char* b2 = last ? nB : cB + (size_t)(t + 2) * kstep;
;             const char* a3 = a2 + kstep; const char* b3 = b2 + kstep;
;             if (last && has_next) S.a_ready(nxt);
;             if constexpr (SP2) {
;             PG8_LDB(B0, 0, 0); PG8_LDB(B1, 0, 1); PG8_SCHED; PG8_LDA(At, 0, 0); PG8_STAGE(PG8_SA(1, 1), a1 + hstep, voffA);
;             PG8_WAIT_V(8); PG8_WAIT_L(0); PG8_BAR; PG8_MMA(0, 0, At, B0); PG8_MMA(0, 1, At, B1); PG8_BAR; PG8_SCHED;
.LBB0_1169:
	s_ashr_i32 s17, s16, 31
	s_lshl_b64 s[20:21], s[16:17], 20
	s_add_u32 s20, s37, s20
	s_addc_u32 s21, s46, s21
	s_and_b64 s[22:23], s[6:7], exec
	s_cselect_b32 s17, s21, s31
	s_cselect_b32 s61, s20, s30
	s_ashr_i32 s19, s18, 31
	s_lshl_b64 s[22:23], s[18:19], 20
	s_add_u32 s22, s47, s22
	s_addc_u32 s23, s48, s23
	s_and_b64 s[34:35], s[6:7], exec
	s_cselect_b32 s19, s23, s29
	s_cselect_b32 s62, s22, s28
	s_add_u32 s63, s28, 0x100
	s_addc_u32 s64, s29, 0
	s_add_u32 s28, s30, 0x80080
	s_addc_u32 s29, s31, 0
	s_mov_b32 s65, -2
	ds_read_b128 v[144:147], v151
	ds_read_b128 v[154:157], v151 offset:1024
	ds_read_b128 v[158:161], v151 offset:2048
	ds_read_b128 v[162:165], v151 offset:3072
	ds_read_b128 v[166:169], v152
	ds_read_b128 v[170:173], v152 offset:1024
	ds_read_b128 v[174:177], v152 offset:2048
	ds_read_b128 v[178:181], v152 offset:3072
	s_add_u32 s30, s28, 0xfff80080
	s_addc_u32 s31, s29, -1
	s_cmp_eq_u32 s65, 28
	s_cselect_b32 s35, s17, s31
	s_cselect_b32 s34, s61, s30
	s_cselect_b32 s31, s19, s64
	s_cselect_b32 s30, s62, s63
	v_lshl_add_u64 v[190:191], s[28:29], 0, v[138:139]
	s_add_i32 m0, s25, 0xc000
	ds_read_b128 v[182:185], v153
	ds_read_b128 v[186:189], v153 offset:1024
	ds_read_b128 v[194:197], v153 offset:2048
	ds_read_b128 v[198:201], v153 offset:3072
	ds_read_b128 v[202:205], v153 offset:4096
	ds_read_b128 v[206:209], v153 offset:5120
	ds_read_b128 v[210:213], v153 offset:6144
	ds_read_b128 v[214:217], v153 offset:7168
	global_load_lds_dwordx4 v[190:191], off
	v_lshl_add_u64 v[190:191], s[28:29], 0, v[136:137]
	s_add_i32 m0, s25, 0xe000
	s_nop 0
	global_load_lds_dwordx4 v[190:191], off
	s_waitcnt vmcnt(8)
	s_waitcnt lgkmcnt(0)
	s_barrier
	s_setprio 1
	s_waitcnt lgkmcnt(0)
	v_mfma_f32_16x16x32_bf16 v[124:127], v[144:147], v[182:185], 0
	v_mfma_f32_16x16x32_bf16 v[120:123], v[158:161], v[182:185], 0
	v_mfma_f32_16x16x32_bf16 v[108:111], v[144:147], v[194:197], 0
	v_mfma_f32_16x16x32_bf16 v[104:107], v[158:161], v[194:197], 0
	v_mfma_f32_16x16x32_bf16 v[92:95], v[144:147], v[202:205], 0
	v_mfma_f32_16x16x32_bf16 v[88:91], v[158:161], v[202:205], 0
	v_mfma_f32_16x16x32_bf16 v[76:79], v[144:147], v[210:213], 0
	v_mfma_f32_16x16x32_bf16 v[72:75], v[158:161], v[210:213], 0
	v_mfma_f32_16x16x32_bf16 v[124:127], v[154:157], v[186:189], v[124:127]
	v_mfma_f32_16x16x32_bf16 v[120:123], v[162:165], v[186:189], v[120:123]
	v_mfma_f32_16x16x32_bf16 v[108:111], v[154:157], v[198:201], v[108:111]
	v_mfma_f32_16x16x32_bf16 v[104:107], v[162:165], v[198:201], v[104:107]
	v_mfma_f32_16x16x32_bf16 v[92:95], v[154:157], v[206:209], v[92:95]
	v_mfma_f32_16x16x32_bf16 v[88:91], v[162:165], v[206:209], v[88:91]
	v_mfma_f32_16x16x32_bf16 v[76:79], v[154:157], v[214:217], v[76:79]
	v_mfma_f32_16x16x32_bf16 v[72:75], v[162:165], v[214:217], v[72:75]
	s_setprio 0
	s_setprio 1
	v_mfma_f32_16x16x32_bf16 v[116:119], v[166:169], v[182:185], 0
	v_mfma_f32_16x16x32_bf16 v[112:115], v[174:177], v[182:185], 0
	v_mfma_f32_16x16x32_bf16 v[100:103], v[166:169], v[194:197], 0
	v_mfma_f32_16x16x32_bf16 v[96:99], v[174:177], v[194:197], 0
	v_mfma_f32_16x16x32_bf16 v[84:87], v[166:169], v[202:205], 0
	v_mfma_f32_16x16x32_bf16 v[80:83], v[174:177], v[202:205], 0
	v_mfma_f32_16x16x32_bf16 v[68:71], v[166:169], v[210:213], 0
	v_mfma_f32_16x16x32_bf16 v[64:67], v[174:177], v[210:213], 0
	v_mfma_f32_16x16x32_bf16 v[116:119], v[170:173], v[186:189], v[116:119]
	v_mfma_f32_16x16x32_bf16 v[112:115], v[178:181], v[186:189], v[112:115]
	v_mfma_f32_16x16x32_bf16 v[100:103], v[170:173], v[198:201], v[100:103]
	v_mfma_f32_16x16x32_bf16 v[96:99], v[178:181], v[198:201], v[96:99]
	v_mfma_f32_16x16x32_bf16 v[84:87], v[170:173], v[206:209], v[84:87]
	v_mfma_f32_16x16x32_bf16 v[80:83], v[178:181], v[206:209], v[80:83]
	v_mfma_f32_16x16x32_bf16 v[68:71], v[170:173], v[214:217], v[68:71]
	v_mfma_f32_16x16x32_bf16 v[64:67], v[178:181], v[214:217], v[64:67]
	s_setprio 0
	s_barrier
	s_add_i32 s66, s58, s49
	v_lshl_add_u64 v[190:191], s[30:31], 0, v[132:133]
	s_mov_b32 m0, s66
	ds_read_b128 v[182:185], v153 offset:16384
	ds_read_b128 v[186:189], v153 offset:17408
	ds_read_b128 v[194:197], v153 offset:18432
	ds_read_b128 v[198:201], v153 offset:19456
	ds_read_b128 v[202:205], v153 offset:20480
	ds_read_b128 v[206:209], v153 offset:21504
	ds_read_b128 v[210:213], v153 offset:22528
	ds_read_b128 v[214:217], v153 offset:23552
	global_load_lds_dwordx4 v[190:191], off
	s_add_i32 m0, s66, 0x2000
	s_add_u32 s66, s30, 0x80000
	v_lshl_add_u64 v[218:219], s[30:31], 0, v[128:129]
	s_addc_u32 s67, s31, 0
	s_add_i32 s68, s59, s49
	global_load_lds_dwordx4 v[218:219], off
	v_lshl_add_u64 v[220:221], s[66:67], 0, v[132:133]
	s_mov_b32 m0, s68
	v_lshl_add_u64 v[222:223], s[34:35], 0, v[130:131]
	global_load_lds_dwordx4 v[220:221], off
	v_lshl_add_u64 v[220:221], s[66:67], 0, v[128:129]
	s_add_i32 m0, s68, 0x2000
	s_nop 0
	global_load_lds_dwordx4 v[220:221], off
	v_lshl_add_u64 v[220:221], s[34:35], 0, v[134:135]
	s_mov_b32 m0, s25
	s_nop 0
	global_load_lds_dwordx4 v[220:221], off
	s_mov_b32 m0, s27
	s_nop 0
	global_load_lds_dwordx4 v[222:223], off
	s_waitcnt vmcnt(8)
	s_waitcnt lgkmcnt(0)
	s_barrier
; #define PG8_STAGE(bufoff, gbase, voff) do { _Pragma("unroll") for (int _i = 0; _i < 2; ++_i) \
;         __builtin_amdgcn_global_load_lds((const unsigned*)((const char*)(gbase) + (voff)[_i]), (PG8_LAS unsigned*)(lds + (bufoff) + ldsw + _i * 8192), 16, 0, 0); } while (0)
; #define PG8_LDA(dst, b, h) do { _Pragma("unroll") for (int m = 0; m < 4; ++m) _Pragma("unroll") for (int k = 0; k < 2; ++k) dst[m][k] = *(const PG8_LAS bf16x8*)(lds + PG8_SA(b, h) + aoff + m * 2048 + k * 1024); } while (0)
; #define PG8_LDB(dst, b, h) do { _Pragma("unroll") for (int n = 0; n < 2; ++n) _Pragma("unroll") for (int k = 0; k < 2; ++k) dst[n][k] = *(const PG8_LAS bf16x8*)(lds + PG8_SB(b, h) + boff + n * 2048 + k * 1024); } while (0)
; #define PG8_MMA(ai, bj, At, Bt) do { __builtin_amdgcn_s_setprio(1); _Pragma("unroll") for (int m = 0; m < 4; ++m) _Pragma("unroll") for (int n = 0; n < 2; ++n) _Pragma("unroll") for (int k = 0; k < 2; ++k) \
;         acc[ai][bj][m][n] = __builtin_amdgcn_mfma_f32_16x16x32_bf16(Bt[n][k], At[m][k], acc[ai][bj][m][n], 0, 0, 0); __builtin_amdgcn_s_setprio(0); } while (0)
; #define PG8_WAIT_V(n) asm volatile("s_waitcnt vmcnt(" #n ")" ::: "memory")
; #define PG8_WAIT_L(n) asm volatile("s_waitcnt lgkmcnt(" #n ")" ::: "memory")
; #define PG8_BAR __builtin_amdgcn_s_barrier()
; #define PG8_SCHED __builtin_amdgcn_sched_barrier(0)
; template <class Epi, class Sched, bool ALIGN_EPI = false, bool SP2 = false>
; __device__ __forceinline__ void gemm_phase(PG8_LAS unsigned char* lds, const Gemm g, const Sched& S, const Epi& E) {
;     ...
;             PG8_WAIT_V(8); PG8_WAIT_L(0); PG8_BAR; PG8_MMA(0, 0, At, B0); PG8_MMA(0, 1, At, B1); PG8_BAR; PG8_SCHED;
;             PG8_LDA(At, 0, 1); PG8_STAGE(PG8_SB(0, 0), b2, voffB); PG8_STAGE(PG8_SB(0, 1), b2 + hstep, voffB); PG8_STAGE(PG8_SA(0, 0), a2, voffA);
;             PG8_WAIT_V(8); PG8_WAIT_L(0); PG8_BAR; PG8_MMA(1, 0, At, B0); PG8_MMA(1, 1, At, B1); PG8_BAR; PG8_SCHED;
;             PG8_LDB(B0, 1, 0); PG8_LDB(B1, 1, 1); PG8_SCHED; PG8_LDA(At, 1, 0); PG8_STAGE(PG8_SA(0, 1), a2 + hstep, voffA);
;             PG8_WAIT_V(8); PG8_WAIT_L(0); PG8_BAR; PG8_MMA(0, 0, At, B0); PG8_MMA(0, 1, At, B1); PG8_BAR; PG8_SCHED;
	s_setprio 1
	s_waitcnt lgkmcnt(0)
	v_mfma_f32_16x16x32_bf16 v[60:63], v[144:147], v[182:185], 0
	v_mfma_f32_16x16x32_bf16 v[56:59], v[158:161], v[182:185], 0
	v_mfma_f32_16x16x32_bf16 v[44:47], v[144:147], v[194:197], 0
	v_mfma_f32_16x16x32_bf16 v[40:43], v[158:161], v[194:197], 0
	v_mfma_f32_16x16x32_bf16 v[28:31], v[144:147], v[202:205], 0
	v_mfma_f32_16x16x32_bf16 v[24:27], v[158:161], v[202:205], 0
	v_mfma_f32_16x16x32_bf16 v[12:15], v[144:147], v[210:213], 0
	v_mfma_f32_16x16x32_bf16 v[8:11], v[158:161], v[210:213], 0
	v_mfma_f32_16x16x32_bf16 v[60:63], v[154:157], v[186:189], v[60:63]
	v_mfma_f32_16x16x32_bf16 v[56:59], v[162:165], v[186:189], v[56:59]
	v_mfma_f32_16x16x32_bf16 v[44:47], v[154:157], v[198:201], v[44:47]
	v_mfma_f32_16x16x32_bf16 v[40:43], v[162:165], v[198:201], v[40:43]
	v_mfma_f32_16x16x32_bf16 v[28:31], v[154:157], v[206:209], v[28:31]
	v_mfma_f32_16x16x32_bf16 v[24:27], v[162:165], v[206:209], v[24:27]
	v_mfma_f32_16x16x32_bf16 v[12:15], v[154:157], v[214:217], v[12:15]
	v_mfma_f32_16x16x32_bf16 v[8:11], v[162:165], v[214:217], v[8:11]
	s_setprio 0
	s_setprio 1
	v_mfma_f32_16x16x32_bf16 v[52:55], v[166:169], v[182:185], 0
	v_mfma_f32_16x16x32_bf16 v[48:51], v[174:177], v[182:185], 0
	v_mfma_f32_16x16x32_bf16 v[36:39], v[166:169], v[194:197], 0
	v_mfma_f32_16x16x32_bf16 v[32:35], v[174:177], v[194:197], 0
	v_mfma_f32_16x16x32_bf16 v[20:23], v[166:169], v[202:205], 0
	v_mfma_f32_16x16x32_bf16 v[16:19], v[174:177], v[202:205], 0
	v_mfma_f32_16x16x32_bf16 v[4:7], v[166:169], v[210:213], 0
	v_mfma_f32_16x16x32_bf16 v[0:3], v[174:177], v[210:213], 0
	v_mfma_f32_16x16x32_bf16 v[52:55], v[170:173], v[186:189], v[52:55]
	v_mfma_f32_16x16x32_bf16 v[48:51], v[178:181], v[186:189], v[48:51]
	v_mfma_f32_16x16x32_bf16 v[36:39], v[170:173], v[198:201], v[36:39]
	v_mfma_f32_16x16x32_bf16 v[32:35], v[178:181], v[198:201], v[32:35]
	v_mfma_f32_16x16x32_bf16 v[20:23], v[170:173], v[206:209], v[20:23]
	v_mfma_f32_16x16x32_bf16 v[16:19], v[178:181], v[206:209], v[16:19]
	v_mfma_f32_16x16x32_bf16 v[4:7], v[170:173], v[214:217], v[4:7]
	v_mfma_f32_16x16x32_bf16 v[0:3], v[178:181], v[214:217], v[0:3]
	s_setprio 0
	s_barrier
	s_add_i32 s66, 0, 0x18000
	s_add_i32 s67, 0, 0x1c000
	v_add_u32_e32 v162, s66, v149
	v_add_u32_e32 v178, s67, v149
	ds_read_b128 v[144:147], v162
	ds_read_b128 v[154:157], v162 offset:1024
	ds_read_b128 v[158:161], v162 offset:2048
	ds_read_b128 v[162:165], v162 offset:3072
	ds_read_b128 v[166:169], v178
	ds_read_b128 v[170:173], v178 offset:1024
	ds_read_b128 v[174:177], v178 offset:2048
	ds_read_b128 v[178:181], v178 offset:3072
	s_add_u32 s34, s34, 0x80000
	s_addc_u32 s35, s35, 0
	s_mov_b32 m0, s52
	v_lshl_add_u64 v[224:225], s[34:35], 0, v[134:135]
	ds_read_b128 v[182:185], v153 offset:32768
	ds_read_b128 v[186:189], v153 offset:33792
	ds_read_b128 v[194:197], v153 offset:34816
	ds_read_b128 v[198:201], v153 offset:35840
	ds_read_b128 v[202:205], v153 offset:36864
	ds_read_b128 v[206:209], v153 offset:37888
	ds_read_b128 v[210:213], v153 offset:38912
	ds_read_b128 v[214:217], v153 offset:39936
	global_load_lds_dwordx4 v[224:225], off
	v_lshl_add_u64 v[224:225], s[34:35], 0, v[130:131]
	s_mov_b32 m0, s53
	s_nop 0
	global_load_lds_dwordx4 v[224:225], off
	s_waitcnt vmcnt(8)
	s_waitcnt lgkmcnt(0)
	s_barrier
	s_setprio 1
	s_waitcnt lgkmcnt(0)
	v_mfma_f32_16x16x32_bf16 v[124:127], v[144:147], v[182:185], v[124:127]
	v_mfma_f32_16x16x32_bf16 v[120:123], v[158:161], v[182:185], v[120:123]
	v_mfma_f32_16x16x32_bf16 v[108:111], v[144:147], v[194:197], v[108:111]
	v_mfma_f32_16x16x32_bf16 v[104:107], v[158:161], v[194:197], v[104:107]
	v_mfma_f32_16x16x32_bf16 v[92:95], v[144:147], v[202:205], v[92:95]
	v_mfma_f32_16x16x32_bf16 v[88:91], v[158:161], v[202:205], v[88:91]
	v_mfma_f32_16x16x32_bf16 v[76:79], v[144:147], v[210:213], v[76:79]
	v_mfma_f32_16x16x32_bf16 v[72:75], v[158:161], v[210:213], v[72:75]
	v_mfma_f32_16x16x32_bf16 v[124:127], v[154:157], v[186:189], v[124:127]
	v_mfma_f32_16x16x32_bf16 v[120:123], v[162:165], v[186:189], v[120:123]
	v_mfma_f32_16x16x32_bf16 v[108:111], v[154:157], v[198:201], v[108:111]
	v_mfma_f32_16x16x32_bf16 v[104:107], v[162:165], v[198:201], v[104:107]
	v_mfma_f32_16x16x32_bf16 v[92:95], v[154:157], v[206:209], v[92:95]
	v_mfma_f32_16x16x32_bf16 v[88:91], v[162:165], v[206:209], v[88:91]
	v_mfma_f32_16x16x32_bf16 v[76:79], v[154:157], v[214:217], v[76:79]
	v_mfma_f32_16x16x32_bf16 v[72:75], v[162:165], v[214:217], v[72:75]
	s_setprio 0
	s_setprio 1
	v_mfma_f32_16x16x32_bf16 v[116:119], v[166:169], v[182:185], v[116:119]
	v_mfma_f32_16x16x32_bf16 v[112:115], v[174:177], v[182:185], v[112:115]
	v_mfma_f32_16x16x32_bf16 v[100:103], v[166:169], v[194:197], v[100:103]
	v_mfma_f32_16x16x32_bf16 v[96:99], v[174:177], v[194:197], v[96:99]
	v_mfma_f32_16x16x32_bf16 v[84:87], v[166:169], v[202:205], v[84:87]
	v_mfma_f32_16x16x32_bf16 v[80:83], v[174:177], v[202:205], v[80:83]
	v_mfma_f32_16x16x32_bf16 v[68:71], v[166:169], v[210:213], v[68:71]
	v_mfma_f32_16x16x32_bf16 v[64:67], v[174:177], v[210:213], v[64:67]
	v_mfma_f32_16x16x32_bf16 v[116:119], v[170:173], v[186:189], v[116:119]
	v_mfma_f32_16x16x32_bf16 v[112:115], v[178:181], v[186:189], v[112:115]
	v_mfma_f32_16x16x32_bf16 v[100:103], v[170:173], v[198:201], v[100:103]
	v_mfma_f32_16x16x32_bf16 v[96:99], v[178:181], v[198:201], v[96:99]
	v_mfma_f32_16x16x32_bf16 v[84:87], v[170:173], v[206:209], v[84:87]
	v_mfma_f32_16x16x32_bf16 v[80:83], v[178:181], v[206:209], v[80:83]
	v_mfma_f32_16x16x32_bf16 v[68:71], v[170:173], v[214:217], v[68:71]
	v_mfma_f32_16x16x32_bf16 v[64:67], v[178:181], v[214:217], v[64:67]
	s_setprio 0
	s_barrier
; #define PG8_STAGE(bufoff, gbase, voff) do { _Pragma("unroll") for (int _i = 0; _i < 2; ++_i) \
;         __builtin_amdgcn_global_load_lds((const unsigned*)((const char*)(gbase) + (voff)[_i]), (PG8_LAS unsigned*)(lds + (bufoff) + ldsw + _i * 8192), 16, 0, 0); } while (0)
; #define PG8_LDA(dst, b, h) do { _Pragma("unroll") for (int m = 0; m < 4; ++m) _Pragma("unroll") for (int k = 0; k < 2; ++k) dst[m][k] = *(const PG8_LAS bf16x8*)(lds + PG8_SA(b, h) + aoff + m * 2048 + k * 1024); } while (0)
; #define PG8_LDB(dst, b, h) do { _Pragma("unroll") for (int n = 0; n < 2; ++n) _Pragma("unroll") for (int k = 0; k < 2; ++k) dst[n][k] = *(const PG8_LAS bf16x8*)(lds + PG8_SB(b, h) + boff + n * 2048 + k * 1024); } while (0)
; template <class Epi, class Sched, bool ALIGN_EPI = false, bool SP2 = false>
; __device__ __forceinline__ void gemm_phase(PG8_LAS unsigned char* lds, const Gemm g, const Sched& S, const Epi& E) {
;     ...
;         for (int t = 0; t < nt; t += 2) {
;             const bool last = (t == nt - 2);
;             const char* a1 = cA + (size_t)(t + 1) * kstep;
;             const char* a2 = last ? nA : cA + (size_t)(t + 2) * kstep; const char* b2 = last ? nB : cB + (size_t)(t + 2) * kstep;
;             const char* a3 = a2 + kstep; const char* b3 = b2 + kstep;
;             if (last && has_next) S.a_ready(nxt);
;             if constexpr (SP2) {
;             PG8_LDB(B0, 0, 0); PG8_LDB(B1, 0, 1); PG8_SCHED; PG8_LDA(At, 0, 0); PG8_STAGE(PG8_SA(1, 1), a1 + hstep, voffA);
;             PG8_WAIT_V(8); PG8_WAIT_L(0); PG8_BAR; PG8_MMA(0, 0, At, B0); PG8_MMA(0, 1, At, B1); PG8_BAR; PG8_SCHED;
;             PG8_LDA(At, 0, 1); PG8_STAGE(PG8_SB(0, 0), b2, voffB); PG8_STAGE(PG8_SB(0, 1), b2 + hstep, voffB); PG8_STAGE(PG8_SA(0, 0), a2, voffA);
;             PG8_WAIT_V(8); PG8_WAIT_L(0); PG8_BAR; PG8_MMA(1, 0, At, B0); PG8_MMA(1, 1, At, B1); PG8_BAR; PG8_SCHED;
;             PG8_LDB(B0, 1, 0); PG8_LDB(B1, 1, 1); PG8_SCHED; PG8_LDA(At, 1, 0); PG8_STAGE(PG8_SA(0, 1), a2 + hstep, voffA);
;             PG8_WAIT_V(8); PG8_WAIT_L(0); PG8_BAR; PG8_MMA(0, 0, At, B0); PG8_MMA(0, 1, At, B1); PG8_BAR; PG8_SCHED;
;             PG8_LDA(At, 1, 1); PG8_STAGE(PG8_SB(1, 0), b3, voffB); PG8_STAGE(PG8_SB(1, 1), b3 + hstep, voffB); PG8_STAGE(PG8_SA(1, 0), a3, voffA);
;             PG8_WAIT_V(8); PG8_WAIT_L(0); PG8_BAR; PG8_MMA(1, 0, At, B0); PG8_MMA(1, 1, At, B1); PG8_BAR; PG8_SCHED;
	s_add_i32 s34, s66, s49
	v_lshl_add_u64 v[190:191], v[190:191], 0, s[12:13]
	s_mov_b32 m0, s34
	ds_read_b128 v[182:185], v153 offset:49152
	ds_read_b128 v[186:189], v153 offset:50176
	ds_read_b128 v[194:197], v153 offset:51200
	ds_read_b128 v[198:201], v153 offset:52224
	ds_read_b128 v[202:205], v153 offset:53248
	ds_read_b128 v[206:209], v153 offset:54272
	ds_read_b128 v[210:213], v153 offset:55296
	ds_read_b128 v[214:217], v153 offset:56320
	global_load_lds_dwordx4 v[190:191], off
	s_add_i32 m0, s34, 0x2000
	s_add_u32 s30, s30, 0x80080
	v_lshl_add_u64 v[190:191], v[218:219], 0, s[12:13]
	s_addc_u32 s31, s31, 0
	s_add_i32 s34, s67, s49
	global_load_lds_dwordx4 v[190:191], off
	v_lshl_add_u64 v[190:191], s[30:31], 0, v[132:133]
	s_mov_b32 m0, s34
	s_nop 0
	global_load_lds_dwordx4 v[190:191], off
	v_lshl_add_u64 v[190:191], s[30:31], 0, v[128:129]
	s_add_i32 m0, s34, 0x2000
	s_nop 0
	global_load_lds_dwordx4 v[190:191], off
	v_lshl_add_u64 v[190:191], v[220:221], 0, s[12:13]
	s_mov_b32 m0, s55
	s_nop 0
	global_load_lds_dwordx4 v[190:191], off
	v_lshl_add_u64 v[190:191], v[222:223], 0, s[12:13]
	s_mov_b32 m0, s56
	s_nop 0
	global_load_lds_dwordx4 v[190:191], off
	s_waitcnt vmcnt(8)
	s_waitcnt lgkmcnt(0)
	s_barrier
	s_setprio 1
	s_waitcnt lgkmcnt(0)
	v_mfma_f32_16x16x32_bf16 v[60:63], v[144:147], v[182:185], v[60:63]
	v_mfma_f32_16x16x32_bf16 v[56:59], v[158:161], v[182:185], v[56:59]
	v_mfma_f32_16x16x32_bf16 v[44:47], v[144:147], v[194:197], v[44:47]
	v_mfma_f32_16x16x32_bf16 v[40:43], v[158:161], v[194:197], v[40:43]
	v_mfma_f32_16x16x32_bf16 v[28:31], v[144:147], v[202:205], v[28:31]
	v_mfma_f32_16x16x32_bf16 v[24:27], v[158:161], v[202:205], v[24:27]
	v_mfma_f32_16x16x32_bf16 v[12:15], v[144:147], v[210:213], v[12:15]
	v_mfma_f32_16x16x32_bf16 v[8:11], v[158:161], v[210:213], v[8:11]
	v_mfma_f32_16x16x32_bf16 v[60:63], v[154:157], v[186:189], v[60:63]
	v_mfma_f32_16x16x32_bf16 v[56:59], v[162:165], v[186:189], v[56:59]
	v_mfma_f32_16x16x32_bf16 v[44:47], v[154:157], v[198:201], v[44:47]
	v_mfma_f32_16x16x32_bf16 v[40:43], v[162:165], v[198:201], v[40:43]
	v_mfma_f32_16x16x32_bf16 v[28:31], v[154:157], v[206:209], v[28:31]
	v_mfma_f32_16x16x32_bf16 v[24:27], v[162:165], v[206:209], v[24:27]
	v_mfma_f32_16x16x32_bf16 v[12:15], v[154:157], v[214:217], v[12:15]
	v_mfma_f32_16x16x32_bf16 v[8:11], v[162:165], v[214:217], v[8:11]
	s_setprio 0
	s_setprio 1
	v_mfma_f32_16x16x32_bf16 v[52:55], v[166:169], v[182:185], v[52:55]
	v_mfma_f32_16x16x32_bf16 v[48:51], v[174:177], v[182:185], v[48:51]
	v_mfma_f32_16x16x32_bf16 v[36:39], v[166:169], v[194:197], v[36:39]
	v_mfma_f32_16x16x32_bf16 v[32:35], v[174:177], v[194:197], v[32:35]
	v_mfma_f32_16x16x32_bf16 v[20:23], v[166:169], v[202:205], v[20:23]
	v_mfma_f32_16x16x32_bf16 v[16:19], v[174:177], v[202:205], v[16:19]
	v_mfma_f32_16x16x32_bf16 v[4:7], v[166:169], v[210:213], v[4:7]
	v_mfma_f32_16x16x32_bf16 v[0:3], v[174:177], v[210:213], v[0:3]
	v_mfma_f32_16x16x32_bf16 v[52:55], v[170:173], v[186:189], v[52:55]
	v_mfma_f32_16x16x32_bf16 v[48:51], v[178:181], v[186:189], v[48:51]
	v_mfma_f32_16x16x32_bf16 v[36:39], v[170:173], v[198:201], v[36:39]
	v_mfma_f32_16x16x32_bf16 v[32:35], v[178:181], v[198:201], v[32:35]
	v_mfma_f32_16x16x32_bf16 v[20:23], v[170:173], v[206:209], v[20:23]
	v_mfma_f32_16x16x32_bf16 v[16:19], v[178:181], v[206:209], v[16:19]
	v_mfma_f32_16x16x32_bf16 v[4:7], v[170:173], v[214:217], v[4:7]
	v_mfma_f32_16x16x32_bf16 v[0:3], v[178:181], v[214:217], v[0:3]
	s_add_i32 s65, s65, 2
	s_add_u32 s63, s63, 0x100
	s_addc_u32 s64, s64, 0
	s_add_u32 s28, s28, 0x100
	s_addc_u32 s29, s29, 0
	s_cmp_gt_u32 s65, 29
	s_setprio 0
	s_barrier
	s_cbranch_scc1 .Lpeel_exit_6
.LBB0_1170:
	ds_read_b128 v[144:147], v151
	ds_read_b128 v[154:157], v151 offset:1024
	ds_read_b128 v[158:161], v151 offset:2048
	ds_read_b128 v[162:165], v151 offset:3072
	ds_read_b128 v[166:169], v152
	ds_read_b128 v[170:173], v152 offset:1024
	ds_read_b128 v[174:177], v152 offset:2048
	ds_read_b128 v[178:181], v152 offset:3072
	s_add_u32 s30, s28, 0xfff80080
	s_addc_u32 s31, s29, -1
	s_cmp_eq_u32 s65, 28
	s_cselect_b32 s35, s17, s31
	s_cselect_b32 s34, s61, s30
	s_cselect_b32 s31, s19, s64
	s_cselect_b32 s30, s62, s63
	v_lshl_add_u64 v[190:191], s[28:29], 0, v[138:139]
	s_add_i32 m0, s25, 0xc000
	ds_read_b128 v[182:185], v153
	ds_read_b128 v[186:189], v153 offset:1024
	ds_read_b128 v[194:197], v153 offset:2048
	ds_read_b128 v[198:201], v153 offset:3072
	ds_read_b128 v[202:205], v153 offset:4096
	ds_read_b128 v[206:209], v153 offset:5120
	ds_read_b128 v[210:213], v153 offset:6144
	ds_read_b128 v[214:217], v153 offset:7168
	global_load_lds_dwordx4 v[190:191], off
	v_lshl_add_u64 v[190:191], s[28:29], 0, v[136:137]
	s_add_i32 m0, s25, 0xe000
	s_nop 0
	global_load_lds_dwordx4 v[190:191], off
	s_waitcnt vmcnt(8)
	s_waitcnt lgkmcnt(0)
	s_barrier
; #define PG8_STAGE(bufoff, gbase, voff) do { _Pragma("unroll") for (int _i = 0; _i < 2; ++_i) \
;         __builtin_amdgcn_global_load_lds((const unsigned*)((const char*)(gbase) + (voff)[_i]), (PG8_LAS unsigned*)(lds + (bufoff) + ldsw + _i * 8192), 16, 0, 0); } while (0)
; #define PG8_LDA(dst, b, h) do { _Pragma("unroll") for (int m = 0; m < 4; ++m) _Pragma("unroll") for (int k = 0; k < 2; ++k) dst[m][k] = *(const PG8_LAS bf16x8*)(lds + PG8_SA(b, h) + aoff + m * 2048 + k * 1024); } while (0)
; #define PG8_LDB(dst, b, h) do { _Pragma("unroll") for (int n = 0; n < 2; ++n) _Pragma("unroll") for (int k = 0; k < 2; ++k) dst[n][k] = *(const PG8_LAS bf16x8*)(lds + PG8_SB(b, h) + boff + n * 2048 + k * 1024); } while (0)
; #define PG8_MMA(ai, bj, At, Bt) do { __builtin_amdgcn_s_setprio(1); _Pragma("unroll") for (int m = 0; m < 4; ++m) _Pragma("unroll") for (int n = 0; n < 2; ++n) _Pragma("unroll") for (int k = 0; k < 2; ++k) \
;         acc[ai][bj][m][n] = __builtin_amdgcn_mfma_f32_16x16x32_bf16(Bt[n][k], At[m][k], acc[ai][bj][m][n], 0, 0, 0); __builtin_amdgcn_s_setprio(0); } while (0)
; #define PG8_WAIT_V(n) asm volatile("s_waitcnt vmcnt(" #n ")" ::: "memory")
; #define PG8_WAIT_L(n) asm volatile("s_waitcnt lgkmcnt(" #n ")" ::: "memory")
; #define PG8_BAR __builtin_amdgcn_s_barrier()
; #define PG8_SCHED __builtin_amdgcn_sched_barrier(0)
; template <class Epi, class Sched, bool ALIGN_EPI = false, bool SP2 = false>
; __device__ __forceinline__ void gemm_phase(PG8_LAS unsigned char* lds, const Gemm g, const Sched& S, const Epi& E) {
;     ...
;             PG8_WAIT_V(8); PG8_WAIT_L(0); PG8_BAR; PG8_MMA(0, 0, At, B0); PG8_MMA(0, 1, At, B1); PG8_BAR; PG8_SCHED;
;             PG8_LDA(At, 0, 1); PG8_STAGE(PG8_SB(0, 0), b2, voffB); PG8_STAGE(PG8_SB(0, 1), b2 + hstep, voffB); PG8_STAGE(PG8_SA(0, 0), a2, voffA);
;             PG8_WAIT_V(8); PG8_WAIT_L(0); PG8_BAR; PG8_MMA(1, 0, At, B0); PG8_MMA(1, 1, At, B1); PG8_BAR; PG8_SCHED;
;             PG8_LDB(B0, 1, 0); PG8_LDB(B1, 1, 1); PG8_SCHED; PG8_LDA(At, 1, 0); PG8_STAGE(PG8_SA(0, 1), a2 + hstep, voffA);
;             PG8_WAIT_V(8); PG8_WAIT_L(0); PG8_BAR; PG8_MMA(0, 0, At, B0); PG8_MMA(0, 1, At, B1); PG8_BAR; PG8_SCHED;
	s_setprio 1
	s_waitcnt lgkmcnt(0)
	v_mfma_f32_16x16x32_bf16 v[124:127], v[144:147], v[182:185], v[124:127]
	v_mfma_f32_16x16x32_bf16 v[120:123], v[158:161], v[182:185], v[120:123]
	v_mfma_f32_16x16x32_bf16 v[108:111], v[144:147], v[194:197], v[108:111]
	v_mfma_f32_16x16x32_bf16 v[104:107], v[158:161], v[194:197], v[104:107]
	v_mfma_f32_16x16x32_bf16 v[92:95], v[144:147], v[202:205], v[92:95]
	v_mfma_f32_16x16x32_bf16 v[88:91], v[158:161], v[202:205], v[88:91]
	v_mfma_f32_16x16x32_bf16 v[76:79], v[144:147], v[210:213], v[76:79]
	v_mfma_f32_16x16x32_bf16 v[72:75], v[158:161], v[210:213], v[72:75]
	v_mfma_f32_16x16x32_bf16 v[124:127], v[154:157], v[186:189], v[124:127]
	v_mfma_f32_16x16x32_bf16 v[120:123], v[162:165], v[186:189], v[120:123]
	v_mfma_f32_16x16x32_bf16 v[108:111], v[154:157], v[198:201], v[108:111]
	v_mfma_f32_16x16x32_bf16 v[104:107], v[162:165], v[198:201], v[104:107]
	v_mfma_f32_16x16x32_bf16 v[92:95], v[154:157], v[206:209], v[92:95]
	v_mfma_f32_16x16x32_bf16 v[88:91], v[162:165], v[206:209], v[88:91]
	v_mfma_f32_16x16x32_bf16 v[76:79], v[154:157], v[214:217], v[76:79]
	v_mfma_f32_16x16x32_bf16 v[72:75], v[162:165], v[214:217], v[72:75]
	s_setprio 0
	s_setprio 1
	v_mfma_f32_16x16x32_bf16 v[116:119], v[166:169], v[182:185], v[116:119]
	v_mfma_f32_16x16x32_bf16 v[112:115], v[174:177], v[182:185], v[112:115]
	v_mfma_f32_16x16x32_bf16 v[100:103], v[166:169], v[194:197], v[100:103]
	v_mfma_f32_16x16x32_bf16 v[96:99], v[174:177], v[194:197], v[96:99]
	v_mfma_f32_16x16x32_bf16 v[84:87], v[166:169], v[202:205], v[84:87]
	v_mfma_f32_16x16x32_bf16 v[80:83], v[174:177], v[202:205], v[80:83]
	v_mfma_f32_16x16x32_bf16 v[68:71], v[166:169], v[210:213], v[68:71]
	v_mfma_f32_16x16x32_bf16 v[64:67], v[174:177], v[210:213], v[64:67]
	v_mfma_f32_16x16x32_bf16 v[116:119], v[170:173], v[186:189], v[116:119]
	v_mfma_f32_16x16x32_bf16 v[112:115], v[178:181], v[186:189], v[112:115]
	v_mfma_f32_16x16x32_bf16 v[100:103], v[170:173], v[198:201], v[100:103]
	v_mfma_f32_16x16x32_bf16 v[96:99], v[178:181], v[198:201], v[96:99]
	v_mfma_f32_16x16x32_bf16 v[84:87], v[170:173], v[206:209], v[84:87]
	v_mfma_f32_16x16x32_bf16 v[80:83], v[178:181], v[206:209], v[80:83]
	v_mfma_f32_16x16x32_bf16 v[68:71], v[170:173], v[214:217], v[68:71]
	v_mfma_f32_16x16x32_bf16 v[64:67], v[178:181], v[214:217], v[64:67]
	s_setprio 0
	s_barrier
	s_add_i32 s66, s58, s49
	v_lshl_add_u64 v[190:191], s[30:31], 0, v[132:133]
	s_mov_b32 m0, s66
	ds_read_b128 v[182:185], v153 offset:16384
	ds_read_b128 v[186:189], v153 offset:17408
	ds_read_b128 v[194:197], v153 offset:18432
	ds_read_b128 v[198:201], v153 offset:19456
	ds_read_b128 v[202:205], v153 offset:20480
	ds_read_b128 v[206:209], v153 offset:21504
	ds_read_b128 v[210:213], v153 offset:22528
	ds_read_b128 v[214:217], v153 offset:23552
	global_load_lds_dwordx4 v[190:191], off
	s_add_i32 m0, s66, 0x2000
	s_add_u32 s66, s30, 0x80000
	v_lshl_add_u64 v[218:219], s[30:31], 0, v[128:129]
	s_addc_u32 s67, s31, 0
	s_add_i32 s68, s59, s49
	global_load_lds_dwordx4 v[218:219], off
	v_lshl_add_u64 v[220:221], s[66:67], 0, v[132:133]
	s_mov_b32 m0, s68
	v_lshl_add_u64 v[222:223], s[34:35], 0, v[130:131]
	global_load_lds_dwordx4 v[220:221], off
	v_lshl_add_u64 v[220:221], s[66:67], 0, v[128:129]
	s_add_i32 m0, s68, 0x2000
	s_nop 0
	global_load_lds_dwordx4 v[220:221], off
	v_lshl_add_u64 v[220:221], s[34:35], 0, v[134:135]
	s_mov_b32 m0, s25
	s_nop 0
	global_load_lds_dwordx4 v[220:221], off
	s_mov_b32 m0, s27
	s_nop 0
	global_load_lds_dwordx4 v[222:223], off
	s_waitcnt vmcnt(8)
	s_waitcnt lgkmcnt(0)
	s_barrier
	s_setprio 1
	s_waitcnt lgkmcnt(0)
	v_mfma_f32_16x16x32_bf16 v[60:63], v[144:147], v[182:185], v[60:63]
	v_mfma_f32_16x16x32_bf16 v[56:59], v[158:161], v[182:185], v[56:59]
	v_mfma_f32_16x16x32_bf16 v[44:47], v[144:147], v[194:197], v[44:47]
	v_mfma_f32_16x16x32_bf16 v[40:43], v[158:161], v[194:197], v[40:43]
	v_mfma_f32_16x16x32_bf16 v[28:31], v[144:147], v[202:205], v[28:31]
	v_mfma_f32_16x16x32_bf16 v[24:27], v[158:161], v[202:205], v[24:27]
	v_mfma_f32_16x16x32_bf16 v[12:15], v[144:147], v[210:213], v[12:15]
	v_mfma_f32_16x16x32_bf16 v[8:11], v[158:161], v[210:213], v[8:11]
	v_mfma_f32_16x16x32_bf16 v[60:63], v[154:157], v[186:189], v[60:63]
	v_mfma_f32_16x16x32_bf16 v[56:59], v[162:165], v[186:189], v[56:59]
	v_mfma_f32_16x16x32_bf16 v[44:47], v[154:157], v[198:201], v[44:47]
	v_mfma_f32_16x16x32_bf16 v[40:43], v[162:165], v[198:201], v[40:43]
	v_mfma_f32_16x16x32_bf16 v[28:31], v[154:157], v[206:209], v[28:31]
	v_mfma_f32_16x16x32_bf16 v[24:27], v[162:165], v[206:209], v[24:27]
	v_mfma_f32_16x16x32_bf16 v[12:15], v[154:157], v[214:217], v[12:15]
	v_mfma_f32_16x16x32_bf16 v[8:11], v[162:165], v[214:217], v[8:11]
	s_setprio 0
	s_setprio 1
	v_mfma_f32_16x16x32_bf16 v[52:55], v[166:169], v[182:185], v[52:55]
	v_mfma_f32_16x16x32_bf16 v[48:51], v[174:177], v[182:185], v[48:51]
	v_mfma_f32_16x16x32_bf16 v[36:39], v[166:169], v[194:197], v[36:39]
	v_mfma_f32_16x16x32_bf16 v[32:35], v[174:177], v[194:197], v[32:35]
	v_mfma_f32_16x16x32_bf16 v[20:23], v[166:169], v[202:205], v[20:23]
	v_mfma_f32_16x16x32_bf16 v[16:19], v[174:177], v[202:205], v[16:19]
	v_mfma_f32_16x16x32_bf16 v[4:7], v[166:169], v[210:213], v[4:7]
	v_mfma_f32_16x16x32_bf16 v[0:3], v[174:177], v[210:213], v[0:3]
	v_mfma_f32_16x16x32_bf16 v[52:55], v[170:173], v[186:189], v[52:55]
	v_mfma_f32_16x16x32_bf16 v[48:51], v[178:181], v[186:189], v[48:51]
	v_mfma_f32_16x16x32_bf16 v[36:39], v[170:173], v[198:201], v[36:39]
	v_mfma_f32_16x16x32_bf16 v[32:35], v[178:181], v[198:201], v[32:35]
	v_mfma_f32_16x16x32_bf16 v[20:23], v[170:173], v[206:209], v[20:23]
	v_mfma_f32_16x16x32_bf16 v[16:19], v[178:181], v[206:209], v[16:19]
	v_mfma_f32_16x16x32_bf16 v[4:7], v[170:173], v[214:217], v[4:7]
	v_mfma_f32_16x16x32_bf16 v[0:3], v[178:181], v[214:217], v[0:3]
	s_setprio 0
	s_barrier
; #define PG8_STAGE(bufoff, gbase, voff) do { _Pragma("unroll") for (int _i = 0; _i < 2; ++_i) \
;         __builtin_amdgcn_global_load_lds((const unsigned*)((const char*)(gbase) + (voff)[_i]), (PG8_LAS unsigned*)(lds + (bufoff) + ldsw + _i * 8192), 16, 0, 0); } while (0)
; #define PG8_LDA(dst, b, h) do { _Pragma("unroll") for (int m = 0; m < 4; ++m) _Pragma("unroll") for (int k = 0; k < 2; ++k) dst[m][k] = *(const PG8_LAS bf16x8*)(lds + PG8_SA(b, h) + aoff + m * 2048 + k * 1024); } while (0)
; #define PG8_LDB(dst, b, h) do { _Pragma("unroll") for (int n = 0; n < 2; ++n) _Pragma("unroll") for (int k = 0; k < 2; ++k) dst[n][k] = *(const PG8_LAS bf16x8*)(lds + PG8_SB(b, h) + boff + n * 2048 + k * 1024); } while (0)
; #define PG8_MMA(ai, bj, At, Bt) do { __builtin_amdgcn_s_setprio(1); _Pragma("unroll") for (int m = 0; m < 4; ++m) _Pragma("unroll") for (int n = 0; n < 2; ++n) _Pragma("unroll") for (int k = 0; k < 2; ++k) \
;         acc[ai][bj][m][n] = __builtin_amdgcn_mfma_f32_16x16x32_bf16(Bt[n][k], At[m][k], acc[ai][bj][m][n], 0, 0, 0); __builtin_amdgcn_s_setprio(0); } while (0)
; #define PG8_WAIT_V(n) asm volatile("s_waitcnt vmcnt(" #n ")" ::: "memory")
; #define PG8_WAIT_L(n) asm volatile("s_waitcnt lgkmcnt(" #n ")" ::: "memory")
; #define PG8_BAR __builtin_amdgcn_s_barrier()
; #define PG8_SCHED __builtin_amdgcn_sched_barrier(0)
; template <class Epi, class Sched, bool ALIGN_EPI = false, bool SP2 = false>
; __device__ __forceinline__ void gemm_phase(PG8_LAS unsigned char* lds, const Gemm g, const Sched& S, const Epi& E) {
;     ...
;             PG8_LDB(B0, 1, 0); PG8_LDB(B1, 1, 1); PG8_SCHED; PG8_LDA(At, 1, 0); PG8_STAGE(PG8_SA(0, 1), a2 + hstep, voffA);
;             PG8_WAIT_V(8); PG8_WAIT_L(0); PG8_BAR; PG8_MMA(0, 0, At, B0); PG8_MMA(0, 1, At, B1); PG8_BAR; PG8_SCHED;
	s_add_i32 s66, 0, 0x18000
	s_add_i32 s67, 0, 0x1c000
	v_add_u32_e32 v162, s66, v149
	v_add_u32_e32 v178, s67, v149
	ds_read_b128 v[144:147], v162
	ds_read_b128 v[154:157], v162 offset:1024
	ds_read_b128 v[158:161], v162 offset:2048
	ds_read_b128 v[162:165], v162 offset:3072
	ds_read_b128 v[166:169], v178
	ds_read_b128 v[170:173], v178 offset:1024
	ds_read_b128 v[174:177], v178 offset:2048
	ds_read_b128 v[178:181], v178 offset:3072
	s_add_u32 s34, s34, 0x80000
	s_addc_u32 s35, s35, 0
	s_mov_b32 m0, s52
	v_lshl_add_u64 v[224:225], s[34:35], 0, v[134:135]
	ds_read_b128 v[182:185], v153 offset:32768
	ds_read_b128 v[186:189], v153 offset:33792
	ds_read_b128 v[194:197], v153 offset:34816
	ds_read_b128 v[198:201], v153 offset:35840
	ds_read_b128 v[202:205], v153 offset:36864
	ds_read_b128 v[206:209], v153 offset:37888
	ds_read_b128 v[210:213], v153 offset:38912
	ds_read_b128 v[214:217], v153 offset:39936
	global_load_lds_dwordx4 v[224:225], off
	v_lshl_add_u64 v[224:225], s[34:35], 0, v[130:131]
	s_mov_b32 m0, s53
	s_nop 0
	global_load_lds_dwordx4 v[224:225], off
	s_waitcnt vmcnt(8)
	s_waitcnt lgkmcnt(0)
	s_barrier
	s_setprio 1
	s_waitcnt lgkmcnt(0)
	v_mfma_f32_16x16x32_bf16 v[124:127], v[144:147], v[182:185], v[124:127]
	v_mfma_f32_16x16x32_bf16 v[120:123], v[158:161], v[182:185], v[120:123]
	v_mfma_f32_16x16x32_bf16 v[108:111], v[144:147], v[194:197], v[108:111]
	v_mfma_f32_16x16x32_bf16 v[104:107], v[158:161], v[194:197], v[104:107]
	v_mfma_f32_16x16x32_bf16 v[92:95], v[144:147], v[202:205], v[92:95]
	v_mfma_f32_16x16x32_bf16 v[88:91], v[158:161], v[202:205], v[88:91]
	v_mfma_f32_16x16x32_bf16 v[76:79], v[144:147], v[210:213], v[76:79]
	v_mfma_f32_16x16x32_bf16 v[72:75], v[158:161], v[210:213], v[72:75]
	v_mfma_f32_16x16x32_bf16 v[124:127], v[154:157], v[186:189], v[124:127]
	v_mfma_f32_16x16x32_bf16 v[120:123], v[162:165], v[186:189], v[120:123]
	v_mfma_f32_16x16x32_bf16 v[108:111], v[154:157], v[198:201], v[108:111]
	v_mfma_f32_16x16x32_bf16 v[104:107], v[162:165], v[198:201], v[104:107]
	v_mfma_f32_16x16x32_bf16 v[92:95], v[154:157], v[206:209], v[92:95]
	v_mfma_f32_16x16x32_bf16 v[88:91], v[162:165], v[206:209], v[88:91]
	v_mfma_f32_16x16x32_bf16 v[76:79], v[154:157], v[214:217], v[76:79]
	v_mfma_f32_16x16x32_bf16 v[72:75], v[162:165], v[214:217], v[72:75]
	s_setprio 0
	s_setprio 1
	v_mfma_f32_16x16x32_bf16 v[116:119], v[166:169], v[182:185], v[116:119]
	v_mfma_f32_16x16x32_bf16 v[112:115], v[174:177], v[182:185], v[112:115]
	v_mfma_f32_16x16x32_bf16 v[100:103], v[166:169], v[194:197], v[100:103]
	v_mfma_f32_16x16x32_bf16 v[96:99], v[174:177], v[194:197], v[96:99]
	v_mfma_f32_16x16x32_bf16 v[84:87], v[166:169], v[202:205], v[84:87]
	v_mfma_f32_16x16x32_bf16 v[80:83], v[174:177], v[202:205], v[80:83]
	v_mfma_f32_16x16x32_bf16 v[68:71], v[166:169], v[210:213], v[68:71]
	v_mfma_f32_16x16x32_bf16 v[64:67], v[174:177], v[210:213], v[64:67]
	v_mfma_f32_16x16x32_bf16 v[116:119], v[170:173], v[186:189], v[116:119]
	v_mfma_f32_16x16x32_bf16 v[112:115], v[178:181], v[186:189], v[112:115]
	v_mfma_f32_16x16x32_bf16 v[100:103], v[170:173], v[198:201], v[100:103]
	v_mfma_f32_16x16x32_bf16 v[96:99], v[178:181], v[198:201], v[96:99]
	v_mfma_f32_16x16x32_bf16 v[84:87], v[170:173], v[206:209], v[84:87]
	v_mfma_f32_16x16x32_bf16 v[80:83], v[178:181], v[206:209], v[80:83]
	v_mfma_f32_16x16x32_bf16 v[68:71], v[170:173], v[214:217], v[68:71]
	v_mfma_f32_16x16x32_bf16 v[64:67], v[178:181], v[214:217], v[64:67]
	s_setprio 0
	s_barrier
; #define PG8_STAGE(bufoff, gbase, voff) do { _Pragma("unroll") for (int _i = 0; _i < 2; ++_i) \
;         __builtin_amdgcn_global_load_lds((const unsigned*)((const char*)(gbase) + (voff)[_i]), (PG8_LAS unsigned*)(lds + (bufoff) + ldsw + _i * 8192), 16, 0, 0); } while (0)
; #define PG8_LDA(dst, b, h) do { _Pragma("unroll") for (int m = 0; m < 4; ++m) _Pragma("unroll") for (int k = 0; k < 2; ++k) dst[m][k] = *(const PG8_LAS bf16x8*)(lds + PG8_SA(b, h) + aoff + m * 2048 + k * 1024); } while (0)
; #define PG8_MMA(ai, bj, At, Bt) do { __builtin_amdgcn_s_setprio(1); _Pragma("unroll") for (int m = 0; m < 4; ++m) _Pragma("unroll") for (int n = 0; n < 2; ++n) _Pragma("unroll") for (int k = 0; k < 2; ++k) \
;         acc[ai][bj][m][n] = __builtin_amdgcn_mfma_f32_16x16x32_bf16(Bt[n][k], At[m][k], acc[ai][bj][m][n], 0, 0, 0); __builtin_amdgcn_s_setprio(0); } while (0)
; #define PG8_WAIT_V(n) asm volatile("s_waitcnt vmcnt(" #n ")" ::: "memory")
; #define PG8_WAIT_L(n) asm volatile("s_waitcnt lgkmcnt(" #n ")" ::: "memory")
; #define PG8_BAR __builtin_amdgcn_s_barrier()
; #define PG8_SCHED __builtin_amdgcn_sched_barrier(0)
; template <class Epi, class Sched, bool ALIGN_EPI = false, bool SP2 = false>
; __device__ __forceinline__ void gemm_phase(PG8_LAS unsigned char* lds, const Gemm g, const Sched& S, const Epi& E) {
;     ...
;         for (int t = 0; t < nt; t += 2) {
;             const bool last = (t == nt - 2);
;             const char* a1 = cA + (size_t)(t + 1) * kstep;
;             const char* a2 = last ? nA : cA + (size_t)(t + 2) * kstep; const char* b2 = last ? nB : cB + (size_t)(t + 2) * kstep;
;     ...
;             PG8_LDA(At, 1, 1); PG8_STAGE(PG8_SB(1, 0), b3, voffB); PG8_STAGE(PG8_SB(1, 1), b3 + hstep, voffB); PG8_STAGE(PG8_SA(1, 0), a3, voffA);
;             PG8_WAIT_V(8); PG8_WAIT_L(0); PG8_BAR; PG8_MMA(1, 0, At, B0); PG8_MMA(1, 1, At, B1); PG8_BAR; PG8_SCHED;
	s_add_i32 s34, s66, s49
	v_lshl_add_u64 v[190:191], v[190:191], 0, s[12:13]
	s_mov_b32 m0, s34
	ds_read_b128 v[182:185], v153 offset:49152
	ds_read_b128 v[186:189], v153 offset:50176
	ds_read_b128 v[194:197], v153 offset:51200
	ds_read_b128 v[198:201], v153 offset:52224
	ds_read_b128 v[202:205], v153 offset:53248
	ds_read_b128 v[206:209], v153 offset:54272
	ds_read_b128 v[210:213], v153 offset:55296
	ds_read_b128 v[214:217], v153 offset:56320
	global_load_lds_dwordx4 v[190:191], off
	s_add_i32 m0, s34, 0x2000
	s_add_u32 s30, s30, 0x80080
	v_lshl_add_u64 v[190:191], v[218:219], 0, s[12:13]
	s_addc_u32 s31, s31, 0
	s_add_i32 s34, s67, s49
	global_load_lds_dwordx4 v[190:191], off
	v_lshl_add_u64 v[190:191], s[30:31], 0, v[132:133]
	s_mov_b32 m0, s34
	s_nop 0
	global_load_lds_dwordx4 v[190:191], off
	v_lshl_add_u64 v[190:191], s[30:31], 0, v[128:129]
	s_add_i32 m0, s34, 0x2000
	s_nop 0
	global_load_lds_dwordx4 v[190:191], off
	v_lshl_add_u64 v[190:191], v[220:221], 0, s[12:13]
	s_mov_b32 m0, s55
	s_nop 0
	global_load_lds_dwordx4 v[190:191], off
	v_lshl_add_u64 v[190:191], v[222:223], 0, s[12:13]
	s_mov_b32 m0, s56
	s_nop 0
	global_load_lds_dwordx4 v[190:191], off
	s_waitcnt vmcnt(8)
	s_waitcnt lgkmcnt(0)
	s_barrier
	s_setprio 1
	s_waitcnt lgkmcnt(0)
	v_mfma_f32_16x16x32_bf16 v[60:63], v[144:147], v[182:185], v[60:63]
	v_mfma_f32_16x16x32_bf16 v[56:59], v[158:161], v[182:185], v[56:59]
	v_mfma_f32_16x16x32_bf16 v[44:47], v[144:147], v[194:197], v[44:47]
	v_mfma_f32_16x16x32_bf16 v[40:43], v[158:161], v[194:197], v[40:43]
	v_mfma_f32_16x16x32_bf16 v[28:31], v[144:147], v[202:205], v[28:31]
	v_mfma_f32_16x16x32_bf16 v[24:27], v[158:161], v[202:205], v[24:27]
	v_mfma_f32_16x16x32_bf16 v[12:15], v[144:147], v[210:213], v[12:15]
	v_mfma_f32_16x16x32_bf16 v[8:11], v[158:161], v[210:213], v[8:11]
	v_mfma_f32_16x16x32_bf16 v[60:63], v[154:157], v[186:189], v[60:63]
	v_mfma_f32_16x16x32_bf16 v[56:59], v[162:165], v[186:189], v[56:59]
	v_mfma_f32_16x16x32_bf16 v[44:47], v[154:157], v[198:201], v[44:47]
	v_mfma_f32_16x16x32_bf16 v[40:43], v[162:165], v[198:201], v[40:43]
	v_mfma_f32_16x16x32_bf16 v[28:31], v[154:157], v[206:209], v[28:31]
	v_mfma_f32_16x16x32_bf16 v[24:27], v[162:165], v[206:209], v[24:27]
	v_mfma_f32_16x16x32_bf16 v[12:15], v[154:157], v[214:217], v[12:15]
	v_mfma_f32_16x16x32_bf16 v[8:11], v[162:165], v[214:217], v[8:11]
	s_setprio 0
	s_setprio 1
	v_mfma_f32_16x16x32_bf16 v[52:55], v[166:169], v[182:185], v[52:55]
	v_mfma_f32_16x16x32_bf16 v[48:51], v[174:177], v[182:185], v[48:51]
	v_mfma_f32_16x16x32_bf16 v[36:39], v[166:169], v[194:197], v[36:39]
	v_mfma_f32_16x16x32_bf16 v[32:35], v[174:177], v[194:197], v[32:35]
	v_mfma_f32_16x16x32_bf16 v[20:23], v[166:169], v[202:205], v[20:23]
	v_mfma_f32_16x16x32_bf16 v[16:19], v[174:177], v[202:205], v[16:19]
	v_mfma_f32_16x16x32_bf16 v[4:7], v[166:169], v[210:213], v[4:7]
	v_mfma_f32_16x16x32_bf16 v[0:3], v[174:177], v[210:213], v[0:3]
	v_mfma_f32_16x16x32_bf16 v[52:55], v[170:173], v[186:189], v[52:55]
	v_mfma_f32_16x16x32_bf16 v[48:51], v[178:181], v[186:189], v[48:51]
	v_mfma_f32_16x16x32_bf16 v[36:39], v[170:173], v[198:201], v[36:39]
	v_mfma_f32_16x16x32_bf16 v[32:35], v[178:181], v[198:201], v[32:35]
	v_mfma_f32_16x16x32_bf16 v[20:23], v[170:173], v[206:209], v[20:23]
	v_mfma_f32_16x16x32_bf16 v[16:19], v[178:181], v[206:209], v[16:19]
	v_mfma_f32_16x16x32_bf16 v[4:7], v[170:173], v[214:217], v[4:7]
	v_mfma_f32_16x16x32_bf16 v[0:3], v[178:181], v[214:217], v[0:3]
	s_add_i32 s65, s65, 2
	s_add_u32 s63, s63, 0x100
	s_addc_u32 s64, s64, 0
	s_add_u32 s28, s28, 0x100
	s_addc_u32 s29, s29, 0
	s_cmp_gt_u32 s65, 29
	s_setprio 0
	s_barrier
	s_cbranch_scc0 .LBB0_1170

; #define PG8_STAGE(bufoff, gbase, voff) do { _Pragma("unroll") for (int _i = 0; _i < 2; ++_i) \
;         __builtin_amdgcn_global_load_lds((const unsigned*)((const char*)(gbase) + (voff)[_i]), (PG8_LAS unsigned*)(lds + (bufoff) + ldsw + _i * 8192), 16, 0, 0); } while (0)
; #define PG8_LDA(dst, b, h) do { _Pragma("unroll") for (int m = 0; m < 4; ++m) _Pragma("unroll") for (int k = 0; k < 2; ++k) dst[m][k] = *(const PG8_LAS bf16x8*)(lds + PG8_SA(b, h) + aoff + m * 2048 + k * 1024); } while (0)
; #define PG8_LDB(dst, b, h) do { _Pragma("unroll") for (int n = 0; n < 2; ++n) _Pragma("unroll") for (int k = 0; k < 2; ++k) dst[n][k] = *(const PG8_LAS bf16x8*)(lds + PG8_SB(b, h) + boff + n * 2048 + k * 1024); } while (0)
; #define PG8_MMA(ai, bj, At, Bt) do { __builtin_amdgcn_s_setprio(1); _Pragma("unroll") for (int m = 0; m < 4; ++m) _Pragma("unroll") for (int n = 0; n < 2; ++n) _Pragma("unroll") for (int k = 0; k < 2; ++k) \
;         acc[ai][bj][m][n] = __builtin_amdgcn_mfma_f32_16x16x32_bf16(Bt[n][k], At[m][k], acc[ai][bj][m][n], 0, 0, 0); __builtin_amdgcn_s_setprio(0); } while (0)
; #define PG8_WAIT_V(n) asm volatile("s_waitcnt vmcnt(" #n ")" ::: "memory")
; #define PG8_WAIT_L(n) asm volatile("s_waitcnt lgkmcnt(" #n ")" ::: "memory")
; #define PG8_BAR __builtin_amdgcn_s_barrier()
; template <class Epi, class Sched, bool ALIGN_EPI = false, bool SP2 = false>
; __device__ __forceinline__ void gemm_phase(PG8_LAS unsigned char* lds, const Gemm g, const Sched& S, const Epi& E) {
;     ...
;         const bool has_next = S.next(ui + 1, nxt);
;         const char* nA = has_next ? (const char*)g.A + (size_t)nxt.pm * tstep : cA; const char* nB = has_next ? (const char*)g.Bt + (size_t)nxt.pn * tstep : cB;
;         for (int t = 0; t < nt; t += 2) {
;             const bool last = (t == nt - 2);
;             const char* a1 = cA + (size_t)(t + 1) * kstep;
;             const char* a2 = last ? nA : cA + (size_t)(t + 2) * kstep; const char* b2 = last ? nB : cB + (size_t)(t + 2) * kstep;
;             const char* a3 = a2 + kstep; const char* b3 = b2 + kstep;
;             if (last && has_next) S.a_ready(nxt);
;             if constexpr (SP2) {
;             PG8_LDB(B0, 0, 0); PG8_LDB(B1, 0, 1); PG8_SCHED; PG8_LDA(At, 0, 0); PG8_STAGE(PG8_SA(1, 1), a1 + hstep, voffA);
;             PG8_WAIT_V(8); PG8_WAIT_L(0); PG8_BAR; PG8_MMA(0, 0, At, B0); PG8_MMA(0, 1, At, B1); PG8_BAR; PG8_SCHED;
.LBB0_1249:
	s_add_u32 s71, s34, 0x100
	s_addc_u32 s72, s35, 0
	s_mov_b32 s73, -2
	ds_read_b128 v[124:127], v169
	ds_read_b128 v[132:135], v169 offset:1024
	ds_read_b128 v[136:139], v169 offset:2048
	ds_read_b128 v[140:143], v169 offset:3072
	ds_read_b128 v[160:163], v170
	ds_read_b128 v[172:175], v170 offset:1024
	ds_read_b128 v[176:179], v170 offset:2048
	ds_read_b128 v[180:183], v170 offset:3072
	s_add_u32 s34, s30, 0x100
	s_addc_u32 s35, s31, 0
	s_cmpk_eq_i32 s73, 0x54
	s_cselect_b32 s47, s9, s35
	s_cselect_b32 s46, s8, s34
	s_cselect_b32 s37, s29, s72
	s_cselect_b32 s36, s28, s71
	v_lshl_add_u64 v[164:165], s[30:31], 0, v[154:155]
	s_add_i32 m0, s55, 0xc000
	ds_read_b128 v[184:187], v171
	ds_read_b128 v[188:191], v171 offset:1024
	ds_read_b128 v[194:197], v171 offset:2048
	ds_read_b128 v[198:201], v171 offset:3072
	ds_read_b128 v[202:205], v171 offset:4096
	ds_read_b128 v[206:209], v171 offset:5120
	ds_read_b128 v[210:213], v171 offset:6144
	ds_read_b128 v[214:217], v171 offset:7168
	global_load_lds_dwordx4 v[164:165], off
	v_lshl_add_u64 v[164:165], s[30:31], 0, v[152:153]
	s_add_i32 m0, s55, 0xe000
	s_nop 0
	global_load_lds_dwordx4 v[164:165], off
	s_waitcnt vmcnt(8)
	s_waitcnt lgkmcnt(0)
	s_barrier
	s_setprio 1
	s_waitcnt lgkmcnt(0)
	v_mfma_f32_16x16x32_bf16 v[128:131], v[124:127], v[184:187], 0
	v_mfma_f32_16x16x32_bf16 v[120:123], v[136:139], v[184:187], 0
	v_mfma_f32_16x16x32_bf16 v[108:111], v[124:127], v[194:197], 0
	v_mfma_f32_16x16x32_bf16 v[104:107], v[136:139], v[194:197], 0
	v_mfma_f32_16x16x32_bf16 v[92:95], v[124:127], v[202:205], 0
	v_mfma_f32_16x16x32_bf16 v[88:91], v[136:139], v[202:205], 0
	v_mfma_f32_16x16x32_bf16 v[76:79], v[124:127], v[210:213], 0
	v_mfma_f32_16x16x32_bf16 v[72:75], v[136:139], v[210:213], 0
	v_mfma_f32_16x16x32_bf16 v[128:131], v[132:135], v[188:191], v[128:131]
	v_mfma_f32_16x16x32_bf16 v[120:123], v[140:143], v[188:191], v[120:123]
	v_mfma_f32_16x16x32_bf16 v[108:111], v[132:135], v[198:201], v[108:111]
	v_mfma_f32_16x16x32_bf16 v[104:107], v[140:143], v[198:201], v[104:107]
	v_mfma_f32_16x16x32_bf16 v[92:95], v[132:135], v[206:209], v[92:95]
	v_mfma_f32_16x16x32_bf16 v[88:91], v[140:143], v[206:209], v[88:91]
	v_mfma_f32_16x16x32_bf16 v[76:79], v[132:135], v[214:217], v[76:79]
	v_mfma_f32_16x16x32_bf16 v[72:75], v[140:143], v[214:217], v[72:75]
	s_setprio 0
	s_setprio 1
	v_mfma_f32_16x16x32_bf16 v[116:119], v[160:163], v[184:187], 0
	v_mfma_f32_16x16x32_bf16 v[112:115], v[176:179], v[184:187], 0
	v_mfma_f32_16x16x32_bf16 v[100:103], v[160:163], v[194:197], 0
	v_mfma_f32_16x16x32_bf16 v[96:99], v[176:179], v[194:197], 0
	v_mfma_f32_16x16x32_bf16 v[84:87], v[160:163], v[202:205], 0
	v_mfma_f32_16x16x32_bf16 v[80:83], v[176:179], v[202:205], 0
	v_mfma_f32_16x16x32_bf16 v[68:71], v[160:163], v[210:213], 0
	v_mfma_f32_16x16x32_bf16 v[64:67], v[176:179], v[210:213], 0
	v_mfma_f32_16x16x32_bf16 v[116:119], v[172:175], v[188:191], v[116:119]
	v_mfma_f32_16x16x32_bf16 v[112:115], v[180:183], v[188:191], v[112:115]
	v_mfma_f32_16x16x32_bf16 v[100:103], v[172:175], v[198:201], v[100:103]
	v_mfma_f32_16x16x32_bf16 v[96:99], v[180:183], v[198:201], v[96:99]
	v_mfma_f32_16x16x32_bf16 v[84:87], v[172:175], v[206:209], v[84:87]
	v_mfma_f32_16x16x32_bf16 v[80:83], v[180:183], v[206:209], v[80:83]
	v_mfma_f32_16x16x32_bf16 v[68:71], v[172:175], v[214:217], v[68:71]
	v_mfma_f32_16x16x32_bf16 v[64:67], v[180:183], v[214:217], v[64:67]
	s_setprio 0
	s_barrier
	s_add_i32 s30, s65, s54
	v_lshl_add_u64 v[164:165], s[36:37], 0, v[146:147]
	s_mov_b32 m0, s30
	ds_read_b128 v[184:187], v171 offset:16384
	ds_read_b128 v[188:191], v171 offset:17408
	ds_read_b128 v[194:197], v171 offset:18432
	ds_read_b128 v[198:201], v171 offset:19456
	ds_read_b128 v[202:205], v171 offset:20480
	ds_read_b128 v[206:209], v171 offset:21504
	ds_read_b128 v[210:213], v171 offset:22528
	ds_read_b128 v[214:217], v171 offset:23552
	global_load_lds_dwordx4 v[164:165], off
	s_add_i32 m0, s30, 0x2000
	s_add_u32 s30, s36, 0x160000
	v_lshl_add_u64 v[218:219], s[36:37], 0, v[150:151]
	s_addc_u32 s31, s37, 0
	s_add_i32 s74, s66, s54
	global_load_lds_dwordx4 v[218:219], off
	v_lshl_add_u64 v[220:221], s[30:31], 0, v[146:147]
	s_mov_b32 m0, s74
	v_lshl_add_u64 v[222:223], s[46:47], 0, v[148:149]
	global_load_lds_dwordx4 v[220:221], off
	v_lshl_add_u64 v[220:221], s[30:31], 0, v[150:151]
	s_add_i32 m0, s74, 0x2000
	s_nop 0
	global_load_lds_dwordx4 v[220:221], off
	v_lshl_add_u64 v[220:221], s[46:47], 0, v[144:145]
	s_mov_b32 m0, s55
	s_nop 0
	global_load_lds_dwordx4 v[220:221], off
	s_mov_b32 m0, s56
	s_nop 0
	global_load_lds_dwordx4 v[222:223], off
	s_waitcnt vmcnt(8)
	s_waitcnt lgkmcnt(0)
	s_barrier
; #define PG8_STAGE(bufoff, gbase, voff) do { _Pragma("unroll") for (int _i = 0; _i < 2; ++_i) \
;         __builtin_amdgcn_global_load_lds((const unsigned*)((const char*)(gbase) + (voff)[_i]), (PG8_LAS unsigned*)(lds + (bufoff) + ldsw + _i * 8192), 16, 0, 0); } while (0)
; #define PG8_LDA(dst, b, h) do { _Pragma("unroll") for (int m = 0; m < 4; ++m) _Pragma("unroll") for (int k = 0; k < 2; ++k) dst[m][k] = *(const PG8_LAS bf16x8*)(lds + PG8_SA(b, h) + aoff + m * 2048 + k * 1024); } while (0)
; #define PG8_LDB(dst, b, h) do { _Pragma("unroll") for (int n = 0; n < 2; ++n) _Pragma("unroll") for (int k = 0; k < 2; ++k) dst[n][k] = *(const PG8_LAS bf16x8*)(lds + PG8_SB(b, h) + boff + n * 2048 + k * 1024); } while (0)
; #define PG8_MMA(ai, bj, At, Bt) do { __builtin_amdgcn_s_setprio(1); _Pragma("unroll") for (int m = 0; m < 4; ++m) _Pragma("unroll") for (int n = 0; n < 2; ++n) _Pragma("unroll") for (int k = 0; k < 2; ++k) \
;         acc[ai][bj][m][n] = __builtin_amdgcn_mfma_f32_16x16x32_bf16(Bt[n][k], At[m][k], acc[ai][bj][m][n], 0, 0, 0); __builtin_amdgcn_s_setprio(0); } while (0)
; #define PG8_WAIT_V(n) asm volatile("s_waitcnt vmcnt(" #n ")" ::: "memory")
; #define PG8_WAIT_L(n) asm volatile("s_waitcnt lgkmcnt(" #n ")" ::: "memory")
; #define PG8_BAR __builtin_amdgcn_s_barrier()
; #define PG8_SCHED __builtin_amdgcn_sched_barrier(0)
; template <class Epi, class Sched, bool ALIGN_EPI = false, bool SP2 = false>
; __device__ __forceinline__ void gemm_phase(PG8_LAS unsigned char* lds, const Gemm g, const Sched& S, const Epi& E) {
;     ...
;             PG8_WAIT_V(8); PG8_WAIT_L(0); PG8_BAR; PG8_MMA(0, 0, At, B0); PG8_MMA(0, 1, At, B1); PG8_BAR; PG8_SCHED;
;             PG8_LDA(At, 0, 1); PG8_STAGE(PG8_SB(0, 0), b2, voffB); PG8_STAGE(PG8_SB(0, 1), b2 + hstep, voffB); PG8_STAGE(PG8_SA(0, 0), a2, voffA);
;             PG8_WAIT_V(8); PG8_WAIT_L(0); PG8_BAR; PG8_MMA(1, 0, At, B0); PG8_MMA(1, 1, At, B1); PG8_BAR; PG8_SCHED;
;             PG8_LDB(B0, 1, 0); PG8_LDB(B1, 1, 1); PG8_SCHED; PG8_LDA(At, 1, 0); PG8_STAGE(PG8_SA(0, 1), a2 + hstep, voffA);
;             PG8_WAIT_V(8); PG8_WAIT_L(0); PG8_BAR; PG8_MMA(0, 0, At, B0); PG8_MMA(0, 1, At, B1); PG8_BAR; PG8_SCHED;
	s_setprio 1
	s_waitcnt lgkmcnt(0)
	v_mfma_f32_16x16x32_bf16 v[60:63], v[124:127], v[184:187], 0
	v_mfma_f32_16x16x32_bf16 v[56:59], v[136:139], v[184:187], 0
	v_mfma_f32_16x16x32_bf16 v[44:47], v[124:127], v[194:197], 0
	v_mfma_f32_16x16x32_bf16 v[40:43], v[136:139], v[194:197], 0
	v_mfma_f32_16x16x32_bf16 v[28:31], v[124:127], v[202:205], 0
	v_mfma_f32_16x16x32_bf16 v[24:27], v[136:139], v[202:205], 0
	v_mfma_f32_16x16x32_bf16 v[12:15], v[124:127], v[210:213], 0
	v_mfma_f32_16x16x32_bf16 v[8:11], v[136:139], v[210:213], 0
	v_mfma_f32_16x16x32_bf16 v[60:63], v[132:135], v[188:191], v[60:63]
	v_mfma_f32_16x16x32_bf16 v[56:59], v[140:143], v[188:191], v[56:59]
	v_mfma_f32_16x16x32_bf16 v[44:47], v[132:135], v[198:201], v[44:47]
	v_mfma_f32_16x16x32_bf16 v[40:43], v[140:143], v[198:201], v[40:43]
	v_mfma_f32_16x16x32_bf16 v[28:31], v[132:135], v[206:209], v[28:31]
	v_mfma_f32_16x16x32_bf16 v[24:27], v[140:143], v[206:209], v[24:27]
	v_mfma_f32_16x16x32_bf16 v[12:15], v[132:135], v[214:217], v[12:15]
	v_mfma_f32_16x16x32_bf16 v[8:11], v[140:143], v[214:217], v[8:11]
	s_setprio 0
	s_setprio 1
	v_mfma_f32_16x16x32_bf16 v[52:55], v[160:163], v[184:187], 0
	v_mfma_f32_16x16x32_bf16 v[48:51], v[176:179], v[184:187], 0
	v_mfma_f32_16x16x32_bf16 v[36:39], v[160:163], v[194:197], 0
	v_mfma_f32_16x16x32_bf16 v[32:35], v[176:179], v[194:197], 0
	v_mfma_f32_16x16x32_bf16 v[20:23], v[160:163], v[202:205], 0
	v_mfma_f32_16x16x32_bf16 v[16:19], v[176:179], v[202:205], 0
	v_mfma_f32_16x16x32_bf16 v[4:7], v[160:163], v[210:213], 0
	v_mfma_f32_16x16x32_bf16 v[0:3], v[176:179], v[210:213], 0
	v_mfma_f32_16x16x32_bf16 v[52:55], v[172:175], v[188:191], v[52:55]
	v_mfma_f32_16x16x32_bf16 v[48:51], v[180:183], v[188:191], v[48:51]
	v_mfma_f32_16x16x32_bf16 v[36:39], v[172:175], v[198:201], v[36:39]
	v_mfma_f32_16x16x32_bf16 v[32:35], v[180:183], v[198:201], v[32:35]
	v_mfma_f32_16x16x32_bf16 v[20:23], v[172:175], v[206:209], v[20:23]
	v_mfma_f32_16x16x32_bf16 v[16:19], v[180:183], v[206:209], v[16:19]
	v_mfma_f32_16x16x32_bf16 v[4:7], v[172:175], v[214:217], v[4:7]
	v_mfma_f32_16x16x32_bf16 v[0:3], v[180:183], v[214:217], v[0:3]
	s_setprio 0
	s_barrier
	s_add_i32 s74, 0, 0x18000
	s_add_i32 s75, 0, 0x1c000
	v_add_u32_e32 v140, s74, v167
	v_add_u32_e32 v180, s75, v167
	ds_read_b128 v[124:127], v140
	ds_read_b128 v[132:135], v140 offset:1024
	ds_read_b128 v[136:139], v140 offset:2048
	ds_read_b128 v[140:143], v140 offset:3072
	ds_read_b128 v[160:163], v180
	ds_read_b128 v[172:175], v180 offset:1024
	ds_read_b128 v[176:179], v180 offset:2048
	ds_read_b128 v[180:183], v180 offset:3072
	s_add_u32 s30, s46, 0x160000
	s_addc_u32 s31, s47, 0
	s_mov_b32 m0, s57
	v_lshl_add_u64 v[224:225], s[30:31], 0, v[144:145]
	ds_read_b128 v[184:187], v171 offset:32768
	ds_read_b128 v[188:191], v171 offset:33792
	ds_read_b128 v[194:197], v171 offset:34816
	ds_read_b128 v[198:201], v171 offset:35840
	ds_read_b128 v[202:205], v171 offset:36864
	ds_read_b128 v[206:209], v171 offset:37888
	ds_read_b128 v[210:213], v171 offset:38912
	ds_read_b128 v[214:217], v171 offset:39936
	global_load_lds_dwordx4 v[224:225], off
	v_lshl_add_u64 v[224:225], s[30:31], 0, v[148:149]
	s_mov_b32 m0, s58
	s_nop 0
	global_load_lds_dwordx4 v[224:225], off
	s_waitcnt vmcnt(8)
	s_waitcnt lgkmcnt(0)
	s_barrier
	s_setprio 1
	s_waitcnt lgkmcnt(0)
	v_mfma_f32_16x16x32_bf16 v[128:131], v[124:127], v[184:187], v[128:131]
	v_mfma_f32_16x16x32_bf16 v[120:123], v[136:139], v[184:187], v[120:123]
	v_mfma_f32_16x16x32_bf16 v[108:111], v[124:127], v[194:197], v[108:111]
	v_mfma_f32_16x16x32_bf16 v[104:107], v[136:139], v[194:197], v[104:107]
	v_mfma_f32_16x16x32_bf16 v[92:95], v[124:127], v[202:205], v[92:95]
	v_mfma_f32_16x16x32_bf16 v[88:91], v[136:139], v[202:205], v[88:91]
	v_mfma_f32_16x16x32_bf16 v[76:79], v[124:127], v[210:213], v[76:79]
	v_mfma_f32_16x16x32_bf16 v[72:75], v[136:139], v[210:213], v[72:75]
	v_mfma_f32_16x16x32_bf16 v[128:131], v[132:135], v[188:191], v[128:131]
	v_mfma_f32_16x16x32_bf16 v[120:123], v[140:143], v[188:191], v[120:123]
	v_mfma_f32_16x16x32_bf16 v[108:111], v[132:135], v[198:201], v[108:111]
	v_mfma_f32_16x16x32_bf16 v[104:107], v[140:143], v[198:201], v[104:107]
	v_mfma_f32_16x16x32_bf16 v[92:95], v[132:135], v[206:209], v[92:95]
	v_mfma_f32_16x16x32_bf16 v[88:91], v[140:143], v[206:209], v[88:91]
	v_mfma_f32_16x16x32_bf16 v[76:79], v[132:135], v[214:217], v[76:79]
	v_mfma_f32_16x16x32_bf16 v[72:75], v[140:143], v[214:217], v[72:75]
	s_setprio 0
	s_setprio 1
	v_mfma_f32_16x16x32_bf16 v[116:119], v[160:163], v[184:187], v[116:119]
	v_mfma_f32_16x16x32_bf16 v[112:115], v[176:179], v[184:187], v[112:115]
	v_mfma_f32_16x16x32_bf16 v[100:103], v[160:163], v[194:197], v[100:103]
	v_mfma_f32_16x16x32_bf16 v[96:99], v[176:179], v[194:197], v[96:99]
	v_mfma_f32_16x16x32_bf16 v[84:87], v[160:163], v[202:205], v[84:87]
	v_mfma_f32_16x16x32_bf16 v[80:83], v[176:179], v[202:205], v[80:83]
	v_mfma_f32_16x16x32_bf16 v[68:71], v[160:163], v[210:213], v[68:71]
	v_mfma_f32_16x16x32_bf16 v[64:67], v[176:179], v[210:213], v[64:67]
	v_mfma_f32_16x16x32_bf16 v[116:119], v[172:175], v[188:191], v[116:119]
	v_mfma_f32_16x16x32_bf16 v[112:115], v[180:183], v[188:191], v[112:115]
	v_mfma_f32_16x16x32_bf16 v[100:103], v[172:175], v[198:201], v[100:103]
	v_mfma_f32_16x16x32_bf16 v[96:99], v[180:183], v[198:201], v[96:99]
	v_mfma_f32_16x16x32_bf16 v[84:87], v[172:175], v[206:209], v[84:87]
	v_mfma_f32_16x16x32_bf16 v[80:83], v[180:183], v[206:209], v[80:83]
	v_mfma_f32_16x16x32_bf16 v[68:71], v[172:175], v[214:217], v[68:71]
	v_mfma_f32_16x16x32_bf16 v[64:67], v[180:183], v[214:217], v[64:67]
	s_setprio 0
	s_barrier
; #define PG8_STAGE(bufoff, gbase, voff) do { _Pragma("unroll") for (int _i = 0; _i < 2; ++_i) \
;         __builtin_amdgcn_global_load_lds((const unsigned*)((const char*)(gbase) + (voff)[_i]), (PG8_LAS unsigned*)(lds + (bufoff) + ldsw + _i * 8192), 16, 0, 0); } while (0)
; #define PG8_LDA(dst, b, h) do { _Pragma("unroll") for (int m = 0; m < 4; ++m) _Pragma("unroll") for (int k = 0; k < 2; ++k) dst[m][k] = *(const PG8_LAS bf16x8*)(lds + PG8_SA(b, h) + aoff + m * 2048 + k * 1024); } while (0)
; #define PG8_LDB(dst, b, h) do { _Pragma("unroll") for (int n = 0; n < 2; ++n) _Pragma("unroll") for (int k = 0; k < 2; ++k) dst[n][k] = *(const PG8_LAS bf16x8*)(lds + PG8_SB(b, h) + boff + n * 2048 + k * 1024); } while (0)
; template <class Epi, class Sched, bool ALIGN_EPI = false, bool SP2 = false>
; __device__ __forceinline__ void gemm_phase(PG8_LAS unsigned char* lds, const Gemm g, const Sched& S, const Epi& E) {
;     ...
;         for (int t = 0; t < nt; t += 2) {
;             const bool last = (t == nt - 2);
;             const char* a1 = cA + (size_t)(t + 1) * kstep;
;             const char* a2 = last ? nA : cA + (size_t)(t + 2) * kstep; const char* b2 = last ? nB : cB + (size_t)(t + 2) * kstep;
;             const char* a3 = a2 + kstep; const char* b3 = b2 + kstep;
;             if (last && has_next) S.a_ready(nxt);
;             if constexpr (SP2) {
;             PG8_LDB(B0, 0, 0); PG8_LDB(B1, 0, 1); PG8_SCHED; PG8_LDA(At, 0, 0); PG8_STAGE(PG8_SA(1, 1), a1 + hstep, voffA);
;             PG8_WAIT_V(8); PG8_WAIT_L(0); PG8_BAR; PG8_MMA(0, 0, At, B0); PG8_MMA(0, 1, At, B1); PG8_BAR; PG8_SCHED;
;             PG8_LDA(At, 0, 1); PG8_STAGE(PG8_SB(0, 0), b2, voffB); PG8_STAGE(PG8_SB(0, 1), b2 + hstep, voffB); PG8_STAGE(PG8_SA(0, 0), a2, voffA);
;             PG8_WAIT_V(8); PG8_WAIT_L(0); PG8_BAR; PG8_MMA(1, 0, At, B0); PG8_MMA(1, 1, At, B1); PG8_BAR; PG8_SCHED;
;             PG8_LDB(B0, 1, 0); PG8_LDB(B1, 1, 1); PG8_SCHED; PG8_LDA(At, 1, 0); PG8_STAGE(PG8_SA(0, 1), a2 + hstep, voffA);
;             PG8_WAIT_V(8); PG8_WAIT_L(0); PG8_BAR; PG8_MMA(0, 0, At, B0); PG8_MMA(0, 1, At, B1); PG8_BAR; PG8_SCHED;
;             PG8_LDA(At, 1, 1); PG8_STAGE(PG8_SB(1, 0), b3, voffB); PG8_STAGE(PG8_SB(1, 1), b3 + hstep, voffB); PG8_STAGE(PG8_SA(1, 0), a3, voffA);
;             PG8_WAIT_V(8); PG8_WAIT_L(0); PG8_BAR; PG8_MMA(1, 0, At, B0); PG8_MMA(1, 1, At, B1); PG8_BAR; PG8_SCHED;
	s_add_i32 s30, s74, s54
	v_lshl_add_u64 v[164:165], v[164:165], 0, s[16:17]
	s_mov_b32 m0, s30
	ds_read_b128 v[184:187], v171 offset:49152
	ds_read_b128 v[188:191], v171 offset:50176
	ds_read_b128 v[194:197], v171 offset:51200
	ds_read_b128 v[198:201], v171 offset:52224
	ds_read_b128 v[202:205], v171 offset:53248
	ds_read_b128 v[206:209], v171 offset:54272
	ds_read_b128 v[210:213], v171 offset:55296
	ds_read_b128 v[214:217], v171 offset:56320
	global_load_lds_dwordx4 v[164:165], off
	s_add_i32 m0, s30, 0x2000
	s_add_u32 s30, s36, 0x160080
	v_lshl_add_u64 v[164:165], v[218:219], 0, s[16:17]
	s_addc_u32 s31, s37, 0
	s_add_i32 s36, s75, s54
	global_load_lds_dwordx4 v[164:165], off
	v_lshl_add_u64 v[164:165], s[30:31], 0, v[146:147]
	s_mov_b32 m0, s36
	s_nop 0
	global_load_lds_dwordx4 v[164:165], off
	v_lshl_add_u64 v[164:165], s[30:31], 0, v[150:151]
	s_add_i32 m0, s36, 0x2000
	s_nop 0
	global_load_lds_dwordx4 v[164:165], off
	v_lshl_add_u64 v[164:165], v[220:221], 0, s[16:17]
	s_mov_b32 m0, s62
	s_nop 0
	global_load_lds_dwordx4 v[164:165], off
	v_lshl_add_u64 v[164:165], v[222:223], 0, s[16:17]
	s_mov_b32 m0, s63
	s_nop 0
	global_load_lds_dwordx4 v[164:165], off
	s_waitcnt vmcnt(8)
	s_waitcnt lgkmcnt(0)
	s_barrier
	s_setprio 1
	s_waitcnt lgkmcnt(0)
	v_mfma_f32_16x16x32_bf16 v[60:63], v[124:127], v[184:187], v[60:63]
	v_mfma_f32_16x16x32_bf16 v[56:59], v[136:139], v[184:187], v[56:59]
	v_mfma_f32_16x16x32_bf16 v[44:47], v[124:127], v[194:197], v[44:47]
	v_mfma_f32_16x16x32_bf16 v[40:43], v[136:139], v[194:197], v[40:43]
	v_mfma_f32_16x16x32_bf16 v[28:31], v[124:127], v[202:205], v[28:31]
	v_mfma_f32_16x16x32_bf16 v[24:27], v[136:139], v[202:205], v[24:27]
	v_mfma_f32_16x16x32_bf16 v[12:15], v[124:127], v[210:213], v[12:15]
	v_mfma_f32_16x16x32_bf16 v[8:11], v[136:139], v[210:213], v[8:11]
	v_mfma_f32_16x16x32_bf16 v[60:63], v[132:135], v[188:191], v[60:63]
	v_mfma_f32_16x16x32_bf16 v[56:59], v[140:143], v[188:191], v[56:59]
	v_mfma_f32_16x16x32_bf16 v[44:47], v[132:135], v[198:201], v[44:47]
	v_mfma_f32_16x16x32_bf16 v[40:43], v[140:143], v[198:201], v[40:43]
	v_mfma_f32_16x16x32_bf16 v[28:31], v[132:135], v[206:209], v[28:31]
	v_mfma_f32_16x16x32_bf16 v[24:27], v[140:143], v[206:209], v[24:27]
	v_mfma_f32_16x16x32_bf16 v[12:15], v[132:135], v[214:217], v[12:15]
	v_mfma_f32_16x16x32_bf16 v[8:11], v[140:143], v[214:217], v[8:11]
	s_setprio 0
	s_setprio 1
	v_mfma_f32_16x16x32_bf16 v[52:55], v[160:163], v[184:187], v[52:55]
	v_mfma_f32_16x16x32_bf16 v[48:51], v[176:179], v[184:187], v[48:51]
	v_mfma_f32_16x16x32_bf16 v[36:39], v[160:163], v[194:197], v[36:39]
	v_mfma_f32_16x16x32_bf16 v[32:35], v[176:179], v[194:197], v[32:35]
	v_mfma_f32_16x16x32_bf16 v[20:23], v[160:163], v[202:205], v[20:23]
	v_mfma_f32_16x16x32_bf16 v[16:19], v[176:179], v[202:205], v[16:19]
	v_mfma_f32_16x16x32_bf16 v[4:7], v[160:163], v[210:213], v[4:7]
	v_mfma_f32_16x16x32_bf16 v[0:3], v[176:179], v[210:213], v[0:3]
	v_mfma_f32_16x16x32_bf16 v[52:55], v[172:175], v[188:191], v[52:55]
	v_mfma_f32_16x16x32_bf16 v[48:51], v[180:183], v[188:191], v[48:51]
	v_mfma_f32_16x16x32_bf16 v[36:39], v[172:175], v[198:201], v[36:39]
	v_mfma_f32_16x16x32_bf16 v[32:35], v[180:183], v[198:201], v[32:35]
	v_mfma_f32_16x16x32_bf16 v[20:23], v[172:175], v[206:209], v[20:23]
	v_mfma_f32_16x16x32_bf16 v[16:19], v[180:183], v[206:209], v[16:19]
	v_mfma_f32_16x16x32_bf16 v[4:7], v[172:175], v[214:217], v[4:7]
	v_mfma_f32_16x16x32_bf16 v[0:3], v[180:183], v[214:217], v[0:3]
	s_add_i32 s73, s73, 2
	s_add_u32 s71, s71, 0x100
	s_addc_u32 s72, s72, 0
	s_cmpk_gt_u32 s73, 0x55
	s_mov_b64 s[30:31], s[34:35]
	s_setprio 0
	s_barrier
	s_cbranch_scc1 .Lpeel_exit_7
.LBB0_1250:
	ds_read_b128 v[124:127], v169
	ds_read_b128 v[132:135], v169 offset:1024
	ds_read_b128 v[136:139], v169 offset:2048
	ds_read_b128 v[140:143], v169 offset:3072
	ds_read_b128 v[160:163], v170
	ds_read_b128 v[172:175], v170 offset:1024
	ds_read_b128 v[176:179], v170 offset:2048
	ds_read_b128 v[180:183], v170 offset:3072
	s_add_u32 s34, s30, 0x100
	s_addc_u32 s35, s31, 0
	s_cmpk_eq_i32 s73, 0x54
	s_cselect_b32 s47, s9, s35
	s_cselect_b32 s46, s8, s34
	s_cselect_b32 s37, s29, s72
	s_cselect_b32 s36, s28, s71
	v_lshl_add_u64 v[164:165], s[30:31], 0, v[154:155]
	s_add_i32 m0, s55, 0xc000
	ds_read_b128 v[184:187], v171
	ds_read_b128 v[188:191], v171 offset:1024
	ds_read_b128 v[194:197], v171 offset:2048
	ds_read_b128 v[198:201], v171 offset:3072
	ds_read_b128 v[202:205], v171 offset:4096
	ds_read_b128 v[206:209], v171 offset:5120
	ds_read_b128 v[210:213], v171 offset:6144
	ds_read_b128 v[214:217], v171 offset:7168
	global_load_lds_dwordx4 v[164:165], off
	v_lshl_add_u64 v[164:165], s[30:31], 0, v[152:153]
	s_add_i32 m0, s55, 0xe000
	s_nop 0
	global_load_lds_dwordx4 v[164:165], off
	s_waitcnt vmcnt(8)
	s_waitcnt lgkmcnt(0)
	s_barrier
; #define PG8_STAGE(bufoff, gbase, voff) do { _Pragma("unroll") for (int _i = 0; _i < 2; ++_i) \
;         __builtin_amdgcn_global_load_lds((const unsigned*)((const char*)(gbase) + (voff)[_i]), (PG8_LAS unsigned*)(lds + (bufoff) + ldsw + _i * 8192), 16, 0, 0); } while (0)
; #define PG8_LDA(dst, b, h) do { _Pragma("unroll") for (int m = 0; m < 4; ++m) _Pragma("unroll") for (int k = 0; k < 2; ++k) dst[m][k] = *(const PG8_LAS bf16x8*)(lds + PG8_SA(b, h) + aoff + m * 2048 + k * 1024); } while (0)
; #define PG8_LDB(dst, b, h) do { _Pragma("unroll") for (int n = 0; n < 2; ++n) _Pragma("unroll") for (int k = 0; k < 2; ++k) dst[n][k] = *(const PG8_LAS bf16x8*)(lds + PG8_SB(b, h) + boff + n * 2048 + k * 1024); } while (0)
; #define PG8_MMA(ai, bj, At, Bt) do { __builtin_amdgcn_s_setprio(1); _Pragma("unroll") for (int m = 0; m < 4; ++m) _Pragma("unroll") for (int n = 0; n < 2; ++n) _Pragma("unroll") for (int k = 0; k < 2; ++k) \
;         acc[ai][bj][m][n] = __builtin_amdgcn_mfma_f32_16x16x32_bf16(Bt[n][k], At[m][k], acc[ai][bj][m][n], 0, 0, 0); __builtin_amdgcn_s_setprio(0); } while (0)
; #define PG8_WAIT_V(n) asm volatile("s_waitcnt vmcnt(" #n ")" ::: "memory")
; #define PG8_WAIT_L(n) asm volatile("s_waitcnt lgkmcnt(" #n ")" ::: "memory")
; #define PG8_BAR __builtin_amdgcn_s_barrier()
; #define PG8_SCHED __builtin_amdgcn_sched_barrier(0)
; template <class Epi, class Sched, bool ALIGN_EPI = false, bool SP2 = false>
; __device__ __forceinline__ void gemm_phase(PG8_LAS unsigned char* lds, const Gemm g, const Sched& S, const Epi& E) {
;     ...
;             PG8_LDB(B0, 0, 0); PG8_LDB(B1, 0, 1); PG8_SCHED; PG8_LDA(At, 0, 0); PG8_STAGE(PG8_SA(1, 1), a1 + hstep, voffA);
;             PG8_WAIT_V(8); PG8_WAIT_L(0); PG8_BAR; PG8_MMA(0, 0, At, B0); PG8_MMA(0, 1, At, B1); PG8_BAR; PG8_SCHED;
;             PG8_LDA(At, 0, 1); PG8_STAGE(PG8_SB(0, 0), b2, voffB); PG8_STAGE(PG8_SB(0, 1), b2 + hstep, voffB); PG8_STAGE(PG8_SA(0, 0), a2, voffA);
;             PG8_WAIT_V(8); PG8_WAIT_L(0); PG8_BAR; PG8_MMA(1, 0, At, B0); PG8_MMA(1, 1, At, B1); PG8_BAR; PG8_SCHED;
	s_setprio 1
	s_waitcnt lgkmcnt(0)
	v_mfma_f32_16x16x32_bf16 v[128:131], v[124:127], v[184:187], v[128:131]
	v_mfma_f32_16x16x32_bf16 v[120:123], v[136:139], v[184:187], v[120:123]
	v_mfma_f32_16x16x32_bf16 v[108:111], v[124:127], v[194:197], v[108:111]
	v_mfma_f32_16x16x32_bf16 v[104:107], v[136:139], v[194:197], v[104:107]
	v_mfma_f32_16x16x32_bf16 v[92:95], v[124:127], v[202:205], v[92:95]
	v_mfma_f32_16x16x32_bf16 v[88:91], v[136:139], v[202:205], v[88:91]
	v_mfma_f32_16x16x32_bf16 v[76:79], v[124:127], v[210:213], v[76:79]
	v_mfma_f32_16x16x32_bf16 v[72:75], v[136:139], v[210:213], v[72:75]
	v_mfma_f32_16x16x32_bf16 v[128:131], v[132:135], v[188:191], v[128:131]
	v_mfma_f32_16x16x32_bf16 v[120:123], v[140:143], v[188:191], v[120:123]
	v_mfma_f32_16x16x32_bf16 v[108:111], v[132:135], v[198:201], v[108:111]
	v_mfma_f32_16x16x32_bf16 v[104:107], v[140:143], v[198:201], v[104:107]
	v_mfma_f32_16x16x32_bf16 v[92:95], v[132:135], v[206:209], v[92:95]
	v_mfma_f32_16x16x32_bf16 v[88:91], v[140:143], v[206:209], v[88:91]
	v_mfma_f32_16x16x32_bf16 v[76:79], v[132:135], v[214:217], v[76:79]
	v_mfma_f32_16x16x32_bf16 v[72:75], v[140:143], v[214:217], v[72:75]
	s_setprio 0
	s_setprio 1
	v_mfma_f32_16x16x32_bf16 v[116:119], v[160:163], v[184:187], v[116:119]
	v_mfma_f32_16x16x32_bf16 v[112:115], v[176:179], v[184:187], v[112:115]
	v_mfma_f32_16x16x32_bf16 v[100:103], v[160:163], v[194:197], v[100:103]
	v_mfma_f32_16x16x32_bf16 v[96:99], v[176:179], v[194:197], v[96:99]
	v_mfma_f32_16x16x32_bf16 v[84:87], v[160:163], v[202:205], v[84:87]
	v_mfma_f32_16x16x32_bf16 v[80:83], v[176:179], v[202:205], v[80:83]
	v_mfma_f32_16x16x32_bf16 v[68:71], v[160:163], v[210:213], v[68:71]
	v_mfma_f32_16x16x32_bf16 v[64:67], v[176:179], v[210:213], v[64:67]
	v_mfma_f32_16x16x32_bf16 v[116:119], v[172:175], v[188:191], v[116:119]
	v_mfma_f32_16x16x32_bf16 v[112:115], v[180:183], v[188:191], v[112:115]
	v_mfma_f32_16x16x32_bf16 v[100:103], v[172:175], v[198:201], v[100:103]
	v_mfma_f32_16x16x32_bf16 v[96:99], v[180:183], v[198:201], v[96:99]
	v_mfma_f32_16x16x32_bf16 v[84:87], v[172:175], v[206:209], v[84:87]
	v_mfma_f32_16x16x32_bf16 v[80:83], v[180:183], v[206:209], v[80:83]
	v_mfma_f32_16x16x32_bf16 v[68:71], v[172:175], v[214:217], v[68:71]
	v_mfma_f32_16x16x32_bf16 v[64:67], v[180:183], v[214:217], v[64:67]
	s_setprio 0
	s_barrier
	s_add_i32 s30, s65, s54
	v_lshl_add_u64 v[164:165], s[36:37], 0, v[146:147]
	s_mov_b32 m0, s30
	ds_read_b128 v[184:187], v171 offset:16384
	ds_read_b128 v[188:191], v171 offset:17408
	ds_read_b128 v[194:197], v171 offset:18432
	ds_read_b128 v[198:201], v171 offset:19456
	ds_read_b128 v[202:205], v171 offset:20480
	ds_read_b128 v[206:209], v171 offset:21504
	ds_read_b128 v[210:213], v171 offset:22528
	ds_read_b128 v[214:217], v171 offset:23552
	global_load_lds_dwordx4 v[164:165], off
	s_add_i32 m0, s30, 0x2000
	s_add_u32 s30, s36, 0x160000
	v_lshl_add_u64 v[218:219], s[36:37], 0, v[150:151]
	s_addc_u32 s31, s37, 0
	s_add_i32 s74, s66, s54
	global_load_lds_dwordx4 v[218:219], off
	v_lshl_add_u64 v[220:221], s[30:31], 0, v[146:147]
	s_mov_b32 m0, s74
	v_lshl_add_u64 v[222:223], s[46:47], 0, v[148:149]
	global_load_lds_dwordx4 v[220:221], off
	v_lshl_add_u64 v[220:221], s[30:31], 0, v[150:151]
	s_add_i32 m0, s74, 0x2000
	s_nop 0
	global_load_lds_dwordx4 v[220:221], off
	v_lshl_add_u64 v[220:221], s[46:47], 0, v[144:145]
	s_mov_b32 m0, s55
	s_nop 0
	global_load_lds_dwordx4 v[220:221], off
	s_mov_b32 m0, s56
	s_nop 0
	global_load_lds_dwordx4 v[222:223], off
	s_waitcnt vmcnt(8)
	s_waitcnt lgkmcnt(0)
	s_barrier
	s_setprio 1
	s_waitcnt lgkmcnt(0)
	v_mfma_f32_16x16x32_bf16 v[60:63], v[124:127], v[184:187], v[60:63]
	v_mfma_f32_16x16x32_bf16 v[56:59], v[136:139], v[184:187], v[56:59]
	v_mfma_f32_16x16x32_bf16 v[44:47], v[124:127], v[194:197], v[44:47]
	v_mfma_f32_16x16x32_bf16 v[40:43], v[136:139], v[194:197], v[40:43]
	v_mfma_f32_16x16x32_bf16 v[28:31], v[124:127], v[202:205], v[28:31]
	v_mfma_f32_16x16x32_bf16 v[24:27], v[136:139], v[202:205], v[24:27]
	v_mfma_f32_16x16x32_bf16 v[12:15], v[124:127], v[210:213], v[12:15]
	v_mfma_f32_16x16x32_bf16 v[8:11], v[136:139], v[210:213], v[8:11]
	v_mfma_f32_16x16x32_bf16 v[60:63], v[132:135], v[188:191], v[60:63]
	v_mfma_f32_16x16x32_bf16 v[56:59], v[140:143], v[188:191], v[56:59]
	v_mfma_f32_16x16x32_bf16 v[44:47], v[132:135], v[198:201], v[44:47]
	v_mfma_f32_16x16x32_bf16 v[40:43], v[140:143], v[198:201], v[40:43]
	v_mfma_f32_16x16x32_bf16 v[28:31], v[132:135], v[206:209], v[28:31]
	v_mfma_f32_16x16x32_bf16 v[24:27], v[140:143], v[206:209], v[24:27]
	v_mfma_f32_16x16x32_bf16 v[12:15], v[132:135], v[214:217], v[12:15]
	v_mfma_f32_16x16x32_bf16 v[8:11], v[140:143], v[214:217], v[8:11]
	s_setprio 0
	s_setprio 1
	v_mfma_f32_16x16x32_bf16 v[52:55], v[160:163], v[184:187], v[52:55]
	v_mfma_f32_16x16x32_bf16 v[48:51], v[176:179], v[184:187], v[48:51]
	v_mfma_f32_16x16x32_bf16 v[36:39], v[160:163], v[194:197], v[36:39]
	v_mfma_f32_16x16x32_bf16 v[32:35], v[176:179], v[194:197], v[32:35]
	v_mfma_f32_16x16x32_bf16 v[20:23], v[160:163], v[202:205], v[20:23]
	v_mfma_f32_16x16x32_bf16 v[16:19], v[176:179], v[202:205], v[16:19]
	v_mfma_f32_16x16x32_bf16 v[4:7], v[160:163], v[210:213], v[4:7]
	v_mfma_f32_16x16x32_bf16 v[0:3], v[176:179], v[210:213], v[0:3]
	v_mfma_f32_16x16x32_bf16 v[52:55], v[172:175], v[188:191], v[52:55]
	v_mfma_f32_16x16x32_bf16 v[48:51], v[180:183], v[188:191], v[48:51]
	v_mfma_f32_16x16x32_bf16 v[36:39], v[172:175], v[198:201], v[36:39]
	v_mfma_f32_16x16x32_bf16 v[32:35], v[180:183], v[198:201], v[32:35]
	v_mfma_f32_16x16x32_bf16 v[20:23], v[172:175], v[206:209], v[20:23]
	v_mfma_f32_16x16x32_bf16 v[16:19], v[180:183], v[206:209], v[16:19]
	v_mfma_f32_16x16x32_bf16 v[4:7], v[172:175], v[214:217], v[4:7]
	v_mfma_f32_16x16x32_bf16 v[0:3], v[180:183], v[214:217], v[0:3]
	s_setprio 0
	s_barrier
; #define PG8_STAGE(bufoff, gbase, voff) do { _Pragma("unroll") for (int _i = 0; _i < 2; ++_i) \
;         __builtin_amdgcn_global_load_lds((const unsigned*)((const char*)(gbase) + (voff)[_i]), (PG8_LAS unsigned*)(lds + (bufoff) + ldsw + _i * 8192), 16, 0, 0); } while (0)
; #define PG8_LDA(dst, b, h) do { _Pragma("unroll") for (int m = 0; m < 4; ++m) _Pragma("unroll") for (int k = 0; k < 2; ++k) dst[m][k] = *(const PG8_LAS bf16x8*)(lds + PG8_SA(b, h) + aoff + m * 2048 + k * 1024); } while (0)
; #define PG8_LDB(dst, b, h) do { _Pragma("unroll") for (int n = 0; n < 2; ++n) _Pragma("unroll") for (int k = 0; k < 2; ++k) dst[n][k] = *(const PG8_LAS bf16x8*)(lds + PG8_SB(b, h) + boff + n * 2048 + k * 1024); } while (0)
; #define PG8_MMA(ai, bj, At, Bt) do { __builtin_amdgcn_s_setprio(1); _Pragma("unroll") for (int m = 0; m < 4; ++m) _Pragma("unroll") for (int n = 0; n < 2; ++n) _Pragma("unroll") for (int k = 0; k < 2; ++k) \
;         acc[ai][bj][m][n] = __builtin_amdgcn_mfma_f32_16x16x32_bf16(Bt[n][k], At[m][k], acc[ai][bj][m][n], 0, 0, 0); __builtin_amdgcn_s_setprio(0); } while (0)
; #define PG8_WAIT_V(n) asm volatile("s_waitcnt vmcnt(" #n ")" ::: "memory")
; #define PG8_WAIT_L(n) asm volatile("s_waitcnt lgkmcnt(" #n ")" ::: "memory")
; #define PG8_BAR __builtin_amdgcn_s_barrier()
; #define PG8_SCHED __builtin_amdgcn_sched_barrier(0)
; template <class Epi, class Sched, bool ALIGN_EPI = false, bool SP2 = false>
; __device__ __forceinline__ void gemm_phase(PG8_LAS unsigned char* lds, const Gemm g, const Sched& S, const Epi& E) {
;     ...
;             PG8_LDB(B0, 1, 0); PG8_LDB(B1, 1, 1); PG8_SCHED; PG8_LDA(At, 1, 0); PG8_STAGE(PG8_SA(0, 1), a2 + hstep, voffA);
;             PG8_WAIT_V(8); PG8_WAIT_L(0); PG8_BAR; PG8_MMA(0, 0, At, B0); PG8_MMA(0, 1, At, B1); PG8_BAR; PG8_SCHED;
	s_add_i32 s74, 0, 0x18000
	s_add_i32 s75, 0, 0x1c000
	v_add_u32_e32 v140, s74, v167
	v_add_u32_e32 v180, s75, v167
	ds_read_b128 v[124:127], v140
	ds_read_b128 v[132:135], v140 offset:1024
	ds_read_b128 v[136:139], v140 offset:2048
	ds_read_b128 v[140:143], v140 offset:3072
	ds_read_b128 v[160:163], v180
	ds_read_b128 v[172:175], v180 offset:1024
	ds_read_b128 v[176:179], v180 offset:2048
	ds_read_b128 v[180:183], v180 offset:3072
	s_add_u32 s30, s46, 0x160000
	s_addc_u32 s31, s47, 0
	s_mov_b32 m0, s57
	v_lshl_add_u64 v[224:225], s[30:31], 0, v[144:145]
	ds_read_b128 v[184:187], v171 offset:32768
	ds_read_b128 v[188:191], v171 offset:33792
	ds_read_b128 v[194:197], v171 offset:34816
	ds_read_b128 v[198:201], v171 offset:35840
	ds_read_b128 v[202:205], v171 offset:36864
	ds_read_b128 v[206:209], v171 offset:37888
	ds_read_b128 v[210:213], v171 offset:38912
	ds_read_b128 v[214:217], v171 offset:39936
	global_load_lds_dwordx4 v[224:225], off
	v_lshl_add_u64 v[224:225], s[30:31], 0, v[148:149]
	s_mov_b32 m0, s58
	s_nop 0
	global_load_lds_dwordx4 v[224:225], off
	s_waitcnt vmcnt(8)
	s_waitcnt lgkmcnt(0)
	s_barrier
	s_setprio 1
	s_waitcnt lgkmcnt(0)
	v_mfma_f32_16x16x32_bf16 v[128:131], v[124:127], v[184:187], v[128:131]
	v_mfma_f32_16x16x32_bf16 v[120:123], v[136:139], v[184:187], v[120:123]
	v_mfma_f32_16x16x32_bf16 v[108:111], v[124:127], v[194:197], v[108:111]
	v_mfma_f32_16x16x32_bf16 v[104:107], v[136:139], v[194:197], v[104:107]
	v_mfma_f32_16x16x32_bf16 v[92:95], v[124:127], v[202:205], v[92:95]
	v_mfma_f32_16x16x32_bf16 v[88:91], v[136:139], v[202:205], v[88:91]
	v_mfma_f32_16x16x32_bf16 v[76:79], v[124:127], v[210:213], v[76:79]
	v_mfma_f32_16x16x32_bf16 v[72:75], v[136:139], v[210:213], v[72:75]
	v_mfma_f32_16x16x32_bf16 v[128:131], v[132:135], v[188:191], v[128:131]
	v_mfma_f32_16x16x32_bf16 v[120:123], v[140:143], v[188:191], v[120:123]
	v_mfma_f32_16x16x32_bf16 v[108:111], v[132:135], v[198:201], v[108:111]
	v_mfma_f32_16x16x32_bf16 v[104:107], v[140:143], v[198:201], v[104:107]
	v_mfma_f32_16x16x32_bf16 v[92:95], v[132:135], v[206:209], v[92:95]
	v_mfma_f32_16x16x32_bf16 v[88:91], v[140:143], v[206:209], v[88:91]
	v_mfma_f32_16x16x32_bf16 v[76:79], v[132:135], v[214:217], v[76:79]
	v_mfma_f32_16x16x32_bf16 v[72:75], v[140:143], v[214:217], v[72:75]
	s_setprio 0
	s_setprio 1
	v_mfma_f32_16x16x32_bf16 v[116:119], v[160:163], v[184:187], v[116:119]
	v_mfma_f32_16x16x32_bf16 v[112:115], v[176:179], v[184:187], v[112:115]
	v_mfma_f32_16x16x32_bf16 v[100:103], v[160:163], v[194:197], v[100:103]
	v_mfma_f32_16x16x32_bf16 v[96:99], v[176:179], v[194:197], v[96:99]
	v_mfma_f32_16x16x32_bf16 v[84:87], v[160:163], v[202:205], v[84:87]
	v_mfma_f32_16x16x32_bf16 v[80:83], v[176:179], v[202:205], v[80:83]
	v_mfma_f32_16x16x32_bf16 v[68:71], v[160:163], v[210:213], v[68:71]
	v_mfma_f32_16x16x32_bf16 v[64:67], v[176:179], v[210:213], v[64:67]
	v_mfma_f32_16x16x32_bf16 v[116:119], v[172:175], v[188:191], v[116:119]
	v_mfma_f32_16x16x32_bf16 v[112:115], v[180:183], v[188:191], v[112:115]
	v_mfma_f32_16x16x32_bf16 v[100:103], v[172:175], v[198:201], v[100:103]
	v_mfma_f32_16x16x32_bf16 v[96:99], v[180:183], v[198:201], v[96:99]
	v_mfma_f32_16x16x32_bf16 v[84:87], v[172:175], v[206:209], v[84:87]
	v_mfma_f32_16x16x32_bf16 v[80:83], v[180:183], v[206:209], v[80:83]
	v_mfma_f32_16x16x32_bf16 v[68:71], v[172:175], v[214:217], v[68:71]
	v_mfma_f32_16x16x32_bf16 v[64:67], v[180:183], v[214:217], v[64:67]
	s_setprio 0
	s_barrier
; #define PG8_STAGE(bufoff, gbase, voff) do { _Pragma("unroll") for (int _i = 0; _i < 2; ++_i) \
;         __builtin_amdgcn_global_load_lds((const unsigned*)((const char*)(gbase) + (voff)[_i]), (PG8_LAS unsigned*)(lds + (bufoff) + ldsw + _i * 8192), 16, 0, 0); } while (0)
; #define PG8_LDA(dst, b, h) do { _Pragma("unroll") for (int m = 0; m < 4; ++m) _Pragma("unroll") for (int k = 0; k < 2; ++k) dst[m][k] = *(const PG8_LAS bf16x8*)(lds + PG8_SA(b, h) + aoff + m * 2048 + k * 1024); } while (0)
; #define PG8_MMA(ai, bj, At, Bt) do { __builtin_amdgcn_s_setprio(1); _Pragma("unroll") for (int m = 0; m < 4; ++m) _Pragma("unroll") for (int n = 0; n < 2; ++n) _Pragma("unroll") for (int k = 0; k < 2; ++k) \
;         acc[ai][bj][m][n] = __builtin_amdgcn_mfma_f32_16x16x32_bf16(Bt[n][k], At[m][k], acc[ai][bj][m][n], 0, 0, 0); __builtin_amdgcn_s_setprio(0); } while (0)
; #define PG8_WAIT_V(n) asm volatile("s_waitcnt vmcnt(" #n ")" ::: "memory")
; #define PG8_WAIT_L(n) asm volatile("s_waitcnt lgkmcnt(" #n ")" ::: "memory")
; #define PG8_BAR __builtin_amdgcn_s_barrier()
; #define PG8_SCHED __builtin_amdgcn_sched_barrier(0)
; template <class Epi, class Sched, bool ALIGN_EPI = false, bool SP2 = false>
; __device__ __forceinline__ void gemm_phase(PG8_LAS unsigned char* lds, const Gemm g, const Sched& S, const Epi& E) {
;     ...
;         for (int t = 0; t < nt; t += 2) {
;             const bool last = (t == nt - 2);
;     ...
;             PG8_LDA(At, 1, 1); PG8_STAGE(PG8_SB(1, 0), b3, voffB); PG8_STAGE(PG8_SB(1, 1), b3 + hstep, voffB); PG8_STAGE(PG8_SA(1, 0), a3, voffA);
;             PG8_WAIT_V(8); PG8_WAIT_L(0); PG8_BAR; PG8_MMA(1, 0, At, B0); PG8_MMA(1, 1, At, B1); PG8_BAR; PG8_SCHED;
	s_add_i32 s30, s74, s54
	v_lshl_add_u64 v[164:165], v[164:165], 0, s[16:17]
	s_mov_b32 m0, s30
	ds_read_b128 v[184:187], v171 offset:49152
	ds_read_b128 v[188:191], v171 offset:50176
	ds_read_b128 v[194:197], v171 offset:51200
	ds_read_b128 v[198:201], v171 offset:52224
	ds_read_b128 v[202:205], v171 offset:53248
	ds_read_b128 v[206:209], v171 offset:54272
	ds_read_b128 v[210:213], v171 offset:55296
	ds_read_b128 v[214:217], v171 offset:56320
	global_load_lds_dwordx4 v[164:165], off
	s_add_i32 m0, s30, 0x2000
	s_add_u32 s30, s36, 0x160080
	v_lshl_add_u64 v[164:165], v[218:219], 0, s[16:17]
	s_addc_u32 s31, s37, 0
	s_add_i32 s36, s75, s54
	global_load_lds_dwordx4 v[164:165], off
	v_lshl_add_u64 v[164:165], s[30:31], 0, v[146:147]
	s_mov_b32 m0, s36
	s_nop 0
	global_load_lds_dwordx4 v[164:165], off
	v_lshl_add_u64 v[164:165], s[30:31], 0, v[150:151]
	s_add_i32 m0, s36, 0x2000
	s_nop 0
	global_load_lds_dwordx4 v[164:165], off
	v_lshl_add_u64 v[164:165], v[220:221], 0, s[16:17]
	s_mov_b32 m0, s62
	s_nop 0
	global_load_lds_dwordx4 v[164:165], off
	v_lshl_add_u64 v[164:165], v[222:223], 0, s[16:17]
	s_mov_b32 m0, s63
	s_nop 0
	global_load_lds_dwordx4 v[164:165], off
	s_waitcnt vmcnt(8)
	s_waitcnt lgkmcnt(0)
	s_barrier
	s_setprio 1
	s_waitcnt lgkmcnt(0)
	v_mfma_f32_16x16x32_bf16 v[60:63], v[124:127], v[184:187], v[60:63]
	v_mfma_f32_16x16x32_bf16 v[56:59], v[136:139], v[184:187], v[56:59]
	v_mfma_f32_16x16x32_bf16 v[44:47], v[124:127], v[194:197], v[44:47]
	v_mfma_f32_16x16x32_bf16 v[40:43], v[136:139], v[194:197], v[40:43]
	v_mfma_f32_16x16x32_bf16 v[28:31], v[124:127], v[202:205], v[28:31]
	v_mfma_f32_16x16x32_bf16 v[24:27], v[136:139], v[202:205], v[24:27]
	v_mfma_f32_16x16x32_bf16 v[12:15], v[124:127], v[210:213], v[12:15]
	v_mfma_f32_16x16x32_bf16 v[8:11], v[136:139], v[210:213], v[8:11]
	v_mfma_f32_16x16x32_bf16 v[60:63], v[132:135], v[188:191], v[60:63]
	v_mfma_f32_16x16x32_bf16 v[56:59], v[140:143], v[188:191], v[56:59]
	v_mfma_f32_16x16x32_bf16 v[44:47], v[132:135], v[198:201], v[44:47]
	v_mfma_f32_16x16x32_bf16 v[40:43], v[140:143], v[198:201], v[40:43]
	v_mfma_f32_16x16x32_bf16 v[28:31], v[132:135], v[206:209], v[28:31]
	v_mfma_f32_16x16x32_bf16 v[24:27], v[140:143], v[206:209], v[24:27]
	v_mfma_f32_16x16x32_bf16 v[12:15], v[132:135], v[214:217], v[12:15]
	v_mfma_f32_16x16x32_bf16 v[8:11], v[140:143], v[214:217], v[8:11]
	s_setprio 0
	s_setprio 1
	v_mfma_f32_16x16x32_bf16 v[52:55], v[160:163], v[184:187], v[52:55]
	v_mfma_f32_16x16x32_bf16 v[48:51], v[176:179], v[184:187], v[48:51]
	v_mfma_f32_16x16x32_bf16 v[36:39], v[160:163], v[194:197], v[36:39]
	v_mfma_f32_16x16x32_bf16 v[32:35], v[176:179], v[194:197], v[32:35]
	v_mfma_f32_16x16x32_bf16 v[20:23], v[160:163], v[202:205], v[20:23]
	v_mfma_f32_16x16x32_bf16 v[16:19], v[176:179], v[202:205], v[16:19]
	v_mfma_f32_16x16x32_bf16 v[4:7], v[160:163], v[210:213], v[4:7]
	v_mfma_f32_16x16x32_bf16 v[0:3], v[176:179], v[210:213], v[0:3]
	v_mfma_f32_16x16x32_bf16 v[52:55], v[172:175], v[188:191], v[52:55]
	v_mfma_f32_16x16x32_bf16 v[48:51], v[180:183], v[188:191], v[48:51]
	v_mfma_f32_16x16x32_bf16 v[36:39], v[172:175], v[198:201], v[36:39]
	v_mfma_f32_16x16x32_bf16 v[32:35], v[180:183], v[198:201], v[32:35]
	v_mfma_f32_16x16x32_bf16 v[20:23], v[172:175], v[206:209], v[20:23]
	v_mfma_f32_16x16x32_bf16 v[16:19], v[180:183], v[206:209], v[16:19]
	v_mfma_f32_16x16x32_bf16 v[4:7], v[172:175], v[214:217], v[4:7]
	v_mfma_f32_16x16x32_bf16 v[0:3], v[180:183], v[214:217], v[0:3]
	s_add_i32 s73, s73, 2
	s_add_u32 s71, s71, 0x100
	s_addc_u32 s72, s72, 0
	s_cmpk_gt_u32 s73, 0x55
	s_mov_b64 s[30:31], s[34:35]
	s_setprio 0
	s_barrier
	s_cbranch_scc0 .LBB0_1250
